# GEMM K-loops: tile-pointer and counter increments moved from the post-MFMA loop tail into the light fourth phase
# speedup vs baseline: 1.0080x; 1.0080x over previous
; #define PG8_STAGE(bufoff, gbase, voff) do { _Pragma("unroll") for (int _i = 0; _i < 2; ++_i) \
;         __builtin_amdgcn_global_load_lds((const unsigned*)((const char*)(gbase) + (voff)[_i]), (PG8_LAS unsigned*)(lds + (bufoff) + ldsw + _i * 8192), 16, 0, 0); } while (0)
; #define PG8_LDA(dst, b, h) do { _Pragma("unroll") for (int m = 0; m < 4; ++m) _Pragma("unroll") for (int k = 0; k < 2; ++k) dst[m][k] = *(const PG8_LAS bf16x8*)(lds + PG8_SA(b, h) + aoff + m * 2048 + k * 1024); } while (0)
; #define PG8_LDB(dst, b, h) do { _Pragma("unroll") for (int n = 0; n < 2; ++n) _Pragma("unroll") for (int k = 0; k < 2; ++k) dst[n][k] = *(const PG8_LAS bf16x8*)(lds + PG8_SB(b, h) + boff + n * 2048 + k * 1024); } while (0)
; #define PG8_MMA(ai, bj, At, Bt) do { __builtin_amdgcn_s_setprio(1); _Pragma("unroll") for (int m = 0; m < 4; ++m) _Pragma("unroll") for (int n = 0; n < 2; ++n) _Pragma("unroll") for (int k = 0; k < 2; ++k) \
;         acc[ai][bj][m][n] = __builtin_amdgcn_mfma_f32_16x16x32_bf16(Bt[n][k], At[m][k], acc[ai][bj][m][n], 0, 0, 0); __builtin_amdgcn_s_setprio(0); } while (0)
; #define PG8_WAIT_V(n) asm volatile("s_waitcnt vmcnt(" #n ")" ::: "memory")
; #define PG8_WAIT_L(n) asm volatile("s_waitcnt lgkmcnt(" #n ")" ::: "memory")
; #define PG8_BAR __builtin_amdgcn_s_barrier()
; #define PG8_SCHED __builtin_amdgcn_sched_barrier(0)
; template <class Epi, class Sched, bool STAMP = false>
; __device__ __forceinline__ void gemm_phase(PG8_LAS unsigned char* lds, const Gemm g, const Sched& S, const Epi& E, unsigned long long* stamps) {
;     ...
;             PG8_LDB(B0, 0, 0); PG8_SCHED; PG8_LDA(At, 0, 0); PG8_STAGE(PG8_SA(1, 1), a1 + hstep, voffA);
;             PG8_WAIT_L(8); PG8_BAR; PG8_WAIT_L(0); PG8_MMA(0, 0, At, B0); PG8_BAR; PG8_SCHED;
;             PG8_LDB(B1, 0, 1); PG8_STAGE(PG8_SB(0, 0), b2, voffB);
;             PG8_BAR; PG8_WAIT_L(0); PG8_MMA(0, 1, At, B1); PG8_BAR;
;             PG8_LDA(At, 0, 1); PG8_STAGE(PG8_SA(0, 0), a2, voffA);
;             PG8_BAR; PG8_WAIT_L(0); PG8_MMA(1, 0, At, B0); PG8_BAR; PG8_SCHED;
;             PG8_STAGE(PG8_SB(0, 1), b2 + hstep, voffB);
;             PG8_WAIT_V(6); PG8_BAR; PG8_MMA(1, 1, At, B1); PG8_BAR;
.LBB0_44:
	s_add_u32 s14, s24, 0xfffc0080
	s_addc_u32 s15, s25, -1
	s_add_i32 s16, 0, 0x10000
	ds_read_b128 v[158:161], v248
	ds_read_b128 v[162:165], v248 offset:1024
	ds_read_b128 v[170:173], v248 offset:2048
	ds_read_b128 v[174:177], v248 offset:3072
	s_cmp_eq_u32 s61, 12
	s_cselect_b32 s31, s7, s15
	s_cselect_b32 s30, s57, s14
	s_cselect_b32 s27, s5, s60
	s_cselect_b32 s26, s58, s59
	s_add_i32 m0, s23, 0xc000
	ds_read_b128 v[178:181], v168
	ds_read_b128 v[192:195], v168 offset:1024
	ds_read_b128 v[196:199], v168 offset:2048
	ds_read_b128 v[200:203], v168 offset:3072
	ds_read_b128 v[204:207], v168 offset:4096
	ds_read_b128 v[208:211], v168 offset:5120
	ds_read_b128 v[212:215], v168 offset:6144
	global_load_lds_dwordx4 v154, s[24:25]
	s_add_i32 m0, s23, 0xe000
	ds_read_b128 v[216:219], v168 offset:7168
	global_load_lds_dwordx4 v156, s[24:25]
	s_waitcnt lgkmcnt(8)
	s_barrier
	s_waitcnt lgkmcnt(0)
	v_mfma_f32_16x16x32_bf16 v[124:127], v[158:161], v[178:181], v[124:127]
	v_mfma_f32_16x16x32_bf16 v[120:123], v[170:173], v[178:181], v[120:123]
	v_mfma_f32_16x16x32_bf16 v[108:111], v[158:161], v[196:199], v[108:111]
	v_mfma_f32_16x16x32_bf16 v[104:107], v[170:173], v[196:199], v[104:107]
	v_mfma_f32_16x16x32_bf16 v[92:95], v[158:161], v[204:207], v[92:95]
	v_mfma_f32_16x16x32_bf16 v[88:91], v[170:173], v[204:207], v[88:91]
	v_mfma_f32_16x16x32_bf16 v[76:79], v[158:161], v[212:215], v[76:79]
	v_mfma_f32_16x16x32_bf16 v[72:75], v[170:173], v[212:215], v[72:75]
	v_mfma_f32_16x16x32_bf16 v[124:127], v[162:165], v[192:195], v[124:127]
	v_mfma_f32_16x16x32_bf16 v[120:123], v[174:177], v[192:195], v[120:123]
	v_mfma_f32_16x16x32_bf16 v[108:111], v[162:165], v[200:203], v[108:111]
	v_mfma_f32_16x16x32_bf16 v[104:107], v[174:177], v[200:203], v[104:107]
	v_mfma_f32_16x16x32_bf16 v[92:95], v[162:165], v[208:211], v[92:95]
	v_mfma_f32_16x16x32_bf16 v[88:91], v[174:177], v[208:211], v[88:91]
	v_mfma_f32_16x16x32_bf16 v[76:79], v[162:165], v[216:219], v[76:79]
	v_mfma_f32_16x16x32_bf16 v[72:75], v[174:177], v[216:219], v[72:75]
	s_barrier
	s_add_i32 s17, 0, 0x14000
	s_add_i32 s14, s16, s43
	s_mov_b32 m0, s14
	ds_read_b128 v[220:223], v249
	ds_read_b128 v[224:227], v249 offset:1024
	ds_read_b128 v[228:231], v249 offset:2048
	global_load_lds_dwordx4 v128, s[26:27]
	s_add_i32 m0, s14, 0x2000
	ds_read_b128 v[232:235], v249 offset:3072
	global_load_lds_dwordx4 v148, s[26:27]
	s_barrier
	s_waitcnt lgkmcnt(0)
	v_mfma_f32_16x16x32_bf16 v[116:119], v[220:223], v[178:181], v[116:119]
	v_mfma_f32_16x16x32_bf16 v[112:115], v[228:231], v[178:181], v[112:115]
	v_mfma_f32_16x16x32_bf16 v[100:103], v[220:223], v[196:199], v[100:103]
	v_mfma_f32_16x16x32_bf16 v[96:99], v[228:231], v[196:199], v[96:99]
	v_mfma_f32_16x16x32_bf16 v[84:87], v[220:223], v[204:207], v[84:87]
	v_mfma_f32_16x16x32_bf16 v[80:83], v[228:231], v[204:207], v[80:83]
	v_mfma_f32_16x16x32_bf16 v[68:71], v[220:223], v[212:215], v[68:71]
	v_mfma_f32_16x16x32_bf16 v[64:67], v[228:231], v[212:215], v[64:67]
	v_mfma_f32_16x16x32_bf16 v[116:119], v[224:227], v[192:195], v[116:119]
	v_mfma_f32_16x16x32_bf16 v[112:115], v[232:235], v[192:195], v[112:115]
	v_mfma_f32_16x16x32_bf16 v[100:103], v[224:227], v[200:203], v[100:103]
	v_mfma_f32_16x16x32_bf16 v[96:99], v[232:235], v[200:203], v[96:99]
	v_mfma_f32_16x16x32_bf16 v[84:87], v[224:227], v[208:211], v[84:87]
	v_mfma_f32_16x16x32_bf16 v[80:83], v[232:235], v[208:211], v[80:83]
	v_mfma_f32_16x16x32_bf16 v[68:71], v[224:227], v[216:219], v[68:71]
	v_mfma_f32_16x16x32_bf16 v[64:67], v[232:235], v[216:219], v[64:67]
	s_mov_b32 m0, s23
	s_barrier
	ds_read_b128 v[178:181], v168 offset:16384
	ds_read_b128 v[192:195], v168 offset:17408
	ds_read_b128 v[196:199], v168 offset:18432
	ds_read_b128 v[200:203], v168 offset:19456
	ds_read_b128 v[204:207], v168 offset:20480
	ds_read_b128 v[208:211], v168 offset:21504
	ds_read_b128 v[212:215], v168 offset:22528
	global_load_lds_dwordx4 v152, s[30:31]
	s_mov_b32 m0, s45
	ds_read_b128 v[216:219], v168 offset:23552
	global_load_lds_dwordx4 v150, s[30:31]
	s_barrier
	s_waitcnt lgkmcnt(0)
	v_mfma_f32_16x16x32_bf16 v[60:63], v[158:161], v[178:181], v[60:63]
	v_mfma_f32_16x16x32_bf16 v[56:59], v[170:173], v[178:181], v[56:59]
	v_mfma_f32_16x16x32_bf16 v[44:47], v[158:161], v[196:199], v[44:47]
	v_mfma_f32_16x16x32_bf16 v[40:43], v[170:173], v[196:199], v[40:43]
	v_mfma_f32_16x16x32_bf16 v[28:31], v[158:161], v[204:207], v[28:31]
	v_mfma_f32_16x16x32_bf16 v[24:27], v[170:173], v[204:207], v[24:27]
	v_mfma_f32_16x16x32_bf16 v[12:15], v[158:161], v[212:215], v[12:15]
	v_mfma_f32_16x16x32_bf16 v[8:11], v[170:173], v[212:215], v[8:11]
	v_mfma_f32_16x16x32_bf16 v[60:63], v[162:165], v[192:195], v[60:63]
	v_mfma_f32_16x16x32_bf16 v[56:59], v[174:177], v[192:195], v[56:59]
	v_mfma_f32_16x16x32_bf16 v[44:47], v[162:165], v[200:203], v[44:47]
	v_mfma_f32_16x16x32_bf16 v[40:43], v[174:177], v[200:203], v[40:43]
	v_mfma_f32_16x16x32_bf16 v[28:31], v[162:165], v[208:211], v[28:31]
	v_mfma_f32_16x16x32_bf16 v[24:27], v[174:177], v[208:211], v[24:27]
	v_mfma_f32_16x16x32_bf16 v[12:15], v[162:165], v[216:219], v[12:15]
	v_mfma_f32_16x16x32_bf16 v[8:11], v[174:177], v[216:219], v[8:11]
	s_barrier
	s_add_u32 s14, s26, 0x40000
	s_addc_u32 s15, s27, 0
	s_add_i32 s16, s17, s43
	s_mov_b32 m0, s16
	s_nop 0
	global_load_lds_dwordx4 v128, s[14:15]
	s_add_i32 m0, s16, 0x2000
	s_nop 0
	global_load_lds_dwordx4 v148, s[14:15]
	s_add_i32 s61, s61, 2
	s_add_u32 s24, s24, 0x100
	s_addc_u32 s25, s25, 0
	s_add_u32 s59, s59, 0x100
	s_addc_u32 s60, s60, 0
	s_waitcnt vmcnt(6)
	s_barrier
; #define PG8_STAGE(bufoff, gbase, voff) do { _Pragma("unroll") for (int _i = 0; _i < 2; ++_i) \
;         __builtin_amdgcn_global_load_lds((const unsigned*)((const char*)(gbase) + (voff)[_i]), (PG8_LAS unsigned*)(lds + (bufoff) + ldsw + _i * 8192), 16, 0, 0); } while (0)
; #define PG8_LDA(dst, b, h) do { _Pragma("unroll") for (int m = 0; m < 4; ++m) _Pragma("unroll") for (int k = 0; k < 2; ++k) dst[m][k] = *(const PG8_LAS bf16x8*)(lds + PG8_SA(b, h) + aoff + m * 2048 + k * 1024); } while (0)
; #define PG8_LDB(dst, b, h) do { _Pragma("unroll") for (int n = 0; n < 2; ++n) _Pragma("unroll") for (int k = 0; k < 2; ++k) dst[n][k] = *(const PG8_LAS bf16x8*)(lds + PG8_SB(b, h) + boff + n * 2048 + k * 1024); } while (0)
; #define PG8_MMA(ai, bj, At, Bt) do { __builtin_amdgcn_s_setprio(1); _Pragma("unroll") for (int m = 0; m < 4; ++m) _Pragma("unroll") for (int n = 0; n < 2; ++n) _Pragma("unroll") for (int k = 0; k < 2; ++k) \
;         acc[ai][bj][m][n] = __builtin_amdgcn_mfma_f32_16x16x32_bf16(Bt[n][k], At[m][k], acc[ai][bj][m][n], 0, 0, 0); __builtin_amdgcn_s_setprio(0); } while (0)
; #define PG8_WAIT_V(n) asm volatile("s_waitcnt vmcnt(" #n ")" ::: "memory")
; #define PG8_WAIT_L(n) asm volatile("s_waitcnt lgkmcnt(" #n ")" ::: "memory")
; #define PG8_BAR __builtin_amdgcn_s_barrier()
; #define PG8_SCHED __builtin_amdgcn_sched_barrier(0)
; template <class Epi, class Sched, bool STAMP = false>
; __device__ __forceinline__ void gemm_phase(PG8_LAS unsigned char* lds, const Gemm g, const Sched& S, const Epi& E, unsigned long long* stamps) {
;     ...
;             PG8_WAIT_V(6); PG8_BAR; PG8_MMA(1, 1, At, B1); PG8_BAR;
;             PG8_LDB(B0, 1, 0); PG8_SCHED; PG8_LDA(At, 1, 0); PG8_STAGE(PG8_SA(0, 1), a2 + hstep, voffA);
;             PG8_WAIT_L(8); PG8_BAR; PG8_WAIT_L(0); PG8_MMA(0, 0, At, B0); PG8_BAR; PG8_SCHED;
;             PG8_LDB(B1, 1, 1); PG8_STAGE(PG8_SB(1, 0), b3, voffB);
;             PG8_BAR; PG8_WAIT_L(0); PG8_MMA(0, 1, At, B1); PG8_BAR;
;             PG8_LDA(At, 1, 1); PG8_STAGE(PG8_SA(1, 0), a3, voffA);
;             PG8_BAR; PG8_WAIT_L(0); PG8_MMA(1, 0, At, B0); PG8_BAR; PG8_SCHED;
	v_mfma_f32_16x16x32_bf16 v[52:55], v[220:223], v[178:181], v[52:55]
	v_mfma_f32_16x16x32_bf16 v[48:51], v[228:231], v[178:181], v[48:51]
	v_mfma_f32_16x16x32_bf16 v[36:39], v[220:223], v[196:199], v[36:39]
	v_mfma_f32_16x16x32_bf16 v[32:35], v[228:231], v[196:199], v[32:35]
	v_mfma_f32_16x16x32_bf16 v[20:23], v[220:223], v[204:207], v[20:23]
	v_mfma_f32_16x16x32_bf16 v[16:19], v[228:231], v[204:207], v[16:19]
	v_mfma_f32_16x16x32_bf16 v[4:7], v[220:223], v[212:215], v[4:7]
	v_mfma_f32_16x16x32_bf16 v[0:3], v[228:231], v[212:215], v[0:3]
	v_mfma_f32_16x16x32_bf16 v[52:55], v[224:227], v[192:195], v[52:55]
	v_mfma_f32_16x16x32_bf16 v[48:51], v[232:235], v[192:195], v[48:51]
	v_mfma_f32_16x16x32_bf16 v[36:39], v[224:227], v[200:203], v[36:39]
	v_mfma_f32_16x16x32_bf16 v[32:35], v[232:235], v[200:203], v[32:35]
	v_mfma_f32_16x16x32_bf16 v[20:23], v[224:227], v[208:211], v[20:23]
	v_mfma_f32_16x16x32_bf16 v[16:19], v[232:235], v[208:211], v[16:19]
	v_mfma_f32_16x16x32_bf16 v[4:7], v[224:227], v[216:219], v[4:7]
	v_mfma_f32_16x16x32_bf16 v[0:3], v[232:235], v[216:219], v[0:3]
	s_add_i32 s16, 0, 0x18000
	s_barrier
	ds_read_b128 v[158:161], v250
	ds_read_b128 v[162:165], v250 offset:1024
	ds_read_b128 v[170:173], v250 offset:2048
	ds_read_b128 v[174:177], v250 offset:3072
	s_add_u32 s14, s30, 0x40000
	s_addc_u32 s15, s31, 0
	s_mov_b32 m0, s46
	ds_read_b128 v[178:181], v168 offset:32768
	ds_read_b128 v[192:195], v168 offset:33792
	ds_read_b128 v[196:199], v168 offset:34816
	ds_read_b128 v[200:203], v168 offset:35840
	ds_read_b128 v[204:207], v168 offset:36864
	ds_read_b128 v[208:211], v168 offset:37888
	ds_read_b128 v[212:215], v168 offset:38912
	global_load_lds_dwordx4 v152, s[14:15]
	s_mov_b32 m0, s47
	ds_read_b128 v[216:219], v168 offset:39936
	global_load_lds_dwordx4 v150, s[14:15]
	s_waitcnt lgkmcnt(8)
	s_barrier
	s_waitcnt lgkmcnt(0)
	v_mfma_f32_16x16x32_bf16 v[124:127], v[158:161], v[178:181], v[124:127]
	v_mfma_f32_16x16x32_bf16 v[120:123], v[170:173], v[178:181], v[120:123]
	v_mfma_f32_16x16x32_bf16 v[108:111], v[158:161], v[196:199], v[108:111]
	v_mfma_f32_16x16x32_bf16 v[104:107], v[170:173], v[196:199], v[104:107]
	v_mfma_f32_16x16x32_bf16 v[92:95], v[158:161], v[204:207], v[92:95]
	v_mfma_f32_16x16x32_bf16 v[88:91], v[170:173], v[204:207], v[88:91]
	v_mfma_f32_16x16x32_bf16 v[76:79], v[158:161], v[212:215], v[76:79]
	v_mfma_f32_16x16x32_bf16 v[72:75], v[170:173], v[212:215], v[72:75]
	v_mfma_f32_16x16x32_bf16 v[124:127], v[162:165], v[192:195], v[124:127]
	v_mfma_f32_16x16x32_bf16 v[120:123], v[174:177], v[192:195], v[120:123]
	v_mfma_f32_16x16x32_bf16 v[108:111], v[162:165], v[200:203], v[108:111]
	v_mfma_f32_16x16x32_bf16 v[104:107], v[174:177], v[200:203], v[104:107]
	v_mfma_f32_16x16x32_bf16 v[92:95], v[162:165], v[208:211], v[92:95]
	v_mfma_f32_16x16x32_bf16 v[88:91], v[174:177], v[208:211], v[88:91]
	v_mfma_f32_16x16x32_bf16 v[76:79], v[162:165], v[216:219], v[76:79]
	v_mfma_f32_16x16x32_bf16 v[72:75], v[174:177], v[216:219], v[72:75]
	s_barrier
	s_add_i32 s17, 0, 0x1c000
	s_add_i32 s14, s16, s43
	s_mov_b32 m0, s14
	ds_read_b128 v[220:223], v251
	ds_read_b128 v[224:227], v251 offset:1024
	ds_read_b128 v[228:231], v251 offset:2048
	global_load_lds_dwordx4 v244, s[26:27]
	s_add_i32 m0, s14, 0x2000
	ds_read_b128 v[232:235], v251 offset:3072
	global_load_lds_dwordx4 v245, s[26:27]
	s_barrier
	s_waitcnt lgkmcnt(0)
	v_mfma_f32_16x16x32_bf16 v[116:119], v[220:223], v[178:181], v[116:119]
	v_mfma_f32_16x16x32_bf16 v[112:115], v[228:231], v[178:181], v[112:115]
	v_mfma_f32_16x16x32_bf16 v[100:103], v[220:223], v[196:199], v[100:103]
	v_mfma_f32_16x16x32_bf16 v[96:99], v[228:231], v[196:199], v[96:99]
	v_mfma_f32_16x16x32_bf16 v[84:87], v[220:223], v[204:207], v[84:87]
	v_mfma_f32_16x16x32_bf16 v[80:83], v[228:231], v[204:207], v[80:83]
	v_mfma_f32_16x16x32_bf16 v[68:71], v[220:223], v[212:215], v[68:71]
	v_mfma_f32_16x16x32_bf16 v[64:67], v[228:231], v[212:215], v[64:67]
	v_mfma_f32_16x16x32_bf16 v[116:119], v[224:227], v[192:195], v[116:119]
	v_mfma_f32_16x16x32_bf16 v[112:115], v[232:235], v[192:195], v[112:115]
	v_mfma_f32_16x16x32_bf16 v[100:103], v[224:227], v[200:203], v[100:103]
	v_mfma_f32_16x16x32_bf16 v[96:99], v[232:235], v[200:203], v[96:99]
	v_mfma_f32_16x16x32_bf16 v[84:87], v[224:227], v[208:211], v[84:87]
	v_mfma_f32_16x16x32_bf16 v[80:83], v[232:235], v[208:211], v[80:83]
	v_mfma_f32_16x16x32_bf16 v[68:71], v[224:227], v[216:219], v[68:71]
	v_mfma_f32_16x16x32_bf16 v[64:67], v[232:235], v[216:219], v[64:67]
	s_mov_b32 m0, s49
	s_barrier
	ds_read_b128 v[178:181], v168 offset:49152
	ds_read_b128 v[192:195], v168 offset:50176
	ds_read_b128 v[196:199], v168 offset:51200
	ds_read_b128 v[200:203], v168 offset:52224
	ds_read_b128 v[204:207], v168 offset:53248
	ds_read_b128 v[208:211], v168 offset:54272
	ds_read_b128 v[212:215], v168 offset:55296
	global_load_lds_dwordx4 v246, s[30:31]
	s_mov_b32 m0, s53
	ds_read_b128 v[216:219], v168 offset:56320
	global_load_lds_dwordx4 v247, s[30:31]
	s_barrier
	s_waitcnt lgkmcnt(0)
	v_mfma_f32_16x16x32_bf16 v[60:63], v[158:161], v[178:181], v[60:63]
	v_mfma_f32_16x16x32_bf16 v[56:59], v[170:173], v[178:181], v[56:59]
	v_mfma_f32_16x16x32_bf16 v[44:47], v[158:161], v[196:199], v[44:47]
	v_mfma_f32_16x16x32_bf16 v[40:43], v[170:173], v[196:199], v[40:43]
	v_mfma_f32_16x16x32_bf16 v[28:31], v[158:161], v[204:207], v[28:31]
	v_mfma_f32_16x16x32_bf16 v[24:27], v[170:173], v[204:207], v[24:27]
	v_mfma_f32_16x16x32_bf16 v[12:15], v[158:161], v[212:215], v[12:15]
	v_mfma_f32_16x16x32_bf16 v[8:11], v[170:173], v[212:215], v[8:11]
	v_mfma_f32_16x16x32_bf16 v[60:63], v[162:165], v[192:195], v[60:63]
	v_mfma_f32_16x16x32_bf16 v[56:59], v[174:177], v[192:195], v[56:59]
	v_mfma_f32_16x16x32_bf16 v[44:47], v[162:165], v[200:203], v[44:47]
	v_mfma_f32_16x16x32_bf16 v[40:43], v[174:177], v[200:203], v[40:43]
	v_mfma_f32_16x16x32_bf16 v[28:31], v[162:165], v[208:211], v[28:31]
	v_mfma_f32_16x16x32_bf16 v[24:27], v[174:177], v[208:211], v[24:27]
	v_mfma_f32_16x16x32_bf16 v[12:15], v[162:165], v[216:219], v[12:15]
	v_mfma_f32_16x16x32_bf16 v[8:11], v[174:177], v[216:219], v[8:11]
	s_barrier
; __device__ __forceinline__ unsigned cvt_pk_bf16(float lo, float hi) { const f32x2_cv v = {lo, hi}; const bf16x2_cv b = __builtin_convertvector(v, bf16x2_cv); return __builtin_bit_cast(unsigned, b); }
; #define PG8_STAGE(bufoff, gbase, voff) do { _Pragma("unroll") for (int _i = 0; _i < 2; ++_i) \
;         __builtin_amdgcn_global_load_lds((const unsigned*)((const char*)(gbase) + (voff)[_i]), (PG8_LAS unsigned*)(lds + (bufoff) + ldsw + _i * 8192), 16, 0, 0); } while (0)
; #define PG8_MMA(ai, bj, At, Bt) do { __builtin_amdgcn_s_setprio(1); _Pragma("unroll") for (int m = 0; m < 4; ++m) _Pragma("unroll") for (int n = 0; n < 2; ++n) _Pragma("unroll") for (int k = 0; k < 2; ++k) \
;         acc[ai][bj][m][n] = __builtin_amdgcn_mfma_f32_16x16x32_bf16(Bt[n][k], At[m][k], acc[ai][bj][m][n], 0, 0, 0); __builtin_amdgcn_s_setprio(0); } while (0)
; #define PG8_WAIT_V(n) asm volatile("s_waitcnt vmcnt(" #n ")" ::: "memory")
; template <class Epi, class Sched, bool STAMP = false>
; __device__ __forceinline__ void gemm_phase(PG8_LAS unsigned char* lds, const Gemm g, const Sched& S, const Epi& E, unsigned long long* stamps) {
;     ...
;             PG8_STAGE(PG8_SB(1, 1), b3 + hstep, voffB);
;             PG8_WAIT_V(6); PG8_BAR; PG8_MMA(1, 1, At, B1); PG8_BAR;
;     __device__ __forceinline__ void operator()(const f32x4 (&acc)[2][2][4][2], const pg8::Unit& u, int wr, int wc, int fr, int fq) const {
;         const int row0 = u.pm * 256 + wr * 64 + fr, col0 = u.pn * 256 + wc * 32 + 8 * fq;
; #pragma unroll
;         for (int ai = 0; ai < 2; ++ai)
; #pragma unroll
;             for (int m = 0; m < 4; ++m) {
;                 const int row = row0 + ai * 128 + m * 16;
;                 const float s = (MODE == 2) ? 1.0f : rstd_of(rowss, row);
;                 bf16_t* rowp = O + (size_t)row * ldc + col0;
; #pragma unroll
;                 for (int bj = 0; bj < 2; ++bj) {
;                     f32x4 v0 = acc[ai][bj][m][0] * s, v1 = acc[ai][bj][m][1] * s;
;                     if (MODE == 1) {
; #pragma unroll
;                         for (int j = 0; j < 4; ++j) { const float a = fmaxf(v0[j], 0.f), b = fmaxf(v1[j], 0.f); v0[j] = a * a; v1[j] = b * b; } }
;                     u32x4 w; w.x = cvt_pk_bf16(v0[0], v0[1]); w.y = cvt_pk_bf16(v0[2], v0[3]); w.z = cvt_pk_bf16(v1[0], v1[1]); w.w = cvt_pk_bf16(v1[2], v1[3]);
;                     *(u32x4*)(rowp + bj * 128) = w; } }
	s_add_u32 s14, s26, 0x40080
	s_addc_u32 s15, s27, 0
	s_add_i32 s16, s17, s43
	s_mov_b32 m0, s16
	s_nop 0
	global_load_lds_dwordx4 v128, s[14:15]
	s_add_i32 m0, s16, 0x2000
	s_nop 0
	global_load_lds_dwordx4 v148, s[14:15]
	s_waitcnt vmcnt(6)
	s_barrier
	v_mfma_f32_16x16x32_bf16 v[52:55], v[220:223], v[178:181], v[52:55]
	v_mfma_f32_16x16x32_bf16 v[48:51], v[228:231], v[178:181], v[48:51]
	v_mfma_f32_16x16x32_bf16 v[36:39], v[220:223], v[196:199], v[36:39]
	v_mfma_f32_16x16x32_bf16 v[32:35], v[228:231], v[196:199], v[32:35]
	v_mfma_f32_16x16x32_bf16 v[20:23], v[220:223], v[204:207], v[20:23]
	v_mfma_f32_16x16x32_bf16 v[16:19], v[228:231], v[204:207], v[16:19]
	v_mfma_f32_16x16x32_bf16 v[4:7], v[220:223], v[212:215], v[4:7]
	v_mfma_f32_16x16x32_bf16 v[0:3], v[228:231], v[212:215], v[0:3]
	v_mfma_f32_16x16x32_bf16 v[52:55], v[224:227], v[192:195], v[52:55]
	v_mfma_f32_16x16x32_bf16 v[48:51], v[232:235], v[192:195], v[48:51]
	v_mfma_f32_16x16x32_bf16 v[36:39], v[224:227], v[200:203], v[36:39]
	v_mfma_f32_16x16x32_bf16 v[32:35], v[232:235], v[200:203], v[32:35]
	v_mfma_f32_16x16x32_bf16 v[20:23], v[224:227], v[208:211], v[20:23]
	v_mfma_f32_16x16x32_bf16 v[16:19], v[232:235], v[208:211], v[16:19]
	v_mfma_f32_16x16x32_bf16 v[4:7], v[224:227], v[216:219], v[4:7]
	v_mfma_f32_16x16x32_bf16 v[0:3], v[232:235], v[216:219], v[0:3]
	s_cmp_gt_u32 s61, 13
	s_barrier
	s_cbranch_scc0 .LBB0_44
	v_lshl_add_u32 v162, s22, 8, v139
	v_ashrrev_i32_e32 v163, 31, v162
	v_lshl_add_u64 v[158:159], v[162:163], 2, s[0:1]
	global_load_dword v164, v[158:159], off
	global_load_dword v193, v[158:159], off offset:64
	global_load_dword v194, v[158:159], off offset:128
	global_load_dword v195, v[158:159], off offset:192
	global_load_dword v196, v[158:159], off offset:512
	global_load_dword v197, v[158:159], off offset:576
	global_load_dword v198, v[158:159], off offset:640
	global_load_dword v199, v[158:159], off offset:704
	v_lshl_or_b32 v160, s56, 8, v167
	v_ashrrev_i32_e32 v161, 31, v160
	s_mov_b32 s5, 0x100000
	s_mov_b64 s[14:15], 0x100000
	s_mov_b32 s56, s4
	s_mov_b32 s22, s6
	s_mov_b64 s[26:27], s[20:21]
	s_mov_b64 s[24:25], s[12:13]
	s_waitcnt vmcnt(0)
	v_fmamk_f32 v164, v164, 0x3a800000, v187
	v_cmp_gt_f32_e32 vcc, s67, v164
	v_mul_f32_e32 v165, 0x4b800000, v164
	s_nop 0
	v_cndmask_b32_e32 v164, v164, v165, vcc
	v_rsq_f32_e32 v164, v164
	s_nop 0
	v_mul_f32_e32 v165, 0x45800000, v164
	v_cndmask_b32_e32 v170, v164, v165, vcc
	v_lshlrev_b64 v[164:165], 13, v[162:163]
	v_pk_mul_f32 v[120:121], v[120:121], v[170:171] op_sel_hi:[1,0]
	v_lshl_add_u64 v[172:173], s[2:3], 0, v[164:165]
	v_lshlrev_b64 v[164:165], 1, v[160:161]
	v_pk_mul_f32 v[126:127], v[126:127], v[170:171] op_sel_hi:[1,0]
	v_pk_mul_f32 v[124:125], v[124:125], v[170:171] op_sel_hi:[1,0]
	v_pk_mul_f32 v[122:123], v[122:123], v[170:171] op_sel_hi:[1,0]
	v_max_f32_e32 v120, 0, v120
	v_max_f32_e32 v121, 0, v121
	v_lshl_add_u64 v[160:161], v[172:173], 0, v[164:165]
	v_max_f32_e32 v124, 0, v124
	v_max_f32_e32 v125, 0, v125
	v_pk_mul_f32 v[172:173], v[120:121], v[120:121]
	v_max_f32_e32 v120, 0, v126
	v_max_f32_e32 v122, 0, v122
	v_max_f32_e32 v121, 0, v127
	v_max_f32_e32 v123, 0, v123
	v_pk_mul_f32 v[124:125], v[124:125], v[124:125]
	v_pk_mul_f32 v[126:127], v[120:121], v[120:121]
	v_pk_mul_f32 v[174:175], v[122:123], v[122:123]
	v_pk_mul_f32 v[112:113], v[112:113], v[170:171] op_sel_hi:[1,0]
	v_cvt_pk_bf16_f32 v120, v124, v125
	v_cvt_pk_bf16_f32 v121, v126, v127
	v_cvt_pk_bf16_f32 v122, v172, v173
	v_cvt_pk_bf16_f32 v123, v174, v175
	v_pk_mul_f32 v[118:119], v[118:119], v[170:171] op_sel_hi:[1,0]
	v_pk_mul_f32 v[116:117], v[116:117], v[170:171] op_sel_hi:[1,0]
	v_pk_mul_f32 v[114:115], v[114:115], v[170:171] op_sel_hi:[1,0]
	v_max_f32_e32 v112, 0, v112
	v_max_f32_e32 v113, 0, v113
	global_store_dwordx4 v[160:161], v[120:123], off
	v_max_f32_e32 v116, 0, v116
	v_max_f32_e32 v117, 0, v117
	v_pk_mul_f32 v[120:121], v[112:113], v[112:113]
	v_max_f32_e32 v112, 0, v118
	v_max_f32_e32 v114, 0, v114
	v_max_f32_e32 v113, 0, v119
	v_max_f32_e32 v115, 0, v115
	v_pk_mul_f32 v[116:117], v[116:117], v[116:117]
	v_pk_mul_f32 v[118:119], v[112:113], v[112:113]
	v_pk_mul_f32 v[122:123], v[114:115], v[114:115]
	v_cvt_pk_bf16_f32 v112, v116, v117
	v_cvt_pk_bf16_f32 v113, v118, v119
	v_cvt_pk_bf16_f32 v114, v120, v121
	v_cvt_pk_bf16_f32 v115, v122, v123
	global_store_dwordx4 v[160:161], v[112:115], off offset:256
	s_nop 1
	v_mov_b32_e32 v114, v193
	s_nop 0
	v_or_b32_e32 v112, 16, v162
	v_ashrrev_i32_e32 v113, 31, v112
	v_lshlrev_b64 v[112:113], 13, v[112:113]
	v_lshl_add_u64 v[112:113], s[2:3], 0, v[112:113]
	v_lshl_add_u64 v[112:113], v[112:113], 0, v[164:165]
	v_fmamk_f32 v114, v114, 0x3a800000, v187
	v_cmp_gt_f32_e32 vcc, s67, v114
	v_mul_f32_e32 v115, 0x4b800000, v114
	s_nop 0
	v_cndmask_b32_e32 v114, v114, v115, vcc
	v_rsq_f32_e32 v114, v114
	s_nop 0
	v_mul_f32_e32 v115, 0x45800000, v114
	v_cndmask_b32_e32 v114, v114, v115, vcc
	v_pk_mul_f32 v[104:105], v[104:105], v[114:115] op_sel_hi:[1,0]
	v_pk_mul_f32 v[110:111], v[110:111], v[114:115] op_sel_hi:[1,0]
	v_pk_mul_f32 v[108:109], v[108:109], v[114:115] op_sel_hi:[1,0]
	v_pk_mul_f32 v[106:107], v[106:107], v[114:115] op_sel_hi:[1,0]
	v_max_f32_e32 v104, 0, v104
	v_max_f32_e32 v105, 0, v105
	v_max_f32_e32 v108, 0, v108
	v_max_f32_e32 v109, 0, v109
	v_pk_mul_f32 v[116:117], v[104:105], v[104:105]
	v_max_f32_e32 v104, 0, v110
	v_max_f32_e32 v106, 0, v106
	v_max_f32_e32 v105, 0, v111
	v_max_f32_e32 v107, 0, v107
	v_pk_mul_f32 v[108:109], v[108:109], v[108:109]
	v_pk_mul_f32 v[110:111], v[104:105], v[104:105]
	v_pk_mul_f32 v[118:119], v[106:107], v[106:107]
; __device__ __forceinline__ unsigned cvt_pk_bf16(float lo, float hi) { const f32x2_cv v = {lo, hi}; const bf16x2_cv b = __builtin_convertvector(v, bf16x2_cv); return __builtin_bit_cast(unsigned, b); }
; __device__ __forceinline__ float rstd_of(const float* rowss, int row) { return rsqrtf(rowss[row] * (1.0f / 1024.0f) + 1e-6f); }
;     __device__ __forceinline__ void operator()(const f32x4 (&acc)[2][2][4][2], const pg8::Unit& u, int wr, int wc, int fr, int fq) const {
;     ...
;             for (int m = 0; m < 4; ++m) {
;                 const int row = row0 + ai * 128 + m * 16;
;                 const float s = (MODE == 2) ? 1.0f : rstd_of(rowss, row);
;                 bf16_t* rowp = O + (size_t)row * ldc + col0;
; #pragma unroll
;                 for (int bj = 0; bj < 2; ++bj) {
;                     f32x4 v0 = acc[ai][bj][m][0] * s, v1 = acc[ai][bj][m][1] * s;
;                     if (MODE == 1) {
; #pragma unroll
;                         for (int j = 0; j < 4; ++j) { const float a = fmaxf(v0[j], 0.f), b = fmaxf(v1[j], 0.f); v0[j] = a * a; v1[j] = b * b; } }
;                     u32x4 w; w.x = cvt_pk_bf16(v0[0], v0[1]); w.y = cvt_pk_bf16(v0[2], v0[3]); w.z = cvt_pk_bf16(v1[0], v1[1]); w.w = cvt_pk_bf16(v1[2], v1[3]);
;                     *(u32x4*)(rowp + bj * 128) = w; } }
	v_pk_mul_f32 v[96:97], v[96:97], v[114:115] op_sel_hi:[1,0]
	v_cvt_pk_bf16_f32 v104, v108, v109
	v_cvt_pk_bf16_f32 v105, v110, v111
	v_cvt_pk_bf16_f32 v106, v116, v117
	v_cvt_pk_bf16_f32 v107, v118, v119
	v_pk_mul_f32 v[102:103], v[102:103], v[114:115] op_sel_hi:[1,0]
	v_pk_mul_f32 v[100:101], v[100:101], v[114:115] op_sel_hi:[1,0]
	v_pk_mul_f32 v[98:99], v[98:99], v[114:115] op_sel_hi:[1,0]
	v_max_f32_e32 v96, 0, v96
	v_max_f32_e32 v97, 0, v97
	global_store_dwordx4 v[112:113], v[104:107], off
	v_max_f32_e32 v100, 0, v100
	v_max_f32_e32 v101, 0, v101
	v_pk_mul_f32 v[104:105], v[96:97], v[96:97]
	v_max_f32_e32 v96, 0, v102
	v_max_f32_e32 v98, 0, v98
	v_max_f32_e32 v97, 0, v103
	v_max_f32_e32 v99, 0, v99
	v_pk_mul_f32 v[100:101], v[100:101], v[100:101]
	v_pk_mul_f32 v[102:103], v[96:97], v[96:97]
	v_pk_mul_f32 v[106:107], v[98:99], v[98:99]
	v_cvt_pk_bf16_f32 v96, v100, v101
	v_cvt_pk_bf16_f32 v97, v102, v103
	v_cvt_pk_bf16_f32 v98, v104, v105
	v_cvt_pk_bf16_f32 v99, v106, v107
	global_store_dwordx4 v[112:113], v[96:99], off offset:256
	s_nop 1
	v_mov_b32_e32 v98, v194
	s_nop 0
	v_or_b32_e32 v96, 32, v162
	v_ashrrev_i32_e32 v97, 31, v96
	v_lshlrev_b64 v[96:97], 13, v[96:97]
	v_lshl_add_u64 v[96:97], s[2:3], 0, v[96:97]
	v_lshl_add_u64 v[96:97], v[96:97], 0, v[164:165]
	v_fmamk_f32 v98, v98, 0x3a800000, v187
	v_cmp_gt_f32_e32 vcc, s67, v98
	v_mul_f32_e32 v99, 0x4b800000, v98
	s_nop 0
	v_cndmask_b32_e32 v98, v98, v99, vcc
	v_rsq_f32_e32 v98, v98
	s_nop 0
	v_mul_f32_e32 v99, 0x45800000, v98
	v_cndmask_b32_e32 v98, v98, v99, vcc
	v_pk_mul_f32 v[88:89], v[88:89], v[98:99] op_sel_hi:[1,0]
	v_pk_mul_f32 v[94:95], v[94:95], v[98:99] op_sel_hi:[1,0]
	v_pk_mul_f32 v[92:93], v[92:93], v[98:99] op_sel_hi:[1,0]
	v_pk_mul_f32 v[90:91], v[90:91], v[98:99] op_sel_hi:[1,0]
	v_max_f32_e32 v88, 0, v88
	v_max_f32_e32 v89, 0, v89
	v_max_f32_e32 v92, 0, v92
	v_max_f32_e32 v93, 0, v93
	v_pk_mul_f32 v[100:101], v[88:89], v[88:89]
	v_max_f32_e32 v88, 0, v94
	v_max_f32_e32 v90, 0, v90
	v_max_f32_e32 v89, 0, v95
	v_max_f32_e32 v91, 0, v91
	v_pk_mul_f32 v[92:93], v[92:93], v[92:93]
	v_pk_mul_f32 v[94:95], v[88:89], v[88:89]
	v_pk_mul_f32 v[102:103], v[90:91], v[90:91]
	v_pk_mul_f32 v[80:81], v[80:81], v[98:99] op_sel_hi:[1,0]
	v_cvt_pk_bf16_f32 v88, v92, v93
	v_cvt_pk_bf16_f32 v89, v94, v95
	v_cvt_pk_bf16_f32 v90, v100, v101
	v_cvt_pk_bf16_f32 v91, v102, v103
	v_pk_mul_f32 v[86:87], v[86:87], v[98:99] op_sel_hi:[1,0]
	v_pk_mul_f32 v[84:85], v[84:85], v[98:99] op_sel_hi:[1,0]
	v_pk_mul_f32 v[82:83], v[82:83], v[98:99] op_sel_hi:[1,0]
	v_max_f32_e32 v80, 0, v80
	v_max_f32_e32 v81, 0, v81
	global_store_dwordx4 v[96:97], v[88:91], off
	v_max_f32_e32 v84, 0, v84
	v_max_f32_e32 v85, 0, v85
	v_pk_mul_f32 v[88:89], v[80:81], v[80:81]
	v_max_f32_e32 v80, 0, v86
	v_max_f32_e32 v82, 0, v82
	v_max_f32_e32 v81, 0, v87
	v_max_f32_e32 v83, 0, v83
	v_pk_mul_f32 v[84:85], v[84:85], v[84:85]
	v_pk_mul_f32 v[86:87], v[80:81], v[80:81]
	v_pk_mul_f32 v[90:91], v[82:83], v[82:83]
	v_cvt_pk_bf16_f32 v80, v84, v85
	v_cvt_pk_bf16_f32 v81, v86, v87
	v_cvt_pk_bf16_f32 v82, v88, v89
	v_cvt_pk_bf16_f32 v83, v90, v91
	global_store_dwordx4 v[96:97], v[80:83], off offset:256
	s_nop 1
	v_mov_b32_e32 v82, v195
	s_nop 0
	v_or_b32_e32 v80, 48, v162
	v_ashrrev_i32_e32 v81, 31, v80
	v_lshlrev_b64 v[80:81], 13, v[80:81]
	v_lshl_add_u64 v[80:81], s[2:3], 0, v[80:81]
	v_lshl_add_u64 v[80:81], v[80:81], 0, v[164:165]
	v_fmamk_f32 v82, v82, 0x3a800000, v187
	v_cmp_gt_f32_e32 vcc, s67, v82
	v_mul_f32_e32 v83, 0x4b800000, v82
	s_nop 0
	v_cndmask_b32_e32 v82, v82, v83, vcc
	v_rsq_f32_e32 v82, v82
	s_nop 0
	v_mul_f32_e32 v83, 0x45800000, v82
	v_cndmask_b32_e32 v82, v82, v83, vcc
	v_pk_mul_f32 v[72:73], v[72:73], v[82:83] op_sel_hi:[1,0]
	v_pk_mul_f32 v[78:79], v[78:79], v[82:83] op_sel_hi:[1,0]
	v_pk_mul_f32 v[76:77], v[76:77], v[82:83] op_sel_hi:[1,0]
	v_pk_mul_f32 v[74:75], v[74:75], v[82:83] op_sel_hi:[1,0]
	v_max_f32_e32 v72, 0, v72
	v_max_f32_e32 v73, 0, v73
	v_max_f32_e32 v76, 0, v76
	v_max_f32_e32 v77, 0, v77
	v_pk_mul_f32 v[84:85], v[72:73], v[72:73]
	v_max_f32_e32 v72, 0, v78
	v_max_f32_e32 v74, 0, v74
	v_max_f32_e32 v73, 0, v79
	v_max_f32_e32 v75, 0, v75
	v_pk_mul_f32 v[76:77], v[76:77], v[76:77]
	v_pk_mul_f32 v[78:79], v[72:73], v[72:73]
	v_pk_mul_f32 v[86:87], v[74:75], v[74:75]
	v_pk_mul_f32 v[64:65], v[64:65], v[82:83] op_sel_hi:[1,0]
	v_cvt_pk_bf16_f32 v72, v76, v77
	v_cvt_pk_bf16_f32 v73, v78, v79
	v_cvt_pk_bf16_f32 v74, v84, v85
	v_cvt_pk_bf16_f32 v75, v86, v87
	v_pk_mul_f32 v[70:71], v[70:71], v[82:83] op_sel_hi:[1,0]
	v_pk_mul_f32 v[68:69], v[68:69], v[82:83] op_sel_hi:[1,0]
	v_pk_mul_f32 v[66:67], v[66:67], v[82:83] op_sel_hi:[1,0]
	v_max_f32_e32 v64, 0, v64
	v_max_f32_e32 v65, 0, v65
	global_store_dwordx4 v[80:81], v[72:75], off
	v_max_f32_e32 v68, 0, v68
	v_max_f32_e32 v69, 0, v69
	v_pk_mul_f32 v[72:73], v[64:65], v[64:65]
	v_max_f32_e32 v64, 0, v70
	v_max_f32_e32 v66, 0, v66
	v_max_f32_e32 v65, 0, v71
	v_max_f32_e32 v67, 0, v67
	v_pk_mul_f32 v[68:69], v[68:69], v[68:69]
	v_pk_mul_f32 v[70:71], v[64:65], v[64:65]
	v_pk_mul_f32 v[74:75], v[66:67], v[66:67]
	v_cvt_pk_bf16_f32 v64, v68, v69
	v_cvt_pk_bf16_f32 v65, v70, v71
	v_cvt_pk_bf16_f32 v66, v72, v73
	v_cvt_pk_bf16_f32 v67, v74, v75
	global_store_dwordx4 v[80:81], v[64:67], off offset:256
	s_nop 1
	v_mov_b32_e32 v64, v196
	v_fmamk_f32 v64, v64, 0x3a800000, v187
	v_cmp_gt_f32_e32 vcc, s67, v64
	v_mul_f32_e32 v65, 0x4b800000, v64
	s_nop 0
	v_cndmask_b32_e32 v64, v64, v65, vcc
	v_rsq_f32_e32 v64, v64
	s_nop 0
	v_mul_f32_e32 v65, 0x45800000, v64
	v_cndmask_b32_e32 v66, v64, v65, vcc
	v_pk_mul_f32 v[60:61], v[60:61], v[66:67] op_sel_hi:[1,0]
; __device__ __forceinline__ unsigned cvt_pk_bf16(float lo, float hi) { const f32x2_cv v = {lo, hi}; const bf16x2_cv b = __builtin_convertvector(v, bf16x2_cv); return __builtin_bit_cast(unsigned, b); }
; __device__ __forceinline__ float rstd_of(const float* rowss, int row) { return rsqrtf(rowss[row] * (1.0f / 1024.0f) + 1e-6f); }
;     __device__ __forceinline__ void operator()(const f32x4 (&acc)[2][2][4][2], const pg8::Unit& u, int wr, int wc, int fr, int fq) const {
;     ...
;             for (int m = 0; m < 4; ++m) {
;                 const int row = row0 + ai * 128 + m * 16;
;                 const float s = (MODE == 2) ? 1.0f : rstd_of(rowss, row);
;                 bf16_t* rowp = O + (size_t)row * ldc + col0;
; #pragma unroll
;                 for (int bj = 0; bj < 2; ++bj) {
;                     f32x4 v0 = acc[ai][bj][m][0] * s, v1 = acc[ai][bj][m][1] * s;
;                     if (MODE == 1) {
; #pragma unroll
;                         for (int j = 0; j < 4; ++j) { const float a = fmaxf(v0[j], 0.f), b = fmaxf(v1[j], 0.f); v0[j] = a * a; v1[j] = b * b; } }
;                     u32x4 w; w.x = cvt_pk_bf16(v0[0], v0[1]); w.y = cvt_pk_bf16(v0[2], v0[3]); w.z = cvt_pk_bf16(v1[0], v1[1]); w.w = cvt_pk_bf16(v1[2], v1[3]);
;                     *(u32x4*)(rowp + bj * 128) = w; } }
	v_pk_mul_f32 v[56:57], v[56:57], v[66:67] op_sel_hi:[1,0]
	v_pk_mul_f32 v[62:63], v[62:63], v[66:67] op_sel_hi:[1,0]
	v_pk_mul_f32 v[58:59], v[58:59], v[66:67] op_sel_hi:[1,0]
	v_max_f32_e32 v60, 0, v60
	v_max_f32_e32 v56, 0, v56
	v_max_f32_e32 v61, 0, v61
	v_max_f32_e32 v57, 0, v57
	v_pk_mul_f32 v[60:61], v[60:61], v[60:61]
	v_pk_mul_f32 v[68:69], v[56:57], v[56:57]
	v_max_f32_e32 v56, 0, v62
	v_max_f32_e32 v58, 0, v58
	v_max_f32_e32 v57, 0, v63
	v_max_f32_e32 v59, 0, v59
	v_pk_mul_f32 v[62:63], v[56:57], v[56:57]
	v_pk_mul_f32 v[70:71], v[58:59], v[58:59]
	v_cvt_pk_bf16_f32 v56, v60, v61
	v_add_co_u32_e32 v60, vcc, s5, v160
	v_pk_mul_f32 v[48:49], v[48:49], v[66:67] op_sel_hi:[1,0]
	v_cvt_pk_bf16_f32 v57, v62, v63
	v_cvt_pk_bf16_f32 v58, v68, v69
	v_cvt_pk_bf16_f32 v59, v70, v71
	v_addc_co_u32_e32 v61, vcc, 0, v161, vcc
	v_pk_mul_f32 v[54:55], v[54:55], v[66:67] op_sel_hi:[1,0]
	v_pk_mul_f32 v[52:53], v[52:53], v[66:67] op_sel_hi:[1,0]
	v_pk_mul_f32 v[50:51], v[50:51], v[66:67] op_sel_hi:[1,0]
	v_max_f32_e32 v48, 0, v48
	v_max_f32_e32 v49, 0, v49
	global_store_dwordx4 v[60:61], v[56:59], off
	v_max_f32_e32 v52, 0, v52
	v_max_f32_e32 v53, 0, v53
	v_pk_mul_f32 v[56:57], v[48:49], v[48:49]
	v_max_f32_e32 v48, 0, v54
	v_max_f32_e32 v50, 0, v50
	v_max_f32_e32 v49, 0, v55
	v_max_f32_e32 v51, 0, v51
	v_pk_mul_f32 v[52:53], v[52:53], v[52:53]
	v_pk_mul_f32 v[54:55], v[48:49], v[48:49]
	v_pk_mul_f32 v[58:59], v[50:51], v[50:51]
	v_lshl_add_u64 v[64:65], v[160:161], 0, s[14:15]
	v_cvt_pk_bf16_f32 v48, v52, v53
	v_cvt_pk_bf16_f32 v49, v54, v55
	v_cvt_pk_bf16_f32 v50, v56, v57
	v_cvt_pk_bf16_f32 v51, v58, v59
	global_store_dwordx4 v[64:65], v[48:51], off offset:256
	s_nop 1
	v_mov_b32_e32 v48, v197
	s_mov_b32 s5, 0x120000
	s_mov_b64 s[14:15], 0x120000
	v_fmamk_f32 v48, v48, 0x3a800000, v187
	v_cmp_gt_f32_e32 vcc, s67, v48
	v_mul_f32_e32 v49, 0x4b800000, v48
	s_nop 0
	v_cndmask_b32_e32 v48, v48, v49, vcc
	v_rsq_f32_e32 v48, v48
	s_nop 0
	v_mul_f32_e32 v49, 0x45800000, v48
	v_cndmask_b32_e32 v50, v48, v49, vcc
	v_pk_mul_f32 v[44:45], v[44:45], v[50:51] op_sel_hi:[1,0]
	v_pk_mul_f32 v[40:41], v[40:41], v[50:51] op_sel_hi:[1,0]
	v_pk_mul_f32 v[46:47], v[46:47], v[50:51] op_sel_hi:[1,0]
	v_pk_mul_f32 v[42:43], v[42:43], v[50:51] op_sel_hi:[1,0]
	v_max_f32_e32 v44, 0, v44
	v_max_f32_e32 v40, 0, v40
	v_max_f32_e32 v45, 0, v45
	v_max_f32_e32 v41, 0, v41
	v_pk_mul_f32 v[44:45], v[44:45], v[44:45]
	v_pk_mul_f32 v[52:53], v[40:41], v[40:41]
	v_max_f32_e32 v40, 0, v46
	v_max_f32_e32 v42, 0, v42
	v_max_f32_e32 v41, 0, v47
	v_max_f32_e32 v43, 0, v43
	v_pk_mul_f32 v[46:47], v[40:41], v[40:41]
	v_pk_mul_f32 v[54:55], v[42:43], v[42:43]
	v_cvt_pk_bf16_f32 v40, v44, v45
	v_add_co_u32_e32 v44, vcc, s5, v160
	v_pk_mul_f32 v[32:33], v[32:33], v[50:51] op_sel_hi:[1,0]
	v_cvt_pk_bf16_f32 v41, v46, v47
	v_cvt_pk_bf16_f32 v42, v52, v53
	v_cvt_pk_bf16_f32 v43, v54, v55
	v_addc_co_u32_e32 v45, vcc, 0, v161, vcc
	v_pk_mul_f32 v[38:39], v[38:39], v[50:51] op_sel_hi:[1,0]
	v_pk_mul_f32 v[36:37], v[36:37], v[50:51] op_sel_hi:[1,0]
	v_pk_mul_f32 v[34:35], v[34:35], v[50:51] op_sel_hi:[1,0]
	v_max_f32_e32 v32, 0, v32
	v_max_f32_e32 v33, 0, v33
	global_store_dwordx4 v[44:45], v[40:43], off
	v_max_f32_e32 v36, 0, v36
	v_max_f32_e32 v37, 0, v37
	v_pk_mul_f32 v[40:41], v[32:33], v[32:33]
	v_max_f32_e32 v32, 0, v38
	v_max_f32_e32 v34, 0, v34
	v_max_f32_e32 v33, 0, v39
	v_max_f32_e32 v35, 0, v35
	v_pk_mul_f32 v[36:37], v[36:37], v[36:37]
	v_pk_mul_f32 v[38:39], v[32:33], v[32:33]
	v_pk_mul_f32 v[42:43], v[34:35], v[34:35]
	v_lshl_add_u64 v[48:49], v[160:161], 0, s[14:15]
	v_cvt_pk_bf16_f32 v32, v36, v37
	v_cvt_pk_bf16_f32 v33, v38, v39
	v_cvt_pk_bf16_f32 v34, v40, v41
	v_cvt_pk_bf16_f32 v35, v42, v43
	global_store_dwordx4 v[48:49], v[32:35], off offset:256
	s_nop 1
	v_mov_b32_e32 v32, v198
	s_mov_b32 s5, 0x140000
	s_mov_b64 s[14:15], 0x140000
	v_fmamk_f32 v32, v32, 0x3a800000, v187
	v_cmp_gt_f32_e32 vcc, s67, v32
	v_mul_f32_e32 v33, 0x4b800000, v32
	s_nop 0
; __device__ __forceinline__ unsigned cvt_pk_bf16(float lo, float hi) { const f32x2_cv v = {lo, hi}; const bf16x2_cv b = __builtin_convertvector(v, bf16x2_cv); return __builtin_bit_cast(unsigned, b); }
; __device__ __forceinline__ float rstd_of(const float* rowss, int row) { return rsqrtf(rowss[row] * (1.0f / 1024.0f) + 1e-6f); }
;     __device__ __forceinline__ void operator()(const f32x4 (&acc)[2][2][4][2], const pg8::Unit& u, int wr, int wc, int fr, int fq) const {
;     ...
;             for (int m = 0; m < 4; ++m) {
;                 const int row = row0 + ai * 128 + m * 16;
;                 const float s = (MODE == 2) ? 1.0f : rstd_of(rowss, row);
;                 bf16_t* rowp = O + (size_t)row * ldc + col0;
; #pragma unroll
;                 for (int bj = 0; bj < 2; ++bj) {
;                     f32x4 v0 = acc[ai][bj][m][0] * s, v1 = acc[ai][bj][m][1] * s;
;                     if (MODE == 1) {
; #pragma unroll
;                         for (int j = 0; j < 4; ++j) { const float a = fmaxf(v0[j], 0.f), b = fmaxf(v1[j], 0.f); v0[j] = a * a; v1[j] = b * b; } }
;                     u32x4 w; w.x = cvt_pk_bf16(v0[0], v0[1]); w.y = cvt_pk_bf16(v0[2], v0[3]); w.z = cvt_pk_bf16(v1[0], v1[1]); w.w = cvt_pk_bf16(v1[2], v1[3]);
;                     *(u32x4*)(rowp + bj * 128) = w; } }
	v_cndmask_b32_e32 v32, v32, v33, vcc
	v_rsq_f32_e32 v32, v32
	s_nop 0
	v_mul_f32_e32 v33, 0x45800000, v32
	v_cndmask_b32_e32 v34, v32, v33, vcc
	v_pk_mul_f32 v[28:29], v[28:29], v[34:35] op_sel_hi:[1,0]
	v_pk_mul_f32 v[24:25], v[24:25], v[34:35] op_sel_hi:[1,0]
	v_pk_mul_f32 v[30:31], v[30:31], v[34:35] op_sel_hi:[1,0]
	v_pk_mul_f32 v[26:27], v[26:27], v[34:35] op_sel_hi:[1,0]
	v_max_f32_e32 v28, 0, v28
	v_max_f32_e32 v24, 0, v24
	v_max_f32_e32 v29, 0, v29
	v_max_f32_e32 v25, 0, v25
	v_pk_mul_f32 v[28:29], v[28:29], v[28:29]
	v_pk_mul_f32 v[36:37], v[24:25], v[24:25]
	v_max_f32_e32 v24, 0, v30
	v_max_f32_e32 v26, 0, v26
	v_max_f32_e32 v25, 0, v31
	v_max_f32_e32 v27, 0, v27
	v_pk_mul_f32 v[30:31], v[24:25], v[24:25]
	v_pk_mul_f32 v[38:39], v[26:27], v[26:27]
	v_cvt_pk_bf16_f32 v24, v28, v29
	v_add_co_u32_e32 v28, vcc, s5, v160
	v_pk_mul_f32 v[16:17], v[16:17], v[34:35] op_sel_hi:[1,0]
	v_cvt_pk_bf16_f32 v25, v30, v31
	v_cvt_pk_bf16_f32 v26, v36, v37
	v_cvt_pk_bf16_f32 v27, v38, v39
	v_addc_co_u32_e32 v29, vcc, 0, v161, vcc
	v_pk_mul_f32 v[22:23], v[22:23], v[34:35] op_sel_hi:[1,0]
	v_pk_mul_f32 v[20:21], v[20:21], v[34:35] op_sel_hi:[1,0]
	v_pk_mul_f32 v[18:19], v[18:19], v[34:35] op_sel_hi:[1,0]
	v_max_f32_e32 v16, 0, v16
	v_max_f32_e32 v17, 0, v17
	global_store_dwordx4 v[28:29], v[24:27], off
	v_max_f32_e32 v20, 0, v20
	v_max_f32_e32 v21, 0, v21
	v_pk_mul_f32 v[24:25], v[16:17], v[16:17]
	v_max_f32_e32 v16, 0, v22
	v_max_f32_e32 v18, 0, v18
	v_max_f32_e32 v17, 0, v23
	v_max_f32_e32 v19, 0, v19
	v_pk_mul_f32 v[20:21], v[20:21], v[20:21]
	v_pk_mul_f32 v[22:23], v[16:17], v[16:17]
	v_pk_mul_f32 v[26:27], v[18:19], v[18:19]
	v_lshl_add_u64 v[32:33], v[160:161], 0, s[14:15]
	v_cvt_pk_bf16_f32 v16, v20, v21
	v_cvt_pk_bf16_f32 v17, v22, v23
	v_cvt_pk_bf16_f32 v18, v24, v25
	v_cvt_pk_bf16_f32 v19, v26, v27
	global_store_dwordx4 v[32:33], v[16:19], off offset:256
	s_nop 1
	v_mov_b32_e32 v16, v199
	s_mov_b32 s5, 0x160000
	s_mov_b64 s[14:15], 0x160000
	v_lshl_add_u64 v[18:19], v[160:161], 0, s[14:15]
	v_fmamk_f32 v16, v16, 0x3a800000, v187
	v_cmp_gt_f32_e32 vcc, s67, v16
	v_mul_f32_e32 v17, 0x4b800000, v16
	s_nop 0
	v_cndmask_b32_e32 v16, v16, v17, vcc
	v_rsq_f32_e32 v16, v16
	s_nop 0
	v_mul_f32_e32 v17, 0x45800000, v16
	v_cndmask_b32_e32 v16, v16, v17, vcc
	v_pk_mul_f32 v[12:13], v[12:13], v[16:17] op_sel_hi:[1,0]
	v_pk_mul_f32 v[8:9], v[8:9], v[16:17] op_sel_hi:[1,0]
	v_pk_mul_f32 v[14:15], v[14:15], v[16:17] op_sel_hi:[1,0]
	v_pk_mul_f32 v[10:11], v[10:11], v[16:17] op_sel_hi:[1,0]
	v_max_f32_e32 v12, 0, v12
	v_max_f32_e32 v8, 0, v8
	v_max_f32_e32 v13, 0, v13
	v_max_f32_e32 v9, 0, v9
	v_pk_mul_f32 v[12:13], v[12:13], v[12:13]
	v_pk_mul_f32 v[20:21], v[8:9], v[8:9]
	v_max_f32_e32 v8, 0, v14
	v_max_f32_e32 v10, 0, v10
	v_max_f32_e32 v9, 0, v15
	v_max_f32_e32 v11, 0, v11
	v_pk_mul_f32 v[14:15], v[8:9], v[8:9]
	v_pk_mul_f32 v[22:23], v[10:11], v[10:11]
	v_cvt_pk_bf16_f32 v8, v12, v13
	v_add_co_u32_e32 v12, vcc, s5, v160
	v_pk_mul_f32 v[0:1], v[0:1], v[16:17] op_sel_hi:[1,0]
	v_cvt_pk_bf16_f32 v9, v14, v15
	v_cvt_pk_bf16_f32 v10, v20, v21
	v_cvt_pk_bf16_f32 v11, v22, v23
	v_addc_co_u32_e32 v13, vcc, 0, v161, vcc
	v_pk_mul_f32 v[6:7], v[6:7], v[16:17] op_sel_hi:[1,0]
	v_pk_mul_f32 v[4:5], v[4:5], v[16:17] op_sel_hi:[1,0]
	v_pk_mul_f32 v[2:3], v[2:3], v[16:17] op_sel_hi:[1,0]
	v_max_f32_e32 v0, 0, v0
	v_max_f32_e32 v1, 0, v1
	global_store_dwordx4 v[12:13], v[8:11], off
	v_max_f32_e32 v4, 0, v4
	v_max_f32_e32 v5, 0, v5
	v_pk_mul_f32 v[8:9], v[0:1], v[0:1]
	v_max_f32_e32 v0, 0, v6
	v_max_f32_e32 v2, 0, v2
	v_max_f32_e32 v1, 0, v7
	v_max_f32_e32 v3, 0, v3
	v_pk_mul_f32 v[4:5], v[4:5], v[4:5]
	v_pk_mul_f32 v[6:7], v[0:1], v[0:1]
	v_pk_mul_f32 v[10:11], v[2:3], v[2:3]
	v_cvt_pk_bf16_f32 v0, v4, v5
	v_cvt_pk_bf16_f32 v1, v6, v7
	v_cvt_pk_bf16_f32 v2, v8, v9
	v_cvt_pk_bf16_f32 v3, v10, v11
	s_and_b64 vcc, exec, s[38:39]
	global_store_dwordx4 v[18:19], v[0:3], off offset:256
	s_cbranch_vccz .LBB0_41
	s_cmpk_gt_u32 s36, 0xff
	s_cbranch_scc1 .LBB0_48
	s_barrier

; #define PG8_STAGE(bufoff, gbase, voff) do { _Pragma("unroll") for (int _i = 0; _i < 2; ++_i) \
;         __builtin_amdgcn_global_load_lds((const unsigned*)((const char*)(gbase) + (voff)[_i]), (PG8_LAS unsigned*)(lds + (bufoff) + ldsw + _i * 8192), 16, 0, 0); } while (0)
; #define PG8_LDA(dst, b, h) do { _Pragma("unroll") for (int m = 0; m < 4; ++m) _Pragma("unroll") for (int k = 0; k < 2; ++k) dst[m][k] = *(const PG8_LAS bf16x8*)(lds + PG8_SA(b, h) + aoff + m * 2048 + k * 1024); } while (0)
; #define PG8_LDB(dst, b, h) do { _Pragma("unroll") for (int n = 0; n < 2; ++n) _Pragma("unroll") for (int k = 0; k < 2; ++k) dst[n][k] = *(const PG8_LAS bf16x8*)(lds + PG8_SB(b, h) + boff + n * 2048 + k * 1024); } while (0)
; #define PG8_MMA(ai, bj, At, Bt) do { __builtin_amdgcn_s_setprio(1); _Pragma("unroll") for (int m = 0; m < 4; ++m) _Pragma("unroll") for (int n = 0; n < 2; ++n) _Pragma("unroll") for (int k = 0; k < 2; ++k) \
;         acc[ai][bj][m][n] = __builtin_amdgcn_mfma_f32_16x16x32_bf16(Bt[n][k], At[m][k], acc[ai][bj][m][n], 0, 0, 0); __builtin_amdgcn_s_setprio(0); } while (0)
; #define PG8_WAIT_V(n) asm volatile("s_waitcnt vmcnt(" #n ")" ::: "memory")
; #define PG8_WAIT_L(n) asm volatile("s_waitcnt lgkmcnt(" #n ")" ::: "memory")
; #define PG8_BAR __builtin_amdgcn_s_barrier()
; #define PG8_SCHED __builtin_amdgcn_sched_barrier(0)
; template <class Epi, class Sched, bool STAMP = false>
; __device__ __forceinline__ void gemm_phase(PG8_LAS unsigned char* lds, const Gemm g, const Sched& S, const Epi& E, unsigned long long* stamps) {
;     ...
;             PG8_LDB(B0, 0, 0); PG8_SCHED; PG8_LDA(At, 0, 0); PG8_STAGE(PG8_SA(1, 1), a1 + hstep, voffA);
;             PG8_WAIT_L(8); PG8_BAR; PG8_WAIT_L(0); PG8_MMA(0, 0, At, B0); PG8_BAR; PG8_SCHED;
;             PG8_LDB(B1, 0, 1); PG8_STAGE(PG8_SB(0, 0), b2, voffB);
;             PG8_BAR; PG8_WAIT_L(0); PG8_MMA(0, 1, At, B1); PG8_BAR;
;             PG8_LDA(At, 0, 1); PG8_STAGE(PG8_SA(0, 0), a2, voffA);
;             PG8_BAR; PG8_WAIT_L(0); PG8_MMA(1, 0, At, B0); PG8_BAR; PG8_SCHED;
;             PG8_STAGE(PG8_SB(0, 1), b2 + hstep, voffB);
;             PG8_WAIT_V(6); PG8_BAR; PG8_MMA(1, 1, At, B1); PG8_BAR;
.LBB0_293:
	s_add_u32 s14, s24, 0xfffe0080
	s_addc_u32 s15, s25, -1
	s_add_i32 s16, 0, 0x10000
	ds_read_b128 v[162:165], v248
	ds_read_b128 v[166:169], v248 offset:1024
	ds_read_b128 v[170:173], v248 offset:2048
	ds_read_b128 v[174:177], v248 offset:3072
	s_cmp_eq_u32 s59, 4
	s_cselect_b32 s31, s7, s15
	s_cselect_b32 s30, s53, s14
	s_cselect_b32 s27, s5, s58
	s_cselect_b32 s26, s56, s57
	s_add_i32 m0, s3, 0xc000
	ds_read_b128 v[178:181], v160
	ds_read_b128 v[192:195], v160 offset:1024
	ds_read_b128 v[196:199], v160 offset:2048
	ds_read_b128 v[200:203], v160 offset:3072
	ds_read_b128 v[204:207], v160 offset:4096
	ds_read_b128 v[208:211], v160 offset:5120
	ds_read_b128 v[212:215], v160 offset:6144
	global_load_lds_dwordx4 v154, s[24:25]
	s_add_i32 m0, s3, 0xe000
	ds_read_b128 v[216:219], v160 offset:7168
	global_load_lds_dwordx4 v156, s[24:25]
	s_waitcnt lgkmcnt(8)
	s_barrier
	s_waitcnt lgkmcnt(0)
	v_mfma_f32_16x16x32_bf16 v[124:127], v[162:165], v[178:181], v[124:127]
	v_mfma_f32_16x16x32_bf16 v[120:123], v[170:173], v[178:181], v[120:123]
	v_mfma_f32_16x16x32_bf16 v[116:119], v[162:165], v[196:199], v[116:119]
	v_mfma_f32_16x16x32_bf16 v[112:115], v[170:173], v[196:199], v[112:115]
	v_mfma_f32_16x16x32_bf16 v[100:103], v[162:165], v[204:207], v[100:103]
	v_mfma_f32_16x16x32_bf16 v[96:99], v[170:173], v[204:207], v[96:99]
	v_mfma_f32_16x16x32_bf16 v[84:87], v[162:165], v[212:215], v[84:87]
	v_mfma_f32_16x16x32_bf16 v[80:83], v[170:173], v[212:215], v[80:83]
	v_mfma_f32_16x16x32_bf16 v[124:127], v[166:169], v[192:195], v[124:127]
	v_mfma_f32_16x16x32_bf16 v[120:123], v[174:177], v[192:195], v[120:123]
	v_mfma_f32_16x16x32_bf16 v[116:119], v[166:169], v[200:203], v[116:119]
	v_mfma_f32_16x16x32_bf16 v[112:115], v[174:177], v[200:203], v[112:115]
	v_mfma_f32_16x16x32_bf16 v[100:103], v[166:169], v[208:211], v[100:103]
	v_mfma_f32_16x16x32_bf16 v[96:99], v[174:177], v[208:211], v[96:99]
	v_mfma_f32_16x16x32_bf16 v[84:87], v[166:169], v[216:219], v[84:87]
	v_mfma_f32_16x16x32_bf16 v[80:83], v[174:177], v[216:219], v[80:83]
	s_barrier
	s_add_i32 s17, 0, 0x14000
	s_add_i32 s14, s16, s40
	s_mov_b32 m0, s14
	ds_read_b128 v[220:223], v249
	ds_read_b128 v[224:227], v249 offset:1024
	ds_read_b128 v[228:231], v249 offset:2048
	global_load_lds_dwordx4 v128, s[26:27]
	s_add_i32 m0, s14, 0x2000
	ds_read_b128 v[232:235], v249 offset:3072
	global_load_lds_dwordx4 v152, s[26:27]
	s_barrier
	s_waitcnt lgkmcnt(0)
	v_mfma_f32_16x16x32_bf16 v[108:111], v[220:223], v[178:181], v[108:111]
	v_mfma_f32_16x16x32_bf16 v[104:107], v[228:231], v[178:181], v[104:107]
	v_mfma_f32_16x16x32_bf16 v[92:95], v[220:223], v[196:199], v[92:95]
	v_mfma_f32_16x16x32_bf16 v[88:91], v[228:231], v[196:199], v[88:91]
	v_mfma_f32_16x16x32_bf16 v[76:79], v[220:223], v[204:207], v[76:79]
	v_mfma_f32_16x16x32_bf16 v[72:75], v[228:231], v[204:207], v[72:75]
	v_mfma_f32_16x16x32_bf16 v[68:71], v[220:223], v[212:215], v[68:71]
	v_mfma_f32_16x16x32_bf16 v[64:67], v[228:231], v[212:215], v[64:67]
	v_mfma_f32_16x16x32_bf16 v[108:111], v[224:227], v[192:195], v[108:111]
	v_mfma_f32_16x16x32_bf16 v[104:107], v[232:235], v[192:195], v[104:107]
	v_mfma_f32_16x16x32_bf16 v[92:95], v[224:227], v[200:203], v[92:95]
	v_mfma_f32_16x16x32_bf16 v[88:91], v[232:235], v[200:203], v[88:91]
	v_mfma_f32_16x16x32_bf16 v[76:79], v[224:227], v[208:211], v[76:79]
	v_mfma_f32_16x16x32_bf16 v[72:75], v[232:235], v[208:211], v[72:75]
	v_mfma_f32_16x16x32_bf16 v[68:71], v[224:227], v[216:219], v[68:71]
	v_mfma_f32_16x16x32_bf16 v[64:67], v[232:235], v[216:219], v[64:67]
	s_mov_b32 m0, s3
	s_barrier
	ds_read_b128 v[178:181], v160 offset:16384
	ds_read_b128 v[192:195], v160 offset:17408
	ds_read_b128 v[196:199], v160 offset:18432
	ds_read_b128 v[200:203], v160 offset:19456
	ds_read_b128 v[204:207], v160 offset:20480
	ds_read_b128 v[208:211], v160 offset:21504
	ds_read_b128 v[212:215], v160 offset:22528
	global_load_lds_dwordx4 v148, s[30:31]
	s_mov_b32 m0, s41
	ds_read_b128 v[216:219], v160 offset:23552
	global_load_lds_dwordx4 v150, s[30:31]
	s_barrier
	s_waitcnt lgkmcnt(0)
	v_mfma_f32_16x16x32_bf16 v[60:63], v[162:165], v[178:181], v[60:63]
	v_mfma_f32_16x16x32_bf16 v[56:59], v[170:173], v[178:181], v[56:59]
	v_mfma_f32_16x16x32_bf16 v[52:55], v[162:165], v[196:199], v[52:55]
	v_mfma_f32_16x16x32_bf16 v[48:51], v[170:173], v[196:199], v[48:51]
	v_mfma_f32_16x16x32_bf16 v[36:39], v[162:165], v[204:207], v[36:39]
	v_mfma_f32_16x16x32_bf16 v[32:35], v[170:173], v[204:207], v[32:35]
	v_mfma_f32_16x16x32_bf16 v[20:23], v[162:165], v[212:215], v[20:23]
	v_mfma_f32_16x16x32_bf16 v[16:19], v[170:173], v[212:215], v[16:19]
	v_mfma_f32_16x16x32_bf16 v[60:63], v[166:169], v[192:195], v[60:63]
	v_mfma_f32_16x16x32_bf16 v[56:59], v[174:177], v[192:195], v[56:59]
	v_mfma_f32_16x16x32_bf16 v[52:55], v[166:169], v[200:203], v[52:55]
	v_mfma_f32_16x16x32_bf16 v[48:51], v[174:177], v[200:203], v[48:51]
	v_mfma_f32_16x16x32_bf16 v[36:39], v[166:169], v[208:211], v[36:39]
	v_mfma_f32_16x16x32_bf16 v[32:35], v[174:177], v[208:211], v[32:35]
	v_mfma_f32_16x16x32_bf16 v[20:23], v[166:169], v[216:219], v[20:23]
	v_mfma_f32_16x16x32_bf16 v[16:19], v[174:177], v[216:219], v[16:19]
	s_barrier
	s_add_u32 s14, s26, 0x20000
	s_addc_u32 s15, s27, 0
	s_add_i32 s16, s17, s40
	s_mov_b32 m0, s16
	s_nop 0
	global_load_lds_dwordx4 v128, s[14:15]
	s_add_i32 m0, s16, 0x2000
	s_nop 0
	global_load_lds_dwordx4 v152, s[14:15]
	s_add_i32 s59, s59, 2
	s_add_u32 s24, s24, 0x100
	s_addc_u32 s25, s25, 0
	s_add_u32 s57, s57, 0x100
	s_addc_u32 s58, s58, 0
	s_waitcnt vmcnt(6)
	s_barrier
; #define PG8_STAGE(bufoff, gbase, voff) do { _Pragma("unroll") for (int _i = 0; _i < 2; ++_i) \
;         __builtin_amdgcn_global_load_lds((const unsigned*)((const char*)(gbase) + (voff)[_i]), (PG8_LAS unsigned*)(lds + (bufoff) + ldsw + _i * 8192), 16, 0, 0); } while (0)
; #define PG8_LDA(dst, b, h) do { _Pragma("unroll") for (int m = 0; m < 4; ++m) _Pragma("unroll") for (int k = 0; k < 2; ++k) dst[m][k] = *(const PG8_LAS bf16x8*)(lds + PG8_SA(b, h) + aoff + m * 2048 + k * 1024); } while (0)
; #define PG8_LDB(dst, b, h) do { _Pragma("unroll") for (int n = 0; n < 2; ++n) _Pragma("unroll") for (int k = 0; k < 2; ++k) dst[n][k] = *(const PG8_LAS bf16x8*)(lds + PG8_SB(b, h) + boff + n * 2048 + k * 1024); } while (0)
; #define PG8_MMA(ai, bj, At, Bt) do { __builtin_amdgcn_s_setprio(1); _Pragma("unroll") for (int m = 0; m < 4; ++m) _Pragma("unroll") for (int n = 0; n < 2; ++n) _Pragma("unroll") for (int k = 0; k < 2; ++k) \
;         acc[ai][bj][m][n] = __builtin_amdgcn_mfma_f32_16x16x32_bf16(Bt[n][k], At[m][k], acc[ai][bj][m][n], 0, 0, 0); __builtin_amdgcn_s_setprio(0); } while (0)
; #define PG8_WAIT_V(n) asm volatile("s_waitcnt vmcnt(" #n ")" ::: "memory")
; #define PG8_WAIT_L(n) asm volatile("s_waitcnt lgkmcnt(" #n ")" ::: "memory")
; #define PG8_BAR __builtin_amdgcn_s_barrier()
; #define PG8_SCHED __builtin_amdgcn_sched_barrier(0)
; template <class Epi, class Sched, bool STAMP = false>
; __device__ __forceinline__ void gemm_phase(PG8_LAS unsigned char* lds, const Gemm g, const Sched& S, const Epi& E, unsigned long long* stamps) {
;     ...
;             PG8_WAIT_V(6); PG8_BAR; PG8_MMA(1, 1, At, B1); PG8_BAR;
;             PG8_LDB(B0, 1, 0); PG8_SCHED; PG8_LDA(At, 1, 0); PG8_STAGE(PG8_SA(0, 1), a2 + hstep, voffA);
;             PG8_WAIT_L(8); PG8_BAR; PG8_WAIT_L(0); PG8_MMA(0, 0, At, B0); PG8_BAR; PG8_SCHED;
;             PG8_LDB(B1, 1, 1); PG8_STAGE(PG8_SB(1, 0), b3, voffB);
;             PG8_BAR; PG8_WAIT_L(0); PG8_MMA(0, 1, At, B1); PG8_BAR;
;             PG8_LDA(At, 1, 1); PG8_STAGE(PG8_SA(1, 0), a3, voffA);
;             PG8_BAR; PG8_WAIT_L(0); PG8_MMA(1, 0, At, B0); PG8_BAR; PG8_SCHED;
	v_mfma_f32_16x16x32_bf16 v[44:47], v[220:223], v[178:181], v[44:47]
	v_mfma_f32_16x16x32_bf16 v[40:43], v[228:231], v[178:181], v[40:43]
	v_mfma_f32_16x16x32_bf16 v[28:31], v[220:223], v[196:199], v[28:31]
	v_mfma_f32_16x16x32_bf16 v[24:27], v[228:231], v[196:199], v[24:27]
	v_mfma_f32_16x16x32_bf16 v[12:15], v[220:223], v[204:207], v[12:15]
	v_mfma_f32_16x16x32_bf16 v[8:11], v[228:231], v[204:207], v[8:11]
	v_mfma_f32_16x16x32_bf16 v[4:7], v[220:223], v[212:215], v[4:7]
	v_mfma_f32_16x16x32_bf16 v[0:3], v[228:231], v[212:215], v[0:3]
	v_mfma_f32_16x16x32_bf16 v[44:47], v[224:227], v[192:195], v[44:47]
	v_mfma_f32_16x16x32_bf16 v[40:43], v[232:235], v[192:195], v[40:43]
	v_mfma_f32_16x16x32_bf16 v[28:31], v[224:227], v[200:203], v[28:31]
	v_mfma_f32_16x16x32_bf16 v[24:27], v[232:235], v[200:203], v[24:27]
	v_mfma_f32_16x16x32_bf16 v[12:15], v[224:227], v[208:211], v[12:15]
	v_mfma_f32_16x16x32_bf16 v[8:11], v[232:235], v[208:211], v[8:11]
	v_mfma_f32_16x16x32_bf16 v[4:7], v[224:227], v[216:219], v[4:7]
	v_mfma_f32_16x16x32_bf16 v[0:3], v[232:235], v[216:219], v[0:3]
	s_add_i32 s16, 0, 0x18000
	s_barrier
	ds_read_b128 v[162:165], v250
	ds_read_b128 v[166:169], v250 offset:1024
	ds_read_b128 v[170:173], v250 offset:2048
	ds_read_b128 v[174:177], v250 offset:3072
	s_add_u32 s14, s30, 0x20000
	s_addc_u32 s15, s31, 0
	s_mov_b32 m0, s42
	ds_read_b128 v[178:181], v160 offset:32768
	ds_read_b128 v[192:195], v160 offset:33792
	ds_read_b128 v[196:199], v160 offset:34816
	ds_read_b128 v[200:203], v160 offset:35840
	ds_read_b128 v[204:207], v160 offset:36864
	ds_read_b128 v[208:211], v160 offset:37888
	ds_read_b128 v[212:215], v160 offset:38912
	global_load_lds_dwordx4 v148, s[14:15]
	s_mov_b32 m0, s43
	ds_read_b128 v[216:219], v160 offset:39936
	global_load_lds_dwordx4 v150, s[14:15]
	s_waitcnt lgkmcnt(8)
	s_barrier
	s_waitcnt lgkmcnt(0)
	v_mfma_f32_16x16x32_bf16 v[124:127], v[162:165], v[178:181], v[124:127]
	v_mfma_f32_16x16x32_bf16 v[120:123], v[170:173], v[178:181], v[120:123]
	v_mfma_f32_16x16x32_bf16 v[116:119], v[162:165], v[196:199], v[116:119]
	v_mfma_f32_16x16x32_bf16 v[112:115], v[170:173], v[196:199], v[112:115]
	v_mfma_f32_16x16x32_bf16 v[100:103], v[162:165], v[204:207], v[100:103]
	v_mfma_f32_16x16x32_bf16 v[96:99], v[170:173], v[204:207], v[96:99]
	v_mfma_f32_16x16x32_bf16 v[84:87], v[162:165], v[212:215], v[84:87]
	v_mfma_f32_16x16x32_bf16 v[80:83], v[170:173], v[212:215], v[80:83]
	v_mfma_f32_16x16x32_bf16 v[124:127], v[166:169], v[192:195], v[124:127]
	v_mfma_f32_16x16x32_bf16 v[120:123], v[174:177], v[192:195], v[120:123]
	v_mfma_f32_16x16x32_bf16 v[116:119], v[166:169], v[200:203], v[116:119]
	v_mfma_f32_16x16x32_bf16 v[112:115], v[174:177], v[200:203], v[112:115]
	v_mfma_f32_16x16x32_bf16 v[100:103], v[166:169], v[208:211], v[100:103]
	v_mfma_f32_16x16x32_bf16 v[96:99], v[174:177], v[208:211], v[96:99]
	v_mfma_f32_16x16x32_bf16 v[84:87], v[166:169], v[216:219], v[84:87]
	v_mfma_f32_16x16x32_bf16 v[80:83], v[174:177], v[216:219], v[80:83]
	s_barrier
	s_add_i32 s17, 0, 0x1c000
	s_add_i32 s14, s16, s40
	s_mov_b32 m0, s14
	ds_read_b128 v[220:223], v251
	ds_read_b128 v[224:227], v251 offset:1024
	ds_read_b128 v[228:231], v251 offset:2048
	global_load_lds_dwordx4 v244, s[26:27]
	s_add_i32 m0, s14, 0x2000
	ds_read_b128 v[232:235], v251 offset:3072
	global_load_lds_dwordx4 v245, s[26:27]
	s_barrier
	s_waitcnt lgkmcnt(0)
	v_mfma_f32_16x16x32_bf16 v[108:111], v[220:223], v[178:181], v[108:111]
	v_mfma_f32_16x16x32_bf16 v[104:107], v[228:231], v[178:181], v[104:107]
	v_mfma_f32_16x16x32_bf16 v[92:95], v[220:223], v[196:199], v[92:95]
	v_mfma_f32_16x16x32_bf16 v[88:91], v[228:231], v[196:199], v[88:91]
	v_mfma_f32_16x16x32_bf16 v[76:79], v[220:223], v[204:207], v[76:79]
	v_mfma_f32_16x16x32_bf16 v[72:75], v[228:231], v[204:207], v[72:75]
	v_mfma_f32_16x16x32_bf16 v[68:71], v[220:223], v[212:215], v[68:71]
	v_mfma_f32_16x16x32_bf16 v[64:67], v[228:231], v[212:215], v[64:67]
	v_mfma_f32_16x16x32_bf16 v[108:111], v[224:227], v[192:195], v[108:111]
	v_mfma_f32_16x16x32_bf16 v[104:107], v[232:235], v[192:195], v[104:107]
	v_mfma_f32_16x16x32_bf16 v[92:95], v[224:227], v[200:203], v[92:95]
	v_mfma_f32_16x16x32_bf16 v[88:91], v[232:235], v[200:203], v[88:91]
	v_mfma_f32_16x16x32_bf16 v[76:79], v[224:227], v[208:211], v[76:79]
	v_mfma_f32_16x16x32_bf16 v[72:75], v[232:235], v[208:211], v[72:75]
	v_mfma_f32_16x16x32_bf16 v[68:71], v[224:227], v[216:219], v[68:71]
	v_mfma_f32_16x16x32_bf16 v[64:67], v[232:235], v[216:219], v[64:67]
	s_mov_b32 m0, s46
	s_barrier
	ds_read_b128 v[178:181], v160 offset:49152
	ds_read_b128 v[192:195], v160 offset:50176
	ds_read_b128 v[196:199], v160 offset:51200
	ds_read_b128 v[200:203], v160 offset:52224
	ds_read_b128 v[204:207], v160 offset:53248
	ds_read_b128 v[208:211], v160 offset:54272
	ds_read_b128 v[212:215], v160 offset:55296
	global_load_lds_dwordx4 v246, s[30:31]
	s_mov_b32 m0, s47
	ds_read_b128 v[216:219], v160 offset:56320
	global_load_lds_dwordx4 v247, s[30:31]
	s_barrier
	s_waitcnt lgkmcnt(0)
	v_mfma_f32_16x16x32_bf16 v[60:63], v[162:165], v[178:181], v[60:63]
	v_mfma_f32_16x16x32_bf16 v[56:59], v[170:173], v[178:181], v[56:59]
	v_mfma_f32_16x16x32_bf16 v[52:55], v[162:165], v[196:199], v[52:55]
	v_mfma_f32_16x16x32_bf16 v[48:51], v[170:173], v[196:199], v[48:51]
	v_mfma_f32_16x16x32_bf16 v[36:39], v[162:165], v[204:207], v[36:39]
	v_mfma_f32_16x16x32_bf16 v[32:35], v[170:173], v[204:207], v[32:35]
	v_mfma_f32_16x16x32_bf16 v[20:23], v[162:165], v[212:215], v[20:23]
	v_mfma_f32_16x16x32_bf16 v[16:19], v[170:173], v[212:215], v[16:19]
	v_mfma_f32_16x16x32_bf16 v[60:63], v[166:169], v[192:195], v[60:63]
	v_mfma_f32_16x16x32_bf16 v[56:59], v[174:177], v[192:195], v[56:59]
	v_mfma_f32_16x16x32_bf16 v[52:55], v[166:169], v[200:203], v[52:55]
	v_mfma_f32_16x16x32_bf16 v[48:51], v[174:177], v[200:203], v[48:51]
	v_mfma_f32_16x16x32_bf16 v[36:39], v[166:169], v[208:211], v[36:39]
	v_mfma_f32_16x16x32_bf16 v[32:35], v[174:177], v[208:211], v[32:35]
	v_mfma_f32_16x16x32_bf16 v[20:23], v[166:169], v[216:219], v[20:23]
	v_mfma_f32_16x16x32_bf16 v[16:19], v[174:177], v[216:219], v[16:19]
	s_barrier
; __device__ __forceinline__ unsigned cvt_pk_bf16(float lo, float hi) { const f32x2_cv v = {lo, hi}; const bf16x2_cv b = __builtin_convertvector(v, bf16x2_cv); return __builtin_bit_cast(unsigned, b); }
; #define PG8_STAGE(bufoff, gbase, voff) do { _Pragma("unroll") for (int _i = 0; _i < 2; ++_i) \
;         __builtin_amdgcn_global_load_lds((const unsigned*)((const char*)(gbase) + (voff)[_i]), (PG8_LAS unsigned*)(lds + (bufoff) + ldsw + _i * 8192), 16, 0, 0); } while (0)
; #define PG8_MMA(ai, bj, At, Bt) do { __builtin_amdgcn_s_setprio(1); _Pragma("unroll") for (int m = 0; m < 4; ++m) _Pragma("unroll") for (int n = 0; n < 2; ++n) _Pragma("unroll") for (int k = 0; k < 2; ++k) \
;         acc[ai][bj][m][n] = __builtin_amdgcn_mfma_f32_16x16x32_bf16(Bt[n][k], At[m][k], acc[ai][bj][m][n], 0, 0, 0); __builtin_amdgcn_s_setprio(0); } while (0)
; #define PG8_WAIT_V(n) asm volatile("s_waitcnt vmcnt(" #n ")" ::: "memory")
; template <class Epi, class Sched, bool STAMP = false>
; __device__ __forceinline__ void gemm_phase(PG8_LAS unsigned char* lds, const Gemm g, const Sched& S, const Epi& E, unsigned long long* stamps) {
;     ...
;             PG8_STAGE(PG8_SB(1, 1), b3 + hstep, voffB);
;             PG8_WAIT_V(6); PG8_BAR; PG8_MMA(1, 1, At, B1); PG8_BAR;
;     __device__ __forceinline__ void operator()(const f32x4 (&acc)[2][2][4][2], const pg8::Unit& u, int wr, int wc, int fr, int fq) const {
;         const int row0 = u.pm * 256 + wr * 64 + fr, col0 = u.pn * 256 + wc * 32 + 8 * fq;
; #pragma unroll
;         for (int ai = 0; ai < 2; ++ai)
; #pragma unroll
;             for (int m = 0; m < 4; ++m) {
;                 const int row = row0 + ai * 128 + m * 16;
;                 const float s = (MODE == 2) ? 1.0f : rstd_of(rowss, row);
;                 bf16_t* rowp = O + (size_t)row * ldc + col0;
; #pragma unroll
;                 for (int bj = 0; bj < 2; ++bj) {
;                     f32x4 v0 = acc[ai][bj][m][0] * s, v1 = acc[ai][bj][m][1] * s;
;                     if (MODE == 1) {
; #pragma unroll
;                         for (int j = 0; j < 4; ++j) { const float a = fmaxf(v0[j], 0.f), b = fmaxf(v1[j], 0.f); v0[j] = a * a; v1[j] = b * b; } }
;                     u32x4 w; w.x = cvt_pk_bf16(v0[0], v0[1]); w.y = cvt_pk_bf16(v0[2], v0[3]); w.z = cvt_pk_bf16(v1[0], v1[1]); w.w = cvt_pk_bf16(v1[2], v1[3]);
;                     *(u32x4*)(rowp + bj * 128) = w; } }
	s_add_u32 s14, s26, 0x20080
	s_addc_u32 s15, s27, 0
	s_add_i32 s16, s17, s40
	s_mov_b32 m0, s16
	s_nop 0
	global_load_lds_dwordx4 v128, s[14:15]
	s_add_i32 m0, s16, 0x2000
	s_nop 0
	global_load_lds_dwordx4 v152, s[14:15]
	s_waitcnt vmcnt(6)
	s_barrier
	v_mfma_f32_16x16x32_bf16 v[44:47], v[220:223], v[178:181], v[44:47]
	v_mfma_f32_16x16x32_bf16 v[40:43], v[228:231], v[178:181], v[40:43]
	v_mfma_f32_16x16x32_bf16 v[28:31], v[220:223], v[196:199], v[28:31]
	v_mfma_f32_16x16x32_bf16 v[24:27], v[228:231], v[196:199], v[24:27]
	v_mfma_f32_16x16x32_bf16 v[12:15], v[220:223], v[204:207], v[12:15]
	v_mfma_f32_16x16x32_bf16 v[8:11], v[228:231], v[204:207], v[8:11]
	v_mfma_f32_16x16x32_bf16 v[4:7], v[220:223], v[212:215], v[4:7]
	v_mfma_f32_16x16x32_bf16 v[0:3], v[228:231], v[212:215], v[0:3]
	v_mfma_f32_16x16x32_bf16 v[44:47], v[224:227], v[192:195], v[44:47]
	v_mfma_f32_16x16x32_bf16 v[40:43], v[232:235], v[192:195], v[40:43]
	v_mfma_f32_16x16x32_bf16 v[28:31], v[224:227], v[200:203], v[28:31]
	v_mfma_f32_16x16x32_bf16 v[24:27], v[232:235], v[200:203], v[24:27]
	v_mfma_f32_16x16x32_bf16 v[12:15], v[224:227], v[208:211], v[12:15]
	v_mfma_f32_16x16x32_bf16 v[8:11], v[232:235], v[208:211], v[8:11]
	v_mfma_f32_16x16x32_bf16 v[4:7], v[224:227], v[216:219], v[4:7]
	v_mfma_f32_16x16x32_bf16 v[0:3], v[232:235], v[216:219], v[0:3]
	s_cmp_gt_u32 s59, 5
	s_barrier
	s_cbranch_scc0 .LBB0_293
	v_lshl_add_u32 v162, s2, 8, v139
	v_lshl_or_b32 v164, s49, 8, v159
	v_ashrrev_i32_e32 v163, 31, v162
	v_ashrrev_i32_e32 v165, 31, v164
	v_lshlrev_b64 v[166:167], 11, v[162:163]
	v_lshl_add_u64 v[166:167], s[0:1], 0, v[166:167]
	v_lshlrev_b64 v[164:165], 1, v[164:165]
	v_lshl_add_u64 v[166:167], v[166:167], 0, v[164:165]
	s_mov_b32 s2, 0x40000
	s_mov_b64 s[14:15], 0x40000
	v_cvt_pk_bf16_f32 v60, v60, v61
	v_cvt_pk_bf16_f32 v61, v62, v63
	v_cvt_pk_bf16_f32 v62, v56, v57
	v_add_co_u32_e32 v56, vcc, s2, v166
	v_cvt_pk_bf16_f32 v68, v68, v69
	v_cvt_pk_bf16_f32 v69, v70, v71
	v_cvt_pk_bf16_f32 v70, v64, v65
	v_lshl_add_u64 v[64:65], v[166:167], 0, s[14:15]
	v_addc_co_u32_e32 v57, vcc, 0, v167, vcc
	v_cvt_pk_bf16_f32 v44, v44, v45
	v_cvt_pk_bf16_f32 v45, v46, v47
	v_cvt_pk_bf16_f32 v46, v40, v41
	v_cvt_pk_bf16_f32 v47, v42, v43
	s_mov_b32 s2, 0x48000
	v_cvt_pk_bf16_f32 v108, v108, v109
	v_cvt_pk_bf16_f32 v109, v110, v111
	v_cvt_pk_bf16_f32 v110, v104, v105
	v_or_b32_e32 v104, 16, v162
	global_store_dwordx4 v[64:65], v[44:47], off offset:256
	s_mov_b64 s[14:15], 0x48000
	v_ashrrev_i32_e32 v105, 31, v104
	v_add_co_u32_e32 v46, vcc, s2, v166
	v_cvt_pk_bf16_f32 v92, v92, v93
	v_cvt_pk_bf16_f32 v93, v94, v95
	v_cvt_pk_bf16_f32 v94, v88, v89
	v_or_b32_e32 v88, 32, v162
	v_lshl_add_u64 v[44:45], v[166:167], 0, s[14:15]
	v_addc_co_u32_e32 v47, vcc, 0, v167, vcc
	v_cvt_pk_bf16_f32 v28, v28, v29
	v_cvt_pk_bf16_f32 v29, v30, v31
	v_cvt_pk_bf16_f32 v30, v24, v25
	v_cvt_pk_bf16_f32 v31, v26, v27
	s_mov_b32 s2, 0x50000
	v_lshlrev_b64 v[104:105], 11, v[104:105]
	v_ashrrev_i32_e32 v89, 31, v88
	v_cvt_pk_bf16_f32 v76, v76, v77
	v_cvt_pk_bf16_f32 v77, v78, v79
	v_cvt_pk_bf16_f32 v78, v72, v73
	v_or_b32_e32 v72, 48, v162
	global_store_dwordx4 v[44:45], v[28:31], off offset:256
	s_mov_b64 s[14:15], 0x50000
	v_cvt_pk_bf16_f32 v111, v106, v107
	v_add_co_u32_e32 v30, vcc, s2, v166
	v_lshl_add_u64 v[104:105], s[0:1], 0, v[104:105]
	v_lshlrev_b64 v[88:89], 11, v[88:89]
	v_ashrrev_i32_e32 v73, 31, v72
	v_lshl_add_u64 v[28:29], v[166:167], 0, s[14:15]
	v_addc_co_u32_e32 v31, vcc, 0, v167, vcc
	v_cvt_pk_bf16_f32 v12, v12, v13
	v_cvt_pk_bf16_f32 v13, v14, v15
	v_cvt_pk_bf16_f32 v14, v8, v9
	v_cvt_pk_bf16_f32 v15, v10, v11
	s_mov_b32 s2, 0x58000
	global_store_dwordx4 v[166:167], v[108:111], off offset:256
	v_cvt_pk_bf16_f32 v95, v90, v91
	v_lshl_add_u64 v[88:89], s[0:1], 0, v[88:89]
	v_lshl_add_u64 v[108:109], v[104:105], 0, v[164:165]
	v_lshlrev_b64 v[72:73], 11, v[72:73]
	global_store_dwordx4 v[28:29], v[12:15], off offset:256
	global_store_dwordx4 v[108:109], v[92:95], off offset:256
	v_cvt_pk_bf16_f32 v79, v74, v75
	v_add_co_u32_e32 v14, vcc, s2, v166
	v_lshl_add_u64 v[92:93], v[88:89], 0, v[164:165]
	v_lshl_add_u64 v[72:73], s[0:1], 0, v[72:73]
	s_mov_b64 s[14:15], 0x58000
	v_addc_co_u32_e32 v15, vcc, 0, v167, vcc
	v_cvt_pk_bf16_f32 v124, v124, v125
	v_cvt_pk_bf16_f32 v125, v126, v127
	v_cvt_pk_bf16_f32 v126, v120, v121
	v_cvt_pk_bf16_f32 v127, v122, v123
	v_cvt_pk_bf16_f32 v104, v116, v117
	v_cvt_pk_bf16_f32 v105, v118, v119
	v_cvt_pk_bf16_f32 v106, v112, v113
	v_cvt_pk_bf16_f32 v107, v114, v115
	v_cvt_pk_bf16_f32 v88, v100, v101
	v_cvt_pk_bf16_f32 v89, v102, v103
	v_cvt_pk_bf16_f32 v90, v96, v97
	v_cvt_pk_bf16_f32 v91, v98, v99
	global_store_dwordx4 v[92:93], v[76:79], off offset:256
	v_cvt_pk_bf16_f32 v74, v80, v81
	v_cvt_pk_bf16_f32 v75, v82, v83
	v_lshl_add_u64 v[76:77], v[72:73], 0, v[164:165]
	v_cvt_pk_bf16_f32 v72, v84, v85
	v_cvt_pk_bf16_f32 v73, v86, v87
	v_cvt_pk_bf16_f32 v71, v66, v67
	v_cvt_pk_bf16_f32 v63, v58, v59
	v_cvt_pk_bf16_f32 v40, v52, v53
	v_cvt_pk_bf16_f32 v41, v54, v55
	v_cvt_pk_bf16_f32 v42, v48, v49
	v_cvt_pk_bf16_f32 v43, v50, v51
	v_cvt_pk_bf16_f32 v24, v36, v37
	v_cvt_pk_bf16_f32 v25, v38, v39
	v_cvt_pk_bf16_f32 v26, v32, v33
	v_cvt_pk_bf16_f32 v27, v34, v35
	v_lshl_add_u64 v[12:13], v[166:167], 0, s[14:15]
	v_cvt_pk_bf16_f32 v8, v20, v21
	v_cvt_pk_bf16_f32 v9, v22, v23
	v_cvt_pk_bf16_f32 v10, v16, v17
	v_cvt_pk_bf16_f32 v11, v18, v19
	v_cvt_pk_bf16_f32 v4, v4, v5
	v_cvt_pk_bf16_f32 v5, v6, v7
	v_cvt_pk_bf16_f32 v6, v0, v1
	v_cvt_pk_bf16_f32 v7, v2, v3
	s_and_b64 vcc, exec, s[38:39]
	s_mov_b32 s49, s4
	s_mov_b32 s2, s6
	s_mov_b64 s[26:27], s[22:23]
	s_mov_b64 s[24:25], s[12:13]
	s_movk_i32 s58, 0xff60
	global_store_dwordx4 v[166:167], v[124:127], off
	global_store_dwordx4 v[108:109], v[104:107], off
	global_store_dwordx4 v[92:93], v[88:91], off
	global_store_dwordx4 v[76:77], v[72:75], off
	global_store_dwordx4 v[76:77], v[68:71], off offset:256
	global_store_dwordx4 v[56:57], v[60:63], off
	global_store_dwordx4 v[46:47], v[40:43], off
	global_store_dwordx4 v[30:31], v[24:27], off
	global_store_dwordx4 v[14:15], v[8:11], off
	global_store_dwordx4 v[12:13], v[4:7], off offset:256
	s_cbranch_vccz .LBB0_286
	s_cmpk_gt_u32 s36, 0xff
	s_cbranch_scc1 .LBB0_297
	s_barrier

; #define PG8_STAGE(bufoff, gbase, voff) do { _Pragma("unroll") for (int _i = 0; _i < 2; ++_i) \
;         __builtin_amdgcn_global_load_lds((const unsigned*)((const char*)(gbase) + (voff)[_i]), (PG8_LAS unsigned*)(lds + (bufoff) + ldsw + _i * 8192), 16, 0, 0); } while (0)
; #define PG8_LDA(dst, b, h) do { _Pragma("unroll") for (int m = 0; m < 4; ++m) _Pragma("unroll") for (int k = 0; k < 2; ++k) dst[m][k] = *(const PG8_LAS bf16x8*)(lds + PG8_SA(b, h) + aoff + m * 2048 + k * 1024); } while (0)
; #define PG8_LDB(dst, b, h) do { _Pragma("unroll") for (int n = 0; n < 2; ++n) _Pragma("unroll") for (int k = 0; k < 2; ++k) dst[n][k] = *(const PG8_LAS bf16x8*)(lds + PG8_SB(b, h) + boff + n * 2048 + k * 1024); } while (0)
; #define PG8_MMA(ai, bj, At, Bt) do { __builtin_amdgcn_s_setprio(1); _Pragma("unroll") for (int m = 0; m < 4; ++m) _Pragma("unroll") for (int n = 0; n < 2; ++n) _Pragma("unroll") for (int k = 0; k < 2; ++k) \
;         acc[ai][bj][m][n] = __builtin_amdgcn_mfma_f32_16x16x32_bf16(Bt[n][k], At[m][k], acc[ai][bj][m][n], 0, 0, 0); __builtin_amdgcn_s_setprio(0); } while (0)
; #define PG8_WAIT_V(n) asm volatile("s_waitcnt vmcnt(" #n ")" ::: "memory")
; #define PG8_WAIT_L(n) asm volatile("s_waitcnt lgkmcnt(" #n ")" ::: "memory")
; #define PG8_BAR __builtin_amdgcn_s_barrier()
; #define PG8_SCHED __builtin_amdgcn_sched_barrier(0)
; template <class Epi, class Sched, bool STAMP = false>
; __device__ __forceinline__ void gemm_phase(PG8_LAS unsigned char* lds, const Gemm g, const Sched& S, const Epi& E, unsigned long long* stamps) {
;     ...
;             PG8_LDB(B0, 0, 0); PG8_SCHED; PG8_LDA(At, 0, 0); PG8_STAGE(PG8_SA(1, 1), a1 + hstep, voffA);
;             PG8_WAIT_L(8); PG8_BAR; PG8_WAIT_L(0); PG8_MMA(0, 0, At, B0); PG8_BAR; PG8_SCHED;
;             PG8_LDB(B1, 0, 1); PG8_STAGE(PG8_SB(0, 0), b2, voffB);
;             PG8_BAR; PG8_WAIT_L(0); PG8_MMA(0, 1, At, B1); PG8_BAR;
;             PG8_LDA(At, 0, 1); PG8_STAGE(PG8_SA(0, 0), a2, voffA);
;             PG8_BAR; PG8_WAIT_L(0); PG8_MMA(1, 0, At, B0); PG8_BAR; PG8_SCHED;
;             PG8_STAGE(PG8_SB(0, 1), b2 + hstep, voffB);
;             PG8_WAIT_V(6); PG8_BAR; PG8_MMA(1, 1, At, B1); PG8_BAR;
.LBB0_313:
	s_add_u32 s12, s4, 0xfffc0080
	s_addc_u32 s13, s5, -1
	s_add_i32 s14, 0, 0x10000
	ds_read_b128 v[158:161], v248
	ds_read_b128 v[162:165], v248 offset:1024
	ds_read_b128 v[170:173], v248 offset:2048
	ds_read_b128 v[174:177], v248 offset:3072
	s_cmp_eq_u32 s65, 12
	s_cselect_b32 s27, s31, s13
	s_cselect_b32 s26, s47, s12
	s_cselect_b32 s13, s7, s63
	s_cselect_b32 s12, s53, s62
	s_add_i32 m0, s3, 0xc000
	ds_read_b128 v[178:181], v169
	ds_read_b128 v[192:195], v169 offset:1024
	ds_read_b128 v[196:199], v169 offset:2048
	ds_read_b128 v[200:203], v169 offset:3072
	ds_read_b128 v[204:207], v169 offset:4096
	ds_read_b128 v[208:211], v169 offset:5120
	ds_read_b128 v[212:215], v169 offset:6144
	global_load_lds_dwordx4 v154, s[4:5]
	s_add_i32 m0, s3, 0xe000
	ds_read_b128 v[216:219], v169 offset:7168
	global_load_lds_dwordx4 v156, s[4:5]
	s_waitcnt lgkmcnt(8)
	s_barrier
	s_waitcnt lgkmcnt(0)
	v_mfma_f32_16x16x32_bf16 v[124:127], v[158:161], v[178:181], v[124:127]
	v_mfma_f32_16x16x32_bf16 v[120:123], v[170:173], v[178:181], v[120:123]
	v_mfma_f32_16x16x32_bf16 v[108:111], v[158:161], v[196:199], v[108:111]
	v_mfma_f32_16x16x32_bf16 v[104:107], v[170:173], v[196:199], v[104:107]
	v_mfma_f32_16x16x32_bf16 v[92:95], v[158:161], v[204:207], v[92:95]
	v_mfma_f32_16x16x32_bf16 v[88:91], v[170:173], v[204:207], v[88:91]
	v_mfma_f32_16x16x32_bf16 v[76:79], v[158:161], v[212:215], v[76:79]
	v_mfma_f32_16x16x32_bf16 v[72:75], v[170:173], v[212:215], v[72:75]
	v_mfma_f32_16x16x32_bf16 v[124:127], v[162:165], v[192:195], v[124:127]
	v_mfma_f32_16x16x32_bf16 v[120:123], v[174:177], v[192:195], v[120:123]
	v_mfma_f32_16x16x32_bf16 v[108:111], v[162:165], v[200:203], v[108:111]
	v_mfma_f32_16x16x32_bf16 v[104:107], v[174:177], v[200:203], v[104:107]
	v_mfma_f32_16x16x32_bf16 v[92:95], v[162:165], v[208:211], v[92:95]
	v_mfma_f32_16x16x32_bf16 v[88:91], v[174:177], v[208:211], v[88:91]
	v_mfma_f32_16x16x32_bf16 v[76:79], v[162:165], v[216:219], v[76:79]
	v_mfma_f32_16x16x32_bf16 v[72:75], v[174:177], v[216:219], v[72:75]
	s_barrier
	s_add_i32 s16, 0, 0x14000
	s_add_i32 s14, s14, s56
	s_mov_b32 m0, s14
	ds_read_b128 v[220:223], v249
	ds_read_b128 v[224:227], v249 offset:1024
	ds_read_b128 v[228:231], v249 offset:2048
	global_load_lds_dwordx4 v128, s[12:13]
	s_add_i32 m0, s14, 0x2000
	ds_read_b128 v[232:235], v249 offset:3072
	global_load_lds_dwordx4 v152, s[12:13]
	s_barrier
	s_waitcnt lgkmcnt(0)
	v_mfma_f32_16x16x32_bf16 v[116:119], v[220:223], v[178:181], v[116:119]
	v_mfma_f32_16x16x32_bf16 v[112:115], v[228:231], v[178:181], v[112:115]
	v_mfma_f32_16x16x32_bf16 v[100:103], v[220:223], v[196:199], v[100:103]
	v_mfma_f32_16x16x32_bf16 v[96:99], v[228:231], v[196:199], v[96:99]
	v_mfma_f32_16x16x32_bf16 v[84:87], v[220:223], v[204:207], v[84:87]
	v_mfma_f32_16x16x32_bf16 v[80:83], v[228:231], v[204:207], v[80:83]
	v_mfma_f32_16x16x32_bf16 v[68:71], v[220:223], v[212:215], v[68:71]
	v_mfma_f32_16x16x32_bf16 v[64:67], v[228:231], v[212:215], v[64:67]
	v_mfma_f32_16x16x32_bf16 v[116:119], v[224:227], v[192:195], v[116:119]
	v_mfma_f32_16x16x32_bf16 v[112:115], v[232:235], v[192:195], v[112:115]
	v_mfma_f32_16x16x32_bf16 v[100:103], v[224:227], v[200:203], v[100:103]
	v_mfma_f32_16x16x32_bf16 v[96:99], v[232:235], v[200:203], v[96:99]
	v_mfma_f32_16x16x32_bf16 v[84:87], v[224:227], v[208:211], v[84:87]
	v_mfma_f32_16x16x32_bf16 v[80:83], v[232:235], v[208:211], v[80:83]
	v_mfma_f32_16x16x32_bf16 v[68:71], v[224:227], v[216:219], v[68:71]
	v_mfma_f32_16x16x32_bf16 v[64:67], v[232:235], v[216:219], v[64:67]
	s_mov_b32 m0, s3
	s_barrier
	ds_read_b128 v[178:181], v169 offset:16384
	ds_read_b128 v[192:195], v169 offset:17408
	ds_read_b128 v[196:199], v169 offset:18432
	ds_read_b128 v[200:203], v169 offset:19456
	ds_read_b128 v[204:207], v169 offset:20480
	ds_read_b128 v[208:211], v169 offset:21504
	ds_read_b128 v[212:215], v169 offset:22528
	global_load_lds_dwordx4 v148, s[26:27]
	s_mov_b32 m0, s57
	ds_read_b128 v[216:219], v169 offset:23552
	global_load_lds_dwordx4 v150, s[26:27]
	s_barrier
	s_waitcnt lgkmcnt(0)
	v_mfma_f32_16x16x32_bf16 v[60:63], v[158:161], v[178:181], v[60:63]
	v_mfma_f32_16x16x32_bf16 v[56:59], v[170:173], v[178:181], v[56:59]
	v_mfma_f32_16x16x32_bf16 v[44:47], v[158:161], v[196:199], v[44:47]
	v_mfma_f32_16x16x32_bf16 v[40:43], v[170:173], v[196:199], v[40:43]
	v_mfma_f32_16x16x32_bf16 v[28:31], v[158:161], v[204:207], v[28:31]
	v_mfma_f32_16x16x32_bf16 v[24:27], v[170:173], v[204:207], v[24:27]
	v_mfma_f32_16x16x32_bf16 v[12:15], v[158:161], v[212:215], v[12:15]
	v_mfma_f32_16x16x32_bf16 v[8:11], v[170:173], v[212:215], v[8:11]
	v_mfma_f32_16x16x32_bf16 v[60:63], v[162:165], v[192:195], v[60:63]
	v_mfma_f32_16x16x32_bf16 v[56:59], v[174:177], v[192:195], v[56:59]
	v_mfma_f32_16x16x32_bf16 v[44:47], v[162:165], v[200:203], v[44:47]
	v_mfma_f32_16x16x32_bf16 v[40:43], v[174:177], v[200:203], v[40:43]
	v_mfma_f32_16x16x32_bf16 v[28:31], v[162:165], v[208:211], v[28:31]
	v_mfma_f32_16x16x32_bf16 v[24:27], v[174:177], v[208:211], v[24:27]
	v_mfma_f32_16x16x32_bf16 v[12:15], v[162:165], v[216:219], v[12:15]
	v_mfma_f32_16x16x32_bf16 v[8:11], v[174:177], v[216:219], v[8:11]
	s_barrier
	s_add_u32 s14, s12, 0x40000
	s_addc_u32 s15, s13, 0
	s_add_i32 s16, s16, s56
	s_mov_b32 m0, s16
	s_nop 0
	global_load_lds_dwordx4 v128, s[14:15]
	s_add_i32 m0, s16, 0x2000
	s_nop 0
	global_load_lds_dwordx4 v152, s[14:15]
	s_add_i32 s65, s65, 2
	s_add_u32 s4, s4, 0x100
	s_addc_u32 s5, s5, 0
	s_add_u32 s62, s62, 0x100
	s_addc_u32 s63, s63, 0
	s_waitcnt vmcnt(6)
	s_barrier
; #define PG8_STAGE(bufoff, gbase, voff) do { _Pragma("unroll") for (int _i = 0; _i < 2; ++_i) \
;         __builtin_amdgcn_global_load_lds((const unsigned*)((const char*)(gbase) + (voff)[_i]), (PG8_LAS unsigned*)(lds + (bufoff) + ldsw + _i * 8192), 16, 0, 0); } while (0)
; #define PG8_LDA(dst, b, h) do { _Pragma("unroll") for (int m = 0; m < 4; ++m) _Pragma("unroll") for (int k = 0; k < 2; ++k) dst[m][k] = *(const PG8_LAS bf16x8*)(lds + PG8_SA(b, h) + aoff + m * 2048 + k * 1024); } while (0)
; #define PG8_LDB(dst, b, h) do { _Pragma("unroll") for (int n = 0; n < 2; ++n) _Pragma("unroll") for (int k = 0; k < 2; ++k) dst[n][k] = *(const PG8_LAS bf16x8*)(lds + PG8_SB(b, h) + boff + n * 2048 + k * 1024); } while (0)
; #define PG8_MMA(ai, bj, At, Bt) do { __builtin_amdgcn_s_setprio(1); _Pragma("unroll") for (int m = 0; m < 4; ++m) _Pragma("unroll") for (int n = 0; n < 2; ++n) _Pragma("unroll") for (int k = 0; k < 2; ++k) \
;         acc[ai][bj][m][n] = __builtin_amdgcn_mfma_f32_16x16x32_bf16(Bt[n][k], At[m][k], acc[ai][bj][m][n], 0, 0, 0); __builtin_amdgcn_s_setprio(0); } while (0)
; #define PG8_WAIT_V(n) asm volatile("s_waitcnt vmcnt(" #n ")" ::: "memory")
; #define PG8_WAIT_L(n) asm volatile("s_waitcnt lgkmcnt(" #n ")" ::: "memory")
; #define PG8_BAR __builtin_amdgcn_s_barrier()
; #define PG8_SCHED __builtin_amdgcn_sched_barrier(0)
; template <class Epi, class Sched, bool STAMP = false>
; __device__ __forceinline__ void gemm_phase(PG8_LAS unsigned char* lds, const Gemm g, const Sched& S, const Epi& E, unsigned long long* stamps) {
;     ...
;             PG8_WAIT_V(6); PG8_BAR; PG8_MMA(1, 1, At, B1); PG8_BAR;
;             PG8_LDB(B0, 1, 0); PG8_SCHED; PG8_LDA(At, 1, 0); PG8_STAGE(PG8_SA(0, 1), a2 + hstep, voffA);
;             PG8_WAIT_L(8); PG8_BAR; PG8_WAIT_L(0); PG8_MMA(0, 0, At, B0); PG8_BAR; PG8_SCHED;
;             PG8_LDB(B1, 1, 1); PG8_STAGE(PG8_SB(1, 0), b3, voffB);
;             PG8_BAR; PG8_WAIT_L(0); PG8_MMA(0, 1, At, B1); PG8_BAR;
;             PG8_LDA(At, 1, 1); PG8_STAGE(PG8_SA(1, 0), a3, voffA);
;             PG8_BAR; PG8_WAIT_L(0); PG8_MMA(1, 0, At, B0); PG8_BAR; PG8_SCHED;
	v_mfma_f32_16x16x32_bf16 v[52:55], v[220:223], v[178:181], v[52:55]
	v_mfma_f32_16x16x32_bf16 v[48:51], v[228:231], v[178:181], v[48:51]
	v_mfma_f32_16x16x32_bf16 v[36:39], v[220:223], v[196:199], v[36:39]
	v_mfma_f32_16x16x32_bf16 v[32:35], v[228:231], v[196:199], v[32:35]
	v_mfma_f32_16x16x32_bf16 v[20:23], v[220:223], v[204:207], v[20:23]
	v_mfma_f32_16x16x32_bf16 v[16:19], v[228:231], v[204:207], v[16:19]
	v_mfma_f32_16x16x32_bf16 v[4:7], v[220:223], v[212:215], v[4:7]
	v_mfma_f32_16x16x32_bf16 v[0:3], v[228:231], v[212:215], v[0:3]
	v_mfma_f32_16x16x32_bf16 v[52:55], v[224:227], v[192:195], v[52:55]
	v_mfma_f32_16x16x32_bf16 v[48:51], v[232:235], v[192:195], v[48:51]
	v_mfma_f32_16x16x32_bf16 v[36:39], v[224:227], v[200:203], v[36:39]
	v_mfma_f32_16x16x32_bf16 v[32:35], v[232:235], v[200:203], v[32:35]
	v_mfma_f32_16x16x32_bf16 v[20:23], v[224:227], v[208:211], v[20:23]
	v_mfma_f32_16x16x32_bf16 v[16:19], v[232:235], v[208:211], v[16:19]
	v_mfma_f32_16x16x32_bf16 v[4:7], v[224:227], v[216:219], v[4:7]
	v_mfma_f32_16x16x32_bf16 v[0:3], v[232:235], v[216:219], v[0:3]
	s_add_i32 s16, 0, 0x18000
	s_barrier
	ds_read_b128 v[158:161], v250
	ds_read_b128 v[162:165], v250 offset:1024
	ds_read_b128 v[170:173], v250 offset:2048
	ds_read_b128 v[174:177], v250 offset:3072
	s_add_u32 s14, s26, 0x40000
	s_addc_u32 s15, s27, 0
	s_mov_b32 m0, s58
	ds_read_b128 v[178:181], v169 offset:32768
	ds_read_b128 v[192:195], v169 offset:33792
	ds_read_b128 v[196:199], v169 offset:34816
	ds_read_b128 v[200:203], v169 offset:35840
	ds_read_b128 v[204:207], v169 offset:36864
	ds_read_b128 v[208:211], v169 offset:37888
	ds_read_b128 v[212:215], v169 offset:38912
	global_load_lds_dwordx4 v148, s[14:15]
	s_mov_b32 m0, s59
	ds_read_b128 v[216:219], v169 offset:39936
	global_load_lds_dwordx4 v150, s[14:15]
	s_waitcnt lgkmcnt(8)
	s_barrier
	s_waitcnt lgkmcnt(0)
	v_mfma_f32_16x16x32_bf16 v[124:127], v[158:161], v[178:181], v[124:127]
	v_mfma_f32_16x16x32_bf16 v[120:123], v[170:173], v[178:181], v[120:123]
	v_mfma_f32_16x16x32_bf16 v[108:111], v[158:161], v[196:199], v[108:111]
	v_mfma_f32_16x16x32_bf16 v[104:107], v[170:173], v[196:199], v[104:107]
	v_mfma_f32_16x16x32_bf16 v[92:95], v[158:161], v[204:207], v[92:95]
	v_mfma_f32_16x16x32_bf16 v[88:91], v[170:173], v[204:207], v[88:91]
	v_mfma_f32_16x16x32_bf16 v[76:79], v[158:161], v[212:215], v[76:79]
	v_mfma_f32_16x16x32_bf16 v[72:75], v[170:173], v[212:215], v[72:75]
	v_mfma_f32_16x16x32_bf16 v[124:127], v[162:165], v[192:195], v[124:127]
	v_mfma_f32_16x16x32_bf16 v[120:123], v[174:177], v[192:195], v[120:123]
	v_mfma_f32_16x16x32_bf16 v[108:111], v[162:165], v[200:203], v[108:111]
	v_mfma_f32_16x16x32_bf16 v[104:107], v[174:177], v[200:203], v[104:107]
	v_mfma_f32_16x16x32_bf16 v[92:95], v[162:165], v[208:211], v[92:95]
	v_mfma_f32_16x16x32_bf16 v[88:91], v[174:177], v[208:211], v[88:91]
	v_mfma_f32_16x16x32_bf16 v[76:79], v[162:165], v[216:219], v[76:79]
	v_mfma_f32_16x16x32_bf16 v[72:75], v[174:177], v[216:219], v[72:75]
	s_barrier
	s_add_i32 s14, 0, 0x1c000
	s_add_i32 s15, s16, s56
	s_mov_b32 m0, s15
	ds_read_b128 v[220:223], v251
	ds_read_b128 v[224:227], v251 offset:1024
	ds_read_b128 v[228:231], v251 offset:2048
	global_load_lds_dwordx4 v244, s[12:13]
	s_add_i32 m0, s15, 0x2000
	ds_read_b128 v[232:235], v251 offset:3072
	global_load_lds_dwordx4 v245, s[12:13]
	s_barrier
	s_waitcnt lgkmcnt(0)
	v_mfma_f32_16x16x32_bf16 v[116:119], v[220:223], v[178:181], v[116:119]
	v_mfma_f32_16x16x32_bf16 v[112:115], v[228:231], v[178:181], v[112:115]
	v_mfma_f32_16x16x32_bf16 v[100:103], v[220:223], v[196:199], v[100:103]
	v_mfma_f32_16x16x32_bf16 v[96:99], v[228:231], v[196:199], v[96:99]
	v_mfma_f32_16x16x32_bf16 v[84:87], v[220:223], v[204:207], v[84:87]
	v_mfma_f32_16x16x32_bf16 v[80:83], v[228:231], v[204:207], v[80:83]
	v_mfma_f32_16x16x32_bf16 v[68:71], v[220:223], v[212:215], v[68:71]
	v_mfma_f32_16x16x32_bf16 v[64:67], v[228:231], v[212:215], v[64:67]
	v_mfma_f32_16x16x32_bf16 v[116:119], v[224:227], v[192:195], v[116:119]
	v_mfma_f32_16x16x32_bf16 v[112:115], v[232:235], v[192:195], v[112:115]
	v_mfma_f32_16x16x32_bf16 v[100:103], v[224:227], v[200:203], v[100:103]
	v_mfma_f32_16x16x32_bf16 v[96:99], v[232:235], v[200:203], v[96:99]
	v_mfma_f32_16x16x32_bf16 v[84:87], v[224:227], v[208:211], v[84:87]
	v_mfma_f32_16x16x32_bf16 v[80:83], v[232:235], v[208:211], v[80:83]
	v_mfma_f32_16x16x32_bf16 v[68:71], v[224:227], v[216:219], v[68:71]
	v_mfma_f32_16x16x32_bf16 v[64:67], v[232:235], v[216:219], v[64:67]
	s_mov_b32 m0, s60
	s_barrier
	ds_read_b128 v[178:181], v169 offset:49152
	ds_read_b128 v[192:195], v169 offset:50176
	ds_read_b128 v[196:199], v169 offset:51200
	ds_read_b128 v[200:203], v169 offset:52224
	ds_read_b128 v[204:207], v169 offset:53248
	ds_read_b128 v[208:211], v169 offset:54272
	ds_read_b128 v[212:215], v169 offset:55296
	global_load_lds_dwordx4 v246, s[26:27]
	s_mov_b32 m0, s61
	ds_read_b128 v[216:219], v169 offset:56320
	global_load_lds_dwordx4 v247, s[26:27]
	s_barrier
	s_waitcnt lgkmcnt(0)
	v_mfma_f32_16x16x32_bf16 v[60:63], v[158:161], v[178:181], v[60:63]
	v_mfma_f32_16x16x32_bf16 v[56:59], v[170:173], v[178:181], v[56:59]
	v_mfma_f32_16x16x32_bf16 v[44:47], v[158:161], v[196:199], v[44:47]
	v_mfma_f32_16x16x32_bf16 v[40:43], v[170:173], v[196:199], v[40:43]
	v_mfma_f32_16x16x32_bf16 v[28:31], v[158:161], v[204:207], v[28:31]
	v_mfma_f32_16x16x32_bf16 v[24:27], v[170:173], v[204:207], v[24:27]
	v_mfma_f32_16x16x32_bf16 v[12:15], v[158:161], v[212:215], v[12:15]
	v_mfma_f32_16x16x32_bf16 v[8:11], v[170:173], v[212:215], v[8:11]
	v_mfma_f32_16x16x32_bf16 v[60:63], v[162:165], v[192:195], v[60:63]
	v_mfma_f32_16x16x32_bf16 v[56:59], v[174:177], v[192:195], v[56:59]
	v_mfma_f32_16x16x32_bf16 v[44:47], v[162:165], v[200:203], v[44:47]
	v_mfma_f32_16x16x32_bf16 v[40:43], v[174:177], v[200:203], v[40:43]
	v_mfma_f32_16x16x32_bf16 v[28:31], v[162:165], v[208:211], v[28:31]
	v_mfma_f32_16x16x32_bf16 v[24:27], v[174:177], v[208:211], v[24:27]
	v_mfma_f32_16x16x32_bf16 v[12:15], v[162:165], v[216:219], v[12:15]
	v_mfma_f32_16x16x32_bf16 v[8:11], v[174:177], v[216:219], v[8:11]
	s_barrier
; __device__ __forceinline__ unsigned cvt_pk_bf16(float lo, float hi) { const f32x2_cv v = {lo, hi}; const bf16x2_cv b = __builtin_convertvector(v, bf16x2_cv); return __builtin_bit_cast(unsigned, b); }
; #define PG8_WAIT_V(n) asm volatile("s_waitcnt vmcnt(" #n ")" ::: "memory")
; #define PG8_BAR __builtin_amdgcn_s_barrier()
; __device__ __forceinline__ float sigm(float x) { return __builtin_amdgcn_rcpf(1.0f + __expf(-x)); }
; template <class Epi, class Sched, bool STAMP = false>
; __device__ __forceinline__ void gemm_phase(PG8_LAS unsigned char* lds, const Gemm g, const Sched& S, const Epi& E, unsigned long long* stamps) {
;     ...
;             PG8_STAGE(PG8_SB(1, 1), b3 + hstep, voffB);
;             PG8_WAIT_V(6); PG8_BAR; PG8_MMA(1, 1, At, B1); PG8_BAR;
;     __device__ __forceinline__ void operator()(const f32x4 (&acc)[2][2][4][2], const pg8::Unit& u, int wr, int wc, int fr, int fq) const {
;         const int row0 = u.pm * 256 + wr * 64 + fr, col0 = u.pn * 256 + wc * 32 + 8 * fq;
; #pragma unroll
;         for (int ai = 0; ai < 2; ++ai)
; #pragma unroll
;             for (int m = 0; m < 4; ++m) {
;                 const int row = row0 + ai * 128 + m * 16;
;                 const float s = rstd_of(rowss, row);
; #pragma unroll
;                 for (int bj = 0; bj < 2; ++bj) {
;                     const size_t off = (size_t)row * 1024 + col0 + bj * 128;
;                     const u32x4 tv = *(const u32x4*)(Tm + off);
;                     u32x4 pv = (u32x4){0u, 0u, 0u, 0u};
;                     if (ACC) pv = *(const u32x4*)(M + off);
;                     const f32x4 a0 = acc[ai][bj][m][0] * s, a1 = acc[ai][bj][m][1] * s;
;                     float o[8];
;                     o[0] = sigm(a0[0]) * lo16(tv.x); o[1] = sigm(a0[1]) * hi16(tv.x); o[2] = sigm(a0[2]) * lo16(tv.y); o[3] = sigm(a0[3]) * hi16(tv.y);
;                     o[4] = sigm(a1[0]) * lo16(tv.z); o[5] = sigm(a1[1]) * hi16(tv.z); o[6] = sigm(a1[2]) * lo16(tv.w); o[7] = sigm(a1[3]) * hi16(tv.w);
;                     if (ACC) { o[0] += lo16(pv.x); o[1] += hi16(pv.x); o[2] += lo16(pv.y); o[3] += hi16(pv.y); o[4] += lo16(pv.z); o[5] += hi16(pv.z); o[6] += lo16(pv.w); o[7] += hi16(pv.w); }
;                     u32x4 w; w.x = cvt_pk_bf16(o[0], o[1]); w.y = cvt_pk_bf16(o[2], o[3]); w.z = cvt_pk_bf16(o[4], o[5]); w.w = cvt_pk_bf16(o[6], o[7]);
;                     *(u32x4*)(M + off) = w; } }
	s_add_u32 s12, s12, 0x40080
	s_addc_u32 s13, s13, 0
	s_add_i32 s14, s14, s56
	s_mov_b32 m0, s14
	s_nop 0
	global_load_lds_dwordx4 v128, s[12:13]
	s_add_i32 m0, s14, 0x2000
	s_nop 0
	global_load_lds_dwordx4 v152, s[12:13]
	s_waitcnt vmcnt(6)
	s_barrier
	v_mfma_f32_16x16x32_bf16 v[52:55], v[220:223], v[178:181], v[52:55]
	v_mfma_f32_16x16x32_bf16 v[48:51], v[228:231], v[178:181], v[48:51]
	v_mfma_f32_16x16x32_bf16 v[36:39], v[220:223], v[196:199], v[36:39]
	v_mfma_f32_16x16x32_bf16 v[32:35], v[228:231], v[196:199], v[32:35]
	v_mfma_f32_16x16x32_bf16 v[20:23], v[220:223], v[204:207], v[20:23]
	v_mfma_f32_16x16x32_bf16 v[16:19], v[228:231], v[204:207], v[16:19]
	v_mfma_f32_16x16x32_bf16 v[4:7], v[220:223], v[212:215], v[4:7]
	v_mfma_f32_16x16x32_bf16 v[0:3], v[228:231], v[212:215], v[0:3]
	v_mfma_f32_16x16x32_bf16 v[52:55], v[224:227], v[192:195], v[52:55]
	v_mfma_f32_16x16x32_bf16 v[48:51], v[232:235], v[192:195], v[48:51]
	v_mfma_f32_16x16x32_bf16 v[36:39], v[224:227], v[200:203], v[36:39]
	v_mfma_f32_16x16x32_bf16 v[32:35], v[232:235], v[200:203], v[32:35]
	v_mfma_f32_16x16x32_bf16 v[20:23], v[224:227], v[208:211], v[20:23]
	v_mfma_f32_16x16x32_bf16 v[16:19], v[232:235], v[208:211], v[16:19]
	v_mfma_f32_16x16x32_bf16 v[4:7], v[224:227], v[216:219], v[4:7]
	v_mfma_f32_16x16x32_bf16 v[0:3], v[232:235], v[216:219], v[0:3]
	s_cmp_gt_u32 s65, 13
	s_barrier
	s_cbranch_scc0 .LBB0_313
	v_lshl_add_u32 v162, s2, 8, v139
	v_ashrrev_i32_e32 v163, 31, v162
	v_lshl_add_u64 v[160:161], v[162:163], 2, s[40:41]
	global_load_dword v164, v[160:161], off
	v_lshl_or_b32 v158, s46, 8, v168
	v_ashrrev_i32_e32 v159, 31, v158
	s_mov_b32 s2, 0x40000
	s_mov_b64 s[4:5], 0x40000
	s_mov_b32 s46, s6
	s_mov_b64 s[12:13], s[24:25]
	s_mov_b32 s62, 0x1800000
	s_waitcnt vmcnt(0)
	v_fmamk_f32 v164, v164, 0x3a800000, v187
	v_cmp_gt_f32_e32 vcc, s67, v164
	v_mul_f32_e32 v165, 0x4b800000, v164
	s_nop 0
	v_cndmask_b32_e32 v164, v164, v165, vcc
	v_rsq_f32_e32 v164, v164
	s_nop 0
	v_mul_f32_e32 v165, 0x45800000, v164
	v_cndmask_b32_e32 v166, v164, v165, vcc
	v_lshlrev_b64 v[164:165], 11, v[162:163]
	v_lshl_add_u64 v[170:171], s[0:1], 0, v[164:165]
	v_lshlrev_b64 v[164:165], 1, v[158:159]
	v_lshl_add_u64 v[158:159], v[170:171], 0, v[164:165]
	v_mov_b32_e32 v170, v158
	v_mov_b32_e32 v171, v159
	global_load_dwordx4 v[192:195], v[170:171], off
	global_load_dwordx4 v[196:199], v[170:171], off offset:256
	v_add_co_u32_e32 v170, vcc, 0x8000, v170
	s_nop 1
	v_addc_co_u32_e32 v171, vcc, 0, v171, vcc
	global_load_dwordx4 v[200:203], v[170:171], off
	global_load_dwordx4 v[204:207], v[170:171], off offset:256
	v_add_co_u32_e32 v170, vcc, 0x8000, v170
	s_nop 1
	v_addc_co_u32_e32 v171, vcc, 0, v171, vcc
	global_load_dwordx4 v[208:211], v[170:171], off
	global_load_dwordx4 v[212:215], v[170:171], off offset:256
	v_add_co_u32_e32 v170, vcc, 0x8000, v170
	s_nop 1
	v_addc_co_u32_e32 v171, vcc, 0, v171, vcc
	global_load_dwordx4 v[216:219], v[170:171], off
	global_load_dwordx4 v[220:223], v[170:171], off offset:256
	v_lshl_add_u64 v[170:171], v[158:159], 0, s[4:5]
	global_load_dwordx4 v[224:227], v[170:171], off
	global_load_dwordx4 v[228:231], v[170:171], off offset:256
	v_add_co_u32_e32 v170, vcc, 0x8000, v170
	s_nop 1
	v_addc_co_u32_e32 v171, vcc, 0, v171, vcc
	global_load_dwordx4 v[232:235], v[170:171], off
	global_load_dwordx4 v[236:239], v[170:171], off offset:256
	v_add_co_u32_e32 v170, vcc, 0x8000, v170
	s_nop 1
	v_addc_co_u32_e32 v171, vcc, 0, v171, vcc
	global_load_dwordx4 v[244:247], v[170:171], off
	global_load_dwordx4 v[248:251], v[170:171], off offset:256
	v_add_co_u32_e32 v170, vcc, 0x8000, v170
	s_nop 1
	v_addc_co_u32_e32 v171, vcc, 0, v171, vcc
	global_load_dwordx4 v[176:179], v[170:171], off
	global_load_dwordx4 v[252:255], v[170:171], off offset:256
	global_load_dword v180, v[160:161], off offset:64
	global_load_dword v181, v[160:161], off offset:128
	global_load_dword v182, v[160:161], off offset:192
	global_load_dword v183, v[160:161], off offset:512
	global_load_dword v240, v[160:161], off offset:576
	global_load_dword v241, v[160:161], off offset:640
	global_load_dword v169, v[160:161], off offset:704
	v_pk_mul_f32 v[126:127], v[126:127], v[166:167] op_sel_hi:[1,0]
	v_pk_mul_f32 v[120:121], v[120:121], v[166:167] op_sel_hi:[1,0]
	v_mul_f32_e32 v126, 0xbfb8aa3b, v126
	v_mul_f32_e32 v127, 0xbfb8aa3b, v127
	v_exp_f32_e32 v126, v126
	v_exp_f32_e32 v127, v127
	v_mul_f32_e32 v120, 0xbfb8aa3b, v120
	v_mul_f32_e32 v121, 0xbfb8aa3b, v121
	v_exp_f32_e32 v120, v120
	v_exp_f32_e32 v121, v121
	v_add_f32_e32 v126, 1.0, v126
	v_add_f32_e32 v127, 1.0, v127
	v_rcp_f32_e32 v126, v126
	v_rcp_f32_e32 v127, v127
	v_add_f32_e32 v120, 1.0, v120
	v_add_f32_e32 v121, 1.0, v121
	v_rcp_f32_e32 v120, v120
	v_rcp_f32_e32 v121, v121
	v_pk_mul_f32 v[124:125], v[124:125], v[166:167] op_sel_hi:[1,0]
	v_pk_mul_f32 v[122:123], v[122:123], v[166:167] op_sel_hi:[1,0]
	v_mul_f32_e32 v124, 0xbfb8aa3b, v124
	v_mul_f32_e32 v125, 0xbfb8aa3b, v125
	v_exp_f32_e32 v124, v124
	v_exp_f32_e32 v125, v125
	v_pk_mul_f32 v[118:119], v[118:119], v[166:167] op_sel_hi:[1,0]
	v_pk_mul_f32 v[112:113], v[112:113], v[166:167] op_sel_hi:[1,0]
	v_add_f32_e32 v124, 1.0, v124
	v_add_f32_e32 v125, 1.0, v125
	v_rcp_f32_e32 v124, v124
	v_rcp_f32_e32 v125, v125
	v_mul_f32_e32 v118, 0xbfb8aa3b, v118
	v_mul_f32_e32 v119, 0xbfb8aa3b, v119
	v_exp_f32_e32 v118, v118
	v_exp_f32_e32 v119, v119
	v_mul_f32_e32 v112, 0xbfb8aa3b, v112
	v_mul_f32_e32 v113, 0xbfb8aa3b, v113
	v_exp_f32_e32 v112, v112
	v_exp_f32_e32 v113, v113
	v_add_f32_e32 v118, 1.0, v118
	v_add_f32_e32 v119, 1.0, v119
	v_rcp_f32_e32 v118, v118
	v_rcp_f32_e32 v119, v119
	v_add_f32_e32 v112, 1.0, v112
	v_add_f32_e32 v113, 1.0, v113
	v_rcp_f32_e32 v112, v112
	v_rcp_f32_e32 v113, v113
	v_pk_mul_f32 v[116:117], v[116:117], v[166:167] op_sel_hi:[1,0]
	v_pk_mul_f32 v[114:115], v[114:115], v[166:167] op_sel_hi:[1,0]
	v_mul_f32_e32 v116, 0xbfb8aa3b, v116
	v_mul_f32_e32 v117, 0xbfb8aa3b, v117
	v_exp_f32_e32 v116, v116
	v_exp_f32_e32 v117, v117
	v_add_f32_e32 v116, 1.0, v116
	v_add_f32_e32 v117, 1.0, v117
	v_rcp_f32_e32 v116, v116
	v_rcp_f32_e32 v117, v117
	s_waitcnt vmcnt(0)
; __device__ __forceinline__ unsigned cvt_pk_bf16(float lo, float hi) { const f32x2_cv v = {lo, hi}; const bf16x2_cv b = __builtin_convertvector(v, bf16x2_cv); return __builtin_bit_cast(unsigned, b); }
; __device__ __forceinline__ float sigm(float x) { return __builtin_amdgcn_rcpf(1.0f + __expf(-x)); }
; __device__ __forceinline__ float lo16(unsigned w) { return __uint_as_float(w << 16); }
; __device__ __forceinline__ float hi16(unsigned w) { return __uint_as_float(w & 0xffff0000u); }
; __device__ __forceinline__ float rstd_of(const float* rowss, int row) { return rsqrtf(rowss[row] * (1.0f / 1024.0f) + 1e-6f); }
;     __device__ __forceinline__ void operator()(const f32x4 (&acc)[2][2][4][2], const pg8::Unit& u, int wr, int wc, int fr, int fq) const {
;     ...
;                 const int row = row0 + ai * 128 + m * 16;
;                 const float s = rstd_of(rowss, row);
; #pragma unroll
;                 for (int bj = 0; bj < 2; ++bj) {
;                     const size_t off = (size_t)row * 1024 + col0 + bj * 128;
;                     const u32x4 tv = *(const u32x4*)(Tm + off);
;                     u32x4 pv = (u32x4){0u, 0u, 0u, 0u};
;                     if (ACC) pv = *(const u32x4*)(M + off);
;                     const f32x4 a0 = acc[ai][bj][m][0] * s, a1 = acc[ai][bj][m][1] * s;
;                     float o[8];
;                     o[0] = sigm(a0[0]) * lo16(tv.x); o[1] = sigm(a0[1]) * hi16(tv.x); o[2] = sigm(a0[2]) * lo16(tv.y); o[3] = sigm(a0[3]) * hi16(tv.y);
;                     o[4] = sigm(a1[0]) * lo16(tv.z); o[5] = sigm(a1[1]) * hi16(tv.z); o[6] = sigm(a1[2]) * lo16(tv.w); o[7] = sigm(a1[3]) * hi16(tv.w);
;                     if (ACC) { o[0] += lo16(pv.x); o[1] += hi16(pv.x); o[2] += lo16(pv.y); o[3] += hi16(pv.y); o[4] += lo16(pv.z); o[5] += hi16(pv.z); o[6] += lo16(pv.w); o[7] += hi16(pv.w); }
;                     u32x4 w; w.x = cvt_pk_bf16(o[0], o[1]); w.y = cvt_pk_bf16(o[2], o[3]); w.z = cvt_pk_bf16(o[4], o[5]); w.w = cvt_pk_bf16(o[6], o[7]);
;                     *(u32x4*)(M + off) = w; } }
	v_mov_b32_e32 v170, v192
	v_mov_b32_e32 v171, v193
	v_mov_b32_e32 v172, v194
	v_mov_b32_e32 v173, v195
	v_lshlrev_b32_e32 v174, 16, v170
	v_and_b32_e32 v175, 0xffff0000, v170
	v_lshlrev_b32_e32 v170, 16, v171
	v_and_b32_e32 v171, 0xffff0000, v171
	v_pk_mul_f32 v[126:127], v[126:127], v[170:171]
	v_lshlrev_b32_e32 v170, 16, v172
	v_and_b32_e32 v171, 0xffff0000, v172
	v_pk_mul_f32 v[170:171], v[120:121], v[170:171]
	v_mul_f32_e32 v120, 0xbfb8aa3b, v122
	v_mul_f32_e32 v121, 0xbfb8aa3b, v123
	v_exp_f32_e32 v120, v120
	v_exp_f32_e32 v121, v121
	v_lshlrev_b32_e32 v122, 16, v173
	v_and_b32_e32 v123, 0xffff0000, v173
	v_add_f32_e32 v120, 1.0, v120
	v_add_f32_e32 v121, 1.0, v121
	v_rcp_f32_e32 v120, v120
	v_rcp_f32_e32 v121, v121
	v_pk_mul_f32 v[124:125], v[124:125], v[174:175]
	v_pk_mul_f32 v[172:173], v[120:121], v[122:123]
	v_cvt_pk_bf16_f32 v120, v124, v125
	v_cvt_pk_bf16_f32 v121, v126, v127
	v_cvt_pk_bf16_f32 v122, v170, v171
	v_cvt_pk_bf16_f32 v123, v172, v173
	global_store_dwordx4 v[158:159], v[120:123], off
	s_nop 1
	v_mov_b32_e32 v120, v196
	v_mov_b32_e32 v121, v197
	v_mov_b32_e32 v122, v198
	v_mov_b32_e32 v123, v199
	v_lshlrev_b32_e32 v124, 16, v120
	v_and_b32_e32 v125, 0xffff0000, v120
	v_lshlrev_b32_e32 v120, 16, v121
	v_and_b32_e32 v121, 0xffff0000, v121
	v_pk_mul_f32 v[118:119], v[118:119], v[120:121]
	v_lshlrev_b32_e32 v120, 16, v122
	v_and_b32_e32 v121, 0xffff0000, v122
	v_pk_mul_f32 v[120:121], v[112:113], v[120:121]
	v_mul_f32_e32 v112, 0xbfb8aa3b, v114
	v_mul_f32_e32 v113, 0xbfb8aa3b, v115
	v_exp_f32_e32 v112, v112
	v_exp_f32_e32 v113, v113
	v_lshlrev_b32_e32 v114, 16, v123
	v_and_b32_e32 v115, 0xffff0000, v123
	v_add_f32_e32 v112, 1.0, v112
	v_add_f32_e32 v113, 1.0, v113
	v_rcp_f32_e32 v112, v112
	v_rcp_f32_e32 v113, v113
	v_pk_mul_f32 v[116:117], v[116:117], v[124:125]
	v_pk_mul_f32 v[122:123], v[112:113], v[114:115]
	v_cvt_pk_bf16_f32 v112, v116, v117
	v_cvt_pk_bf16_f32 v113, v118, v119
	v_cvt_pk_bf16_f32 v114, v120, v121
	v_cvt_pk_bf16_f32 v115, v122, v123
	global_store_dwordx4 v[158:159], v[112:115], off offset:256
	s_nop 1
	v_mov_b32_e32 v114, v180
	s_nop 0
	v_or_b32_e32 v112, 16, v162
	v_ashrrev_i32_e32 v113, 31, v112
	v_lshlrev_b64 v[112:113], 11, v[112:113]
	v_lshl_add_u64 v[112:113], s[0:1], 0, v[112:113]
	v_lshl_add_u64 v[112:113], v[112:113], 0, v[164:165]
	s_nop 1
	v_mov_b32_e32 v116, v200
	v_mov_b32_e32 v117, v201
	v_mov_b32_e32 v118, v202
	v_mov_b32_e32 v119, v203
	v_fmamk_f32 v114, v114, 0x3a800000, v187
	v_cmp_gt_f32_e32 vcc, s67, v114
	v_mul_f32_e32 v115, 0x4b800000, v114
	v_lshlrev_b32_e32 v120, 16, v116
	v_cndmask_b32_e32 v114, v114, v115, vcc
	v_rsq_f32_e32 v114, v114
	v_and_b32_e32 v121, 0xffff0000, v116
	v_lshlrev_b32_e32 v116, 16, v117
	v_and_b32_e32 v117, 0xffff0000, v117
	v_mul_f32_e32 v115, 0x45800000, v114
	v_cndmask_b32_e32 v114, v114, v115, vcc
	v_pk_mul_f32 v[110:111], v[110:111], v[114:115] op_sel_hi:[1,0]
	v_pk_mul_f32 v[104:105], v[104:105], v[114:115] op_sel_hi:[1,0]
	v_mul_f32_e32 v110, 0xbfb8aa3b, v110
	v_mul_f32_e32 v111, 0xbfb8aa3b, v111
	v_exp_f32_e32 v110, v110
	v_exp_f32_e32 v111, v111
	v_mul_f32_e32 v104, 0xbfb8aa3b, v104
	v_mul_f32_e32 v105, 0xbfb8aa3b, v105
	v_exp_f32_e32 v104, v104
	v_exp_f32_e32 v105, v105
	v_add_f32_e32 v110, 1.0, v110
	v_add_f32_e32 v111, 1.0, v111
	v_rcp_f32_e32 v110, v110
	v_rcp_f32_e32 v111, v111
	v_add_f32_e32 v104, 1.0, v104
	v_add_f32_e32 v105, 1.0, v105
	v_rcp_f32_e32 v104, v104
	v_rcp_f32_e32 v105, v105
	v_pk_mul_f32 v[108:109], v[108:109], v[114:115] op_sel_hi:[1,0]
	v_pk_mul_f32 v[106:107], v[106:107], v[114:115] op_sel_hi:[1,0]
	v_pk_mul_f32 v[110:111], v[110:111], v[116:117]
	v_lshlrev_b32_e32 v116, 16, v118
	v_and_b32_e32 v117, 0xffff0000, v118
	v_mul_f32_e32 v108, 0xbfb8aa3b, v108
	v_mul_f32_e32 v109, 0xbfb8aa3b, v109
	v_pk_mul_f32 v[116:117], v[104:105], v[116:117]
	v_mul_f32_e32 v104, 0xbfb8aa3b, v106
	v_mul_f32_e32 v105, 0xbfb8aa3b, v107
	v_exp_f32_e32 v108, v108
	v_exp_f32_e32 v109, v109
	v_exp_f32_e32 v104, v104
	v_exp_f32_e32 v105, v105
	v_add_f32_e32 v108, 1.0, v108
	v_add_f32_e32 v109, 1.0, v109
	v_add_f32_e32 v104, 1.0, v104
	v_add_f32_e32 v105, 1.0, v105
	v_rcp_f32_e32 v108, v108
	v_rcp_f32_e32 v109, v109
	v_rcp_f32_e32 v104, v104
	v_rcp_f32_e32 v105, v105
	v_lshlrev_b32_e32 v106, 16, v119
	v_and_b32_e32 v107, 0xffff0000, v119
	v_pk_mul_f32 v[108:109], v[108:109], v[120:121]
	v_pk_mul_f32 v[118:119], v[104:105], v[106:107]
	v_cvt_pk_bf16_f32 v104, v108, v109
	v_cvt_pk_bf16_f32 v105, v110, v111
	v_cvt_pk_bf16_f32 v106, v116, v117
	v_cvt_pk_bf16_f32 v107, v118, v119
	global_store_dwordx4 v[112:113], v[104:107], off
	s_nop 1
	v_mov_b32_e32 v104, v204
	v_mov_b32_e32 v105, v205
	v_mov_b32_e32 v106, v206
	v_mov_b32_e32 v107, v207
	v_pk_mul_f32 v[102:103], v[102:103], v[114:115] op_sel_hi:[1,0]
	v_pk_mul_f32 v[96:97], v[96:97], v[114:115] op_sel_hi:[1,0]
	v_mul_f32_e32 v102, 0xbfb8aa3b, v102
	v_mul_f32_e32 v103, 0xbfb8aa3b, v103
	v_exp_f32_e32 v102, v102
	v_exp_f32_e32 v103, v103
	v_mul_f32_e32 v96, 0xbfb8aa3b, v96
	v_mul_f32_e32 v97, 0xbfb8aa3b, v97
	v_exp_f32_e32 v96, v96
	v_exp_f32_e32 v97, v97
	v_add_f32_e32 v102, 1.0, v102
	v_add_f32_e32 v103, 1.0, v103
	v_rcp_f32_e32 v102, v102
	v_rcp_f32_e32 v103, v103
	v_add_f32_e32 v96, 1.0, v96
	v_add_f32_e32 v97, 1.0, v97
	v_rcp_f32_e32 v96, v96
	v_rcp_f32_e32 v97, v97
	v_pk_mul_f32 v[100:101], v[100:101], v[114:115] op_sel_hi:[1,0]
	v_pk_mul_f32 v[98:99], v[98:99], v[114:115] op_sel_hi:[1,0]
	v_mul_f32_e32 v100, 0xbfb8aa3b, v100
	v_mul_f32_e32 v101, 0xbfb8aa3b, v101
	v_exp_f32_e32 v100, v100
	v_exp_f32_e32 v101, v101
	v_add_f32_e32 v100, 1.0, v100
	v_add_f32_e32 v101, 1.0, v101
	v_rcp_f32_e32 v100, v100
; __device__ __forceinline__ unsigned cvt_pk_bf16(float lo, float hi) { const f32x2_cv v = {lo, hi}; const bf16x2_cv b = __builtin_convertvector(v, bf16x2_cv); return __builtin_bit_cast(unsigned, b); }
; __device__ __forceinline__ float sigm(float x) { return __builtin_amdgcn_rcpf(1.0f + __expf(-x)); }
; __device__ __forceinline__ float lo16(unsigned w) { return __uint_as_float(w << 16); }
; __device__ __forceinline__ float hi16(unsigned w) { return __uint_as_float(w & 0xffff0000u); }
; __device__ __forceinline__ float rstd_of(const float* rowss, int row) { return rsqrtf(rowss[row] * (1.0f / 1024.0f) + 1e-6f); }
;     __device__ __forceinline__ void operator()(const f32x4 (&acc)[2][2][4][2], const pg8::Unit& u, int wr, int wc, int fr, int fq) const {
;     ...
;                 const int row = row0 + ai * 128 + m * 16;
;                 const float s = rstd_of(rowss, row);
; #pragma unroll
;                 for (int bj = 0; bj < 2; ++bj) {
;                     const size_t off = (size_t)row * 1024 + col0 + bj * 128;
;                     const u32x4 tv = *(const u32x4*)(Tm + off);
;                     u32x4 pv = (u32x4){0u, 0u, 0u, 0u};
;                     if (ACC) pv = *(const u32x4*)(M + off);
;                     const f32x4 a0 = acc[ai][bj][m][0] * s, a1 = acc[ai][bj][m][1] * s;
;                     float o[8];
;                     o[0] = sigm(a0[0]) * lo16(tv.x); o[1] = sigm(a0[1]) * hi16(tv.x); o[2] = sigm(a0[2]) * lo16(tv.y); o[3] = sigm(a0[3]) * hi16(tv.y);
;                     o[4] = sigm(a1[0]) * lo16(tv.z); o[5] = sigm(a1[1]) * hi16(tv.z); o[6] = sigm(a1[2]) * lo16(tv.w); o[7] = sigm(a1[3]) * hi16(tv.w);
;                     if (ACC) { o[0] += lo16(pv.x); o[1] += hi16(pv.x); o[2] += lo16(pv.y); o[3] += hi16(pv.y); o[4] += lo16(pv.z); o[5] += hi16(pv.z); o[6] += lo16(pv.w); o[7] += hi16(pv.w); }
;                     u32x4 w; w.x = cvt_pk_bf16(o[0], o[1]); w.y = cvt_pk_bf16(o[2], o[3]); w.z = cvt_pk_bf16(o[4], o[5]); w.w = cvt_pk_bf16(o[6], o[7]);
;                     *(u32x4*)(M + off) = w; } }
	v_rcp_f32_e32 v101, v101
	v_lshlrev_b32_e32 v108, 16, v104
	v_and_b32_e32 v109, 0xffff0000, v104
	v_lshlrev_b32_e32 v104, 16, v105
	v_and_b32_e32 v105, 0xffff0000, v105
	v_pk_mul_f32 v[102:103], v[102:103], v[104:105]
	v_lshlrev_b32_e32 v104, 16, v106
	v_and_b32_e32 v105, 0xffff0000, v106
	v_pk_mul_f32 v[104:105], v[96:97], v[104:105]
	v_mul_f32_e32 v96, 0xbfb8aa3b, v98
	v_mul_f32_e32 v97, 0xbfb8aa3b, v99
	v_exp_f32_e32 v96, v96
	v_exp_f32_e32 v97, v97
	v_lshlrev_b32_e32 v98, 16, v107
	v_and_b32_e32 v99, 0xffff0000, v107
	v_add_f32_e32 v96, 1.0, v96
	v_add_f32_e32 v97, 1.0, v97
	v_rcp_f32_e32 v96, v96
	v_rcp_f32_e32 v97, v97
	v_pk_mul_f32 v[100:101], v[100:101], v[108:109]
	v_pk_mul_f32 v[106:107], v[96:97], v[98:99]
	v_cvt_pk_bf16_f32 v96, v100, v101
	v_cvt_pk_bf16_f32 v97, v102, v103
	v_cvt_pk_bf16_f32 v98, v104, v105
	v_cvt_pk_bf16_f32 v99, v106, v107
	global_store_dwordx4 v[112:113], v[96:99], off offset:256
	s_nop 1
	v_mov_b32_e32 v98, v181
	s_nop 0
	v_or_b32_e32 v96, 32, v162
	v_ashrrev_i32_e32 v97, 31, v96
	v_lshlrev_b64 v[96:97], 11, v[96:97]
	v_lshl_add_u64 v[96:97], s[0:1], 0, v[96:97]
	v_lshl_add_u64 v[96:97], v[96:97], 0, v[164:165]
	s_nop 1
	v_mov_b32_e32 v100, v208
	v_mov_b32_e32 v101, v209
	v_mov_b32_e32 v102, v210
	v_mov_b32_e32 v103, v211
	v_fmamk_f32 v98, v98, 0x3a800000, v187
	v_cmp_gt_f32_e32 vcc, s67, v98
	v_mul_f32_e32 v99, 0x4b800000, v98
	v_lshlrev_b32_e32 v104, 16, v100
	v_cndmask_b32_e32 v98, v98, v99, vcc
	v_rsq_f32_e32 v98, v98
	v_and_b32_e32 v105, 0xffff0000, v100
	v_lshlrev_b32_e32 v100, 16, v101
	v_and_b32_e32 v101, 0xffff0000, v101
	v_mul_f32_e32 v99, 0x45800000, v98
	v_cndmask_b32_e32 v98, v98, v99, vcc
	v_pk_mul_f32 v[94:95], v[94:95], v[98:99] op_sel_hi:[1,0]
	v_pk_mul_f32 v[88:89], v[88:89], v[98:99] op_sel_hi:[1,0]
	v_mul_f32_e32 v94, 0xbfb8aa3b, v94
	v_mul_f32_e32 v95, 0xbfb8aa3b, v95
	v_exp_f32_e32 v94, v94
	v_exp_f32_e32 v95, v95
	v_mul_f32_e32 v88, 0xbfb8aa3b, v88
	v_mul_f32_e32 v89, 0xbfb8aa3b, v89
	v_exp_f32_e32 v88, v88
	v_exp_f32_e32 v89, v89
	v_add_f32_e32 v94, 1.0, v94
	v_add_f32_e32 v95, 1.0, v95
	v_rcp_f32_e32 v94, v94
	v_rcp_f32_e32 v95, v95
	v_add_f32_e32 v88, 1.0, v88
	v_add_f32_e32 v89, 1.0, v89
	v_rcp_f32_e32 v88, v88
	v_rcp_f32_e32 v89, v89
	v_pk_mul_f32 v[92:93], v[92:93], v[98:99] op_sel_hi:[1,0]
	v_pk_mul_f32 v[90:91], v[90:91], v[98:99] op_sel_hi:[1,0]
	v_pk_mul_f32 v[94:95], v[94:95], v[100:101]
	v_lshlrev_b32_e32 v100, 16, v102
	v_and_b32_e32 v101, 0xffff0000, v102
	v_mul_f32_e32 v92, 0xbfb8aa3b, v92
	v_mul_f32_e32 v93, 0xbfb8aa3b, v93
	v_pk_mul_f32 v[100:101], v[88:89], v[100:101]
	v_mul_f32_e32 v88, 0xbfb8aa3b, v90
	v_mul_f32_e32 v89, 0xbfb8aa3b, v91
	v_exp_f32_e32 v92, v92
	v_exp_f32_e32 v93, v93
	v_exp_f32_e32 v88, v88
	v_exp_f32_e32 v89, v89
	v_add_f32_e32 v92, 1.0, v92
	v_add_f32_e32 v93, 1.0, v93
	v_add_f32_e32 v88, 1.0, v88
	v_add_f32_e32 v89, 1.0, v89
	v_rcp_f32_e32 v92, v92
	v_rcp_f32_e32 v93, v93
	v_rcp_f32_e32 v88, v88
	v_rcp_f32_e32 v89, v89
	v_lshlrev_b32_e32 v90, 16, v103
	v_and_b32_e32 v91, 0xffff0000, v103
	v_pk_mul_f32 v[92:93], v[92:93], v[104:105]
	v_pk_mul_f32 v[102:103], v[88:89], v[90:91]
	v_cvt_pk_bf16_f32 v88, v92, v93
	v_cvt_pk_bf16_f32 v89, v94, v95
	v_cvt_pk_bf16_f32 v90, v100, v101
	v_cvt_pk_bf16_f32 v91, v102, v103
	global_store_dwordx4 v[96:97], v[88:91], off
	s_nop 1
	v_mov_b32_e32 v88, v212
	v_mov_b32_e32 v89, v213
	v_mov_b32_e32 v90, v214
	v_mov_b32_e32 v91, v215
	v_pk_mul_f32 v[86:87], v[86:87], v[98:99] op_sel_hi:[1,0]
	v_pk_mul_f32 v[80:81], v[80:81], v[98:99] op_sel_hi:[1,0]
	v_mul_f32_e32 v86, 0xbfb8aa3b, v86
	v_mul_f32_e32 v87, 0xbfb8aa3b, v87
	v_exp_f32_e32 v86, v86
	v_exp_f32_e32 v87, v87
	v_mul_f32_e32 v80, 0xbfb8aa3b, v80
	v_mul_f32_e32 v81, 0xbfb8aa3b, v81
	v_exp_f32_e32 v80, v80
	v_exp_f32_e32 v81, v81
	v_add_f32_e32 v86, 1.0, v86
	v_add_f32_e32 v87, 1.0, v87
	v_rcp_f32_e32 v86, v86
	v_rcp_f32_e32 v87, v87
	v_add_f32_e32 v80, 1.0, v80
	v_add_f32_e32 v81, 1.0, v81
	v_rcp_f32_e32 v80, v80
	v_rcp_f32_e32 v81, v81
	v_pk_mul_f32 v[84:85], v[84:85], v[98:99] op_sel_hi:[1,0]
	v_pk_mul_f32 v[82:83], v[82:83], v[98:99] op_sel_hi:[1,0]
	v_mul_f32_e32 v84, 0xbfb8aa3b, v84
	v_mul_f32_e32 v85, 0xbfb8aa3b, v85
	v_exp_f32_e32 v84, v84
	v_exp_f32_e32 v85, v85
	v_add_f32_e32 v84, 1.0, v84
	v_add_f32_e32 v85, 1.0, v85
	v_rcp_f32_e32 v84, v84
	v_rcp_f32_e32 v85, v85
	v_lshlrev_b32_e32 v92, 16, v88
	v_and_b32_e32 v93, 0xffff0000, v88
	v_lshlrev_b32_e32 v88, 16, v89
	v_and_b32_e32 v89, 0xffff0000, v89
	v_pk_mul_f32 v[86:87], v[86:87], v[88:89]
	v_lshlrev_b32_e32 v88, 16, v90
	v_and_b32_e32 v89, 0xffff0000, v90
	v_pk_mul_f32 v[88:89], v[80:81], v[88:89]
	v_mul_f32_e32 v80, 0xbfb8aa3b, v82
	v_mul_f32_e32 v81, 0xbfb8aa3b, v83
	v_exp_f32_e32 v80, v80
	v_exp_f32_e32 v81, v81
	v_lshlrev_b32_e32 v82, 16, v91
	v_and_b32_e32 v83, 0xffff0000, v91
	v_add_f32_e32 v80, 1.0, v80
	v_add_f32_e32 v81, 1.0, v81
	v_rcp_f32_e32 v80, v80
	v_rcp_f32_e32 v81, v81
	v_pk_mul_f32 v[84:85], v[84:85], v[92:93]
	v_pk_mul_f32 v[90:91], v[80:81], v[82:83]
	v_cvt_pk_bf16_f32 v80, v84, v85
	v_cvt_pk_bf16_f32 v81, v86, v87
	v_cvt_pk_bf16_f32 v82, v88, v89
	v_cvt_pk_bf16_f32 v83, v90, v91
	global_store_dwordx4 v[96:97], v[80:83], off offset:256
	s_nop 1
	v_mov_b32_e32 v82, v182
	s_nop 0
	v_or_b32_e32 v80, 48, v162
	v_ashrrev_i32_e32 v81, 31, v80
	v_lshlrev_b64 v[80:81], 11, v[80:81]
	v_lshl_add_u64 v[80:81], s[0:1], 0, v[80:81]
	v_lshl_add_u64 v[80:81], v[80:81], 0, v[164:165]
	s_nop 1
	v_mov_b32_e32 v84, v216
	v_mov_b32_e32 v85, v217
	v_mov_b32_e32 v86, v218
	v_mov_b32_e32 v87, v219
	v_fmamk_f32 v82, v82, 0x3a800000, v187
	v_cmp_gt_f32_e32 vcc, s67, v82
	v_mul_f32_e32 v83, 0x4b800000, v82
; __device__ __forceinline__ unsigned cvt_pk_bf16(float lo, float hi) { const f32x2_cv v = {lo, hi}; const bf16x2_cv b = __builtin_convertvector(v, bf16x2_cv); return __builtin_bit_cast(unsigned, b); }
; __device__ __forceinline__ float sigm(float x) { return __builtin_amdgcn_rcpf(1.0f + __expf(-x)); }
; __device__ __forceinline__ float lo16(unsigned w) { return __uint_as_float(w << 16); }
; __device__ __forceinline__ float hi16(unsigned w) { return __uint_as_float(w & 0xffff0000u); }
; __device__ __forceinline__ float rstd_of(const float* rowss, int row) { return rsqrtf(rowss[row] * (1.0f / 1024.0f) + 1e-6f); }
;     __device__ __forceinline__ void operator()(const f32x4 (&acc)[2][2][4][2], const pg8::Unit& u, int wr, int wc, int fr, int fq) const {
;     ...
;                 const int row = row0 + ai * 128 + m * 16;
;                 const float s = rstd_of(rowss, row);
; #pragma unroll
;                 for (int bj = 0; bj < 2; ++bj) {
;                     const size_t off = (size_t)row * 1024 + col0 + bj * 128;
;                     const u32x4 tv = *(const u32x4*)(Tm + off);
;                     u32x4 pv = (u32x4){0u, 0u, 0u, 0u};
;                     if (ACC) pv = *(const u32x4*)(M + off);
;                     const f32x4 a0 = acc[ai][bj][m][0] * s, a1 = acc[ai][bj][m][1] * s;
;                     float o[8];
;                     o[0] = sigm(a0[0]) * lo16(tv.x); o[1] = sigm(a0[1]) * hi16(tv.x); o[2] = sigm(a0[2]) * lo16(tv.y); o[3] = sigm(a0[3]) * hi16(tv.y);
;                     o[4] = sigm(a1[0]) * lo16(tv.z); o[5] = sigm(a1[1]) * hi16(tv.z); o[6] = sigm(a1[2]) * lo16(tv.w); o[7] = sigm(a1[3]) * hi16(tv.w);
;                     if (ACC) { o[0] += lo16(pv.x); o[1] += hi16(pv.x); o[2] += lo16(pv.y); o[3] += hi16(pv.y); o[4] += lo16(pv.z); o[5] += hi16(pv.z); o[6] += lo16(pv.w); o[7] += hi16(pv.w); }
;                     u32x4 w; w.x = cvt_pk_bf16(o[0], o[1]); w.y = cvt_pk_bf16(o[2], o[3]); w.z = cvt_pk_bf16(o[4], o[5]); w.w = cvt_pk_bf16(o[6], o[7]);
;                     *(u32x4*)(M + off) = w; } }
	v_lshlrev_b32_e32 v88, 16, v84
	v_cndmask_b32_e32 v82, v82, v83, vcc
	v_rsq_f32_e32 v82, v82
	v_and_b32_e32 v89, 0xffff0000, v84
	v_lshlrev_b32_e32 v84, 16, v85
	v_and_b32_e32 v85, 0xffff0000, v85
	v_mul_f32_e32 v83, 0x45800000, v82
	v_cndmask_b32_e32 v82, v82, v83, vcc
	v_pk_mul_f32 v[78:79], v[78:79], v[82:83] op_sel_hi:[1,0]
	v_pk_mul_f32 v[72:73], v[72:73], v[82:83] op_sel_hi:[1,0]
	v_mul_f32_e32 v78, 0xbfb8aa3b, v78
	v_mul_f32_e32 v79, 0xbfb8aa3b, v79
	v_exp_f32_e32 v78, v78
	v_exp_f32_e32 v79, v79
	v_mul_f32_e32 v72, 0xbfb8aa3b, v72
	v_mul_f32_e32 v73, 0xbfb8aa3b, v73
	v_exp_f32_e32 v72, v72
	v_exp_f32_e32 v73, v73
	v_add_f32_e32 v78, 1.0, v78
	v_add_f32_e32 v79, 1.0, v79
	v_rcp_f32_e32 v78, v78
	v_rcp_f32_e32 v79, v79
	v_add_f32_e32 v72, 1.0, v72
	v_add_f32_e32 v73, 1.0, v73
	v_rcp_f32_e32 v72, v72
	v_rcp_f32_e32 v73, v73
	v_pk_mul_f32 v[76:77], v[76:77], v[82:83] op_sel_hi:[1,0]
	v_pk_mul_f32 v[74:75], v[74:75], v[82:83] op_sel_hi:[1,0]
	v_pk_mul_f32 v[78:79], v[78:79], v[84:85]
	v_lshlrev_b32_e32 v84, 16, v86
	v_and_b32_e32 v85, 0xffff0000, v86
	v_mul_f32_e32 v76, 0xbfb8aa3b, v76
	v_mul_f32_e32 v77, 0xbfb8aa3b, v77
	v_pk_mul_f32 v[84:85], v[72:73], v[84:85]
	v_mul_f32_e32 v72, 0xbfb8aa3b, v74
	v_mul_f32_e32 v73, 0xbfb8aa3b, v75
	v_exp_f32_e32 v76, v76
	v_exp_f32_e32 v77, v77
	v_exp_f32_e32 v72, v72
	v_exp_f32_e32 v73, v73
	v_add_f32_e32 v76, 1.0, v76
	v_add_f32_e32 v77, 1.0, v77
	v_add_f32_e32 v72, 1.0, v72
	v_add_f32_e32 v73, 1.0, v73
	v_rcp_f32_e32 v76, v76
	v_rcp_f32_e32 v77, v77
	v_rcp_f32_e32 v72, v72
	v_rcp_f32_e32 v73, v73
	v_lshlrev_b32_e32 v74, 16, v87
	v_and_b32_e32 v75, 0xffff0000, v87
	v_pk_mul_f32 v[76:77], v[76:77], v[88:89]
	v_pk_mul_f32 v[86:87], v[72:73], v[74:75]
	v_cvt_pk_bf16_f32 v72, v76, v77
	v_cvt_pk_bf16_f32 v73, v78, v79
	v_cvt_pk_bf16_f32 v74, v84, v85
	v_cvt_pk_bf16_f32 v75, v86, v87
	global_store_dwordx4 v[80:81], v[72:75], off
	s_nop 1
	v_mov_b32_e32 v72, v220
	v_mov_b32_e32 v73, v221
	v_mov_b32_e32 v74, v222
	v_mov_b32_e32 v75, v223
	v_pk_mul_f32 v[70:71], v[70:71], v[82:83] op_sel_hi:[1,0]
	v_pk_mul_f32 v[64:65], v[64:65], v[82:83] op_sel_hi:[1,0]
	v_mul_f32_e32 v70, 0xbfb8aa3b, v70
	v_mul_f32_e32 v71, 0xbfb8aa3b, v71
	v_exp_f32_e32 v70, v70
	v_exp_f32_e32 v71, v71
	v_mul_f32_e32 v64, 0xbfb8aa3b, v64
	v_mul_f32_e32 v65, 0xbfb8aa3b, v65
	v_exp_f32_e32 v64, v64
	v_exp_f32_e32 v65, v65
	v_add_f32_e32 v70, 1.0, v70
	v_add_f32_e32 v71, 1.0, v71
	v_rcp_f32_e32 v70, v70
	v_rcp_f32_e32 v71, v71
	v_add_f32_e32 v64, 1.0, v64
	v_add_f32_e32 v65, 1.0, v65
	v_rcp_f32_e32 v64, v64
	v_rcp_f32_e32 v65, v65
	v_pk_mul_f32 v[68:69], v[68:69], v[82:83] op_sel_hi:[1,0]
	v_pk_mul_f32 v[66:67], v[66:67], v[82:83] op_sel_hi:[1,0]
	v_mul_f32_e32 v68, 0xbfb8aa3b, v68
	v_mul_f32_e32 v69, 0xbfb8aa3b, v69
	v_exp_f32_e32 v68, v68
	v_exp_f32_e32 v69, v69
	v_add_f32_e32 v68, 1.0, v68
	v_add_f32_e32 v69, 1.0, v69
	v_rcp_f32_e32 v68, v68
	v_rcp_f32_e32 v69, v69
	v_lshlrev_b32_e32 v76, 16, v72
	v_and_b32_e32 v77, 0xffff0000, v72
	v_lshlrev_b32_e32 v72, 16, v73
	v_and_b32_e32 v73, 0xffff0000, v73
	v_pk_mul_f32 v[70:71], v[70:71], v[72:73]
	v_lshlrev_b32_e32 v72, 16, v74
	v_and_b32_e32 v73, 0xffff0000, v74
	v_pk_mul_f32 v[72:73], v[64:65], v[72:73]
	v_mul_f32_e32 v64, 0xbfb8aa3b, v66
	v_mul_f32_e32 v65, 0xbfb8aa3b, v67
	v_exp_f32_e32 v64, v64
	v_exp_f32_e32 v65, v65
	v_lshlrev_b32_e32 v66, 16, v75
	v_and_b32_e32 v67, 0xffff0000, v75
	v_add_f32_e32 v64, 1.0, v64
	v_add_f32_e32 v65, 1.0, v65
	v_rcp_f32_e32 v64, v64
	v_rcp_f32_e32 v65, v65
	v_pk_mul_f32 v[68:69], v[68:69], v[76:77]
	v_pk_mul_f32 v[74:75], v[64:65], v[66:67]
	v_cvt_pk_bf16_f32 v64, v68, v69
	v_cvt_pk_bf16_f32 v65, v70, v71
	v_cvt_pk_bf16_f32 v66, v72, v73
	v_cvt_pk_bf16_f32 v67, v74, v75
	global_store_dwordx4 v[80:81], v[64:67], off offset:256
	s_nop 1
	v_mov_b32_e32 v64, v183
	v_fmamk_f32 v64, v64, 0x3a800000, v187
	v_cmp_gt_f32_e32 vcc, s67, v64
	v_mul_f32_e32 v65, 0x4b800000, v64
	s_nop 0
	v_cndmask_b32_e32 v64, v64, v65, vcc
	v_rsq_f32_e32 v64, v64
	s_nop 0
	v_mul_f32_e32 v65, 0x45800000, v64
	v_cndmask_b32_e32 v66, v64, v65, vcc
	v_add_co_u32_e32 v72, vcc, s2, v158
	v_pk_mul_f32 v[62:63], v[62:63], v[66:67] op_sel_hi:[1,0]
	s_nop 0
	v_addc_co_u32_e32 v73, vcc, 0, v159, vcc
	s_nop 1
	v_mov_b32_e32 v68, v224
	v_mov_b32_e32 v69, v225
	v_mov_b32_e32 v70, v226
	v_mov_b32_e32 v71, v227
	v_pk_mul_f32 v[56:57], v[56:57], v[66:67] op_sel_hi:[1,0]
	v_mul_f32_e32 v62, 0xbfb8aa3b, v62
	v_mul_f32_e32 v63, 0xbfb8aa3b, v63
	v_exp_f32_e32 v62, v62
	v_exp_f32_e32 v63, v63
	v_mul_f32_e32 v56, 0xbfb8aa3b, v56
	v_mul_f32_e32 v57, 0xbfb8aa3b, v57
	v_exp_f32_e32 v56, v56
	v_exp_f32_e32 v57, v57
	v_add_f32_e32 v62, 1.0, v62
	v_add_f32_e32 v63, 1.0, v63
	v_rcp_f32_e32 v62, v62
	v_rcp_f32_e32 v63, v63
	v_add_f32_e32 v56, 1.0, v56
	v_add_f32_e32 v57, 1.0, v57
	v_rcp_f32_e32 v56, v56
	v_rcp_f32_e32 v57, v57
	v_pk_mul_f32 v[60:61], v[60:61], v[66:67] op_sel_hi:[1,0]
	v_pk_mul_f32 v[58:59], v[58:59], v[66:67] op_sel_hi:[1,0]
	v_mul_f32_e32 v60, 0xbfb8aa3b, v60
	v_mul_f32_e32 v61, 0xbfb8aa3b, v61
	v_exp_f32_e32 v60, v60
	v_exp_f32_e32 v61, v61
	v_lshl_add_u64 v[64:65], v[158:159], 0, s[4:5]
	v_pk_mul_f32 v[54:55], v[54:55], v[66:67] op_sel_hi:[1,0]
	v_add_f32_e32 v60, 1.0, v60
	v_add_f32_e32 v61, 1.0, v61
	v_rcp_f32_e32 v60, v60
	v_rcp_f32_e32 v61, v61
	v_pk_mul_f32 v[48:49], v[48:49], v[66:67] op_sel_hi:[1,0]
	v_mul_f32_e32 v54, 0xbfb8aa3b, v54
	v_mul_f32_e32 v55, 0xbfb8aa3b, v55
	v_exp_f32_e32 v54, v54
	v_exp_f32_e32 v55, v55
	v_mul_f32_e32 v48, 0xbfb8aa3b, v48
	v_mul_f32_e32 v49, 0xbfb8aa3b, v49
	v_exp_f32_e32 v48, v48
	v_exp_f32_e32 v49, v49
	v_add_f32_e32 v54, 1.0, v54
	v_add_f32_e32 v55, 1.0, v55
; __device__ __forceinline__ unsigned cvt_pk_bf16(float lo, float hi) { const f32x2_cv v = {lo, hi}; const bf16x2_cv b = __builtin_convertvector(v, bf16x2_cv); return __builtin_bit_cast(unsigned, b); }
; __device__ __forceinline__ float sigm(float x) { return __builtin_amdgcn_rcpf(1.0f + __expf(-x)); }
; __device__ __forceinline__ float lo16(unsigned w) { return __uint_as_float(w << 16); }
; __device__ __forceinline__ float hi16(unsigned w) { return __uint_as_float(w & 0xffff0000u); }
; __device__ __forceinline__ float rstd_of(const float* rowss, int row) { return rsqrtf(rowss[row] * (1.0f / 1024.0f) + 1e-6f); }
;     __device__ __forceinline__ void operator()(const f32x4 (&acc)[2][2][4][2], const pg8::Unit& u, int wr, int wc, int fr, int fq) const {
;     ...
;                 const int row = row0 + ai * 128 + m * 16;
;                 const float s = rstd_of(rowss, row);
; #pragma unroll
;                 for (int bj = 0; bj < 2; ++bj) {
;                     const size_t off = (size_t)row * 1024 + col0 + bj * 128;
;                     const u32x4 tv = *(const u32x4*)(Tm + off);
;                     u32x4 pv = (u32x4){0u, 0u, 0u, 0u};
;                     if (ACC) pv = *(const u32x4*)(M + off);
;                     const f32x4 a0 = acc[ai][bj][m][0] * s, a1 = acc[ai][bj][m][1] * s;
;                     float o[8];
;                     o[0] = sigm(a0[0]) * lo16(tv.x); o[1] = sigm(a0[1]) * hi16(tv.x); o[2] = sigm(a0[2]) * lo16(tv.y); o[3] = sigm(a0[3]) * hi16(tv.y);
;                     o[4] = sigm(a1[0]) * lo16(tv.z); o[5] = sigm(a1[1]) * hi16(tv.z); o[6] = sigm(a1[2]) * lo16(tv.w); o[7] = sigm(a1[3]) * hi16(tv.w);
;                     if (ACC) { o[0] += lo16(pv.x); o[1] += hi16(pv.x); o[2] += lo16(pv.y); o[3] += hi16(pv.y); o[4] += lo16(pv.z); o[5] += hi16(pv.z); o[6] += lo16(pv.w); o[7] += hi16(pv.w); }
;                     u32x4 w; w.x = cvt_pk_bf16(o[0], o[1]); w.y = cvt_pk_bf16(o[2], o[3]); w.z = cvt_pk_bf16(o[4], o[5]); w.w = cvt_pk_bf16(o[6], o[7]);
;                     *(u32x4*)(M + off) = w; } }
	v_rcp_f32_e32 v54, v54
	v_rcp_f32_e32 v55, v55
	v_add_f32_e32 v48, 1.0, v48
	v_add_f32_e32 v49, 1.0, v49
	v_rcp_f32_e32 v48, v48
	v_rcp_f32_e32 v49, v49
	v_pk_mul_f32 v[52:53], v[52:53], v[66:67] op_sel_hi:[1,0]
	v_pk_mul_f32 v[50:51], v[50:51], v[66:67] op_sel_hi:[1,0]
	v_mul_f32_e32 v52, 0xbfb8aa3b, v52
	v_mul_f32_e32 v53, 0xbfb8aa3b, v53
	v_exp_f32_e32 v52, v52
	v_exp_f32_e32 v53, v53
	s_mov_b32 s2, 0x48000
	s_mov_b64 s[4:5], 0x48000
	v_add_f32_e32 v52, 1.0, v52
	v_add_f32_e32 v53, 1.0, v53
	v_rcp_f32_e32 v52, v52
	v_rcp_f32_e32 v53, v53
	v_lshlrev_b32_e32 v74, 16, v68
	v_and_b32_e32 v75, 0xffff0000, v68
	v_lshlrev_b32_e32 v68, 16, v69
	v_and_b32_e32 v69, 0xffff0000, v69
	v_pk_mul_f32 v[62:63], v[62:63], v[68:69]
	v_lshlrev_b32_e32 v68, 16, v70
	v_and_b32_e32 v69, 0xffff0000, v70
	v_pk_mul_f32 v[68:69], v[56:57], v[68:69]
	v_mul_f32_e32 v56, 0xbfb8aa3b, v58
	v_mul_f32_e32 v57, 0xbfb8aa3b, v59
	v_exp_f32_e32 v56, v56
	v_exp_f32_e32 v57, v57
	v_lshlrev_b32_e32 v58, 16, v71
	v_and_b32_e32 v59, 0xffff0000, v71
	v_add_f32_e32 v56, 1.0, v56
	v_add_f32_e32 v57, 1.0, v57
	v_rcp_f32_e32 v56, v56
	v_rcp_f32_e32 v57, v57
	v_pk_mul_f32 v[60:61], v[60:61], v[74:75]
	v_pk_mul_f32 v[70:71], v[56:57], v[58:59]
	v_cvt_pk_bf16_f32 v56, v60, v61
	v_cvt_pk_bf16_f32 v57, v62, v63
	v_cvt_pk_bf16_f32 v58, v68, v69
	v_cvt_pk_bf16_f32 v59, v70, v71
	global_store_dwordx4 v[72:73], v[56:59], off
	s_nop 1
	v_mov_b32_e32 v56, v228
	v_mov_b32_e32 v57, v229
	v_mov_b32_e32 v58, v230
	v_mov_b32_e32 v59, v231
	v_lshlrev_b32_e32 v60, 16, v56
	v_and_b32_e32 v61, 0xffff0000, v56
	v_lshlrev_b32_e32 v56, 16, v57
	v_and_b32_e32 v57, 0xffff0000, v57
	v_pk_mul_f32 v[54:55], v[54:55], v[56:57]
	v_lshlrev_b32_e32 v56, 16, v58
	v_and_b32_e32 v57, 0xffff0000, v58
	v_pk_mul_f32 v[56:57], v[48:49], v[56:57]
	v_mul_f32_e32 v48, 0xbfb8aa3b, v50
	v_mul_f32_e32 v49, 0xbfb8aa3b, v51
	v_exp_f32_e32 v48, v48
	v_exp_f32_e32 v49, v49
	v_lshlrev_b32_e32 v50, 16, v59
	v_and_b32_e32 v51, 0xffff0000, v59
	v_add_f32_e32 v48, 1.0, v48
	v_add_f32_e32 v49, 1.0, v49
	v_rcp_f32_e32 v48, v48
	v_rcp_f32_e32 v49, v49
	v_pk_mul_f32 v[52:53], v[52:53], v[60:61]
	v_pk_mul_f32 v[58:59], v[48:49], v[50:51]
	v_cvt_pk_bf16_f32 v48, v52, v53
	v_cvt_pk_bf16_f32 v49, v54, v55
	v_cvt_pk_bf16_f32 v50, v56, v57
	v_cvt_pk_bf16_f32 v51, v58, v59
	global_store_dwordx4 v[64:65], v[48:51], off offset:256
	s_nop 1
	v_mov_b32_e32 v48, v240
	v_fmamk_f32 v48, v48, 0x3a800000, v187
	v_cmp_gt_f32_e32 vcc, s67, v48
	v_mul_f32_e32 v49, 0x4b800000, v48
	s_nop 0
	v_cndmask_b32_e32 v48, v48, v49, vcc
	v_rsq_f32_e32 v48, v48
	s_nop 0
	v_mul_f32_e32 v49, 0x45800000, v48
	v_cndmask_b32_e32 v50, v48, v49, vcc
	v_add_co_u32_e32 v56, vcc, s2, v158
	v_pk_mul_f32 v[46:47], v[46:47], v[50:51] op_sel_hi:[1,0]
	s_nop 0
	v_addc_co_u32_e32 v57, vcc, 0, v159, vcc
	s_nop 1
	v_mov_b32_e32 v52, v232
	v_mov_b32_e32 v53, v233
	v_mov_b32_e32 v54, v234
	v_mov_b32_e32 v55, v235
	v_pk_mul_f32 v[40:41], v[40:41], v[50:51] op_sel_hi:[1,0]
	v_mul_f32_e32 v46, 0xbfb8aa3b, v46
	v_mul_f32_e32 v47, 0xbfb8aa3b, v47
	v_exp_f32_e32 v46, v46
	v_exp_f32_e32 v47, v47
	v_mul_f32_e32 v40, 0xbfb8aa3b, v40
	v_mul_f32_e32 v41, 0xbfb8aa3b, v41
	v_exp_f32_e32 v40, v40
	v_exp_f32_e32 v41, v41
	v_add_f32_e32 v46, 1.0, v46
	v_add_f32_e32 v47, 1.0, v47
	v_rcp_f32_e32 v46, v46
	v_rcp_f32_e32 v47, v47
	v_add_f32_e32 v40, 1.0, v40
	v_add_f32_e32 v41, 1.0, v41
	v_rcp_f32_e32 v40, v40
	v_rcp_f32_e32 v41, v41
	v_pk_mul_f32 v[44:45], v[44:45], v[50:51] op_sel_hi:[1,0]
	v_pk_mul_f32 v[42:43], v[42:43], v[50:51] op_sel_hi:[1,0]
	v_mul_f32_e32 v44, 0xbfb8aa3b, v44
	v_mul_f32_e32 v45, 0xbfb8aa3b, v45
	v_exp_f32_e32 v44, v44
	v_exp_f32_e32 v45, v45
	v_lshl_add_u64 v[48:49], v[158:159], 0, s[4:5]
	v_pk_mul_f32 v[38:39], v[38:39], v[50:51] op_sel_hi:[1,0]
	v_add_f32_e32 v44, 1.0, v44
	v_add_f32_e32 v45, 1.0, v45
	v_rcp_f32_e32 v44, v44
	v_rcp_f32_e32 v45, v45
	v_pk_mul_f32 v[32:33], v[32:33], v[50:51] op_sel_hi:[1,0]
	v_mul_f32_e32 v38, 0xbfb8aa3b, v38
	v_mul_f32_e32 v39, 0xbfb8aa3b, v39
	v_exp_f32_e32 v38, v38
	v_exp_f32_e32 v39, v39
	v_mul_f32_e32 v32, 0xbfb8aa3b, v32
	v_mul_f32_e32 v33, 0xbfb8aa3b, v33
	v_exp_f32_e32 v32, v32
	v_exp_f32_e32 v33, v33
	v_add_f32_e32 v38, 1.0, v38
	v_add_f32_e32 v39, 1.0, v39
	v_rcp_f32_e32 v38, v38
	v_rcp_f32_e32 v39, v39
	v_add_f32_e32 v32, 1.0, v32
	v_add_f32_e32 v33, 1.0, v33
	v_rcp_f32_e32 v32, v32
	v_rcp_f32_e32 v33, v33
	v_pk_mul_f32 v[36:37], v[36:37], v[50:51] op_sel_hi:[1,0]
	v_pk_mul_f32 v[34:35], v[34:35], v[50:51] op_sel_hi:[1,0]
	v_mul_f32_e32 v36, 0xbfb8aa3b, v36
	v_mul_f32_e32 v37, 0xbfb8aa3b, v37
	v_exp_f32_e32 v36, v36
	v_exp_f32_e32 v37, v37
	s_mov_b32 s2, 0x50000
	s_mov_b64 s[4:5], 0x50000
	v_add_f32_e32 v36, 1.0, v36
	v_add_f32_e32 v37, 1.0, v37
	v_rcp_f32_e32 v36, v36
	v_rcp_f32_e32 v37, v37
	v_lshlrev_b32_e32 v58, 16, v52
	v_and_b32_e32 v59, 0xffff0000, v52
	v_lshlrev_b32_e32 v52, 16, v53
	v_and_b32_e32 v53, 0xffff0000, v53
	v_pk_mul_f32 v[46:47], v[46:47], v[52:53]
	v_lshlrev_b32_e32 v52, 16, v54
	v_and_b32_e32 v53, 0xffff0000, v54
	v_pk_mul_f32 v[52:53], v[40:41], v[52:53]
	v_mul_f32_e32 v40, 0xbfb8aa3b, v42
	v_mul_f32_e32 v41, 0xbfb8aa3b, v43
	v_exp_f32_e32 v40, v40
	v_exp_f32_e32 v41, v41
	v_lshlrev_b32_e32 v42, 16, v55
	v_and_b32_e32 v43, 0xffff0000, v55
	v_add_f32_e32 v40, 1.0, v40
	v_add_f32_e32 v41, 1.0, v41
	v_rcp_f32_e32 v40, v40
	v_rcp_f32_e32 v41, v41
	v_pk_mul_f32 v[44:45], v[44:45], v[58:59]
	v_pk_mul_f32 v[54:55], v[40:41], v[42:43]
	v_cvt_pk_bf16_f32 v40, v44, v45
	v_cvt_pk_bf16_f32 v41, v46, v47
	v_cvt_pk_bf16_f32 v42, v52, v53
	v_cvt_pk_bf16_f32 v43, v54, v55
	global_store_dwordx4 v[56:57], v[40:43], off
	s_nop 1
; __device__ __forceinline__ unsigned cvt_pk_bf16(float lo, float hi) { const f32x2_cv v = {lo, hi}; const bf16x2_cv b = __builtin_convertvector(v, bf16x2_cv); return __builtin_bit_cast(unsigned, b); }
; __device__ __forceinline__ float sigm(float x) { return __builtin_amdgcn_rcpf(1.0f + __expf(-x)); }
; __device__ __forceinline__ float lo16(unsigned w) { return __uint_as_float(w << 16); }
; __device__ __forceinline__ float hi16(unsigned w) { return __uint_as_float(w & 0xffff0000u); }
; __device__ __forceinline__ float rstd_of(const float* rowss, int row) { return rsqrtf(rowss[row] * (1.0f / 1024.0f) + 1e-6f); }
;     __device__ __forceinline__ void operator()(const f32x4 (&acc)[2][2][4][2], const pg8::Unit& u, int wr, int wc, int fr, int fq) const {
;     ...
;                 const int row = row0 + ai * 128 + m * 16;
;                 const float s = rstd_of(rowss, row);
; #pragma unroll
;                 for (int bj = 0; bj < 2; ++bj) {
;                     const size_t off = (size_t)row * 1024 + col0 + bj * 128;
;                     const u32x4 tv = *(const u32x4*)(Tm + off);
;                     u32x4 pv = (u32x4){0u, 0u, 0u, 0u};
;                     if (ACC) pv = *(const u32x4*)(M + off);
;                     const f32x4 a0 = acc[ai][bj][m][0] * s, a1 = acc[ai][bj][m][1] * s;
;                     float o[8];
;                     o[0] = sigm(a0[0]) * lo16(tv.x); o[1] = sigm(a0[1]) * hi16(tv.x); o[2] = sigm(a0[2]) * lo16(tv.y); o[3] = sigm(a0[3]) * hi16(tv.y);
;                     o[4] = sigm(a1[0]) * lo16(tv.z); o[5] = sigm(a1[1]) * hi16(tv.z); o[6] = sigm(a1[2]) * lo16(tv.w); o[7] = sigm(a1[3]) * hi16(tv.w);
;                     if (ACC) { o[0] += lo16(pv.x); o[1] += hi16(pv.x); o[2] += lo16(pv.y); o[3] += hi16(pv.y); o[4] += lo16(pv.z); o[5] += hi16(pv.z); o[6] += lo16(pv.w); o[7] += hi16(pv.w); }
;                     u32x4 w; w.x = cvt_pk_bf16(o[0], o[1]); w.y = cvt_pk_bf16(o[2], o[3]); w.z = cvt_pk_bf16(o[4], o[5]); w.w = cvt_pk_bf16(o[6], o[7]);
;                     *(u32x4*)(M + off) = w; } }
	v_mov_b32_e32 v40, v236
	v_mov_b32_e32 v41, v237
	v_mov_b32_e32 v42, v238
	v_mov_b32_e32 v43, v239
	v_lshlrev_b32_e32 v44, 16, v40
	v_and_b32_e32 v45, 0xffff0000, v40
	v_lshlrev_b32_e32 v40, 16, v41
	v_and_b32_e32 v41, 0xffff0000, v41
	v_pk_mul_f32 v[38:39], v[38:39], v[40:41]
	v_lshlrev_b32_e32 v40, 16, v42
	v_and_b32_e32 v41, 0xffff0000, v42
	v_pk_mul_f32 v[40:41], v[32:33], v[40:41]
	v_mul_f32_e32 v32, 0xbfb8aa3b, v34
	v_mul_f32_e32 v33, 0xbfb8aa3b, v35
	v_exp_f32_e32 v32, v32
	v_exp_f32_e32 v33, v33
	v_lshlrev_b32_e32 v34, 16, v43
	v_and_b32_e32 v35, 0xffff0000, v43
	v_add_f32_e32 v32, 1.0, v32
	v_add_f32_e32 v33, 1.0, v33
	v_rcp_f32_e32 v32, v32
	v_rcp_f32_e32 v33, v33
	v_pk_mul_f32 v[36:37], v[36:37], v[44:45]
	v_pk_mul_f32 v[42:43], v[32:33], v[34:35]
	v_cvt_pk_bf16_f32 v32, v36, v37
	v_cvt_pk_bf16_f32 v33, v38, v39
	v_cvt_pk_bf16_f32 v34, v40, v41
	v_cvt_pk_bf16_f32 v35, v42, v43
	global_store_dwordx4 v[48:49], v[32:35], off offset:256
	s_nop 1
	v_mov_b32_e32 v32, v241
	v_fmamk_f32 v32, v32, 0x3a800000, v187
	v_cmp_gt_f32_e32 vcc, s67, v32
	v_mul_f32_e32 v33, 0x4b800000, v32
	s_nop 0
	v_cndmask_b32_e32 v32, v32, v33, vcc
	v_rsq_f32_e32 v32, v32
	s_nop 0
	v_mul_f32_e32 v33, 0x45800000, v32
	v_cndmask_b32_e32 v34, v32, v33, vcc
	v_add_co_u32_e32 v40, vcc, s2, v158
	v_pk_mul_f32 v[30:31], v[30:31], v[34:35] op_sel_hi:[1,0]
	s_nop 0
	v_addc_co_u32_e32 v41, vcc, 0, v159, vcc
	s_nop 1
	v_mov_b32_e32 v36, v244
	v_mov_b32_e32 v37, v245
	v_mov_b32_e32 v38, v246
	v_mov_b32_e32 v39, v247
	v_pk_mul_f32 v[24:25], v[24:25], v[34:35] op_sel_hi:[1,0]
	v_mul_f32_e32 v30, 0xbfb8aa3b, v30
	v_mul_f32_e32 v31, 0xbfb8aa3b, v31
	v_exp_f32_e32 v30, v30
	v_exp_f32_e32 v31, v31
	v_mul_f32_e32 v24, 0xbfb8aa3b, v24
	v_mul_f32_e32 v25, 0xbfb8aa3b, v25
	v_exp_f32_e32 v24, v24
	v_exp_f32_e32 v25, v25
	v_add_f32_e32 v30, 1.0, v30
	v_add_f32_e32 v31, 1.0, v31
	v_rcp_f32_e32 v30, v30
	v_rcp_f32_e32 v31, v31
	v_add_f32_e32 v24, 1.0, v24
	v_add_f32_e32 v25, 1.0, v25
	v_rcp_f32_e32 v24, v24
	v_rcp_f32_e32 v25, v25
	v_pk_mul_f32 v[28:29], v[28:29], v[34:35] op_sel_hi:[1,0]
	v_pk_mul_f32 v[26:27], v[26:27], v[34:35] op_sel_hi:[1,0]
	v_mul_f32_e32 v28, 0xbfb8aa3b, v28
	v_mul_f32_e32 v29, 0xbfb8aa3b, v29
	v_exp_f32_e32 v28, v28
	v_exp_f32_e32 v29, v29
	v_lshl_add_u64 v[32:33], v[158:159], 0, s[4:5]
	v_pk_mul_f32 v[22:23], v[22:23], v[34:35] op_sel_hi:[1,0]
	v_add_f32_e32 v28, 1.0, v28
	v_add_f32_e32 v29, 1.0, v29
	v_rcp_f32_e32 v28, v28
	v_rcp_f32_e32 v29, v29
	v_pk_mul_f32 v[16:17], v[16:17], v[34:35] op_sel_hi:[1,0]
	v_mul_f32_e32 v22, 0xbfb8aa3b, v22
	v_mul_f32_e32 v23, 0xbfb8aa3b, v23
	v_exp_f32_e32 v22, v22
	v_exp_f32_e32 v23, v23
	v_mul_f32_e32 v16, 0xbfb8aa3b, v16
	v_mul_f32_e32 v17, 0xbfb8aa3b, v17
	v_exp_f32_e32 v16, v16
	v_exp_f32_e32 v17, v17
	v_add_f32_e32 v22, 1.0, v22
	v_add_f32_e32 v23, 1.0, v23
	v_rcp_f32_e32 v22, v22
	v_rcp_f32_e32 v23, v23
	v_add_f32_e32 v16, 1.0, v16
	v_add_f32_e32 v17, 1.0, v17
	v_rcp_f32_e32 v16, v16
	v_rcp_f32_e32 v17, v17
	v_pk_mul_f32 v[20:21], v[20:21], v[34:35] op_sel_hi:[1,0]
	v_pk_mul_f32 v[18:19], v[18:19], v[34:35] op_sel_hi:[1,0]
	v_mul_f32_e32 v20, 0xbfb8aa3b, v20
	v_mul_f32_e32 v21, 0xbfb8aa3b, v21
	v_exp_f32_e32 v20, v20
	v_exp_f32_e32 v21, v21
	s_mov_b32 s2, 0x58000
	s_mov_b64 s[4:5], 0x58000
	v_add_f32_e32 v20, 1.0, v20
	v_add_f32_e32 v21, 1.0, v21
	v_rcp_f32_e32 v20, v20
	v_rcp_f32_e32 v21, v21
	v_lshlrev_b32_e32 v42, 16, v36
	v_and_b32_e32 v43, 0xffff0000, v36
	v_lshlrev_b32_e32 v36, 16, v37
	v_and_b32_e32 v37, 0xffff0000, v37
	v_pk_mul_f32 v[30:31], v[30:31], v[36:37]
	v_lshlrev_b32_e32 v36, 16, v38
	v_and_b32_e32 v37, 0xffff0000, v38
	v_pk_mul_f32 v[36:37], v[24:25], v[36:37]
	v_mul_f32_e32 v24, 0xbfb8aa3b, v26
	v_mul_f32_e32 v25, 0xbfb8aa3b, v27
	v_exp_f32_e32 v24, v24
	v_exp_f32_e32 v25, v25
	v_lshlrev_b32_e32 v26, 16, v39
	v_and_b32_e32 v27, 0xffff0000, v39
	v_add_f32_e32 v24, 1.0, v24
	v_add_f32_e32 v25, 1.0, v25
	v_rcp_f32_e32 v24, v24
	v_rcp_f32_e32 v25, v25
	v_pk_mul_f32 v[28:29], v[28:29], v[42:43]
	v_pk_mul_f32 v[38:39], v[24:25], v[26:27]
	v_cvt_pk_bf16_f32 v24, v28, v29
	v_cvt_pk_bf16_f32 v25, v30, v31
	v_cvt_pk_bf16_f32 v26, v36, v37
	v_cvt_pk_bf16_f32 v27, v38, v39
	global_store_dwordx4 v[40:41], v[24:27], off
	s_nop 1
	v_mov_b32_e32 v24, v248
	v_mov_b32_e32 v25, v249
	v_mov_b32_e32 v26, v250
	v_mov_b32_e32 v27, v251
	v_lshlrev_b32_e32 v28, 16, v24
	v_and_b32_e32 v29, 0xffff0000, v24
	v_lshlrev_b32_e32 v24, 16, v25
	v_and_b32_e32 v25, 0xffff0000, v25
	v_pk_mul_f32 v[22:23], v[22:23], v[24:25]
	v_lshlrev_b32_e32 v24, 16, v26
	v_and_b32_e32 v25, 0xffff0000, v26
	v_pk_mul_f32 v[24:25], v[16:17], v[24:25]
	v_mul_f32_e32 v16, 0xbfb8aa3b, v18
	v_mul_f32_e32 v17, 0xbfb8aa3b, v19
; __device__ __forceinline__ unsigned cvt_pk_bf16(float lo, float hi) { const f32x2_cv v = {lo, hi}; const bf16x2_cv b = __builtin_convertvector(v, bf16x2_cv); return __builtin_bit_cast(unsigned, b); }
; __device__ __forceinline__ float sigm(float x) { return __builtin_amdgcn_rcpf(1.0f + __expf(-x)); }
; __device__ __forceinline__ float lo16(unsigned w) { return __uint_as_float(w << 16); }
; __device__ __forceinline__ float hi16(unsigned w) { return __uint_as_float(w & 0xffff0000u); }
; __device__ __forceinline__ float rstd_of(const float* rowss, int row) { return rsqrtf(rowss[row] * (1.0f / 1024.0f) + 1e-6f); }
;     __device__ __forceinline__ void operator()(const f32x4 (&acc)[2][2][4][2], const pg8::Unit& u, int wr, int wc, int fr, int fq) const {
;     ...
;                 const int row = row0 + ai * 128 + m * 16;
;                 const float s = rstd_of(rowss, row);
; #pragma unroll
;                 for (int bj = 0; bj < 2; ++bj) {
;                     const size_t off = (size_t)row * 1024 + col0 + bj * 128;
;                     const u32x4 tv = *(const u32x4*)(Tm + off);
;                     u32x4 pv = (u32x4){0u, 0u, 0u, 0u};
;                     if (ACC) pv = *(const u32x4*)(M + off);
;                     const f32x4 a0 = acc[ai][bj][m][0] * s, a1 = acc[ai][bj][m][1] * s;
;                     float o[8];
;                     o[0] = sigm(a0[0]) * lo16(tv.x); o[1] = sigm(a0[1]) * hi16(tv.x); o[2] = sigm(a0[2]) * lo16(tv.y); o[3] = sigm(a0[3]) * hi16(tv.y);
;                     o[4] = sigm(a1[0]) * lo16(tv.z); o[5] = sigm(a1[1]) * hi16(tv.z); o[6] = sigm(a1[2]) * lo16(tv.w); o[7] = sigm(a1[3]) * hi16(tv.w);
;                     if (ACC) { o[0] += lo16(pv.x); o[1] += hi16(pv.x); o[2] += lo16(pv.y); o[3] += hi16(pv.y); o[4] += lo16(pv.z); o[5] += hi16(pv.z); o[6] += lo16(pv.w); o[7] += hi16(pv.w); }
;                     u32x4 w; w.x = cvt_pk_bf16(o[0], o[1]); w.y = cvt_pk_bf16(o[2], o[3]); w.z = cvt_pk_bf16(o[4], o[5]); w.w = cvt_pk_bf16(o[6], o[7]);
;                     *(u32x4*)(M + off) = w; } }
	v_exp_f32_e32 v16, v16
	v_exp_f32_e32 v17, v17
	v_lshlrev_b32_e32 v18, 16, v27
	v_and_b32_e32 v19, 0xffff0000, v27
	v_add_f32_e32 v16, 1.0, v16
	v_add_f32_e32 v17, 1.0, v17
	v_rcp_f32_e32 v16, v16
	v_rcp_f32_e32 v17, v17
	v_pk_mul_f32 v[20:21], v[20:21], v[28:29]
	v_pk_mul_f32 v[26:27], v[16:17], v[18:19]
	v_cvt_pk_bf16_f32 v16, v20, v21
	v_cvt_pk_bf16_f32 v17, v22, v23
	v_cvt_pk_bf16_f32 v18, v24, v25
	v_cvt_pk_bf16_f32 v19, v26, v27
	global_store_dwordx4 v[32:33], v[16:19], off offset:256
	s_nop 1
	v_mov_b32_e32 v16, v169
	v_fmamk_f32 v16, v16, 0x3a800000, v187
	v_cmp_gt_f32_e32 vcc, s67, v16
	v_mul_f32_e32 v17, 0x4b800000, v16
	s_nop 0
	v_cndmask_b32_e32 v16, v16, v17, vcc
	v_rsq_f32_e32 v16, v16
	s_nop 0
	v_mul_f32_e32 v17, 0x45800000, v16
	v_cndmask_b32_e32 v18, v16, v17, vcc
	v_add_co_u32_e32 v24, vcc, s2, v158
	v_pk_mul_f32 v[14:15], v[14:15], v[18:19] op_sel_hi:[1,0]
	s_nop 0
	v_addc_co_u32_e32 v25, vcc, 0, v159, vcc
	s_nop 1
	v_mov_b32_e32 v20, v176
	v_mov_b32_e32 v21, v177
	v_mov_b32_e32 v22, v178
	v_mov_b32_e32 v23, v179
	v_pk_mul_f32 v[8:9], v[8:9], v[18:19] op_sel_hi:[1,0]
	v_mul_f32_e32 v14, 0xbfb8aa3b, v14
	v_mul_f32_e32 v15, 0xbfb8aa3b, v15
	v_exp_f32_e32 v14, v14
	v_exp_f32_e32 v15, v15
	v_mul_f32_e32 v8, 0xbfb8aa3b, v8
	v_mul_f32_e32 v9, 0xbfb8aa3b, v9
	v_exp_f32_e32 v8, v8
	v_exp_f32_e32 v9, v9
	v_add_f32_e32 v14, 1.0, v14
	v_add_f32_e32 v15, 1.0, v15
	v_rcp_f32_e32 v14, v14
	v_rcp_f32_e32 v15, v15
	v_add_f32_e32 v8, 1.0, v8
	v_add_f32_e32 v9, 1.0, v9
	v_rcp_f32_e32 v8, v8
	v_rcp_f32_e32 v9, v9
	v_pk_mul_f32 v[12:13], v[12:13], v[18:19] op_sel_hi:[1,0]
	v_pk_mul_f32 v[10:11], v[10:11], v[18:19] op_sel_hi:[1,0]
	v_mul_f32_e32 v12, 0xbfb8aa3b, v12
	v_mul_f32_e32 v13, 0xbfb8aa3b, v13
	v_exp_f32_e32 v12, v12
	v_exp_f32_e32 v13, v13
	v_lshl_add_u64 v[16:17], v[158:159], 0, s[4:5]
	v_pk_mul_f32 v[6:7], v[6:7], v[18:19] op_sel_hi:[1,0]
	v_add_f32_e32 v12, 1.0, v12
	v_add_f32_e32 v13, 1.0, v13
	v_rcp_f32_e32 v12, v12
	v_rcp_f32_e32 v13, v13
	v_pk_mul_f32 v[0:1], v[0:1], v[18:19] op_sel_hi:[1,0]
	v_mul_f32_e32 v6, 0xbfb8aa3b, v6
	v_mul_f32_e32 v7, 0xbfb8aa3b, v7
	v_exp_f32_e32 v6, v6
	v_exp_f32_e32 v7, v7
	v_mul_f32_e32 v0, 0xbfb8aa3b, v0
	v_mul_f32_e32 v1, 0xbfb8aa3b, v1
	v_exp_f32_e32 v0, v0
	v_exp_f32_e32 v1, v1
	v_add_f32_e32 v6, 1.0, v6
	v_add_f32_e32 v7, 1.0, v7
	v_rcp_f32_e32 v6, v6
	v_rcp_f32_e32 v7, v7
	v_add_f32_e32 v0, 1.0, v0
	v_add_f32_e32 v1, 1.0, v1
	v_rcp_f32_e32 v0, v0
	v_rcp_f32_e32 v1, v1
	v_pk_mul_f32 v[4:5], v[4:5], v[18:19] op_sel_hi:[1,0]
	v_pk_mul_f32 v[2:3], v[2:3], v[18:19] op_sel_hi:[1,0]
	v_mul_f32_e32 v4, 0xbfb8aa3b, v4
	v_mul_f32_e32 v5, 0xbfb8aa3b, v5
	v_exp_f32_e32 v4, v4
	v_exp_f32_e32 v5, v5
	s_and_b64 vcc, exec, s[38:39]
	s_mov_b32 s2, s30
	v_add_f32_e32 v4, 1.0, v4
	v_add_f32_e32 v5, 1.0, v5
	v_rcp_f32_e32 v4, v4
	v_rcp_f32_e32 v5, v5
	s_mov_b64 s[4:5], s[48:49]
	v_lshlrev_b32_e32 v26, 16, v20
	v_and_b32_e32 v27, 0xffff0000, v20
	v_lshlrev_b32_e32 v20, 16, v21
	v_and_b32_e32 v21, 0xffff0000, v21
	v_pk_mul_f32 v[14:15], v[14:15], v[20:21]
	v_lshlrev_b32_e32 v20, 16, v22
	v_and_b32_e32 v21, 0xffff0000, v22
	v_pk_mul_f32 v[20:21], v[8:9], v[20:21]
	v_mul_f32_e32 v8, 0xbfb8aa3b, v10
	v_mul_f32_e32 v9, 0xbfb8aa3b, v11
	v_exp_f32_e32 v8, v8
	v_exp_f32_e32 v9, v9
	v_lshlrev_b32_e32 v10, 16, v23
	v_and_b32_e32 v11, 0xffff0000, v23
	v_add_f32_e32 v8, 1.0, v8
	v_add_f32_e32 v9, 1.0, v9
	v_rcp_f32_e32 v8, v8
	v_rcp_f32_e32 v9, v9
	v_pk_mul_f32 v[12:13], v[12:13], v[26:27]
	v_pk_mul_f32 v[22:23], v[8:9], v[10:11]
	v_cvt_pk_bf16_f32 v8, v12, v13
	v_cvt_pk_bf16_f32 v9, v14, v15
	v_cvt_pk_bf16_f32 v10, v20, v21
	v_cvt_pk_bf16_f32 v11, v22, v23
	global_store_dwordx4 v[24:25], v[8:11], off
	s_nop 1
	v_mov_b32_e32 v8, v252
	v_mov_b32_e32 v9, v253
	v_mov_b32_e32 v10, v254
	v_mov_b32_e32 v11, v255
	v_lshlrev_b32_e32 v12, 16, v8
	v_and_b32_e32 v13, 0xffff0000, v8
	v_lshlrev_b32_e32 v8, 16, v9
	v_and_b32_e32 v9, 0xffff0000, v9
	v_pk_mul_f32 v[6:7], v[6:7], v[8:9]
	v_lshlrev_b32_e32 v8, 16, v10
	v_and_b32_e32 v9, 0xffff0000, v10
	v_pk_mul_f32 v[8:9], v[0:1], v[8:9]
	v_mul_f32_e32 v0, 0xbfb8aa3b, v2
	v_mul_f32_e32 v1, 0xbfb8aa3b, v3
	v_exp_f32_e32 v0, v0
	v_exp_f32_e32 v1, v1
	v_lshlrev_b32_e32 v2, 16, v11
	v_and_b32_e32 v3, 0xffff0000, v11
	v_add_f32_e32 v0, 1.0, v0
	v_add_f32_e32 v1, 1.0, v1
	v_rcp_f32_e32 v0, v0
	v_rcp_f32_e32 v1, v1
	v_pk_mul_f32 v[4:5], v[4:5], v[12:13]
	v_pk_mul_f32 v[10:11], v[0:1], v[2:3]
	v_cvt_pk_bf16_f32 v0, v4, v5
	v_cvt_pk_bf16_f32 v1, v6, v7
	v_cvt_pk_bf16_f32 v2, v8, v9
	v_cvt_pk_bf16_f32 v3, v10, v11
	global_store_dwordx4 v[16:17], v[0:3], off offset:256
	s_cbranch_vccz .LBB0_306
	s_cmpk_gt_u32 s36, 0xff
	s_cbranch_scc1 .LBB0_317
	s_barrier

; #define PG8_STAGE(bufoff, gbase, voff) do { _Pragma("unroll") for (int _i = 0; _i < 2; ++_i) \
;         __builtin_amdgcn_global_load_lds((const unsigned*)((const char*)(gbase) + (voff)[_i]), (PG8_LAS unsigned*)(lds + (bufoff) + ldsw + _i * 8192), 16, 0, 0); } while (0)
; #define PG8_LDA(dst, b, h) do { _Pragma("unroll") for (int m = 0; m < 4; ++m) _Pragma("unroll") for (int k = 0; k < 2; ++k) dst[m][k] = *(const PG8_LAS bf16x8*)(lds + PG8_SA(b, h) + aoff + m * 2048 + k * 1024); } while (0)
; #define PG8_LDB(dst, b, h) do { _Pragma("unroll") for (int n = 0; n < 2; ++n) _Pragma("unroll") for (int k = 0; k < 2; ++k) dst[n][k] = *(const PG8_LAS bf16x8*)(lds + PG8_SB(b, h) + boff + n * 2048 + k * 1024); } while (0)
; #define PG8_MMA(ai, bj, At, Bt) do { __builtin_amdgcn_s_setprio(1); _Pragma("unroll") for (int m = 0; m < 4; ++m) _Pragma("unroll") for (int n = 0; n < 2; ++n) _Pragma("unroll") for (int k = 0; k < 2; ++k) \
;         acc[ai][bj][m][n] = __builtin_amdgcn_mfma_f32_16x16x32_bf16(Bt[n][k], At[m][k], acc[ai][bj][m][n], 0, 0, 0); __builtin_amdgcn_s_setprio(0); } while (0)
; #define PG8_WAIT_V(n) asm volatile("s_waitcnt vmcnt(" #n ")" ::: "memory")
; #define PG8_WAIT_L(n) asm volatile("s_waitcnt lgkmcnt(" #n ")" ::: "memory")
; #define PG8_BAR __builtin_amdgcn_s_barrier()
; #define PG8_SCHED __builtin_amdgcn_sched_barrier(0)
; template <class Epi, class Sched, bool STAMP = false>
; __device__ __forceinline__ void gemm_phase(PG8_LAS unsigned char* lds, const Gemm g, const Sched& S, const Epi& E, unsigned long long* stamps) {
;     ...
;             PG8_LDB(B0, 0, 0); PG8_SCHED; PG8_LDA(At, 0, 0); PG8_STAGE(PG8_SA(1, 1), a1 + hstep, voffA);
;             PG8_WAIT_L(8); PG8_BAR; PG8_WAIT_L(0); PG8_MMA(0, 0, At, B0); PG8_BAR; PG8_SCHED;
;             PG8_LDB(B1, 0, 1); PG8_STAGE(PG8_SB(0, 0), b2, voffB);
;             PG8_BAR; PG8_WAIT_L(0); PG8_MMA(0, 1, At, B1); PG8_BAR;
;             PG8_LDA(At, 0, 1); PG8_STAGE(PG8_SA(0, 0), a2, voffA);
;             PG8_BAR; PG8_WAIT_L(0); PG8_MMA(1, 0, At, B0); PG8_BAR; PG8_SCHED;
;             PG8_STAGE(PG8_SB(0, 1), b2 + hstep, voffB);
;             PG8_WAIT_V(6); PG8_BAR; PG8_MMA(1, 1, At, B1); PG8_BAR;
.LBB0_333:
	s_add_u32 s14, s36, 0xfffe0080
	s_addc_u32 s15, s37, -1
	s_add_i32 s16, 0, 0x10000
	ds_read_b128 v[162:165], v248
	ds_read_b128 v[166:169], v248 offset:1024
	ds_read_b128 v[170:173], v248 offset:2048
	ds_read_b128 v[174:177], v248 offset:3072
	s_cmp_eq_u32 s97, 4
	s_cselect_b32 s59, s13, s15
	s_cselect_b32 s58, s77, s14
	s_cselect_b32 s57, s5, s96
	s_cselect_b32 s56, s88, s89
	s_add_i32 m0, s3, 0xc000
	ds_read_b128 v[178:181], v160
	ds_read_b128 v[192:195], v160 offset:1024
	ds_read_b128 v[196:199], v160 offset:2048
	ds_read_b128 v[200:203], v160 offset:3072
	ds_read_b128 v[204:207], v160 offset:4096
	ds_read_b128 v[208:211], v160 offset:5120
	ds_read_b128 v[212:215], v160 offset:6144
	global_load_lds_dwordx4 v154, s[36:37]
	s_add_i32 m0, s3, 0xe000
	ds_read_b128 v[216:219], v160 offset:7168
	global_load_lds_dwordx4 v156, s[36:37]
	s_waitcnt lgkmcnt(8)
	s_barrier
	s_waitcnt lgkmcnt(0)
	v_mfma_f32_16x16x32_bf16 v[124:127], v[162:165], v[178:181], v[124:127]
	v_mfma_f32_16x16x32_bf16 v[120:123], v[170:173], v[178:181], v[120:123]
	v_mfma_f32_16x16x32_bf16 v[116:119], v[162:165], v[196:199], v[116:119]
	v_mfma_f32_16x16x32_bf16 v[112:115], v[170:173], v[196:199], v[112:115]
	v_mfma_f32_16x16x32_bf16 v[100:103], v[162:165], v[204:207], v[100:103]
	v_mfma_f32_16x16x32_bf16 v[96:99], v[170:173], v[204:207], v[96:99]
	v_mfma_f32_16x16x32_bf16 v[84:87], v[162:165], v[212:215], v[84:87]
	v_mfma_f32_16x16x32_bf16 v[80:83], v[170:173], v[212:215], v[80:83]
	v_mfma_f32_16x16x32_bf16 v[124:127], v[166:169], v[192:195], v[124:127]
	v_mfma_f32_16x16x32_bf16 v[120:123], v[174:177], v[192:195], v[120:123]
	v_mfma_f32_16x16x32_bf16 v[116:119], v[166:169], v[200:203], v[116:119]
	v_mfma_f32_16x16x32_bf16 v[112:115], v[174:177], v[200:203], v[112:115]
	v_mfma_f32_16x16x32_bf16 v[100:103], v[166:169], v[208:211], v[100:103]
	v_mfma_f32_16x16x32_bf16 v[96:99], v[174:177], v[208:211], v[96:99]
	v_mfma_f32_16x16x32_bf16 v[84:87], v[166:169], v[216:219], v[84:87]
	v_mfma_f32_16x16x32_bf16 v[80:83], v[174:177], v[216:219], v[80:83]
	s_barrier
	s_add_i32 s17, 0, 0x14000
	s_add_i32 s14, s16, s53
	s_mov_b32 m0, s14
	ds_read_b128 v[220:223], v249
	ds_read_b128 v[224:227], v249 offset:1024
	ds_read_b128 v[228:231], v249 offset:2048
	global_load_lds_dwordx4 v128, s[56:57]
	s_add_i32 m0, s14, 0x2000
	ds_read_b128 v[232:235], v249 offset:3072
	global_load_lds_dwordx4 v152, s[56:57]
	s_barrier
	s_waitcnt lgkmcnt(0)
	v_mfma_f32_16x16x32_bf16 v[108:111], v[220:223], v[178:181], v[108:111]
	v_mfma_f32_16x16x32_bf16 v[104:107], v[228:231], v[178:181], v[104:107]
	v_mfma_f32_16x16x32_bf16 v[92:95], v[220:223], v[196:199], v[92:95]
	v_mfma_f32_16x16x32_bf16 v[88:91], v[228:231], v[196:199], v[88:91]
	v_mfma_f32_16x16x32_bf16 v[76:79], v[220:223], v[204:207], v[76:79]
	v_mfma_f32_16x16x32_bf16 v[72:75], v[228:231], v[204:207], v[72:75]
	v_mfma_f32_16x16x32_bf16 v[68:71], v[220:223], v[212:215], v[68:71]
	v_mfma_f32_16x16x32_bf16 v[64:67], v[228:231], v[212:215], v[64:67]
	v_mfma_f32_16x16x32_bf16 v[108:111], v[224:227], v[192:195], v[108:111]
	v_mfma_f32_16x16x32_bf16 v[104:107], v[232:235], v[192:195], v[104:107]
	v_mfma_f32_16x16x32_bf16 v[92:95], v[224:227], v[200:203], v[92:95]
	v_mfma_f32_16x16x32_bf16 v[88:91], v[232:235], v[200:203], v[88:91]
	v_mfma_f32_16x16x32_bf16 v[76:79], v[224:227], v[208:211], v[76:79]
	v_mfma_f32_16x16x32_bf16 v[72:75], v[232:235], v[208:211], v[72:75]
	v_mfma_f32_16x16x32_bf16 v[68:71], v[224:227], v[216:219], v[68:71]
	v_mfma_f32_16x16x32_bf16 v[64:67], v[232:235], v[216:219], v[64:67]
	s_mov_b32 m0, s3
	s_barrier
	ds_read_b128 v[178:181], v160 offset:16384
	ds_read_b128 v[192:195], v160 offset:17408
	ds_read_b128 v[196:199], v160 offset:18432
	ds_read_b128 v[200:203], v160 offset:19456
	ds_read_b128 v[204:207], v160 offset:20480
	ds_read_b128 v[208:211], v160 offset:21504
	ds_read_b128 v[212:215], v160 offset:22528
	global_load_lds_dwordx4 v148, s[58:59]
	s_mov_b32 m0, s60
	ds_read_b128 v[216:219], v160 offset:23552
	global_load_lds_dwordx4 v150, s[58:59]
	s_barrier
	s_waitcnt lgkmcnt(0)
	v_mfma_f32_16x16x32_bf16 v[60:63], v[162:165], v[178:181], v[60:63]
	v_mfma_f32_16x16x32_bf16 v[56:59], v[170:173], v[178:181], v[56:59]
	v_mfma_f32_16x16x32_bf16 v[52:55], v[162:165], v[196:199], v[52:55]
	v_mfma_f32_16x16x32_bf16 v[48:51], v[170:173], v[196:199], v[48:51]
	v_mfma_f32_16x16x32_bf16 v[36:39], v[162:165], v[204:207], v[36:39]
	v_mfma_f32_16x16x32_bf16 v[32:35], v[170:173], v[204:207], v[32:35]
	v_mfma_f32_16x16x32_bf16 v[20:23], v[162:165], v[212:215], v[20:23]
	v_mfma_f32_16x16x32_bf16 v[16:19], v[170:173], v[212:215], v[16:19]
	v_mfma_f32_16x16x32_bf16 v[60:63], v[166:169], v[192:195], v[60:63]
	v_mfma_f32_16x16x32_bf16 v[56:59], v[174:177], v[192:195], v[56:59]
	v_mfma_f32_16x16x32_bf16 v[52:55], v[166:169], v[200:203], v[52:55]
	v_mfma_f32_16x16x32_bf16 v[48:51], v[174:177], v[200:203], v[48:51]
	v_mfma_f32_16x16x32_bf16 v[36:39], v[166:169], v[208:211], v[36:39]
	v_mfma_f32_16x16x32_bf16 v[32:35], v[174:177], v[208:211], v[32:35]
	v_mfma_f32_16x16x32_bf16 v[20:23], v[166:169], v[216:219], v[20:23]
	v_mfma_f32_16x16x32_bf16 v[16:19], v[174:177], v[216:219], v[16:19]
	s_barrier
	s_add_u32 s14, s56, 0x20000
	s_addc_u32 s15, s57, 0
	s_add_i32 s16, s17, s53
	s_mov_b32 m0, s16
	s_nop 0
	global_load_lds_dwordx4 v128, s[14:15]
	s_add_i32 m0, s16, 0x2000
	s_nop 0
	global_load_lds_dwordx4 v152, s[14:15]
	s_add_i32 s97, s97, 2
	s_add_u32 s36, s36, 0x100
	s_addc_u32 s37, s37, 0
	s_add_u32 s89, s89, 0x100
	s_addc_u32 s96, s96, 0
	s_waitcnt vmcnt(6)
	s_barrier
; #define PG8_STAGE(bufoff, gbase, voff) do { _Pragma("unroll") for (int _i = 0; _i < 2; ++_i) \
;         __builtin_amdgcn_global_load_lds((const unsigned*)((const char*)(gbase) + (voff)[_i]), (PG8_LAS unsigned*)(lds + (bufoff) + ldsw + _i * 8192), 16, 0, 0); } while (0)
; #define PG8_LDA(dst, b, h) do { _Pragma("unroll") for (int m = 0; m < 4; ++m) _Pragma("unroll") for (int k = 0; k < 2; ++k) dst[m][k] = *(const PG8_LAS bf16x8*)(lds + PG8_SA(b, h) + aoff + m * 2048 + k * 1024); } while (0)
; #define PG8_LDB(dst, b, h) do { _Pragma("unroll") for (int n = 0; n < 2; ++n) _Pragma("unroll") for (int k = 0; k < 2; ++k) dst[n][k] = *(const PG8_LAS bf16x8*)(lds + PG8_SB(b, h) + boff + n * 2048 + k * 1024); } while (0)
; #define PG8_MMA(ai, bj, At, Bt) do { __builtin_amdgcn_s_setprio(1); _Pragma("unroll") for (int m = 0; m < 4; ++m) _Pragma("unroll") for (int n = 0; n < 2; ++n) _Pragma("unroll") for (int k = 0; k < 2; ++k) \
;         acc[ai][bj][m][n] = __builtin_amdgcn_mfma_f32_16x16x32_bf16(Bt[n][k], At[m][k], acc[ai][bj][m][n], 0, 0, 0); __builtin_amdgcn_s_setprio(0); } while (0)
; #define PG8_WAIT_V(n) asm volatile("s_waitcnt vmcnt(" #n ")" ::: "memory")
; #define PG8_WAIT_L(n) asm volatile("s_waitcnt lgkmcnt(" #n ")" ::: "memory")
; #define PG8_BAR __builtin_amdgcn_s_barrier()
; #define PG8_SCHED __builtin_amdgcn_sched_barrier(0)
; template <class Epi, class Sched, bool STAMP = false>
; __device__ __forceinline__ void gemm_phase(PG8_LAS unsigned char* lds, const Gemm g, const Sched& S, const Epi& E, unsigned long long* stamps) {
;     ...
;             PG8_WAIT_V(6); PG8_BAR; PG8_MMA(1, 1, At, B1); PG8_BAR;
;             PG8_LDB(B0, 1, 0); PG8_SCHED; PG8_LDA(At, 1, 0); PG8_STAGE(PG8_SA(0, 1), a2 + hstep, voffA);
;             PG8_WAIT_L(8); PG8_BAR; PG8_WAIT_L(0); PG8_MMA(0, 0, At, B0); PG8_BAR; PG8_SCHED;
;             PG8_LDB(B1, 1, 1); PG8_STAGE(PG8_SB(1, 0), b3, voffB);
;             PG8_BAR; PG8_WAIT_L(0); PG8_MMA(0, 1, At, B1); PG8_BAR;
;             PG8_LDA(At, 1, 1); PG8_STAGE(PG8_SA(1, 0), a3, voffA);
;             PG8_BAR; PG8_WAIT_L(0); PG8_MMA(1, 0, At, B0); PG8_BAR; PG8_SCHED;
	v_mfma_f32_16x16x32_bf16 v[44:47], v[220:223], v[178:181], v[44:47]
	v_mfma_f32_16x16x32_bf16 v[40:43], v[228:231], v[178:181], v[40:43]
	v_mfma_f32_16x16x32_bf16 v[28:31], v[220:223], v[196:199], v[28:31]
	v_mfma_f32_16x16x32_bf16 v[24:27], v[228:231], v[196:199], v[24:27]
	v_mfma_f32_16x16x32_bf16 v[12:15], v[220:223], v[204:207], v[12:15]
	v_mfma_f32_16x16x32_bf16 v[8:11], v[228:231], v[204:207], v[8:11]
	v_mfma_f32_16x16x32_bf16 v[4:7], v[220:223], v[212:215], v[4:7]
	v_mfma_f32_16x16x32_bf16 v[0:3], v[228:231], v[212:215], v[0:3]
	v_mfma_f32_16x16x32_bf16 v[44:47], v[224:227], v[192:195], v[44:47]
	v_mfma_f32_16x16x32_bf16 v[40:43], v[232:235], v[192:195], v[40:43]
	v_mfma_f32_16x16x32_bf16 v[28:31], v[224:227], v[200:203], v[28:31]
	v_mfma_f32_16x16x32_bf16 v[24:27], v[232:235], v[200:203], v[24:27]
	v_mfma_f32_16x16x32_bf16 v[12:15], v[224:227], v[208:211], v[12:15]
	v_mfma_f32_16x16x32_bf16 v[8:11], v[232:235], v[208:211], v[8:11]
	v_mfma_f32_16x16x32_bf16 v[4:7], v[224:227], v[216:219], v[4:7]
	v_mfma_f32_16x16x32_bf16 v[0:3], v[232:235], v[216:219], v[0:3]
	s_add_i32 s16, 0, 0x18000
	s_barrier
	ds_read_b128 v[162:165], v250
	ds_read_b128 v[166:169], v250 offset:1024
	ds_read_b128 v[170:173], v250 offset:2048
	ds_read_b128 v[174:177], v250 offset:3072
	s_add_u32 s14, s58, 0x20000
	s_addc_u32 s15, s59, 0
	s_mov_b32 m0, s61
	ds_read_b128 v[178:181], v160 offset:32768
	ds_read_b128 v[192:195], v160 offset:33792
	ds_read_b128 v[196:199], v160 offset:34816
	ds_read_b128 v[200:203], v160 offset:35840
	ds_read_b128 v[204:207], v160 offset:36864
	ds_read_b128 v[208:211], v160 offset:37888
	ds_read_b128 v[212:215], v160 offset:38912
	global_load_lds_dwordx4 v148, s[14:15]
	s_mov_b32 m0, s62
	ds_read_b128 v[216:219], v160 offset:39936
	global_load_lds_dwordx4 v150, s[14:15]
	s_waitcnt lgkmcnt(8)
	s_barrier
	s_waitcnt lgkmcnt(0)
	v_mfma_f32_16x16x32_bf16 v[124:127], v[162:165], v[178:181], v[124:127]
	v_mfma_f32_16x16x32_bf16 v[120:123], v[170:173], v[178:181], v[120:123]
	v_mfma_f32_16x16x32_bf16 v[116:119], v[162:165], v[196:199], v[116:119]
	v_mfma_f32_16x16x32_bf16 v[112:115], v[170:173], v[196:199], v[112:115]
	v_mfma_f32_16x16x32_bf16 v[100:103], v[162:165], v[204:207], v[100:103]
	v_mfma_f32_16x16x32_bf16 v[96:99], v[170:173], v[204:207], v[96:99]
	v_mfma_f32_16x16x32_bf16 v[84:87], v[162:165], v[212:215], v[84:87]
	v_mfma_f32_16x16x32_bf16 v[80:83], v[170:173], v[212:215], v[80:83]
	v_mfma_f32_16x16x32_bf16 v[124:127], v[166:169], v[192:195], v[124:127]
	v_mfma_f32_16x16x32_bf16 v[120:123], v[174:177], v[192:195], v[120:123]
	v_mfma_f32_16x16x32_bf16 v[116:119], v[166:169], v[200:203], v[116:119]
	v_mfma_f32_16x16x32_bf16 v[112:115], v[174:177], v[200:203], v[112:115]
	v_mfma_f32_16x16x32_bf16 v[100:103], v[166:169], v[208:211], v[100:103]
	v_mfma_f32_16x16x32_bf16 v[96:99], v[174:177], v[208:211], v[96:99]
	v_mfma_f32_16x16x32_bf16 v[84:87], v[166:169], v[216:219], v[84:87]
	v_mfma_f32_16x16x32_bf16 v[80:83], v[174:177], v[216:219], v[80:83]
	s_barrier
	s_add_i32 s17, 0, 0x1c000
	s_add_i32 s14, s16, s53
	s_mov_b32 m0, s14
	ds_read_b128 v[220:223], v251
	ds_read_b128 v[224:227], v251 offset:1024
	ds_read_b128 v[228:231], v251 offset:2048
	global_load_lds_dwordx4 v244, s[56:57]
	s_add_i32 m0, s14, 0x2000
	ds_read_b128 v[232:235], v251 offset:3072
	global_load_lds_dwordx4 v245, s[56:57]
	s_barrier
	s_waitcnt lgkmcnt(0)
	v_mfma_f32_16x16x32_bf16 v[108:111], v[220:223], v[178:181], v[108:111]
	v_mfma_f32_16x16x32_bf16 v[104:107], v[228:231], v[178:181], v[104:107]
	v_mfma_f32_16x16x32_bf16 v[92:95], v[220:223], v[196:199], v[92:95]
	v_mfma_f32_16x16x32_bf16 v[88:91], v[228:231], v[196:199], v[88:91]
	v_mfma_f32_16x16x32_bf16 v[76:79], v[220:223], v[204:207], v[76:79]
	v_mfma_f32_16x16x32_bf16 v[72:75], v[228:231], v[204:207], v[72:75]
	v_mfma_f32_16x16x32_bf16 v[68:71], v[220:223], v[212:215], v[68:71]
	v_mfma_f32_16x16x32_bf16 v[64:67], v[228:231], v[212:215], v[64:67]
	v_mfma_f32_16x16x32_bf16 v[108:111], v[224:227], v[192:195], v[108:111]
	v_mfma_f32_16x16x32_bf16 v[104:107], v[232:235], v[192:195], v[104:107]
	v_mfma_f32_16x16x32_bf16 v[92:95], v[224:227], v[200:203], v[92:95]
	v_mfma_f32_16x16x32_bf16 v[88:91], v[232:235], v[200:203], v[88:91]
	v_mfma_f32_16x16x32_bf16 v[76:79], v[224:227], v[208:211], v[76:79]
	v_mfma_f32_16x16x32_bf16 v[72:75], v[232:235], v[208:211], v[72:75]
	v_mfma_f32_16x16x32_bf16 v[68:71], v[224:227], v[216:219], v[68:71]
	v_mfma_f32_16x16x32_bf16 v[64:67], v[232:235], v[216:219], v[64:67]
	s_mov_b32 m0, s63
	s_barrier
	ds_read_b128 v[178:181], v160 offset:49152
	ds_read_b128 v[192:195], v160 offset:50176
	ds_read_b128 v[196:199], v160 offset:51200
	ds_read_b128 v[200:203], v160 offset:52224
	ds_read_b128 v[204:207], v160 offset:53248
	ds_read_b128 v[208:211], v160 offset:54272
	ds_read_b128 v[212:215], v160 offset:55296
	global_load_lds_dwordx4 v246, s[58:59]
	s_mov_b32 m0, s64
	ds_read_b128 v[216:219], v160 offset:56320
	global_load_lds_dwordx4 v247, s[58:59]
	s_barrier
	s_waitcnt lgkmcnt(0)
	v_mfma_f32_16x16x32_bf16 v[60:63], v[162:165], v[178:181], v[60:63]
	v_mfma_f32_16x16x32_bf16 v[56:59], v[170:173], v[178:181], v[56:59]
	v_mfma_f32_16x16x32_bf16 v[52:55], v[162:165], v[196:199], v[52:55]
	v_mfma_f32_16x16x32_bf16 v[48:51], v[170:173], v[196:199], v[48:51]
	v_mfma_f32_16x16x32_bf16 v[36:39], v[162:165], v[204:207], v[36:39]
	v_mfma_f32_16x16x32_bf16 v[32:35], v[170:173], v[204:207], v[32:35]
	v_mfma_f32_16x16x32_bf16 v[20:23], v[162:165], v[212:215], v[20:23]
	v_mfma_f32_16x16x32_bf16 v[16:19], v[170:173], v[212:215], v[16:19]
	v_mfma_f32_16x16x32_bf16 v[60:63], v[166:169], v[192:195], v[60:63]
	v_mfma_f32_16x16x32_bf16 v[56:59], v[174:177], v[192:195], v[56:59]
	v_mfma_f32_16x16x32_bf16 v[52:55], v[166:169], v[200:203], v[52:55]
	v_mfma_f32_16x16x32_bf16 v[48:51], v[174:177], v[200:203], v[48:51]
	v_mfma_f32_16x16x32_bf16 v[36:39], v[166:169], v[208:211], v[36:39]
	v_mfma_f32_16x16x32_bf16 v[32:35], v[174:177], v[208:211], v[32:35]
	v_mfma_f32_16x16x32_bf16 v[20:23], v[166:169], v[216:219], v[20:23]
	v_mfma_f32_16x16x32_bf16 v[16:19], v[174:177], v[216:219], v[16:19]
	s_barrier
; __device__ __forceinline__ unsigned cvt_pk_bf16(float lo, float hi) { const f32x2_cv v = {lo, hi}; const bf16x2_cv b = __builtin_convertvector(v, bf16x2_cv); return __builtin_bit_cast(unsigned, b); }
; #define PG8_STAGE(bufoff, gbase, voff) do { _Pragma("unroll") for (int _i = 0; _i < 2; ++_i) \
;         __builtin_amdgcn_global_load_lds((const unsigned*)((const char*)(gbase) + (voff)[_i]), (PG8_LAS unsigned*)(lds + (bufoff) + ldsw + _i * 8192), 16, 0, 0); } while (0)
; #define PG8_MMA(ai, bj, At, Bt) do { __builtin_amdgcn_s_setprio(1); _Pragma("unroll") for (int m = 0; m < 4; ++m) _Pragma("unroll") for (int n = 0; n < 2; ++n) _Pragma("unroll") for (int k = 0; k < 2; ++k) \
;         acc[ai][bj][m][n] = __builtin_amdgcn_mfma_f32_16x16x32_bf16(Bt[n][k], At[m][k], acc[ai][bj][m][n], 0, 0, 0); __builtin_amdgcn_s_setprio(0); } while (0)
; #define PG8_WAIT_V(n) asm volatile("s_waitcnt vmcnt(" #n ")" ::: "memory")
; template <class Epi, class Sched, bool STAMP = false>
; __device__ __forceinline__ void gemm_phase(PG8_LAS unsigned char* lds, const Gemm g, const Sched& S, const Epi& E, unsigned long long* stamps) {
;     ...
;             PG8_STAGE(PG8_SB(1, 1), b3 + hstep, voffB);
;             PG8_WAIT_V(6); PG8_BAR; PG8_MMA(1, 1, At, B1); PG8_BAR;
;     __device__ __forceinline__ void operator()(const f32x4 (&acc)[2][2][4][2], const pg8::Unit& u, int wr, int wc, int fr, int fq) const {
;         const int row0 = u.pm * 256 + wr * 64 + fr, col0 = u.pn * 256 + wc * 32 + 8 * fq;
; #pragma unroll
;         for (int ai = 0; ai < 2; ++ai)
; #pragma unroll
;             for (int m = 0; m < 4; ++m) {
;                 const int row = row0 + ai * 128 + m * 16;
;                 const float s = (MODE == 2) ? 1.0f : rstd_of(rowss, row);
;                 bf16_t* rowp = O + (size_t)row * ldc + col0;
; #pragma unroll
;                 for (int bj = 0; bj < 2; ++bj) {
;                     f32x4 v0 = acc[ai][bj][m][0] * s, v1 = acc[ai][bj][m][1] * s;
;                     if (MODE == 1) {
; #pragma unroll
;                         for (int j = 0; j < 4; ++j) { const float a = fmaxf(v0[j], 0.f), b = fmaxf(v1[j], 0.f); v0[j] = a * a; v1[j] = b * b; } }
;                     u32x4 w; w.x = cvt_pk_bf16(v0[0], v0[1]); w.y = cvt_pk_bf16(v0[2], v0[3]); w.z = cvt_pk_bf16(v1[0], v1[1]); w.w = cvt_pk_bf16(v1[2], v1[3]);
;                     *(u32x4*)(rowp + bj * 128) = w; } }
	s_add_u32 s14, s56, 0x20080
	s_addc_u32 s15, s57, 0
	s_add_i32 s16, s17, s53
	s_mov_b32 m0, s16
	s_nop 0
	global_load_lds_dwordx4 v128, s[14:15]
	s_add_i32 m0, s16, 0x2000
	s_nop 0
	global_load_lds_dwordx4 v152, s[14:15]
	s_waitcnt vmcnt(6)
	s_barrier
	v_mfma_f32_16x16x32_bf16 v[44:47], v[220:223], v[178:181], v[44:47]
	v_mfma_f32_16x16x32_bf16 v[40:43], v[228:231], v[178:181], v[40:43]
	v_mfma_f32_16x16x32_bf16 v[28:31], v[220:223], v[196:199], v[28:31]
	v_mfma_f32_16x16x32_bf16 v[24:27], v[228:231], v[196:199], v[24:27]
	v_mfma_f32_16x16x32_bf16 v[12:15], v[220:223], v[204:207], v[12:15]
	v_mfma_f32_16x16x32_bf16 v[8:11], v[228:231], v[204:207], v[8:11]
	v_mfma_f32_16x16x32_bf16 v[4:7], v[220:223], v[212:215], v[4:7]
	v_mfma_f32_16x16x32_bf16 v[0:3], v[228:231], v[212:215], v[0:3]
	v_mfma_f32_16x16x32_bf16 v[44:47], v[224:227], v[192:195], v[44:47]
	v_mfma_f32_16x16x32_bf16 v[40:43], v[232:235], v[192:195], v[40:43]
	v_mfma_f32_16x16x32_bf16 v[28:31], v[224:227], v[200:203], v[28:31]
	v_mfma_f32_16x16x32_bf16 v[24:27], v[232:235], v[200:203], v[24:27]
	v_mfma_f32_16x16x32_bf16 v[12:15], v[224:227], v[208:211], v[12:15]
	v_mfma_f32_16x16x32_bf16 v[8:11], v[232:235], v[208:211], v[8:11]
	v_mfma_f32_16x16x32_bf16 v[4:7], v[224:227], v[216:219], v[4:7]
	v_mfma_f32_16x16x32_bf16 v[0:3], v[232:235], v[216:219], v[0:3]
	s_cmp_gt_u32 s97, 5
	s_barrier
	s_cbranch_scc0 .LBB0_333
	v_lshl_add_u32 v162, s2, 8, v139
	v_lshl_or_b32 v164, s76, 8, v159
	v_ashrrev_i32_e32 v163, 31, v162
	v_ashrrev_i32_e32 v165, 31, v164
	v_lshlrev_b64 v[166:167], 11, v[162:163]
	v_lshl_add_u64 v[166:167], s[30:31], 0, v[166:167]
	v_lshlrev_b64 v[164:165], 1, v[164:165]
	v_lshl_add_u64 v[166:167], v[166:167], 0, v[164:165]
	s_mov_b32 s2, 0x40000
	s_mov_b64 s[14:15], 0x40000
	v_cvt_pk_bf16_f32 v60, v60, v61
	v_cvt_pk_bf16_f32 v61, v62, v63
	v_cvt_pk_bf16_f32 v62, v56, v57
	v_add_co_u32_e32 v56, vcc, s2, v166
	v_cvt_pk_bf16_f32 v68, v68, v69
	v_cvt_pk_bf16_f32 v69, v70, v71
	v_cvt_pk_bf16_f32 v70, v64, v65
	v_lshl_add_u64 v[64:65], v[166:167], 0, s[14:15]
	v_addc_co_u32_e32 v57, vcc, 0, v167, vcc
	v_cvt_pk_bf16_f32 v44, v44, v45
	v_cvt_pk_bf16_f32 v45, v46, v47
	v_cvt_pk_bf16_f32 v46, v40, v41
	v_cvt_pk_bf16_f32 v47, v42, v43
	s_mov_b32 s2, 0x48000
	v_cvt_pk_bf16_f32 v108, v108, v109
	v_cvt_pk_bf16_f32 v109, v110, v111
	v_cvt_pk_bf16_f32 v110, v104, v105
	v_or_b32_e32 v104, 16, v162
	global_store_dwordx4 v[64:65], v[44:47], off offset:256
	s_mov_b64 s[14:15], 0x48000
	v_ashrrev_i32_e32 v105, 31, v104
	v_add_co_u32_e32 v46, vcc, s2, v166
	v_cvt_pk_bf16_f32 v92, v92, v93
	v_cvt_pk_bf16_f32 v93, v94, v95
	v_cvt_pk_bf16_f32 v94, v88, v89
	v_or_b32_e32 v88, 32, v162
	v_lshl_add_u64 v[44:45], v[166:167], 0, s[14:15]
	v_addc_co_u32_e32 v47, vcc, 0, v167, vcc
	v_cvt_pk_bf16_f32 v28, v28, v29
	v_cvt_pk_bf16_f32 v29, v30, v31
	v_cvt_pk_bf16_f32 v30, v24, v25
	v_cvt_pk_bf16_f32 v31, v26, v27
	s_mov_b32 s2, 0x50000
	v_lshlrev_b64 v[104:105], 11, v[104:105]
	v_ashrrev_i32_e32 v89, 31, v88
	v_cvt_pk_bf16_f32 v76, v76, v77
	v_cvt_pk_bf16_f32 v77, v78, v79
	v_cvt_pk_bf16_f32 v78, v72, v73
	v_or_b32_e32 v72, 48, v162
	global_store_dwordx4 v[44:45], v[28:31], off offset:256
	s_mov_b64 s[14:15], 0x50000
	v_cvt_pk_bf16_f32 v111, v106, v107
	v_add_co_u32_e32 v30, vcc, s2, v166
	v_lshl_add_u64 v[104:105], s[30:31], 0, v[104:105]
	v_lshlrev_b64 v[88:89], 11, v[88:89]
	v_ashrrev_i32_e32 v73, 31, v72
	v_lshl_add_u64 v[28:29], v[166:167], 0, s[14:15]
	v_addc_co_u32_e32 v31, vcc, 0, v167, vcc
	v_cvt_pk_bf16_f32 v12, v12, v13
	v_cvt_pk_bf16_f32 v13, v14, v15
	v_cvt_pk_bf16_f32 v14, v8, v9
	v_cvt_pk_bf16_f32 v15, v10, v11
	s_mov_b32 s2, 0x58000
	global_store_dwordx4 v[166:167], v[108:111], off offset:256
	v_cvt_pk_bf16_f32 v95, v90, v91
	v_lshl_add_u64 v[88:89], s[30:31], 0, v[88:89]
	v_lshl_add_u64 v[108:109], v[104:105], 0, v[164:165]
	v_lshlrev_b64 v[72:73], 11, v[72:73]
	global_store_dwordx4 v[28:29], v[12:15], off offset:256
	global_store_dwordx4 v[108:109], v[92:95], off offset:256
	v_cvt_pk_bf16_f32 v79, v74, v75
	v_add_co_u32_e32 v14, vcc, s2, v166
	v_lshl_add_u64 v[92:93], v[88:89], 0, v[164:165]
	v_lshl_add_u64 v[72:73], s[30:31], 0, v[72:73]
	s_mov_b64 s[14:15], 0x58000
	v_addc_co_u32_e32 v15, vcc, 0, v167, vcc
	v_readlane_b32 s88, v242, 39
	v_cvt_pk_bf16_f32 v124, v124, v125
	v_cvt_pk_bf16_f32 v125, v126, v127
	v_cvt_pk_bf16_f32 v126, v120, v121
	v_cvt_pk_bf16_f32 v127, v122, v123
	v_cvt_pk_bf16_f32 v104, v116, v117
	v_cvt_pk_bf16_f32 v105, v118, v119
	v_cvt_pk_bf16_f32 v106, v112, v113
	v_cvt_pk_bf16_f32 v107, v114, v115
	v_cvt_pk_bf16_f32 v88, v100, v101
	v_cvt_pk_bf16_f32 v89, v102, v103
	v_cvt_pk_bf16_f32 v90, v96, v97
	v_cvt_pk_bf16_f32 v91, v98, v99
	global_store_dwordx4 v[92:93], v[76:79], off offset:256
	v_cvt_pk_bf16_f32 v74, v80, v81
	v_cvt_pk_bf16_f32 v75, v82, v83
	v_lshl_add_u64 v[76:77], v[72:73], 0, v[164:165]
	v_cvt_pk_bf16_f32 v72, v84, v85
	v_cvt_pk_bf16_f32 v73, v86, v87
	v_cvt_pk_bf16_f32 v71, v66, v67
	v_cvt_pk_bf16_f32 v63, v58, v59
	v_cvt_pk_bf16_f32 v40, v52, v53
	v_cvt_pk_bf16_f32 v41, v54, v55
	v_cvt_pk_bf16_f32 v42, v48, v49
	v_cvt_pk_bf16_f32 v43, v50, v51
	v_cvt_pk_bf16_f32 v24, v36, v37
	v_cvt_pk_bf16_f32 v25, v38, v39
	v_cvt_pk_bf16_f32 v26, v32, v33
	v_cvt_pk_bf16_f32 v27, v34, v35
	v_lshl_add_u64 v[12:13], v[166:167], 0, s[14:15]
	v_cvt_pk_bf16_f32 v8, v20, v21
	v_cvt_pk_bf16_f32 v9, v22, v23
	v_cvt_pk_bf16_f32 v10, v16, v17
	v_cvt_pk_bf16_f32 v11, v18, v19
	v_cvt_pk_bf16_f32 v4, v4, v5
	v_cvt_pk_bf16_f32 v5, v6, v7
	v_cvt_pk_bf16_f32 v6, v0, v1
	v_cvt_pk_bf16_f32 v7, v2, v3
	s_and_b64 vcc, exec, s[38:39]
	s_mov_b32 s76, s4
	s_mov_b32 s2, s12
	s_mov_b64 s[56:57], s[26:27]
	s_mov_b64 s[36:37], s[24:25]
	s_movk_i32 s77, 0xa0
	s_movk_i32 s58, 0xff60
	v_readlane_b32 s89, v242, 40
	global_store_dwordx4 v[166:167], v[124:127], off
	global_store_dwordx4 v[108:109], v[104:107], off
	global_store_dwordx4 v[92:93], v[88:91], off
	global_store_dwordx4 v[76:77], v[72:75], off
	global_store_dwordx4 v[76:77], v[68:71], off offset:256
	global_store_dwordx4 v[56:57], v[60:63], off
	global_store_dwordx4 v[46:47], v[40:43], off
	global_store_dwordx4 v[30:31], v[24:27], off
	global_store_dwordx4 v[14:15], v[8:11], off
	global_store_dwordx4 v[12:13], v[4:7], off offset:256
	s_cbranch_vccz .LBB0_326
	s_cmpk_gt_u32 s46, 0xff
	s_cbranch_scc1 .LBB0_337
	s_barrier

; #define PG8_STAGE(bufoff, gbase, voff) do { _Pragma("unroll") for (int _i = 0; _i < 2; ++_i) \
;         __builtin_amdgcn_global_load_lds((const unsigned*)((const char*)(gbase) + (voff)[_i]), (PG8_LAS unsigned*)(lds + (bufoff) + ldsw + _i * 8192), 16, 0, 0); } while (0)
; #define PG8_LDA(dst, b, h) do { _Pragma("unroll") for (int m = 0; m < 4; ++m) _Pragma("unroll") for (int k = 0; k < 2; ++k) dst[m][k] = *(const PG8_LAS bf16x8*)(lds + PG8_SA(b, h) + aoff + m * 2048 + k * 1024); } while (0)
; #define PG8_LDB(dst, b, h) do { _Pragma("unroll") for (int n = 0; n < 2; ++n) _Pragma("unroll") for (int k = 0; k < 2; ++k) dst[n][k] = *(const PG8_LAS bf16x8*)(lds + PG8_SB(b, h) + boff + n * 2048 + k * 1024); } while (0)
; #define PG8_MMA(ai, bj, At, Bt) do { __builtin_amdgcn_s_setprio(1); _Pragma("unroll") for (int m = 0; m < 4; ++m) _Pragma("unroll") for (int n = 0; n < 2; ++n) _Pragma("unroll") for (int k = 0; k < 2; ++k) \
;         acc[ai][bj][m][n] = __builtin_amdgcn_mfma_f32_16x16x32_bf16(Bt[n][k], At[m][k], acc[ai][bj][m][n], 0, 0, 0); __builtin_amdgcn_s_setprio(0); } while (0)
; #define PG8_WAIT_V(n) asm volatile("s_waitcnt vmcnt(" #n ")" ::: "memory")
; #define PG8_WAIT_L(n) asm volatile("s_waitcnt lgkmcnt(" #n ")" ::: "memory")
; #define PG8_BAR __builtin_amdgcn_s_barrier()
; #define PG8_SCHED __builtin_amdgcn_sched_barrier(0)
; template <class Epi, class Sched, bool STAMP = false>
; __device__ __forceinline__ void gemm_phase(PG8_LAS unsigned char* lds, const Gemm g, const Sched& S, const Epi& E, unsigned long long* stamps) {
;     ...
;             PG8_LDB(B0, 0, 0); PG8_SCHED; PG8_LDA(At, 0, 0); PG8_STAGE(PG8_SA(1, 1), a1 + hstep, voffA);
;             PG8_WAIT_L(8); PG8_BAR; PG8_WAIT_L(0); PG8_MMA(0, 0, At, B0); PG8_BAR; PG8_SCHED;
;             PG8_LDB(B1, 0, 1); PG8_STAGE(PG8_SB(0, 0), b2, voffB);
;             PG8_BAR; PG8_WAIT_L(0); PG8_MMA(0, 1, At, B1); PG8_BAR;
;             PG8_LDA(At, 0, 1); PG8_STAGE(PG8_SA(0, 0), a2, voffA);
;             PG8_BAR; PG8_WAIT_L(0); PG8_MMA(1, 0, At, B0); PG8_BAR; PG8_SCHED;
;             PG8_STAGE(PG8_SB(0, 1), b2 + hstep, voffB);
;             PG8_WAIT_V(6); PG8_BAR; PG8_MMA(1, 1, At, B1); PG8_BAR;
.LBB0_495:
	s_add_u32 s14, s24, 0xfffc0080
	s_addc_u32 s15, s25, -1
	s_add_i32 s16, 0, 0x10000
	ds_read_b128 v[158:161], v248
	ds_read_b128 v[162:165], v248 offset:1024
	ds_read_b128 v[170:173], v248 offset:2048
	ds_read_b128 v[174:177], v248 offset:3072
	s_cmp_eq_u32 s61, 12
	s_cselect_b32 s31, s7, s15
	s_cselect_b32 s30, s57, s14
	s_cselect_b32 s27, s5, s60
	s_cselect_b32 s26, s58, s59
	s_add_i32 m0, s23, 0xc000
	ds_read_b128 v[178:181], v168
	ds_read_b128 v[192:195], v168 offset:1024
	ds_read_b128 v[196:199], v168 offset:2048
	ds_read_b128 v[200:203], v168 offset:3072
	ds_read_b128 v[204:207], v168 offset:4096
	ds_read_b128 v[208:211], v168 offset:5120
	ds_read_b128 v[212:215], v168 offset:6144
	global_load_lds_dwordx4 v154, s[24:25]
	s_add_i32 m0, s23, 0xe000
	ds_read_b128 v[216:219], v168 offset:7168
	global_load_lds_dwordx4 v156, s[24:25]
	s_waitcnt lgkmcnt(8)
	s_barrier
	s_waitcnt lgkmcnt(0)
	v_mfma_f32_16x16x32_bf16 v[124:127], v[158:161], v[178:181], v[124:127]
	v_mfma_f32_16x16x32_bf16 v[120:123], v[170:173], v[178:181], v[120:123]
	v_mfma_f32_16x16x32_bf16 v[108:111], v[158:161], v[196:199], v[108:111]
	v_mfma_f32_16x16x32_bf16 v[104:107], v[170:173], v[196:199], v[104:107]
	v_mfma_f32_16x16x32_bf16 v[92:95], v[158:161], v[204:207], v[92:95]
	v_mfma_f32_16x16x32_bf16 v[88:91], v[170:173], v[204:207], v[88:91]
	v_mfma_f32_16x16x32_bf16 v[76:79], v[158:161], v[212:215], v[76:79]
	v_mfma_f32_16x16x32_bf16 v[72:75], v[170:173], v[212:215], v[72:75]
	v_mfma_f32_16x16x32_bf16 v[124:127], v[162:165], v[192:195], v[124:127]
	v_mfma_f32_16x16x32_bf16 v[120:123], v[174:177], v[192:195], v[120:123]
	v_mfma_f32_16x16x32_bf16 v[108:111], v[162:165], v[200:203], v[108:111]
	v_mfma_f32_16x16x32_bf16 v[104:107], v[174:177], v[200:203], v[104:107]
	v_mfma_f32_16x16x32_bf16 v[92:95], v[162:165], v[208:211], v[92:95]
	v_mfma_f32_16x16x32_bf16 v[88:91], v[174:177], v[208:211], v[88:91]
	v_mfma_f32_16x16x32_bf16 v[76:79], v[162:165], v[216:219], v[76:79]
	v_mfma_f32_16x16x32_bf16 v[72:75], v[174:177], v[216:219], v[72:75]
	s_barrier
	s_add_i32 s17, 0, 0x14000
	s_add_i32 s14, s16, s43
	s_mov_b32 m0, s14
	ds_read_b128 v[220:223], v249
	ds_read_b128 v[224:227], v249 offset:1024
	ds_read_b128 v[228:231], v249 offset:2048
	global_load_lds_dwordx4 v128, s[26:27]
	s_add_i32 m0, s14, 0x2000
	ds_read_b128 v[232:235], v249 offset:3072
	global_load_lds_dwordx4 v148, s[26:27]
	s_barrier
	s_waitcnt lgkmcnt(0)
	v_mfma_f32_16x16x32_bf16 v[116:119], v[220:223], v[178:181], v[116:119]
	v_mfma_f32_16x16x32_bf16 v[112:115], v[228:231], v[178:181], v[112:115]
	v_mfma_f32_16x16x32_bf16 v[100:103], v[220:223], v[196:199], v[100:103]
	v_mfma_f32_16x16x32_bf16 v[96:99], v[228:231], v[196:199], v[96:99]
	v_mfma_f32_16x16x32_bf16 v[84:87], v[220:223], v[204:207], v[84:87]
	v_mfma_f32_16x16x32_bf16 v[80:83], v[228:231], v[204:207], v[80:83]
	v_mfma_f32_16x16x32_bf16 v[68:71], v[220:223], v[212:215], v[68:71]
	v_mfma_f32_16x16x32_bf16 v[64:67], v[228:231], v[212:215], v[64:67]
	v_mfma_f32_16x16x32_bf16 v[116:119], v[224:227], v[192:195], v[116:119]
	v_mfma_f32_16x16x32_bf16 v[112:115], v[232:235], v[192:195], v[112:115]
	v_mfma_f32_16x16x32_bf16 v[100:103], v[224:227], v[200:203], v[100:103]
	v_mfma_f32_16x16x32_bf16 v[96:99], v[232:235], v[200:203], v[96:99]
	v_mfma_f32_16x16x32_bf16 v[84:87], v[224:227], v[208:211], v[84:87]
	v_mfma_f32_16x16x32_bf16 v[80:83], v[232:235], v[208:211], v[80:83]
	v_mfma_f32_16x16x32_bf16 v[68:71], v[224:227], v[216:219], v[68:71]
	v_mfma_f32_16x16x32_bf16 v[64:67], v[232:235], v[216:219], v[64:67]
	s_mov_b32 m0, s23
	s_barrier
	ds_read_b128 v[178:181], v168 offset:16384
	ds_read_b128 v[192:195], v168 offset:17408
	ds_read_b128 v[196:199], v168 offset:18432
	ds_read_b128 v[200:203], v168 offset:19456
	ds_read_b128 v[204:207], v168 offset:20480
	ds_read_b128 v[208:211], v168 offset:21504
	ds_read_b128 v[212:215], v168 offset:22528
	global_load_lds_dwordx4 v152, s[30:31]
	s_mov_b32 m0, s45
	ds_read_b128 v[216:219], v168 offset:23552
	global_load_lds_dwordx4 v150, s[30:31]
	s_barrier
	s_waitcnt lgkmcnt(0)
	v_mfma_f32_16x16x32_bf16 v[60:63], v[158:161], v[178:181], v[60:63]
	v_mfma_f32_16x16x32_bf16 v[56:59], v[170:173], v[178:181], v[56:59]
	v_mfma_f32_16x16x32_bf16 v[44:47], v[158:161], v[196:199], v[44:47]
	v_mfma_f32_16x16x32_bf16 v[40:43], v[170:173], v[196:199], v[40:43]
	v_mfma_f32_16x16x32_bf16 v[28:31], v[158:161], v[204:207], v[28:31]
	v_mfma_f32_16x16x32_bf16 v[24:27], v[170:173], v[204:207], v[24:27]
	v_mfma_f32_16x16x32_bf16 v[12:15], v[158:161], v[212:215], v[12:15]
	v_mfma_f32_16x16x32_bf16 v[8:11], v[170:173], v[212:215], v[8:11]
	v_mfma_f32_16x16x32_bf16 v[60:63], v[162:165], v[192:195], v[60:63]
	v_mfma_f32_16x16x32_bf16 v[56:59], v[174:177], v[192:195], v[56:59]
	v_mfma_f32_16x16x32_bf16 v[44:47], v[162:165], v[200:203], v[44:47]
	v_mfma_f32_16x16x32_bf16 v[40:43], v[174:177], v[200:203], v[40:43]
	v_mfma_f32_16x16x32_bf16 v[28:31], v[162:165], v[208:211], v[28:31]
	v_mfma_f32_16x16x32_bf16 v[24:27], v[174:177], v[208:211], v[24:27]
	v_mfma_f32_16x16x32_bf16 v[12:15], v[162:165], v[216:219], v[12:15]
	v_mfma_f32_16x16x32_bf16 v[8:11], v[174:177], v[216:219], v[8:11]
	s_barrier
	s_add_u32 s14, s26, 0x40000
	s_addc_u32 s15, s27, 0
	s_add_i32 s16, s17, s43
	s_mov_b32 m0, s16
	s_nop 0
	global_load_lds_dwordx4 v128, s[14:15]
	s_add_i32 m0, s16, 0x2000
	s_nop 0
	global_load_lds_dwordx4 v148, s[14:15]
	s_add_i32 s61, s61, 2
	s_add_u32 s24, s24, 0x100
	s_addc_u32 s25, s25, 0
	s_add_u32 s59, s59, 0x100
	s_addc_u32 s60, s60, 0
	s_waitcnt vmcnt(6)
	s_barrier
; #define PG8_STAGE(bufoff, gbase, voff) do { _Pragma("unroll") for (int _i = 0; _i < 2; ++_i) \
;         __builtin_amdgcn_global_load_lds((const unsigned*)((const char*)(gbase) + (voff)[_i]), (PG8_LAS unsigned*)(lds + (bufoff) + ldsw + _i * 8192), 16, 0, 0); } while (0)
; #define PG8_LDA(dst, b, h) do { _Pragma("unroll") for (int m = 0; m < 4; ++m) _Pragma("unroll") for (int k = 0; k < 2; ++k) dst[m][k] = *(const PG8_LAS bf16x8*)(lds + PG8_SA(b, h) + aoff + m * 2048 + k * 1024); } while (0)
; #define PG8_LDB(dst, b, h) do { _Pragma("unroll") for (int n = 0; n < 2; ++n) _Pragma("unroll") for (int k = 0; k < 2; ++k) dst[n][k] = *(const PG8_LAS bf16x8*)(lds + PG8_SB(b, h) + boff + n * 2048 + k * 1024); } while (0)
; #define PG8_MMA(ai, bj, At, Bt) do { __builtin_amdgcn_s_setprio(1); _Pragma("unroll") for (int m = 0; m < 4; ++m) _Pragma("unroll") for (int n = 0; n < 2; ++n) _Pragma("unroll") for (int k = 0; k < 2; ++k) \
;         acc[ai][bj][m][n] = __builtin_amdgcn_mfma_f32_16x16x32_bf16(Bt[n][k], At[m][k], acc[ai][bj][m][n], 0, 0, 0); __builtin_amdgcn_s_setprio(0); } while (0)
; #define PG8_WAIT_V(n) asm volatile("s_waitcnt vmcnt(" #n ")" ::: "memory")
; #define PG8_WAIT_L(n) asm volatile("s_waitcnt lgkmcnt(" #n ")" ::: "memory")
; #define PG8_BAR __builtin_amdgcn_s_barrier()
; #define PG8_SCHED __builtin_amdgcn_sched_barrier(0)
; template <class Epi, class Sched, bool STAMP = false>
; __device__ __forceinline__ void gemm_phase(PG8_LAS unsigned char* lds, const Gemm g, const Sched& S, const Epi& E, unsigned long long* stamps) {
;     ...
;             PG8_WAIT_V(6); PG8_BAR; PG8_MMA(1, 1, At, B1); PG8_BAR;
;             PG8_LDB(B0, 1, 0); PG8_SCHED; PG8_LDA(At, 1, 0); PG8_STAGE(PG8_SA(0, 1), a2 + hstep, voffA);
;             PG8_WAIT_L(8); PG8_BAR; PG8_WAIT_L(0); PG8_MMA(0, 0, At, B0); PG8_BAR; PG8_SCHED;
;             PG8_LDB(B1, 1, 1); PG8_STAGE(PG8_SB(1, 0), b3, voffB);
;             PG8_BAR; PG8_WAIT_L(0); PG8_MMA(0, 1, At, B1); PG8_BAR;
;             PG8_LDA(At, 1, 1); PG8_STAGE(PG8_SA(1, 0), a3, voffA);
;             PG8_BAR; PG8_WAIT_L(0); PG8_MMA(1, 0, At, B0); PG8_BAR; PG8_SCHED;
	v_mfma_f32_16x16x32_bf16 v[52:55], v[220:223], v[178:181], v[52:55]
	v_mfma_f32_16x16x32_bf16 v[48:51], v[228:231], v[178:181], v[48:51]
	v_mfma_f32_16x16x32_bf16 v[36:39], v[220:223], v[196:199], v[36:39]
	v_mfma_f32_16x16x32_bf16 v[32:35], v[228:231], v[196:199], v[32:35]
	v_mfma_f32_16x16x32_bf16 v[20:23], v[220:223], v[204:207], v[20:23]
	v_mfma_f32_16x16x32_bf16 v[16:19], v[228:231], v[204:207], v[16:19]
	v_mfma_f32_16x16x32_bf16 v[4:7], v[220:223], v[212:215], v[4:7]
	v_mfma_f32_16x16x32_bf16 v[0:3], v[228:231], v[212:215], v[0:3]
	v_mfma_f32_16x16x32_bf16 v[52:55], v[224:227], v[192:195], v[52:55]
	v_mfma_f32_16x16x32_bf16 v[48:51], v[232:235], v[192:195], v[48:51]
	v_mfma_f32_16x16x32_bf16 v[36:39], v[224:227], v[200:203], v[36:39]
	v_mfma_f32_16x16x32_bf16 v[32:35], v[232:235], v[200:203], v[32:35]
	v_mfma_f32_16x16x32_bf16 v[20:23], v[224:227], v[208:211], v[20:23]
	v_mfma_f32_16x16x32_bf16 v[16:19], v[232:235], v[208:211], v[16:19]
	v_mfma_f32_16x16x32_bf16 v[4:7], v[224:227], v[216:219], v[4:7]
	v_mfma_f32_16x16x32_bf16 v[0:3], v[232:235], v[216:219], v[0:3]
	s_add_i32 s16, 0, 0x18000
	s_barrier
	ds_read_b128 v[158:161], v250
	ds_read_b128 v[162:165], v250 offset:1024
	ds_read_b128 v[170:173], v250 offset:2048
	ds_read_b128 v[174:177], v250 offset:3072
	s_add_u32 s14, s30, 0x40000
	s_addc_u32 s15, s31, 0
	s_mov_b32 m0, s46
	ds_read_b128 v[178:181], v168 offset:32768
	ds_read_b128 v[192:195], v168 offset:33792
	ds_read_b128 v[196:199], v168 offset:34816
	ds_read_b128 v[200:203], v168 offset:35840
	ds_read_b128 v[204:207], v168 offset:36864
	ds_read_b128 v[208:211], v168 offset:37888
	ds_read_b128 v[212:215], v168 offset:38912
	global_load_lds_dwordx4 v152, s[14:15]
	s_mov_b32 m0, s47
	ds_read_b128 v[216:219], v168 offset:39936
	global_load_lds_dwordx4 v150, s[14:15]
	s_waitcnt lgkmcnt(8)
	s_barrier
	s_waitcnt lgkmcnt(0)
	v_mfma_f32_16x16x32_bf16 v[124:127], v[158:161], v[178:181], v[124:127]
	v_mfma_f32_16x16x32_bf16 v[120:123], v[170:173], v[178:181], v[120:123]
	v_mfma_f32_16x16x32_bf16 v[108:111], v[158:161], v[196:199], v[108:111]
	v_mfma_f32_16x16x32_bf16 v[104:107], v[170:173], v[196:199], v[104:107]
	v_mfma_f32_16x16x32_bf16 v[92:95], v[158:161], v[204:207], v[92:95]
	v_mfma_f32_16x16x32_bf16 v[88:91], v[170:173], v[204:207], v[88:91]
	v_mfma_f32_16x16x32_bf16 v[76:79], v[158:161], v[212:215], v[76:79]
	v_mfma_f32_16x16x32_bf16 v[72:75], v[170:173], v[212:215], v[72:75]
	v_mfma_f32_16x16x32_bf16 v[124:127], v[162:165], v[192:195], v[124:127]
	v_mfma_f32_16x16x32_bf16 v[120:123], v[174:177], v[192:195], v[120:123]
	v_mfma_f32_16x16x32_bf16 v[108:111], v[162:165], v[200:203], v[108:111]
	v_mfma_f32_16x16x32_bf16 v[104:107], v[174:177], v[200:203], v[104:107]
	v_mfma_f32_16x16x32_bf16 v[92:95], v[162:165], v[208:211], v[92:95]
	v_mfma_f32_16x16x32_bf16 v[88:91], v[174:177], v[208:211], v[88:91]
	v_mfma_f32_16x16x32_bf16 v[76:79], v[162:165], v[216:219], v[76:79]
	v_mfma_f32_16x16x32_bf16 v[72:75], v[174:177], v[216:219], v[72:75]
	s_barrier
	s_add_i32 s17, 0, 0x1c000
	s_add_i32 s14, s16, s43
	s_mov_b32 m0, s14
	ds_read_b128 v[220:223], v251
	ds_read_b128 v[224:227], v251 offset:1024
	ds_read_b128 v[228:231], v251 offset:2048
	global_load_lds_dwordx4 v244, s[26:27]
	s_add_i32 m0, s14, 0x2000
	ds_read_b128 v[232:235], v251 offset:3072
	global_load_lds_dwordx4 v245, s[26:27]
	s_barrier
	s_waitcnt lgkmcnt(0)
	v_mfma_f32_16x16x32_bf16 v[116:119], v[220:223], v[178:181], v[116:119]
	v_mfma_f32_16x16x32_bf16 v[112:115], v[228:231], v[178:181], v[112:115]
	v_mfma_f32_16x16x32_bf16 v[100:103], v[220:223], v[196:199], v[100:103]
	v_mfma_f32_16x16x32_bf16 v[96:99], v[228:231], v[196:199], v[96:99]
	v_mfma_f32_16x16x32_bf16 v[84:87], v[220:223], v[204:207], v[84:87]
	v_mfma_f32_16x16x32_bf16 v[80:83], v[228:231], v[204:207], v[80:83]
	v_mfma_f32_16x16x32_bf16 v[68:71], v[220:223], v[212:215], v[68:71]
	v_mfma_f32_16x16x32_bf16 v[64:67], v[228:231], v[212:215], v[64:67]
	v_mfma_f32_16x16x32_bf16 v[116:119], v[224:227], v[192:195], v[116:119]
	v_mfma_f32_16x16x32_bf16 v[112:115], v[232:235], v[192:195], v[112:115]
	v_mfma_f32_16x16x32_bf16 v[100:103], v[224:227], v[200:203], v[100:103]
	v_mfma_f32_16x16x32_bf16 v[96:99], v[232:235], v[200:203], v[96:99]
	v_mfma_f32_16x16x32_bf16 v[84:87], v[224:227], v[208:211], v[84:87]
	v_mfma_f32_16x16x32_bf16 v[80:83], v[232:235], v[208:211], v[80:83]
	v_mfma_f32_16x16x32_bf16 v[68:71], v[224:227], v[216:219], v[68:71]
	v_mfma_f32_16x16x32_bf16 v[64:67], v[232:235], v[216:219], v[64:67]
	s_mov_b32 m0, s49
	s_barrier
	ds_read_b128 v[178:181], v168 offset:49152
	ds_read_b128 v[192:195], v168 offset:50176
	ds_read_b128 v[196:199], v168 offset:51200
	ds_read_b128 v[200:203], v168 offset:52224
	ds_read_b128 v[204:207], v168 offset:53248
	ds_read_b128 v[208:211], v168 offset:54272
	ds_read_b128 v[212:215], v168 offset:55296
	global_load_lds_dwordx4 v246, s[30:31]
	s_mov_b32 m0, s53
	ds_read_b128 v[216:219], v168 offset:56320
	global_load_lds_dwordx4 v247, s[30:31]
	s_barrier
	s_waitcnt lgkmcnt(0)
	v_mfma_f32_16x16x32_bf16 v[60:63], v[158:161], v[178:181], v[60:63]
	v_mfma_f32_16x16x32_bf16 v[56:59], v[170:173], v[178:181], v[56:59]
	v_mfma_f32_16x16x32_bf16 v[44:47], v[158:161], v[196:199], v[44:47]
	v_mfma_f32_16x16x32_bf16 v[40:43], v[170:173], v[196:199], v[40:43]
	v_mfma_f32_16x16x32_bf16 v[28:31], v[158:161], v[204:207], v[28:31]
	v_mfma_f32_16x16x32_bf16 v[24:27], v[170:173], v[204:207], v[24:27]
	v_mfma_f32_16x16x32_bf16 v[12:15], v[158:161], v[212:215], v[12:15]
	v_mfma_f32_16x16x32_bf16 v[8:11], v[170:173], v[212:215], v[8:11]
	v_mfma_f32_16x16x32_bf16 v[60:63], v[162:165], v[192:195], v[60:63]
	v_mfma_f32_16x16x32_bf16 v[56:59], v[174:177], v[192:195], v[56:59]
	v_mfma_f32_16x16x32_bf16 v[44:47], v[162:165], v[200:203], v[44:47]
	v_mfma_f32_16x16x32_bf16 v[40:43], v[174:177], v[200:203], v[40:43]
	v_mfma_f32_16x16x32_bf16 v[28:31], v[162:165], v[208:211], v[28:31]
	v_mfma_f32_16x16x32_bf16 v[24:27], v[174:177], v[208:211], v[24:27]
	v_mfma_f32_16x16x32_bf16 v[12:15], v[162:165], v[216:219], v[12:15]
	v_mfma_f32_16x16x32_bf16 v[8:11], v[174:177], v[216:219], v[8:11]
	s_barrier
; __device__ __forceinline__ unsigned cvt_pk_bf16(float lo, float hi) { const f32x2_cv v = {lo, hi}; const bf16x2_cv b = __builtin_convertvector(v, bf16x2_cv); return __builtin_bit_cast(unsigned, b); }
; #define PG8_STAGE(bufoff, gbase, voff) do { _Pragma("unroll") for (int _i = 0; _i < 2; ++_i) \
;         __builtin_amdgcn_global_load_lds((const unsigned*)((const char*)(gbase) + (voff)[_i]), (PG8_LAS unsigned*)(lds + (bufoff) + ldsw + _i * 8192), 16, 0, 0); } while (0)
; #define PG8_MMA(ai, bj, At, Bt) do { __builtin_amdgcn_s_setprio(1); _Pragma("unroll") for (int m = 0; m < 4; ++m) _Pragma("unroll") for (int n = 0; n < 2; ++n) _Pragma("unroll") for (int k = 0; k < 2; ++k) \
;         acc[ai][bj][m][n] = __builtin_amdgcn_mfma_f32_16x16x32_bf16(Bt[n][k], At[m][k], acc[ai][bj][m][n], 0, 0, 0); __builtin_amdgcn_s_setprio(0); } while (0)
; #define PG8_WAIT_V(n) asm volatile("s_waitcnt vmcnt(" #n ")" ::: "memory")
; template <class Epi, class Sched, bool STAMP = false>
; __device__ __forceinline__ void gemm_phase(PG8_LAS unsigned char* lds, const Gemm g, const Sched& S, const Epi& E, unsigned long long* stamps) {
;     ...
;             PG8_STAGE(PG8_SB(1, 1), b3 + hstep, voffB);
;             PG8_WAIT_V(6); PG8_BAR; PG8_MMA(1, 1, At, B1); PG8_BAR;
;     __device__ __forceinline__ void operator()(const f32x4 (&acc)[2][2][4][2], const pg8::Unit& u, int wr, int wc, int fr, int fq) const {
;         const int row0 = u.pm * 256 + wr * 64 + fr, col0 = u.pn * 256 + wc * 32 + 8 * fq;
; #pragma unroll
;         for (int ai = 0; ai < 2; ++ai)
; #pragma unroll
;             for (int m = 0; m < 4; ++m) {
;                 const int row = row0 + ai * 128 + m * 16;
;                 const float s = (MODE == 2) ? 1.0f : rstd_of(rowss, row);
;                 bf16_t* rowp = O + (size_t)row * ldc + col0;
; #pragma unroll
;                 for (int bj = 0; bj < 2; ++bj) {
;                     f32x4 v0 = acc[ai][bj][m][0] * s, v1 = acc[ai][bj][m][1] * s;
;                     if (MODE == 1) {
; #pragma unroll
;                         for (int j = 0; j < 4; ++j) { const float a = fmaxf(v0[j], 0.f), b = fmaxf(v1[j], 0.f); v0[j] = a * a; v1[j] = b * b; } }
;                     u32x4 w; w.x = cvt_pk_bf16(v0[0], v0[1]); w.y = cvt_pk_bf16(v0[2], v0[3]); w.z = cvt_pk_bf16(v1[0], v1[1]); w.w = cvt_pk_bf16(v1[2], v1[3]);
;                     *(u32x4*)(rowp + bj * 128) = w; } }
	s_add_u32 s14, s26, 0x40080
	s_addc_u32 s15, s27, 0
	s_add_i32 s16, s17, s43
	s_mov_b32 m0, s16
	s_nop 0
	global_load_lds_dwordx4 v128, s[14:15]
	s_add_i32 m0, s16, 0x2000
	s_nop 0
	global_load_lds_dwordx4 v148, s[14:15]
	s_waitcnt vmcnt(6)
	s_barrier
	v_mfma_f32_16x16x32_bf16 v[52:55], v[220:223], v[178:181], v[52:55]
	v_mfma_f32_16x16x32_bf16 v[48:51], v[228:231], v[178:181], v[48:51]
	v_mfma_f32_16x16x32_bf16 v[36:39], v[220:223], v[196:199], v[36:39]
	v_mfma_f32_16x16x32_bf16 v[32:35], v[228:231], v[196:199], v[32:35]
	v_mfma_f32_16x16x32_bf16 v[20:23], v[220:223], v[204:207], v[20:23]
	v_mfma_f32_16x16x32_bf16 v[16:19], v[228:231], v[204:207], v[16:19]
	v_mfma_f32_16x16x32_bf16 v[4:7], v[220:223], v[212:215], v[4:7]
	v_mfma_f32_16x16x32_bf16 v[0:3], v[228:231], v[212:215], v[0:3]
	v_mfma_f32_16x16x32_bf16 v[52:55], v[224:227], v[192:195], v[52:55]
	v_mfma_f32_16x16x32_bf16 v[48:51], v[232:235], v[192:195], v[48:51]
	v_mfma_f32_16x16x32_bf16 v[36:39], v[224:227], v[200:203], v[36:39]
	v_mfma_f32_16x16x32_bf16 v[32:35], v[232:235], v[200:203], v[32:35]
	v_mfma_f32_16x16x32_bf16 v[20:23], v[224:227], v[208:211], v[20:23]
	v_mfma_f32_16x16x32_bf16 v[16:19], v[232:235], v[208:211], v[16:19]
	v_mfma_f32_16x16x32_bf16 v[4:7], v[224:227], v[216:219], v[4:7]
	v_mfma_f32_16x16x32_bf16 v[0:3], v[232:235], v[216:219], v[0:3]
	s_cmp_gt_u32 s61, 13
	s_barrier
	s_cbranch_scc0 .LBB0_495
	v_lshl_add_u32 v162, s22, 8, v139
	v_ashrrev_i32_e32 v163, 31, v162
	v_lshl_add_u64 v[158:159], v[162:163], 2, s[0:1]
	global_load_dword v164, v[158:159], off
	global_load_dword v193, v[158:159], off offset:64
	global_load_dword v194, v[158:159], off offset:128
	global_load_dword v195, v[158:159], off offset:192
	global_load_dword v196, v[158:159], off offset:512
	global_load_dword v197, v[158:159], off offset:576
	global_load_dword v198, v[158:159], off offset:640
	global_load_dword v199, v[158:159], off offset:704
	v_lshl_or_b32 v160, s56, 8, v167
	v_ashrrev_i32_e32 v161, 31, v160
	s_mov_b32 s5, 0x80000
	s_mov_b64 s[14:15], 0x80000
	s_mov_b32 s56, s4
	s_mov_b32 s22, s6
	s_mov_b64 s[26:27], s[20:21]
	s_mov_b64 s[24:25], s[12:13]
	s_waitcnt vmcnt(0)
	v_fmamk_f32 v164, v164, 0x3a800000, v187
	v_cmp_gt_f32_e32 vcc, s67, v164
	v_mul_f32_e32 v165, 0x4b800000, v164
	s_nop 0
	v_cndmask_b32_e32 v164, v164, v165, vcc
	v_rsq_f32_e32 v164, v164
	s_nop 0
	v_mul_f32_e32 v165, 0x45800000, v164
	v_cndmask_b32_e32 v170, v164, v165, vcc
	v_lshlrev_b64 v[164:165], 12, v[162:163]
	v_lshl_add_u64 v[172:173], s[2:3], 0, v[164:165]
	v_lshlrev_b64 v[164:165], 1, v[160:161]
	v_lshl_add_u64 v[160:161], v[172:173], 0, v[164:165]
	v_pk_mul_f32 v[126:127], v[126:127], v[170:171] op_sel_hi:[1,0]
	v_pk_mul_f32 v[124:125], v[124:125], v[170:171] op_sel_hi:[1,0]
	v_pk_mul_f32 v[172:173], v[122:123], v[170:171] op_sel_hi:[1,0]
	v_pk_mul_f32 v[122:123], v[120:121], v[170:171] op_sel_hi:[1,0]
	v_cvt_pk_bf16_f32 v120, v124, v125
	v_cvt_pk_bf16_f32 v121, v126, v127
	v_cvt_pk_bf16_f32 v122, v122, v123
	v_cvt_pk_bf16_f32 v123, v172, v173
	global_store_dwordx4 v[160:161], v[120:123], off
	v_pk_mul_f32 v[118:119], v[118:119], v[170:171] op_sel_hi:[1,0]
	v_pk_mul_f32 v[116:117], v[116:117], v[170:171] op_sel_hi:[1,0]
	v_pk_mul_f32 v[120:121], v[114:115], v[170:171] op_sel_hi:[1,0]
	v_pk_mul_f32 v[114:115], v[112:113], v[170:171] op_sel_hi:[1,0]
	v_cvt_pk_bf16_f32 v112, v116, v117
	v_cvt_pk_bf16_f32 v113, v118, v119
	v_cvt_pk_bf16_f32 v114, v114, v115
	v_cvt_pk_bf16_f32 v115, v120, v121
	global_store_dwordx4 v[160:161], v[112:115], off offset:256
	s_nop 1
	v_mov_b32_e32 v114, v193
	s_nop 0
	v_or_b32_e32 v112, 16, v162
	v_ashrrev_i32_e32 v113, 31, v112
	v_lshlrev_b64 v[112:113], 12, v[112:113]
	v_lshl_add_u64 v[112:113], s[2:3], 0, v[112:113]
	v_lshl_add_u64 v[112:113], v[112:113], 0, v[164:165]
	v_fmamk_f32 v114, v114, 0x3a800000, v187
	v_cmp_gt_f32_e32 vcc, s67, v114
	v_mul_f32_e32 v115, 0x4b800000, v114
	s_nop 0
	v_cndmask_b32_e32 v114, v114, v115, vcc
	v_rsq_f32_e32 v114, v114
	s_nop 0
	v_mul_f32_e32 v115, 0x45800000, v114
	v_cndmask_b32_e32 v114, v114, v115, vcc
	v_pk_mul_f32 v[110:111], v[110:111], v[114:115] op_sel_hi:[1,0]
	v_pk_mul_f32 v[108:109], v[108:109], v[114:115] op_sel_hi:[1,0]
	v_pk_mul_f32 v[116:117], v[106:107], v[114:115] op_sel_hi:[1,0]
	v_pk_mul_f32 v[106:107], v[104:105], v[114:115] op_sel_hi:[1,0]
	v_cvt_pk_bf16_f32 v104, v108, v109
	v_cvt_pk_bf16_f32 v105, v110, v111
	v_cvt_pk_bf16_f32 v106, v106, v107
	v_cvt_pk_bf16_f32 v107, v116, v117
	global_store_dwordx4 v[112:113], v[104:107], off
	v_pk_mul_f32 v[102:103], v[102:103], v[114:115] op_sel_hi:[1,0]
	v_pk_mul_f32 v[100:101], v[100:101], v[114:115] op_sel_hi:[1,0]
	v_pk_mul_f32 v[104:105], v[98:99], v[114:115] op_sel_hi:[1,0]
	v_pk_mul_f32 v[98:99], v[96:97], v[114:115] op_sel_hi:[1,0]
	v_cvt_pk_bf16_f32 v96, v100, v101
	v_cvt_pk_bf16_f32 v97, v102, v103
	v_cvt_pk_bf16_f32 v98, v98, v99
	v_cvt_pk_bf16_f32 v99, v104, v105
	global_store_dwordx4 v[112:113], v[96:99], off offset:256
	s_nop 1
	v_mov_b32_e32 v98, v194
	s_nop 0
	v_or_b32_e32 v96, 32, v162
	v_ashrrev_i32_e32 v97, 31, v96
	v_lshlrev_b64 v[96:97], 12, v[96:97]
	v_lshl_add_u64 v[96:97], s[2:3], 0, v[96:97]
	v_lshl_add_u64 v[96:97], v[96:97], 0, v[164:165]
	v_fmamk_f32 v98, v98, 0x3a800000, v187
	v_cmp_gt_f32_e32 vcc, s67, v98
	v_mul_f32_e32 v99, 0x4b800000, v98
	s_nop 0
	v_cndmask_b32_e32 v98, v98, v99, vcc
	v_rsq_f32_e32 v98, v98
	s_nop 0
	v_mul_f32_e32 v99, 0x45800000, v98
	v_cndmask_b32_e32 v98, v98, v99, vcc
	v_pk_mul_f32 v[94:95], v[94:95], v[98:99] op_sel_hi:[1,0]
	v_pk_mul_f32 v[92:93], v[92:93], v[98:99] op_sel_hi:[1,0]
	v_pk_mul_f32 v[100:101], v[90:91], v[98:99] op_sel_hi:[1,0]
; __device__ __forceinline__ unsigned cvt_pk_bf16(float lo, float hi) { const f32x2_cv v = {lo, hi}; const bf16x2_cv b = __builtin_convertvector(v, bf16x2_cv); return __builtin_bit_cast(unsigned, b); }
; __device__ __forceinline__ float rstd_of(const float* rowss, int row) { return rsqrtf(rowss[row] * (1.0f / 1024.0f) + 1e-6f); }
;     __device__ __forceinline__ void operator()(const f32x4 (&acc)[2][2][4][2], const pg8::Unit& u, int wr, int wc, int fr, int fq) const {
;     ...
;             for (int m = 0; m < 4; ++m) {
;                 const int row = row0 + ai * 128 + m * 16;
;                 const float s = (MODE == 2) ? 1.0f : rstd_of(rowss, row);
;                 bf16_t* rowp = O + (size_t)row * ldc + col0;
; #pragma unroll
;                 for (int bj = 0; bj < 2; ++bj) {
;                     f32x4 v0 = acc[ai][bj][m][0] * s, v1 = acc[ai][bj][m][1] * s;
;                     if (MODE == 1) {
; #pragma unroll
;                         for (int j = 0; j < 4; ++j) { const float a = fmaxf(v0[j], 0.f), b = fmaxf(v1[j], 0.f); v0[j] = a * a; v1[j] = b * b; } }
;                     u32x4 w; w.x = cvt_pk_bf16(v0[0], v0[1]); w.y = cvt_pk_bf16(v0[2], v0[3]); w.z = cvt_pk_bf16(v1[0], v1[1]); w.w = cvt_pk_bf16(v1[2], v1[3]);
;                     *(u32x4*)(rowp + bj * 128) = w; } }
	v_pk_mul_f32 v[90:91], v[88:89], v[98:99] op_sel_hi:[1,0]
	v_cvt_pk_bf16_f32 v88, v92, v93
	v_cvt_pk_bf16_f32 v89, v94, v95
	v_cvt_pk_bf16_f32 v90, v90, v91
	v_cvt_pk_bf16_f32 v91, v100, v101
	global_store_dwordx4 v[96:97], v[88:91], off
	v_pk_mul_f32 v[86:87], v[86:87], v[98:99] op_sel_hi:[1,0]
	v_pk_mul_f32 v[84:85], v[84:85], v[98:99] op_sel_hi:[1,0]
	v_pk_mul_f32 v[88:89], v[82:83], v[98:99] op_sel_hi:[1,0]
	v_pk_mul_f32 v[82:83], v[80:81], v[98:99] op_sel_hi:[1,0]
	v_cvt_pk_bf16_f32 v80, v84, v85
	v_cvt_pk_bf16_f32 v81, v86, v87
	v_cvt_pk_bf16_f32 v82, v82, v83
	v_cvt_pk_bf16_f32 v83, v88, v89
	global_store_dwordx4 v[96:97], v[80:83], off offset:256
	s_nop 1
	v_mov_b32_e32 v82, v195
	s_nop 0
	v_or_b32_e32 v80, 48, v162
	v_ashrrev_i32_e32 v81, 31, v80
	v_lshlrev_b64 v[80:81], 12, v[80:81]
	v_lshl_add_u64 v[80:81], s[2:3], 0, v[80:81]
	v_lshl_add_u64 v[80:81], v[80:81], 0, v[164:165]
	v_fmamk_f32 v82, v82, 0x3a800000, v187
	v_cmp_gt_f32_e32 vcc, s67, v82
	v_mul_f32_e32 v83, 0x4b800000, v82
	s_nop 0
	v_cndmask_b32_e32 v82, v82, v83, vcc
	v_rsq_f32_e32 v82, v82
	s_nop 0
	v_mul_f32_e32 v83, 0x45800000, v82
	v_cndmask_b32_e32 v82, v82, v83, vcc
	v_pk_mul_f32 v[78:79], v[78:79], v[82:83] op_sel_hi:[1,0]
	v_pk_mul_f32 v[76:77], v[76:77], v[82:83] op_sel_hi:[1,0]
	v_pk_mul_f32 v[84:85], v[74:75], v[82:83] op_sel_hi:[1,0]
	v_pk_mul_f32 v[74:75], v[72:73], v[82:83] op_sel_hi:[1,0]
	v_cvt_pk_bf16_f32 v72, v76, v77
	v_cvt_pk_bf16_f32 v73, v78, v79
	v_cvt_pk_bf16_f32 v74, v74, v75
	v_cvt_pk_bf16_f32 v75, v84, v85
	global_store_dwordx4 v[80:81], v[72:75], off
	v_pk_mul_f32 v[70:71], v[70:71], v[82:83] op_sel_hi:[1,0]
	v_pk_mul_f32 v[68:69], v[68:69], v[82:83] op_sel_hi:[1,0]
	v_pk_mul_f32 v[72:73], v[66:67], v[82:83] op_sel_hi:[1,0]
	v_pk_mul_f32 v[66:67], v[64:65], v[82:83] op_sel_hi:[1,0]
	v_cvt_pk_bf16_f32 v64, v68, v69
	v_cvt_pk_bf16_f32 v65, v70, v71
	v_cvt_pk_bf16_f32 v66, v66, v67
	v_cvt_pk_bf16_f32 v67, v72, v73
	global_store_dwordx4 v[80:81], v[64:67], off offset:256
	s_nop 1
	v_mov_b32_e32 v64, v196
	s_nop 0
	v_lshl_add_u64 v[66:67], v[160:161], 0, s[14:15]
	s_mov_b64 s[14:15], 0x90000
	v_fmamk_f32 v64, v64, 0x3a800000, v187
	v_cmp_gt_f32_e32 vcc, s67, v64
	v_mul_f32_e32 v65, 0x4b800000, v64
	s_nop 0
	v_cndmask_b32_e32 v64, v64, v65, vcc
	v_rsq_f32_e32 v64, v64
	s_nop 0
	v_mul_f32_e32 v65, 0x45800000, v64
	v_cndmask_b32_e32 v64, v64, v65, vcc
	v_pk_mul_f32 v[60:61], v[60:61], v[64:65] op_sel_hi:[1,0]
	v_pk_mul_f32 v[62:63], v[62:63], v[64:65] op_sel_hi:[1,0]
	v_pk_mul_f32 v[68:69], v[58:59], v[64:65] op_sel_hi:[1,0]
	v_pk_mul_f32 v[58:59], v[56:57], v[64:65] op_sel_hi:[1,0]
	v_cvt_pk_bf16_f32 v56, v60, v61
	v_add_co_u32_e32 v60, vcc, s5, v160
	v_cvt_pk_bf16_f32 v57, v62, v63
	v_cvt_pk_bf16_f32 v58, v58, v59
	v_cvt_pk_bf16_f32 v59, v68, v69
	v_addc_co_u32_e32 v61, vcc, 0, v161, vcc
	global_store_dwordx4 v[60:61], v[56:59], off
	v_pk_mul_f32 v[54:55], v[54:55], v[64:65] op_sel_hi:[1,0]
	v_pk_mul_f32 v[52:53], v[52:53], v[64:65] op_sel_hi:[1,0]
	v_pk_mul_f32 v[56:57], v[50:51], v[64:65] op_sel_hi:[1,0]
	v_pk_mul_f32 v[50:51], v[48:49], v[64:65] op_sel_hi:[1,0]
	v_cvt_pk_bf16_f32 v48, v52, v53
	v_cvt_pk_bf16_f32 v49, v54, v55
	v_cvt_pk_bf16_f32 v50, v50, v51
	v_cvt_pk_bf16_f32 v51, v56, v57
	global_store_dwordx4 v[66:67], v[48:51], off offset:256
	s_nop 1
	v_mov_b32_e32 v48, v197
	s_mov_b32 s5, 0x90000
	v_lshl_add_u64 v[50:51], v[160:161], 0, s[14:15]
	s_mov_b64 s[14:15], 0xa0000
	v_fmamk_f32 v48, v48, 0x3a800000, v187
	v_cmp_gt_f32_e32 vcc, s67, v48
	v_mul_f32_e32 v49, 0x4b800000, v48
	s_nop 0
	v_cndmask_b32_e32 v48, v48, v49, vcc
	v_rsq_f32_e32 v48, v48
	s_nop 0
	v_mul_f32_e32 v49, 0x45800000, v48
; __device__ __forceinline__ unsigned cvt_pk_bf16(float lo, float hi) { const f32x2_cv v = {lo, hi}; const bf16x2_cv b = __builtin_convertvector(v, bf16x2_cv); return __builtin_bit_cast(unsigned, b); }
; #define PG8_WAIT_V(n) asm volatile("s_waitcnt vmcnt(" #n ")" ::: "memory")
; #define PG8_BAR __builtin_amdgcn_s_barrier()
; __device__ __forceinline__ float rstd_of(const float* rowss, int row) { return rsqrtf(rowss[row] * (1.0f / 1024.0f) + 1e-6f); }
; template <class Epi, class Sched, bool STAMP = false>
; __device__ __forceinline__ void gemm_phase(PG8_LAS unsigned char* lds, const Gemm g, const Sched& S, const Epi& E, unsigned long long* stamps) {
;     ...
;         if (!has_next) break;
; #pragma unroll
;         for (int a = 0; a < 2; ++a)
; #pragma unroll
;             for (int b = 0; b < 2; ++b)
; #pragma unroll
;                 for (int m = 0; m < 4; ++m)
; #pragma unroll
;                     for (int n = 0; n < 2; ++n) acc[a][b][m][n] = (f32x4){0.f, 0.f, 0.f, 0.f};
;         cur = nxt; cA = nA; cB = nB; ++ui;
;     }
;     PG8_WAIT_V(0);
;     if (wr == 0) PG8_BAR;
;     PG8_BAR;
;     __device__ __forceinline__ void operator()(const f32x4 (&acc)[2][2][4][2], const pg8::Unit& u, int wr, int wc, int fr, int fq) const {
;     ...
;             for (int m = 0; m < 4; ++m) {
;                 const int row = row0 + ai * 128 + m * 16;
;                 const float s = (MODE == 2) ? 1.0f : rstd_of(rowss, row);
;                 bf16_t* rowp = O + (size_t)row * ldc + col0;
; #pragma unroll
;                 for (int bj = 0; bj < 2; ++bj) {
;                     f32x4 v0 = acc[ai][bj][m][0] * s, v1 = acc[ai][bj][m][1] * s;
;                     if (MODE == 1) {
; #pragma unroll
;                         for (int j = 0; j < 4; ++j) { const float a = fmaxf(v0[j], 0.f), b = fmaxf(v1[j], 0.f); v0[j] = a * a; v1[j] = b * b; } }
;                     u32x4 w; w.x = cvt_pk_bf16(v0[0], v0[1]); w.y = cvt_pk_bf16(v0[2], v0[3]); w.z = cvt_pk_bf16(v1[0], v1[1]); w.w = cvt_pk_bf16(v1[2], v1[3]);
;                     *(u32x4*)(rowp + bj * 128) = w; } }
	v_cndmask_b32_e32 v48, v48, v49, vcc
	v_pk_mul_f32 v[44:45], v[44:45], v[48:49] op_sel_hi:[1,0]
	v_pk_mul_f32 v[46:47], v[46:47], v[48:49] op_sel_hi:[1,0]
	v_pk_mul_f32 v[52:53], v[42:43], v[48:49] op_sel_hi:[1,0]
	v_pk_mul_f32 v[42:43], v[40:41], v[48:49] op_sel_hi:[1,0]
	v_cvt_pk_bf16_f32 v40, v44, v45
	v_add_co_u32_e32 v44, vcc, s5, v160
	v_cvt_pk_bf16_f32 v41, v46, v47
	v_cvt_pk_bf16_f32 v42, v42, v43
	v_cvt_pk_bf16_f32 v43, v52, v53
	v_addc_co_u32_e32 v45, vcc, 0, v161, vcc
	global_store_dwordx4 v[44:45], v[40:43], off
	v_pk_mul_f32 v[38:39], v[38:39], v[48:49] op_sel_hi:[1,0]
	v_pk_mul_f32 v[36:37], v[36:37], v[48:49] op_sel_hi:[1,0]
	v_pk_mul_f32 v[40:41], v[34:35], v[48:49] op_sel_hi:[1,0]
	v_pk_mul_f32 v[34:35], v[32:33], v[48:49] op_sel_hi:[1,0]
	v_cvt_pk_bf16_f32 v32, v36, v37
	v_cvt_pk_bf16_f32 v33, v38, v39
	v_cvt_pk_bf16_f32 v34, v34, v35
	v_cvt_pk_bf16_f32 v35, v40, v41
	global_store_dwordx4 v[50:51], v[32:35], off offset:256
	s_nop 1
	v_mov_b32_e32 v32, v198
	s_mov_b32 s5, 0xa0000
	v_lshl_add_u64 v[34:35], v[160:161], 0, s[14:15]
	s_mov_b64 s[14:15], 0xb0000
	v_fmamk_f32 v32, v32, 0x3a800000, v187
	v_cmp_gt_f32_e32 vcc, s67, v32
	v_mul_f32_e32 v33, 0x4b800000, v32
	s_nop 0
	v_cndmask_b32_e32 v32, v32, v33, vcc
	v_rsq_f32_e32 v32, v32
	s_nop 0
	v_mul_f32_e32 v33, 0x45800000, v32
	v_cndmask_b32_e32 v32, v32, v33, vcc
	v_pk_mul_f32 v[28:29], v[28:29], v[32:33] op_sel_hi:[1,0]
	v_pk_mul_f32 v[30:31], v[30:31], v[32:33] op_sel_hi:[1,0]
	v_pk_mul_f32 v[36:37], v[26:27], v[32:33] op_sel_hi:[1,0]
	v_pk_mul_f32 v[26:27], v[24:25], v[32:33] op_sel_hi:[1,0]
	v_cvt_pk_bf16_f32 v24, v28, v29
	v_add_co_u32_e32 v28, vcc, s5, v160
	v_cvt_pk_bf16_f32 v25, v30, v31
	v_cvt_pk_bf16_f32 v26, v26, v27
	v_cvt_pk_bf16_f32 v27, v36, v37
	v_addc_co_u32_e32 v29, vcc, 0, v161, vcc
	global_store_dwordx4 v[28:29], v[24:27], off
	v_pk_mul_f32 v[22:23], v[22:23], v[32:33] op_sel_hi:[1,0]
	v_pk_mul_f32 v[20:21], v[20:21], v[32:33] op_sel_hi:[1,0]
	v_pk_mul_f32 v[24:25], v[18:19], v[32:33] op_sel_hi:[1,0]
	v_pk_mul_f32 v[18:19], v[16:17], v[32:33] op_sel_hi:[1,0]
	v_cvt_pk_bf16_f32 v16, v20, v21
	v_cvt_pk_bf16_f32 v17, v22, v23
	v_cvt_pk_bf16_f32 v18, v18, v19
	v_cvt_pk_bf16_f32 v19, v24, v25
	global_store_dwordx4 v[34:35], v[16:19], off offset:256
	s_nop 1
	v_mov_b32_e32 v16, v199
	s_mov_b32 s5, 0xb0000
	v_lshl_add_u64 v[18:19], v[160:161], 0, s[14:15]
	v_fmamk_f32 v16, v16, 0x3a800000, v187
	v_cmp_gt_f32_e32 vcc, s67, v16
	v_mul_f32_e32 v17, 0x4b800000, v16
	s_nop 0
	v_cndmask_b32_e32 v16, v16, v17, vcc
	v_rsq_f32_e32 v16, v16
	s_nop 0
	v_mul_f32_e32 v17, 0x45800000, v16
	v_cndmask_b32_e32 v16, v16, v17, vcc
	v_pk_mul_f32 v[12:13], v[12:13], v[16:17] op_sel_hi:[1,0]
	v_pk_mul_f32 v[14:15], v[14:15], v[16:17] op_sel_hi:[1,0]
	v_pk_mul_f32 v[20:21], v[10:11], v[16:17] op_sel_hi:[1,0]
	v_pk_mul_f32 v[10:11], v[8:9], v[16:17] op_sel_hi:[1,0]
	v_cvt_pk_bf16_f32 v8, v12, v13
	v_add_co_u32_e32 v12, vcc, s5, v160
	v_cvt_pk_bf16_f32 v9, v14, v15
	v_cvt_pk_bf16_f32 v10, v10, v11
	v_cvt_pk_bf16_f32 v11, v20, v21
	v_addc_co_u32_e32 v13, vcc, 0, v161, vcc
	global_store_dwordx4 v[12:13], v[8:11], off
	v_pk_mul_f32 v[6:7], v[6:7], v[16:17] op_sel_hi:[1,0]
	v_pk_mul_f32 v[4:5], v[4:5], v[16:17] op_sel_hi:[1,0]
	v_pk_mul_f32 v[8:9], v[2:3], v[16:17] op_sel_hi:[1,0]
	v_pk_mul_f32 v[2:3], v[0:1], v[16:17] op_sel_hi:[1,0]
	v_cvt_pk_bf16_f32 v0, v4, v5
	v_cvt_pk_bf16_f32 v1, v6, v7
	v_cvt_pk_bf16_f32 v2, v2, v3
	v_cvt_pk_bf16_f32 v3, v8, v9
	s_and_b64 vcc, exec, s[38:39]
	global_store_dwordx4 v[18:19], v[0:3], off offset:256
	s_cbranch_vccz .LBB0_492
	s_waitcnt vmcnt(0)
	s_cmpk_gt_u32 s36, 0xff
	s_cbranch_scc1 .LBB0_499
	s_barrier

; #define PG8_STAGE(bufoff, gbase, voff) do { _Pragma("unroll") for (int _i = 0; _i < 2; ++_i) \
;         __builtin_amdgcn_global_load_lds((const unsigned*)((const char*)(gbase) + (voff)[_i]), (PG8_LAS unsigned*)(lds + (bufoff) + ldsw + _i * 8192), 16, 0, 0); } while (0)
; #define PG8_LDA(dst, b, h) do { _Pragma("unroll") for (int m = 0; m < 4; ++m) _Pragma("unroll") for (int k = 0; k < 2; ++k) dst[m][k] = *(const PG8_LAS bf16x8*)(lds + PG8_SA(b, h) + aoff + m * 2048 + k * 1024); } while (0)
; #define PG8_LDB(dst, b, h) do { _Pragma("unroll") for (int n = 0; n < 2; ++n) _Pragma("unroll") for (int k = 0; k < 2; ++k) dst[n][k] = *(const PG8_LAS bf16x8*)(lds + PG8_SB(b, h) + boff + n * 2048 + k * 1024); } while (0)
; #define PG8_MMA(ai, bj, At, Bt) do { __builtin_amdgcn_s_setprio(1); _Pragma("unroll") for (int m = 0; m < 4; ++m) _Pragma("unroll") for (int n = 0; n < 2; ++n) _Pragma("unroll") for (int k = 0; k < 2; ++k) \
;         acc[ai][bj][m][n] = __builtin_amdgcn_mfma_f32_16x16x32_bf16(Bt[n][k], At[m][k], acc[ai][bj][m][n], 0, 0, 0); __builtin_amdgcn_s_setprio(0); } while (0)
; #define PG8_BAR __builtin_amdgcn_s_barrier()
; template <class Epi, class Sched, bool STAMP = false>
; __device__ __forceinline__ void gemm_phase(PG8_LAS unsigned char* lds, const Gemm g, const Sched& S, const Epi& E, unsigned long long* stamps) {
;     ...
;         for (int t = 0; t < nt; t += 2) {
;             const bool last = (t == nt - 2);
;             const char* a1 = cA + (size_t)(t + 1) * kstep;
;             const char* a2 = last ? nA : cA + (size_t)(t + 2) * kstep; const char* b2 = last ? nB : cB + (size_t)(t + 2) * kstep;
;             const char* a3 = a2 + kstep; const char* b3 = b2 + kstep;
;             if (last && has_next) S.a_ready(nxt);
;             PG8_LDB(B0, 0, 0); PG8_SCHED; PG8_LDA(At, 0, 0); PG8_STAGE(PG8_SA(1, 1), a1 + hstep, voffA);
;             PG8_WAIT_L(8); PG8_BAR; PG8_WAIT_L(0); PG8_MMA(0, 0, At, B0); PG8_BAR; PG8_SCHED;
;             PG8_LDB(B1, 0, 1); PG8_STAGE(PG8_SB(0, 0), b2, voffB);
;             PG8_BAR; PG8_WAIT_L(0); PG8_MMA(0, 1, At, B1); PG8_BAR;
;             PG8_LDA(At, 0, 1); PG8_STAGE(PG8_SA(0, 0), a2, voffA);
;             PG8_BAR; PG8_WAIT_L(0); PG8_MMA(1, 0, At, B0); PG8_BAR; PG8_SCHED;
;             PG8_STAGE(PG8_SB(0, 1), b2 + hstep, voffB);
;             PG8_WAIT_V(6); PG8_BAR; PG8_MMA(1, 1, At, B1); PG8_BAR;
.LBB0_1183:
	s_add_u32 s30, s26, 0x100
	s_addc_u32 s31, s27, 0
	s_add_i32 s14, 0, 0x10000
	ds_read_b128 v[154:157], v248
	ds_read_b128 v[162:165], v248 offset:1024
	ds_read_b128 v[166:169], v248 offset:2048
	ds_read_b128 v[170:173], v248 offset:3072
	s_cmp_eq_u32 s65, 60
	s_cselect_b32 s37, s7, s31
	s_cselect_b32 s36, s23, s30
	s_cselect_b32 s35, s5, s64
	s_cselect_b32 s34, s62, s63
	s_add_i32 m0, s25, 0xc000
	ds_read_b128 v[174:177], v160
	ds_read_b128 v[178:181], v160 offset:1024
	ds_read_b128 v[192:195], v160 offset:2048
	ds_read_b128 v[196:199], v160 offset:3072
	ds_read_b128 v[200:203], v160 offset:4096
	ds_read_b128 v[204:207], v160 offset:5120
	ds_read_b128 v[208:211], v160 offset:6144
	global_load_lds_dwordx4 v150, s[26:27]
	s_add_i32 m0, s25, 0xe000
	ds_read_b128 v[212:215], v160 offset:7168
	global_load_lds_dwordx4 v152, s[26:27]
	s_waitcnt lgkmcnt(8)
	s_barrier
	s_waitcnt lgkmcnt(0)
	v_mfma_f32_16x16x32_bf16 v[124:127], v[154:157], v[174:177], v[124:127]
	v_mfma_f32_16x16x32_bf16 v[120:123], v[166:169], v[174:177], v[120:123]
	v_mfma_f32_16x16x32_bf16 v[108:111], v[154:157], v[192:195], v[108:111]
	v_mfma_f32_16x16x32_bf16 v[104:107], v[166:169], v[192:195], v[104:107]
	v_mfma_f32_16x16x32_bf16 v[92:95], v[154:157], v[200:203], v[92:95]
	v_mfma_f32_16x16x32_bf16 v[88:91], v[166:169], v[200:203], v[88:91]
	v_mfma_f32_16x16x32_bf16 v[76:79], v[154:157], v[208:211], v[76:79]
	v_mfma_f32_16x16x32_bf16 v[72:75], v[166:169], v[208:211], v[72:75]
	v_mfma_f32_16x16x32_bf16 v[124:127], v[162:165], v[178:181], v[124:127]
	v_mfma_f32_16x16x32_bf16 v[120:123], v[170:173], v[178:181], v[120:123]
	v_mfma_f32_16x16x32_bf16 v[108:111], v[162:165], v[196:199], v[108:111]
	v_mfma_f32_16x16x32_bf16 v[104:107], v[170:173], v[196:199], v[104:107]
	v_mfma_f32_16x16x32_bf16 v[92:95], v[162:165], v[204:207], v[92:95]
	v_mfma_f32_16x16x32_bf16 v[88:91], v[170:173], v[204:207], v[88:91]
	v_mfma_f32_16x16x32_bf16 v[76:79], v[162:165], v[212:215], v[76:79]
	v_mfma_f32_16x16x32_bf16 v[72:75], v[170:173], v[212:215], v[72:75]
	s_barrier
	s_add_i32 s16, 0, 0x14000
	s_add_i32 s14, s14, s49
	s_mov_b32 m0, s14
	ds_read_b128 v[216:219], v249
	ds_read_b128 v[220:223], v249 offset:1024
	ds_read_b128 v[224:227], v249 offset:2048
	global_load_lds_dwordx4 v128, s[34:35]
	s_add_i32 m0, s14, 0x2000
	ds_read_b128 v[228:231], v249 offset:3072
	global_load_lds_dwordx4 v148, s[34:35]
	s_barrier
	s_waitcnt lgkmcnt(0)
	v_mfma_f32_16x16x32_bf16 v[116:119], v[216:219], v[174:177], v[116:119]
	v_mfma_f32_16x16x32_bf16 v[112:115], v[224:227], v[174:177], v[112:115]
	v_mfma_f32_16x16x32_bf16 v[100:103], v[216:219], v[192:195], v[100:103]
	v_mfma_f32_16x16x32_bf16 v[96:99], v[224:227], v[192:195], v[96:99]
	v_mfma_f32_16x16x32_bf16 v[84:87], v[216:219], v[200:203], v[84:87]
	v_mfma_f32_16x16x32_bf16 v[80:83], v[224:227], v[200:203], v[80:83]
	v_mfma_f32_16x16x32_bf16 v[68:71], v[216:219], v[208:211], v[68:71]
	v_mfma_f32_16x16x32_bf16 v[64:67], v[224:227], v[208:211], v[64:67]
	v_mfma_f32_16x16x32_bf16 v[116:119], v[220:223], v[178:181], v[116:119]
	v_mfma_f32_16x16x32_bf16 v[112:115], v[228:231], v[178:181], v[112:115]
	v_mfma_f32_16x16x32_bf16 v[100:103], v[220:223], v[196:199], v[100:103]
	v_mfma_f32_16x16x32_bf16 v[96:99], v[228:231], v[196:199], v[96:99]
	v_mfma_f32_16x16x32_bf16 v[84:87], v[220:223], v[204:207], v[84:87]
	v_mfma_f32_16x16x32_bf16 v[80:83], v[228:231], v[204:207], v[80:83]
	v_mfma_f32_16x16x32_bf16 v[68:71], v[220:223], v[212:215], v[68:71]
	v_mfma_f32_16x16x32_bf16 v[64:67], v[228:231], v[212:215], v[64:67]
	s_mov_b32 m0, s25
	s_barrier
	ds_read_b128 v[174:177], v160 offset:16384
	ds_read_b128 v[178:181], v160 offset:17408
	ds_read_b128 v[192:195], v160 offset:18432
	ds_read_b128 v[196:199], v160 offset:19456
	ds_read_b128 v[200:203], v160 offset:20480
	ds_read_b128 v[204:207], v160 offset:21504
	ds_read_b128 v[208:211], v160 offset:22528
	global_load_lds_dwordx4 v128, s[36:37]
	s_mov_b32 m0, s53
	ds_read_b128 v[212:215], v160 offset:23552
	global_load_lds_dwordx4 v148, s[36:37]
	s_barrier
	s_waitcnt lgkmcnt(0)
	v_mfma_f32_16x16x32_bf16 v[60:63], v[154:157], v[174:177], v[60:63]
	v_mfma_f32_16x16x32_bf16 v[56:59], v[166:169], v[174:177], v[56:59]
	v_mfma_f32_16x16x32_bf16 v[44:47], v[154:157], v[192:195], v[44:47]
	v_mfma_f32_16x16x32_bf16 v[40:43], v[166:169], v[192:195], v[40:43]
	v_mfma_f32_16x16x32_bf16 v[28:31], v[154:157], v[200:203], v[28:31]
	v_mfma_f32_16x16x32_bf16 v[24:27], v[166:169], v[200:203], v[24:27]
	v_mfma_f32_16x16x32_bf16 v[12:15], v[154:157], v[208:211], v[12:15]
	v_mfma_f32_16x16x32_bf16 v[8:11], v[166:169], v[208:211], v[8:11]
	v_mfma_f32_16x16x32_bf16 v[60:63], v[162:165], v[178:181], v[60:63]
	v_mfma_f32_16x16x32_bf16 v[56:59], v[170:173], v[178:181], v[56:59]
	v_mfma_f32_16x16x32_bf16 v[44:47], v[162:165], v[196:199], v[44:47]
	v_mfma_f32_16x16x32_bf16 v[40:43], v[170:173], v[196:199], v[40:43]
	v_mfma_f32_16x16x32_bf16 v[28:31], v[162:165], v[204:207], v[28:31]
	v_mfma_f32_16x16x32_bf16 v[24:27], v[170:173], v[204:207], v[24:27]
	v_mfma_f32_16x16x32_bf16 v[12:15], v[162:165], v[212:215], v[12:15]
	v_mfma_f32_16x16x32_bf16 v[8:11], v[170:173], v[212:215], v[8:11]
	s_barrier
	s_add_u32 s14, s34, 0x100000
	s_addc_u32 s15, s35, 0
	s_add_i32 s16, s16, s49
	s_mov_b32 m0, s16
	s_nop 0
	global_load_lds_dwordx4 v128, s[14:15]
	s_add_i32 m0, s16, 0x2000
	s_nop 0
	global_load_lds_dwordx4 v148, s[14:15]
	s_add_i32 s65, s65, 2
	s_add_u32 s63, s63, 0x100
	s_addc_u32 s64, s64, 0
	s_waitcnt vmcnt(6)
	s_barrier
; #define PG8_STAGE(bufoff, gbase, voff) do { _Pragma("unroll") for (int _i = 0; _i < 2; ++_i) \
;         __builtin_amdgcn_global_load_lds((const unsigned*)((const char*)(gbase) + (voff)[_i]), (PG8_LAS unsigned*)(lds + (bufoff) + ldsw + _i * 8192), 16, 0, 0); } while (0)
; #define PG8_LDA(dst, b, h) do { _Pragma("unroll") for (int m = 0; m < 4; ++m) _Pragma("unroll") for (int k = 0; k < 2; ++k) dst[m][k] = *(const PG8_LAS bf16x8*)(lds + PG8_SA(b, h) + aoff + m * 2048 + k * 1024); } while (0)
; #define PG8_LDB(dst, b, h) do { _Pragma("unroll") for (int n = 0; n < 2; ++n) _Pragma("unroll") for (int k = 0; k < 2; ++k) dst[n][k] = *(const PG8_LAS bf16x8*)(lds + PG8_SB(b, h) + boff + n * 2048 + k * 1024); } while (0)
; #define PG8_MMA(ai, bj, At, Bt) do { __builtin_amdgcn_s_setprio(1); _Pragma("unroll") for (int m = 0; m < 4; ++m) _Pragma("unroll") for (int n = 0; n < 2; ++n) _Pragma("unroll") for (int k = 0; k < 2; ++k) \
;         acc[ai][bj][m][n] = __builtin_amdgcn_mfma_f32_16x16x32_bf16(Bt[n][k], At[m][k], acc[ai][bj][m][n], 0, 0, 0); __builtin_amdgcn_s_setprio(0); } while (0)
; #define PG8_WAIT_V(n) asm volatile("s_waitcnt vmcnt(" #n ")" ::: "memory")
; #define PG8_WAIT_L(n) asm volatile("s_waitcnt lgkmcnt(" #n ")" ::: "memory")
; #define PG8_BAR __builtin_amdgcn_s_barrier()
; #define PG8_SCHED __builtin_amdgcn_sched_barrier(0)
; template <class Epi, class Sched, bool STAMP = false>
; __device__ __forceinline__ void gemm_phase(PG8_LAS unsigned char* lds, const Gemm g, const Sched& S, const Epi& E, unsigned long long* stamps) {
;     ...
;             PG8_WAIT_V(6); PG8_BAR; PG8_MMA(1, 1, At, B1); PG8_BAR;
;             PG8_LDB(B0, 1, 0); PG8_SCHED; PG8_LDA(At, 1, 0); PG8_STAGE(PG8_SA(0, 1), a2 + hstep, voffA);
;             PG8_WAIT_L(8); PG8_BAR; PG8_WAIT_L(0); PG8_MMA(0, 0, At, B0); PG8_BAR; PG8_SCHED;
;             PG8_LDB(B1, 1, 1); PG8_STAGE(PG8_SB(1, 0), b3, voffB);
;             PG8_BAR; PG8_WAIT_L(0); PG8_MMA(0, 1, At, B1); PG8_BAR;
;             PG8_LDA(At, 1, 1); PG8_STAGE(PG8_SA(1, 0), a3, voffA);
;             PG8_BAR; PG8_WAIT_L(0); PG8_MMA(1, 0, At, B0); PG8_BAR; PG8_SCHED;
	v_mfma_f32_16x16x32_bf16 v[52:55], v[216:219], v[174:177], v[52:55]
	v_mfma_f32_16x16x32_bf16 v[48:51], v[224:227], v[174:177], v[48:51]
	v_mfma_f32_16x16x32_bf16 v[36:39], v[216:219], v[192:195], v[36:39]
	v_mfma_f32_16x16x32_bf16 v[32:35], v[224:227], v[192:195], v[32:35]
	v_mfma_f32_16x16x32_bf16 v[20:23], v[216:219], v[200:203], v[20:23]
	v_mfma_f32_16x16x32_bf16 v[16:19], v[224:227], v[200:203], v[16:19]
	v_mfma_f32_16x16x32_bf16 v[4:7], v[216:219], v[208:211], v[4:7]
	v_mfma_f32_16x16x32_bf16 v[0:3], v[224:227], v[208:211], v[0:3]
	v_mfma_f32_16x16x32_bf16 v[52:55], v[220:223], v[178:181], v[52:55]
	v_mfma_f32_16x16x32_bf16 v[48:51], v[228:231], v[178:181], v[48:51]
	v_mfma_f32_16x16x32_bf16 v[36:39], v[220:223], v[196:199], v[36:39]
	v_mfma_f32_16x16x32_bf16 v[32:35], v[228:231], v[196:199], v[32:35]
	v_mfma_f32_16x16x32_bf16 v[20:23], v[220:223], v[204:207], v[20:23]
	v_mfma_f32_16x16x32_bf16 v[16:19], v[228:231], v[204:207], v[16:19]
	v_mfma_f32_16x16x32_bf16 v[4:7], v[220:223], v[212:215], v[4:7]
	v_mfma_f32_16x16x32_bf16 v[0:3], v[228:231], v[212:215], v[0:3]
	s_add_i32 s16, 0, 0x18000
	s_barrier
	ds_read_b128 v[154:157], v250
	ds_read_b128 v[162:165], v250 offset:1024
	ds_read_b128 v[166:169], v250 offset:2048
	ds_read_b128 v[170:173], v250 offset:3072
	s_add_u32 s14, s36, 0x100000
	s_addc_u32 s15, s37, 0
	s_mov_b32 m0, s56
	ds_read_b128 v[174:177], v160 offset:32768
	ds_read_b128 v[178:181], v160 offset:33792
	ds_read_b128 v[192:195], v160 offset:34816
	ds_read_b128 v[196:199], v160 offset:35840
	ds_read_b128 v[200:203], v160 offset:36864
	ds_read_b128 v[204:207], v160 offset:37888
	ds_read_b128 v[208:211], v160 offset:38912
	global_load_lds_dwordx4 v128, s[14:15]
	s_mov_b32 m0, s57
	ds_read_b128 v[212:215], v160 offset:39936
	global_load_lds_dwordx4 v148, s[14:15]
	s_waitcnt lgkmcnt(8)
	s_barrier
	s_waitcnt lgkmcnt(0)
	v_mfma_f32_16x16x32_bf16 v[124:127], v[154:157], v[174:177], v[124:127]
	v_mfma_f32_16x16x32_bf16 v[120:123], v[166:169], v[174:177], v[120:123]
	v_mfma_f32_16x16x32_bf16 v[108:111], v[154:157], v[192:195], v[108:111]
	v_mfma_f32_16x16x32_bf16 v[104:107], v[166:169], v[192:195], v[104:107]
	v_mfma_f32_16x16x32_bf16 v[92:95], v[154:157], v[200:203], v[92:95]
	v_mfma_f32_16x16x32_bf16 v[88:91], v[166:169], v[200:203], v[88:91]
	v_mfma_f32_16x16x32_bf16 v[76:79], v[154:157], v[208:211], v[76:79]
	v_mfma_f32_16x16x32_bf16 v[72:75], v[166:169], v[208:211], v[72:75]
	v_mfma_f32_16x16x32_bf16 v[124:127], v[162:165], v[178:181], v[124:127]
	v_mfma_f32_16x16x32_bf16 v[120:123], v[170:173], v[178:181], v[120:123]
	v_mfma_f32_16x16x32_bf16 v[108:111], v[162:165], v[196:199], v[108:111]
	v_mfma_f32_16x16x32_bf16 v[104:107], v[170:173], v[196:199], v[104:107]
	v_mfma_f32_16x16x32_bf16 v[92:95], v[162:165], v[204:207], v[92:95]
	v_mfma_f32_16x16x32_bf16 v[88:91], v[170:173], v[204:207], v[88:91]
	v_mfma_f32_16x16x32_bf16 v[76:79], v[162:165], v[212:215], v[76:79]
	v_mfma_f32_16x16x32_bf16 v[72:75], v[170:173], v[212:215], v[72:75]
	s_barrier
	s_add_i32 s17, 0, 0x1c000
	s_add_i32 s14, s16, s49
	s_mov_b32 m0, s14
	ds_read_b128 v[216:219], v251
	ds_read_b128 v[220:223], v251 offset:1024
	ds_read_b128 v[224:227], v251 offset:2048
	global_load_lds_dwordx4 v244, s[34:35]
	s_add_i32 m0, s14, 0x2000
	ds_read_b128 v[228:231], v251 offset:3072
	global_load_lds_dwordx4 v245, s[34:35]
	s_barrier
	s_waitcnt lgkmcnt(0)
	v_mfma_f32_16x16x32_bf16 v[116:119], v[216:219], v[174:177], v[116:119]
	v_mfma_f32_16x16x32_bf16 v[112:115], v[224:227], v[174:177], v[112:115]
	v_mfma_f32_16x16x32_bf16 v[100:103], v[216:219], v[192:195], v[100:103]
	v_mfma_f32_16x16x32_bf16 v[96:99], v[224:227], v[192:195], v[96:99]
	v_mfma_f32_16x16x32_bf16 v[84:87], v[216:219], v[200:203], v[84:87]
	v_mfma_f32_16x16x32_bf16 v[80:83], v[224:227], v[200:203], v[80:83]
	v_mfma_f32_16x16x32_bf16 v[68:71], v[216:219], v[208:211], v[68:71]
	v_mfma_f32_16x16x32_bf16 v[64:67], v[224:227], v[208:211], v[64:67]
	v_mfma_f32_16x16x32_bf16 v[116:119], v[220:223], v[178:181], v[116:119]
	v_mfma_f32_16x16x32_bf16 v[112:115], v[228:231], v[178:181], v[112:115]
	v_mfma_f32_16x16x32_bf16 v[100:103], v[220:223], v[196:199], v[100:103]
	v_mfma_f32_16x16x32_bf16 v[96:99], v[228:231], v[196:199], v[96:99]
	v_mfma_f32_16x16x32_bf16 v[84:87], v[220:223], v[204:207], v[84:87]
	v_mfma_f32_16x16x32_bf16 v[80:83], v[228:231], v[204:207], v[80:83]
	v_mfma_f32_16x16x32_bf16 v[68:71], v[220:223], v[212:215], v[68:71]
	v_mfma_f32_16x16x32_bf16 v[64:67], v[228:231], v[212:215], v[64:67]
	s_mov_b32 m0, s59
	s_barrier
	ds_read_b128 v[174:177], v160 offset:49152
	ds_read_b128 v[178:181], v160 offset:50176
	ds_read_b128 v[192:195], v160 offset:51200
	ds_read_b128 v[196:199], v160 offset:52224
	ds_read_b128 v[200:203], v160 offset:53248
	ds_read_b128 v[204:207], v160 offset:54272
	ds_read_b128 v[208:211], v160 offset:55296
	global_load_lds_dwordx4 v244, s[36:37]
	s_mov_b32 m0, s60
	ds_read_b128 v[212:215], v160 offset:56320
	global_load_lds_dwordx4 v245, s[36:37]
	s_barrier
	s_waitcnt lgkmcnt(0)
	v_mfma_f32_16x16x32_bf16 v[60:63], v[154:157], v[174:177], v[60:63]
	v_mfma_f32_16x16x32_bf16 v[56:59], v[166:169], v[174:177], v[56:59]
	v_mfma_f32_16x16x32_bf16 v[44:47], v[154:157], v[192:195], v[44:47]
	v_mfma_f32_16x16x32_bf16 v[40:43], v[166:169], v[192:195], v[40:43]
	v_mfma_f32_16x16x32_bf16 v[28:31], v[154:157], v[200:203], v[28:31]
	v_mfma_f32_16x16x32_bf16 v[24:27], v[166:169], v[200:203], v[24:27]
	v_mfma_f32_16x16x32_bf16 v[12:15], v[154:157], v[208:211], v[12:15]
	v_mfma_f32_16x16x32_bf16 v[8:11], v[166:169], v[208:211], v[8:11]
	v_mfma_f32_16x16x32_bf16 v[60:63], v[162:165], v[178:181], v[60:63]
	v_mfma_f32_16x16x32_bf16 v[56:59], v[170:173], v[178:181], v[56:59]
	v_mfma_f32_16x16x32_bf16 v[44:47], v[162:165], v[196:199], v[44:47]
	v_mfma_f32_16x16x32_bf16 v[40:43], v[170:173], v[196:199], v[40:43]
	v_mfma_f32_16x16x32_bf16 v[28:31], v[162:165], v[204:207], v[28:31]
	v_mfma_f32_16x16x32_bf16 v[24:27], v[170:173], v[204:207], v[24:27]
	v_mfma_f32_16x16x32_bf16 v[12:15], v[162:165], v[212:215], v[12:15]
	v_mfma_f32_16x16x32_bf16 v[8:11], v[170:173], v[212:215], v[8:11]
	s_barrier
; __device__ __forceinline__ unsigned cvt_pk_bf16(float lo, float hi) { const f32x2_cv v = {lo, hi}; const bf16x2_cv b = __builtin_convertvector(v, bf16x2_cv); return __builtin_bit_cast(unsigned, b); }
; #define PG8_STAGE(bufoff, gbase, voff) do { _Pragma("unroll") for (int _i = 0; _i < 2; ++_i) \
;         __builtin_amdgcn_global_load_lds((const unsigned*)((const char*)(gbase) + (voff)[_i]), (PG8_LAS unsigned*)(lds + (bufoff) + ldsw + _i * 8192), 16, 0, 0); } while (0)
; #define PG8_WAIT_V(n) asm volatile("s_waitcnt vmcnt(" #n ")" ::: "memory")
; #define PG8_BAR __builtin_amdgcn_s_barrier()
; template <class Epi, class Sched, bool STAMP = false>
; __device__ __forceinline__ void gemm_phase(PG8_LAS unsigned char* lds, const Gemm g, const Sched& S, const Epi& E, unsigned long long* stamps) {
;     ...
;             PG8_STAGE(PG8_SB(1, 1), b3 + hstep, voffB);
;             PG8_WAIT_V(6); PG8_BAR; PG8_MMA(1, 1, At, B1); PG8_BAR;
;     __device__ __forceinline__ void operator()(const f32x4 (&acc)[2][2][4][2], const pg8::Unit& u, int wr, int wc, int fr, int fq) const {
;         const int row0 = u.pm * 256 + wr * 64 + fr, col0 = u.pn * 256 + wc * 32 + 4 * fq;
; #pragma unroll
;         for (int ai = 0; ai < 2; ++ai)
; #pragma unroll
;             for (int m = 0; m < 4; ++m) {
;                 const int row = row0 + ai * 128 + m * 16;
;                 float* xp = X + (size_t)row * 1024 + col0; bf16_t* bp = XB + (size_t)row * 1024 + col0;
;                 const float* xi = Xp0 ? (row < T_P ? Xp0 + (size_t)row * 1024 + col0 : Xs0 + (size_t)(row - T_P) * 1024 + col0) : xp;
;                 float ss = 0.f;
; #pragma unroll
;                 for (int bj = 0; bj < 2; ++bj)
; #pragma unroll
;                     for (int n = 0; n < 2; ++n) {
;                         f32x4 xv = *(const f32x4*)(xi + bj * 128 + n * 16) + acc[ai][bj][m][n];
;                         *(f32x4*)(xp + bj * 128 + n * 16) = xv;
;                         ss += (xv[0] * xv[0] + xv[1] * xv[1]) + (xv[2] * xv[2] + xv[3] * xv[3]);
;                         u32x2 w; w.x = cvt_pk_bf16(xv[0], xv[1]); w.y = cvt_pk_bf16(xv[2], xv[3]);
;                         *(u32x2*)(bp + bj * 128 + n * 16) = w; }
;                 ss += __shfl_xor(ss, 16); ss += __shfl_xor(ss, 32);
;                 if (fq == 0) atomicAdd(rowss_out + row, ss); }
	s_add_u32 s14, s34, 0x100080
	s_addc_u32 s15, s35, 0
	s_add_i32 s16, s17, s49
	s_mov_b32 m0, s16
	s_nop 0
	global_load_lds_dwordx4 v128, s[14:15]
	s_add_i32 m0, s16, 0x2000
	s_nop 0
	global_load_lds_dwordx4 v148, s[14:15]
	s_waitcnt vmcnt(6)
	s_barrier
	v_mfma_f32_16x16x32_bf16 v[52:55], v[216:219], v[174:177], v[52:55]
	v_mfma_f32_16x16x32_bf16 v[48:51], v[224:227], v[174:177], v[48:51]
	v_mfma_f32_16x16x32_bf16 v[36:39], v[216:219], v[192:195], v[36:39]
	v_mfma_f32_16x16x32_bf16 v[32:35], v[224:227], v[192:195], v[32:35]
	v_mfma_f32_16x16x32_bf16 v[20:23], v[216:219], v[200:203], v[20:23]
	v_mfma_f32_16x16x32_bf16 v[16:19], v[224:227], v[200:203], v[16:19]
	v_mfma_f32_16x16x32_bf16 v[4:7], v[216:219], v[208:211], v[4:7]
	v_mfma_f32_16x16x32_bf16 v[0:3], v[224:227], v[208:211], v[0:3]
	v_mfma_f32_16x16x32_bf16 v[52:55], v[220:223], v[178:181], v[52:55]
	v_mfma_f32_16x16x32_bf16 v[48:51], v[228:231], v[178:181], v[48:51]
	v_mfma_f32_16x16x32_bf16 v[36:39], v[220:223], v[196:199], v[36:39]
	v_mfma_f32_16x16x32_bf16 v[32:35], v[228:231], v[196:199], v[32:35]
	v_mfma_f32_16x16x32_bf16 v[20:23], v[220:223], v[204:207], v[20:23]
	v_mfma_f32_16x16x32_bf16 v[16:19], v[228:231], v[204:207], v[16:19]
	v_mfma_f32_16x16x32_bf16 v[4:7], v[220:223], v[212:215], v[4:7]
	v_mfma_f32_16x16x32_bf16 v[0:3], v[228:231], v[212:215], v[0:3]
	s_cmp_gt_u32 s65, 61
	s_mov_b64 s[26:27], s[30:31]
	s_barrier
	s_cbranch_scc0 .LBB0_1183
	v_lshl_add_u32 v156, s22, 8, v139
	v_ashrrev_i32_e32 v157, 31, v156
	v_lshl_or_b32 v154, s24, 8, v159
	v_lshlrev_b64 v[162:163], 12, v[156:157]
	v_ashrrev_i32_e32 v155, 31, v154
	v_lshl_add_u64 v[162:163], s[84:85], 0, v[162:163]
	v_lshl_add_u64 v[170:171], v[154:155], 2, v[162:163]
	global_load_dwordx4 v[192:195], v[170:171], off
	global_load_dwordx4 v[196:199], v[170:171], off offset:64
	global_load_dwordx4 v[200:203], v[170:171], off offset:512
	global_load_dwordx4 v[204:207], v[170:171], off offset:576
	v_add_co_u32_e32 v224, vcc, 0x10000, v170
	s_nop 1
	v_addc_co_u32_e32 v225, vcc, 0, v171, vcc
	global_load_dwordx4 v[208:211], v[224:225], off
	global_load_dwordx4 v[212:215], v[224:225], off offset:64
	global_load_dwordx4 v[216:219], v[224:225], off offset:512
	global_load_dwordx4 v[220:223], v[224:225], off offset:576
	v_lshlrev_b64 v[166:167], 11, v[156:157]
	v_lshl_add_u64 v[166:167], s[0:1], 0, v[166:167]
	v_lshl_add_u64 v[172:173], v[154:155], 1, v[166:167]
	v_xor_b32_e32 v161, 32, v189
	s_waitcnt vmcnt(4)
	v_mov_b32_e32 v162, v192
	v_mov_b32_e32 v163, v193
	v_mov_b32_e32 v164, v194
	v_mov_b32_e32 v165, v195
	v_pk_add_f32 v[126:127], v[126:127], v[164:165]
	v_pk_add_f32 v[124:125], v[124:125], v[162:163]
	v_cvt_pk_bf16_f32 v163, v126, v127
	v_cvt_pk_bf16_f32 v162, v124, v125
	global_store_dwordx4 v[170:171], v[124:127], off
	global_store_dwordx2 v[172:173], v[162:163], off
	s_nop 1
	v_mov_b32_e32 v162, v196
	v_mov_b32_e32 v163, v197
	v_mov_b32_e32 v164, v198
	v_mov_b32_e32 v165, v199
	v_pk_add_f32 v[122:123], v[122:123], v[164:165]
	v_pk_add_f32 v[120:121], v[120:121], v[162:163]
	v_cvt_pk_bf16_f32 v163, v122, v123
	v_cvt_pk_bf16_f32 v162, v120, v121
	global_store_dwordx4 v[170:171], v[120:123], off offset:64
	global_store_dwordx2 v[172:173], v[162:163], off offset:32
	s_nop 1
	v_mov_b32_e32 v162, v200
	v_mov_b32_e32 v163, v201
	v_mov_b32_e32 v164, v202
	v_mov_b32_e32 v165, v203
	v_pk_add_f32 v[164:165], v[118:119], v[164:165]
	v_pk_add_f32 v[162:163], v[116:117], v[162:163]
	v_cvt_pk_bf16_f32 v117, v164, v165
	v_cvt_pk_bf16_f32 v116, v162, v163
	global_store_dwordx4 v[170:171], v[162:165], off offset:512
	global_store_dwordx2 v[172:173], v[116:117], off offset:256
	s_nop 1
	v_mov_b32_e32 v166, v204
	v_mov_b32_e32 v167, v205
	v_mov_b32_e32 v168, v206
	v_mov_b32_e32 v169, v207
	v_mul_f32_e32 v118, v125, v125
	v_mul_f32_e32 v119, v127, v127
	v_fmac_f32_e32 v118, v124, v124
	v_fmac_f32_e32 v119, v126, v126
	v_add_f32_e32 v118, v118, v119
	v_mul_f32_e32 v119, v121, v121
	v_mul_f32_e32 v121, v123, v123
	v_fmac_f32_e32 v119, v120, v120
	v_fmac_f32_e32 v121, v122, v122
	v_add_f32_e32 v119, v119, v121
	v_add_f32_e32 v118, v118, v119
	v_mul_f32_e32 v119, v163, v163
	v_mul_f32_e32 v120, v165, v165
	v_fmac_f32_e32 v119, v162, v162
	v_fmac_f32_e32 v120, v164, v164
	v_add_f32_e32 v119, v119, v120
	v_and_b32_e32 v117, 64, v189
	v_add_f32_e32 v122, v118, v119
	v_xor_b32_e32 v116, 16, v189
	v_add_u32_e32 v117, 64, v117
	v_cmp_lt_i32_e32 vcc, v116, v117
	v_pk_add_f32 v[120:121], v[114:115], v[168:169]
	v_pk_add_f32 v[118:119], v[112:113], v[166:167]
	v_mul_f32_e32 v113, v121, v121
	v_mul_f32_e32 v112, v119, v119
	v_fmac_f32_e32 v112, v118, v118
	v_fmac_f32_e32 v113, v120, v120
	v_cndmask_b32_e32 v116, v189, v116, vcc
	v_add_f32_e32 v112, v112, v113
	v_lshlrev_b32_e32 v116, 2, v116
	v_add_f32_e32 v112, v122, v112
	ds_bpermute_b32 v113, v116, v112
	v_cmp_lt_i32_e32 vcc, v161, v117
	global_store_dwordx4 v[170:171], v[118:121], off offset:576
	s_waitcnt lgkmcnt(0)
	v_add_f32_e32 v115, v112, v113
	v_cndmask_b32_e32 v114, v189, v161, vcc
	v_lshlrev_b32_e32 v114, 2, v114
	ds_bpermute_b32 v117, v114, v115
	v_cvt_pk_bf16_f32 v112, v118, v119
	v_cvt_pk_bf16_f32 v113, v120, v121
	global_store_dwordx2 v[172:173], v[112:113], off offset:288
	v_lshl_add_u64 v[112:113], v[156:157], 2, s[2:3]
	s_and_saveexec_b64 s[22:23], s[38:39]
	s_cbranch_execz .LBB0_1186
	s_waitcnt lgkmcnt(0)
	v_add_f32_e32 v115, v115, v117
	global_atomic_add_f32 v[112:113], v115, off

; #define PG8_STAGE(bufoff, gbase, voff) do { _Pragma("unroll") for (int _i = 0; _i < 2; ++_i) \
;         __builtin_amdgcn_global_load_lds((const unsigned*)((const char*)(gbase) + (voff)[_i]), (PG8_LAS unsigned*)(lds + (bufoff) + ldsw + _i * 8192), 16, 0, 0); } while (0)
; #define PG8_LDA(dst, b, h) do { _Pragma("unroll") for (int m = 0; m < 4; ++m) _Pragma("unroll") for (int k = 0; k < 2; ++k) dst[m][k] = *(const PG8_LAS bf16x8*)(lds + PG8_SA(b, h) + aoff + m * 2048 + k * 1024); } while (0)
; #define PG8_LDB(dst, b, h) do { _Pragma("unroll") for (int n = 0; n < 2; ++n) _Pragma("unroll") for (int k = 0; k < 2; ++k) dst[n][k] = *(const PG8_LAS bf16x8*)(lds + PG8_SB(b, h) + boff + n * 2048 + k * 1024); } while (0)
; #define PG8_MMA(ai, bj, At, Bt) do { __builtin_amdgcn_s_setprio(1); _Pragma("unroll") for (int m = 0; m < 4; ++m) _Pragma("unroll") for (int n = 0; n < 2; ++n) _Pragma("unroll") for (int k = 0; k < 2; ++k) \
;         acc[ai][bj][m][n] = __builtin_amdgcn_mfma_f32_16x16x32_bf16(Bt[n][k], At[m][k], acc[ai][bj][m][n], 0, 0, 0); __builtin_amdgcn_s_setprio(0); } while (0)
; #define PG8_BAR __builtin_amdgcn_s_barrier()
; template <class Epi, class Sched, bool STAMP = false>
; __device__ __forceinline__ void gemm_phase(PG8_LAS unsigned char* lds, const Gemm g, const Sched& S, const Epi& E, unsigned long long* stamps) {
;     ...
;         for (int t = 0; t < nt; t += 2) {
;             const bool last = (t == nt - 2);
;             const char* a1 = cA + (size_t)(t + 1) * kstep;
;             const char* a2 = last ? nA : cA + (size_t)(t + 2) * kstep; const char* b2 = last ? nB : cB + (size_t)(t + 2) * kstep;
;             const char* a3 = a2 + kstep; const char* b3 = b2 + kstep;
;             if (last && has_next) S.a_ready(nxt);
;             PG8_LDB(B0, 0, 0); PG8_SCHED; PG8_LDA(At, 0, 0); PG8_STAGE(PG8_SA(1, 1), a1 + hstep, voffA);
;             PG8_WAIT_L(8); PG8_BAR; PG8_WAIT_L(0); PG8_MMA(0, 0, At, B0); PG8_BAR; PG8_SCHED;
;             PG8_LDB(B1, 0, 1); PG8_STAGE(PG8_SB(0, 0), b2, voffB);
;             PG8_BAR; PG8_WAIT_L(0); PG8_MMA(0, 1, At, B1); PG8_BAR;
;             PG8_LDA(At, 0, 1); PG8_STAGE(PG8_SA(0, 0), a2, voffA);
;             PG8_BAR; PG8_WAIT_L(0); PG8_MMA(1, 0, At, B0); PG8_BAR; PG8_SCHED;
;             PG8_STAGE(PG8_SB(0, 1), b2 + hstep, voffB);
;             PG8_WAIT_V(6); PG8_BAR; PG8_MMA(1, 1, At, B1); PG8_BAR;
.LBB0_1207:
	s_add_u32 s6, s4, 0x100
	s_addc_u32 s7, s5, 0
	s_cmp_lg_u32 s39, 4
	s_cselect_b32 s12, s6, 0
	s_cselect_b32 s13, s7, 0
	s_add_u32 s20, s2, s12
	s_addc_u32 s21, s3, s13
	s_add_i32 s14, 0, 0x10000
	ds_read_b128 v[158:161], v248
	ds_read_b128 v[162:165], v248 offset:1024
	ds_read_b128 v[166:169], v248 offset:2048
	ds_read_b128 v[170:173], v248 offset:3072
	s_add_u32 s12, s0, s12
	s_addc_u32 s13, s1, s13
	v_lshl_add_u64 v[182:183], v[150:151], 0, s[4:5]
	s_add_i32 m0, s27, 0xc000
	ds_read_b128 v[174:177], v156
	ds_read_b128 v[178:181], v156 offset:1024
	ds_read_b128 v[192:195], v156 offset:2048
	ds_read_b128 v[196:199], v156 offset:3072
	ds_read_b128 v[200:203], v156 offset:4096
	ds_read_b128 v[204:207], v156 offset:5120
	ds_read_b128 v[208:211], v156 offset:6144
	ds_read_b128 v[212:215], v156 offset:7168
	global_load_lds_dwordx4 v[182:183], off
	v_lshl_add_u64 v[182:183], v[152:153], 0, s[4:5]
	s_add_i32 m0, s27, 0xe000
	s_nop 0
	global_load_lds_dwordx4 v[182:183], off
	s_waitcnt lgkmcnt(8)
	s_barrier
	s_waitcnt lgkmcnt(0)
	v_mfma_f32_16x16x32_bf16 v[124:127], v[158:161], v[174:177], v[124:127]
	v_mfma_f32_16x16x32_bf16 v[120:123], v[166:169], v[174:177], v[120:123]
	v_mfma_f32_16x16x32_bf16 v[116:119], v[158:161], v[192:195], v[116:119]
	v_mfma_f32_16x16x32_bf16 v[112:115], v[166:169], v[192:195], v[112:115]
	v_mfma_f32_16x16x32_bf16 v[104:107], v[158:161], v[200:203], v[104:107]
	v_mfma_f32_16x16x32_bf16 v[96:99], v[166:169], v[200:203], v[96:99]
	v_mfma_f32_16x16x32_bf16 v[88:91], v[158:161], v[208:211], v[88:91]
	v_mfma_f32_16x16x32_bf16 v[80:83], v[166:169], v[208:211], v[80:83]
	v_mfma_f32_16x16x32_bf16 v[124:127], v[162:165], v[178:181], v[124:127]
	v_mfma_f32_16x16x32_bf16 v[120:123], v[170:173], v[178:181], v[120:123]
	v_mfma_f32_16x16x32_bf16 v[116:119], v[162:165], v[196:199], v[116:119]
	v_mfma_f32_16x16x32_bf16 v[112:115], v[170:173], v[196:199], v[112:115]
	v_mfma_f32_16x16x32_bf16 v[104:107], v[162:165], v[204:207], v[104:107]
	v_mfma_f32_16x16x32_bf16 v[96:99], v[170:173], v[204:207], v[96:99]
	v_mfma_f32_16x16x32_bf16 v[88:91], v[162:165], v[212:215], v[88:91]
	v_mfma_f32_16x16x32_bf16 v[80:83], v[170:173], v[212:215], v[80:83]
	s_barrier
	s_add_i32 s15, 0, 0x14000
	s_add_i32 s4, s14, s26
	v_lshl_add_u64 v[182:183], s[12:13], 0, v[128:129]
	s_mov_b32 m0, s4
	ds_read_b128 v[216:219], v249
	ds_read_b128 v[220:223], v249 offset:1024
	ds_read_b128 v[224:227], v249 offset:2048
	ds_read_b128 v[228:231], v249 offset:3072
	global_load_lds_dwordx4 v128, s[12:13]
	v_lshl_add_u64 v[232:233], s[12:13], 0, v[148:149]
	s_add_i32 m0, s4, 0x2000
	s_nop 0
	global_load_lds_dwordx4 v148, s[12:13]
	s_barrier
	s_waitcnt lgkmcnt(0)
	v_mfma_f32_16x16x32_bf16 v[108:111], v[216:219], v[174:177], v[108:111]
	v_mfma_f32_16x16x32_bf16 v[100:103], v[224:227], v[174:177], v[100:103]
	v_mfma_f32_16x16x32_bf16 v[92:95], v[216:219], v[192:195], v[92:95]
	v_mfma_f32_16x16x32_bf16 v[84:87], v[224:227], v[192:195], v[84:87]
	v_mfma_f32_16x16x32_bf16 v[76:79], v[216:219], v[200:203], v[76:79]
	v_mfma_f32_16x16x32_bf16 v[72:75], v[224:227], v[200:203], v[72:75]
	v_mfma_f32_16x16x32_bf16 v[68:71], v[216:219], v[208:211], v[68:71]
	v_mfma_f32_16x16x32_bf16 v[64:67], v[224:227], v[208:211], v[64:67]
	v_mfma_f32_16x16x32_bf16 v[108:111], v[220:223], v[178:181], v[108:111]
	v_mfma_f32_16x16x32_bf16 v[100:103], v[228:231], v[178:181], v[100:103]
	v_mfma_f32_16x16x32_bf16 v[92:95], v[220:223], v[196:199], v[92:95]
	v_mfma_f32_16x16x32_bf16 v[84:87], v[228:231], v[196:199], v[84:87]
	v_mfma_f32_16x16x32_bf16 v[76:79], v[220:223], v[204:207], v[76:79]
	v_mfma_f32_16x16x32_bf16 v[72:75], v[228:231], v[204:207], v[72:75]
	v_mfma_f32_16x16x32_bf16 v[68:71], v[220:223], v[212:215], v[68:71]
	v_mfma_f32_16x16x32_bf16 v[64:67], v[228:231], v[212:215], v[64:67]
	s_mov_b32 m0, s27
	v_lshl_add_u64 v[234:235], s[20:21], 0, v[128:129]
	s_barrier
	ds_read_b128 v[174:177], v156 offset:16384
	ds_read_b128 v[178:181], v156 offset:17408
	ds_read_b128 v[192:195], v156 offset:18432
	ds_read_b128 v[196:199], v156 offset:19456
	ds_read_b128 v[200:203], v156 offset:20480
	ds_read_b128 v[204:207], v156 offset:21504
	ds_read_b128 v[208:211], v156 offset:22528
	ds_read_b128 v[212:215], v156 offset:23552
	global_load_lds_dwordx4 v128, s[20:21]
	v_lshl_add_u64 v[236:237], s[20:21], 0, v[148:149]
	s_mov_b32 m0, s30
	s_nop 0
	global_load_lds_dwordx4 v148, s[20:21]
	s_barrier
	s_waitcnt lgkmcnt(0)
	v_mfma_f32_16x16x32_bf16 v[60:63], v[158:161], v[174:177], v[60:63]
	v_mfma_f32_16x16x32_bf16 v[56:59], v[166:169], v[174:177], v[56:59]
	v_mfma_f32_16x16x32_bf16 v[52:55], v[158:161], v[192:195], v[52:55]
	v_mfma_f32_16x16x32_bf16 v[48:51], v[166:169], v[192:195], v[48:51]
	v_mfma_f32_16x16x32_bf16 v[36:39], v[158:161], v[200:203], v[36:39]
	v_mfma_f32_16x16x32_bf16 v[32:35], v[166:169], v[200:203], v[32:35]
	v_mfma_f32_16x16x32_bf16 v[20:23], v[158:161], v[208:211], v[20:23]
	v_mfma_f32_16x16x32_bf16 v[16:19], v[166:169], v[208:211], v[16:19]
	v_mfma_f32_16x16x32_bf16 v[60:63], v[162:165], v[178:181], v[60:63]
	v_mfma_f32_16x16x32_bf16 v[56:59], v[170:173], v[178:181], v[56:59]
	v_mfma_f32_16x16x32_bf16 v[52:55], v[162:165], v[196:199], v[52:55]
	v_mfma_f32_16x16x32_bf16 v[48:51], v[170:173], v[196:199], v[48:51]
	v_mfma_f32_16x16x32_bf16 v[36:39], v[162:165], v[204:207], v[36:39]
	v_mfma_f32_16x16x32_bf16 v[32:35], v[170:173], v[204:207], v[32:35]
	v_mfma_f32_16x16x32_bf16 v[20:23], v[162:165], v[212:215], v[20:23]
	v_mfma_f32_16x16x32_bf16 v[16:19], v[170:173], v[212:215], v[16:19]
	s_barrier
; #define PG8_STAGE(bufoff, gbase, voff) do { _Pragma("unroll") for (int _i = 0; _i < 2; ++_i) \
;         __builtin_amdgcn_global_load_lds((const unsigned*)((const char*)(gbase) + (voff)[_i]), (PG8_LAS unsigned*)(lds + (bufoff) + ldsw + _i * 8192), 16, 0, 0); } while (0)
; #define PG8_LDA(dst, b, h) do { _Pragma("unroll") for (int m = 0; m < 4; ++m) _Pragma("unroll") for (int k = 0; k < 2; ++k) dst[m][k] = *(const PG8_LAS bf16x8*)(lds + PG8_SA(b, h) + aoff + m * 2048 + k * 1024); } while (0)
; #define PG8_LDB(dst, b, h) do { _Pragma("unroll") for (int n = 0; n < 2; ++n) _Pragma("unroll") for (int k = 0; k < 2; ++k) dst[n][k] = *(const PG8_LAS bf16x8*)(lds + PG8_SB(b, h) + boff + n * 2048 + k * 1024); } while (0)
; #define PG8_MMA(ai, bj, At, Bt) do { __builtin_amdgcn_s_setprio(1); _Pragma("unroll") for (int m = 0; m < 4; ++m) _Pragma("unroll") for (int n = 0; n < 2; ++n) _Pragma("unroll") for (int k = 0; k < 2; ++k) \
;         acc[ai][bj][m][n] = __builtin_amdgcn_mfma_f32_16x16x32_bf16(Bt[n][k], At[m][k], acc[ai][bj][m][n], 0, 0, 0); __builtin_amdgcn_s_setprio(0); } while (0)
; #define PG8_WAIT_V(n) asm volatile("s_waitcnt vmcnt(" #n ")" ::: "memory")
; #define PG8_WAIT_L(n) asm volatile("s_waitcnt lgkmcnt(" #n ")" ::: "memory")
; #define PG8_BAR __builtin_amdgcn_s_barrier()
; #define PG8_SCHED __builtin_amdgcn_sched_barrier(0)
; template <class Epi, class Sched, bool STAMP = false>
; __device__ __forceinline__ void gemm_phase(PG8_LAS unsigned char* lds, const Gemm g, const Sched& S, const Epi& E, unsigned long long* stamps) {
;     ...
;             PG8_STAGE(PG8_SB(0, 1), b2 + hstep, voffB);
;             PG8_WAIT_V(6); PG8_BAR; PG8_MMA(1, 1, At, B1); PG8_BAR;
;             PG8_LDB(B0, 1, 0); PG8_SCHED; PG8_LDA(At, 1, 0); PG8_STAGE(PG8_SA(0, 1), a2 + hstep, voffA);
;             PG8_WAIT_L(8); PG8_BAR; PG8_WAIT_L(0); PG8_MMA(0, 0, At, B0); PG8_BAR; PG8_SCHED;
;             PG8_LDB(B1, 1, 1); PG8_STAGE(PG8_SB(1, 0), b3, voffB);
;             PG8_BAR; PG8_WAIT_L(0); PG8_MMA(0, 1, At, B1); PG8_BAR;
;             PG8_LDA(At, 1, 1); PG8_STAGE(PG8_SA(1, 0), a3, voffA);
;             PG8_BAR; PG8_WAIT_L(0); PG8_MMA(1, 0, At, B0); PG8_BAR; PG8_SCHED;
	s_add_u32 s4, s12, 0x100000
	s_addc_u32 s5, s13, 0
	s_add_i32 s14, s15, s26
	s_mov_b32 m0, s14
	s_nop 0
	global_load_lds_dwordx4 v128, s[4:5]
	s_add_i32 m0, s14, 0x2000
	s_nop 0
	global_load_lds_dwordx4 v148, s[4:5]
	s_add_i32 s39, s39, 2
	s_waitcnt vmcnt(6)
	s_barrier
	v_mfma_f32_16x16x32_bf16 v[44:47], v[216:219], v[174:177], v[44:47]
	v_mfma_f32_16x16x32_bf16 v[40:43], v[224:227], v[174:177], v[40:43]
	v_mfma_f32_16x16x32_bf16 v[28:31], v[216:219], v[192:195], v[28:31]
	v_mfma_f32_16x16x32_bf16 v[24:27], v[224:227], v[192:195], v[24:27]
	v_mfma_f32_16x16x32_bf16 v[12:15], v[216:219], v[200:203], v[12:15]
	v_mfma_f32_16x16x32_bf16 v[8:11], v[224:227], v[200:203], v[8:11]
	v_mfma_f32_16x16x32_bf16 v[4:7], v[216:219], v[208:211], v[4:7]
	v_mfma_f32_16x16x32_bf16 v[0:3], v[224:227], v[208:211], v[0:3]
	v_mfma_f32_16x16x32_bf16 v[44:47], v[220:223], v[178:181], v[44:47]
	v_mfma_f32_16x16x32_bf16 v[40:43], v[228:231], v[178:181], v[40:43]
	v_mfma_f32_16x16x32_bf16 v[28:31], v[220:223], v[196:199], v[28:31]
	v_mfma_f32_16x16x32_bf16 v[24:27], v[228:231], v[196:199], v[24:27]
	v_mfma_f32_16x16x32_bf16 v[12:15], v[220:223], v[204:207], v[12:15]
	v_mfma_f32_16x16x32_bf16 v[8:11], v[228:231], v[204:207], v[8:11]
	v_mfma_f32_16x16x32_bf16 v[4:7], v[220:223], v[212:215], v[4:7]
	v_mfma_f32_16x16x32_bf16 v[0:3], v[228:231], v[212:215], v[0:3]
	s_add_i32 s14, 0, 0x18000
	s_barrier
	ds_read_b128 v[158:161], v250
	ds_read_b128 v[162:165], v250 offset:1024
	ds_read_b128 v[166:169], v250 offset:2048
	ds_read_b128 v[170:173], v250 offset:3072
	s_add_u32 s4, s20, 0x100000
	s_addc_u32 s5, s21, 0
	s_mov_b32 m0, s31
	ds_read_b128 v[174:177], v156 offset:32768
	ds_read_b128 v[178:181], v156 offset:33792
	ds_read_b128 v[192:195], v156 offset:34816
	ds_read_b128 v[196:199], v156 offset:35840
	ds_read_b128 v[200:203], v156 offset:36864
	ds_read_b128 v[204:207], v156 offset:37888
	ds_read_b128 v[208:211], v156 offset:38912
	global_load_lds_dwordx4 v128, s[4:5]
	s_mov_b32 m0, s34
	ds_read_b128 v[212:215], v156 offset:39936
	global_load_lds_dwordx4 v148, s[4:5]
	s_waitcnt lgkmcnt(8)
	s_barrier
	s_waitcnt lgkmcnt(0)
	v_mfma_f32_16x16x32_bf16 v[124:127], v[158:161], v[174:177], v[124:127]
	v_mfma_f32_16x16x32_bf16 v[120:123], v[166:169], v[174:177], v[120:123]
	v_mfma_f32_16x16x32_bf16 v[116:119], v[158:161], v[192:195], v[116:119]
	v_mfma_f32_16x16x32_bf16 v[112:115], v[166:169], v[192:195], v[112:115]
	v_mfma_f32_16x16x32_bf16 v[104:107], v[158:161], v[200:203], v[104:107]
	v_mfma_f32_16x16x32_bf16 v[96:99], v[166:169], v[200:203], v[96:99]
	v_mfma_f32_16x16x32_bf16 v[88:91], v[158:161], v[208:211], v[88:91]
	v_mfma_f32_16x16x32_bf16 v[80:83], v[166:169], v[208:211], v[80:83]
	v_mfma_f32_16x16x32_bf16 v[124:127], v[162:165], v[178:181], v[124:127]
	v_mfma_f32_16x16x32_bf16 v[120:123], v[170:173], v[178:181], v[120:123]
	v_mfma_f32_16x16x32_bf16 v[116:119], v[162:165], v[196:199], v[116:119]
	v_mfma_f32_16x16x32_bf16 v[112:115], v[170:173], v[196:199], v[112:115]
	v_mfma_f32_16x16x32_bf16 v[104:107], v[162:165], v[204:207], v[104:107]
	v_mfma_f32_16x16x32_bf16 v[96:99], v[170:173], v[204:207], v[96:99]
	v_mfma_f32_16x16x32_bf16 v[88:91], v[162:165], v[212:215], v[88:91]
	v_mfma_f32_16x16x32_bf16 v[80:83], v[170:173], v[212:215], v[80:83]
	s_barrier
	s_add_i32 s15, 0, 0x1c000
	s_add_i32 s4, s14, s26
	v_lshl_add_u64 v[182:183], v[182:183], 0, s[18:19]
	s_mov_b32 m0, s4
	ds_read_b128 v[216:219], v251
	ds_read_b128 v[220:223], v251 offset:1024
	ds_read_b128 v[224:227], v251 offset:2048
	ds_read_b128 v[228:231], v251 offset:3072
	global_load_lds_dwordx4 v244, s[12:13]
	v_lshl_add_u64 v[182:183], v[232:233], 0, s[18:19]
	s_add_i32 m0, s4, 0x2000
	s_nop 0
	global_load_lds_dwordx4 v245, s[12:13]
	s_barrier
	s_waitcnt lgkmcnt(0)
	v_mfma_f32_16x16x32_bf16 v[108:111], v[216:219], v[174:177], v[108:111]
	v_mfma_f32_16x16x32_bf16 v[100:103], v[224:227], v[174:177], v[100:103]
	v_mfma_f32_16x16x32_bf16 v[92:95], v[216:219], v[192:195], v[92:95]
	v_mfma_f32_16x16x32_bf16 v[84:87], v[224:227], v[192:195], v[84:87]
	v_mfma_f32_16x16x32_bf16 v[76:79], v[216:219], v[200:203], v[76:79]
	v_mfma_f32_16x16x32_bf16 v[72:75], v[224:227], v[200:203], v[72:75]
	v_mfma_f32_16x16x32_bf16 v[68:71], v[216:219], v[208:211], v[68:71]
	v_mfma_f32_16x16x32_bf16 v[64:67], v[224:227], v[208:211], v[64:67]
	v_mfma_f32_16x16x32_bf16 v[108:111], v[220:223], v[178:181], v[108:111]
	v_mfma_f32_16x16x32_bf16 v[100:103], v[228:231], v[178:181], v[100:103]
	v_mfma_f32_16x16x32_bf16 v[92:95], v[220:223], v[196:199], v[92:95]
	v_mfma_f32_16x16x32_bf16 v[84:87], v[228:231], v[196:199], v[84:87]
	v_mfma_f32_16x16x32_bf16 v[76:79], v[220:223], v[204:207], v[76:79]
	v_mfma_f32_16x16x32_bf16 v[72:75], v[228:231], v[204:207], v[72:75]
	v_mfma_f32_16x16x32_bf16 v[68:71], v[220:223], v[212:215], v[68:71]
	v_mfma_f32_16x16x32_bf16 v[64:67], v[228:231], v[212:215], v[64:67]
	s_mov_b32 m0, s37
	v_lshl_add_u64 v[182:183], v[234:235], 0, s[18:19]
	s_barrier
	ds_read_b128 v[174:177], v156 offset:49152
	ds_read_b128 v[178:181], v156 offset:50176
	ds_read_b128 v[192:195], v156 offset:51200
	ds_read_b128 v[196:199], v156 offset:52224
	ds_read_b128 v[200:203], v156 offset:53248
	ds_read_b128 v[204:207], v156 offset:54272
	ds_read_b128 v[208:211], v156 offset:55296
	ds_read_b128 v[212:215], v156 offset:56320
	global_load_lds_dwordx4 v244, s[20:21]
	v_lshl_add_u64 v[182:183], v[236:237], 0, s[18:19]
	s_mov_b32 m0, s38
	s_nop 0
	global_load_lds_dwordx4 v245, s[20:21]
	s_barrier
; #define PG8_STAGE(bufoff, gbase, voff) do { _Pragma("unroll") for (int _i = 0; _i < 2; ++_i) \
;         __builtin_amdgcn_global_load_lds((const unsigned*)((const char*)(gbase) + (voff)[_i]), (PG8_LAS unsigned*)(lds + (bufoff) + ldsw + _i * 8192), 16, 0, 0); } while (0)
; #define PG8_MMA(ai, bj, At, Bt) do { __builtin_amdgcn_s_setprio(1); _Pragma("unroll") for (int m = 0; m < 4; ++m) _Pragma("unroll") for (int n = 0; n < 2; ++n) _Pragma("unroll") for (int k = 0; k < 2; ++k) \
;         acc[ai][bj][m][n] = __builtin_amdgcn_mfma_f32_16x16x32_bf16(Bt[n][k], At[m][k], acc[ai][bj][m][n], 0, 0, 0); __builtin_amdgcn_s_setprio(0); } while (0)
; #define PG8_WAIT_V(n) asm volatile("s_waitcnt vmcnt(" #n ")" ::: "memory")
; #define PG8_WAIT_L(n) asm volatile("s_waitcnt lgkmcnt(" #n ")" ::: "memory")
; #define PG8_BAR __builtin_amdgcn_s_barrier()
; #define PG8_SCHED __builtin_amdgcn_sched_barrier(0)
; template <class Epi, class Sched, bool STAMP = false>
; __device__ __forceinline__ void gemm_phase(PG8_LAS unsigned char* lds, const Gemm g, const Sched& S, const Epi& E, unsigned long long* stamps) {
;     ...
;             PG8_BAR; PG8_WAIT_L(0); PG8_MMA(1, 0, At, B0); PG8_BAR; PG8_SCHED;
;             PG8_STAGE(PG8_SB(1, 1), b3 + hstep, voffB);
;             PG8_WAIT_V(6); PG8_BAR; PG8_MMA(1, 1, At, B1); PG8_BAR;
;     ...
;     PG8_WAIT_V(0);
;     if (wr == 0) PG8_BAR;
;     PG8_BAR;
;     __device__ __forceinline__ void operator()(const f32x4 (&acc)[2][2][4][2], const pg8::Unit& u, int wr, int wc, int fr, int fq) const {
;         const int row0 = (u.pm - 64) * 256 + wr * 64 + fr, col0 = u.pn * 256 + wc * 32 + 4 * fq;
; #pragma unroll
;         for (int ai = 0; ai < 2; ++ai)
; #pragma unroll
;             for (int m = 0; m < 4; ++m) { float* xp = PART + (size_t)(row0 + ai * 128 + m * 16) * ldp + col0;
; #pragma unroll
;                 for (int bj = 0; bj < 2; ++bj)
; #pragma unroll
;                     for (int n = 0; n < 2; ++n) *(f32x4*)(xp + bj * 128 + n * 16) = acc[ai][bj][m][n]; }
	s_waitcnt lgkmcnt(0)
	v_mfma_f32_16x16x32_bf16 v[60:63], v[158:161], v[174:177], v[60:63]
	v_mfma_f32_16x16x32_bf16 v[56:59], v[166:169], v[174:177], v[56:59]
	v_mfma_f32_16x16x32_bf16 v[52:55], v[158:161], v[192:195], v[52:55]
	v_mfma_f32_16x16x32_bf16 v[48:51], v[166:169], v[192:195], v[48:51]
	v_mfma_f32_16x16x32_bf16 v[36:39], v[158:161], v[200:203], v[36:39]
	v_mfma_f32_16x16x32_bf16 v[32:35], v[166:169], v[200:203], v[32:35]
	v_mfma_f32_16x16x32_bf16 v[20:23], v[158:161], v[208:211], v[20:23]
	v_mfma_f32_16x16x32_bf16 v[16:19], v[166:169], v[208:211], v[16:19]
	v_mfma_f32_16x16x32_bf16 v[60:63], v[162:165], v[178:181], v[60:63]
	v_mfma_f32_16x16x32_bf16 v[56:59], v[170:173], v[178:181], v[56:59]
	v_mfma_f32_16x16x32_bf16 v[52:55], v[162:165], v[196:199], v[52:55]
	v_mfma_f32_16x16x32_bf16 v[48:51], v[170:173], v[196:199], v[48:51]
	v_mfma_f32_16x16x32_bf16 v[36:39], v[162:165], v[204:207], v[36:39]
	v_mfma_f32_16x16x32_bf16 v[32:35], v[170:173], v[204:207], v[32:35]
	v_mfma_f32_16x16x32_bf16 v[20:23], v[162:165], v[212:215], v[20:23]
	v_mfma_f32_16x16x32_bf16 v[16:19], v[170:173], v[212:215], v[16:19]
	s_barrier
	s_add_u32 s4, s12, 0x100080
	s_addc_u32 s5, s13, 0
	s_add_i32 s12, s15, s26
	s_mov_b32 m0, s12
	s_nop 0
	global_load_lds_dwordx4 v128, s[4:5]
	s_add_i32 m0, s12, 0x2000
	s_nop 0
	global_load_lds_dwordx4 v148, s[4:5]
	s_waitcnt vmcnt(6)
	s_barrier
	v_mfma_f32_16x16x32_bf16 v[44:47], v[216:219], v[174:177], v[44:47]
	v_mfma_f32_16x16x32_bf16 v[40:43], v[224:227], v[174:177], v[40:43]
	v_mfma_f32_16x16x32_bf16 v[28:31], v[216:219], v[192:195], v[28:31]
	v_mfma_f32_16x16x32_bf16 v[24:27], v[224:227], v[192:195], v[24:27]
	v_mfma_f32_16x16x32_bf16 v[12:15], v[216:219], v[200:203], v[12:15]
	v_mfma_f32_16x16x32_bf16 v[8:11], v[224:227], v[200:203], v[8:11]
	v_mfma_f32_16x16x32_bf16 v[4:7], v[216:219], v[208:211], v[4:7]
	v_mfma_f32_16x16x32_bf16 v[0:3], v[224:227], v[208:211], v[0:3]
	v_mfma_f32_16x16x32_bf16 v[44:47], v[220:223], v[178:181], v[44:47]
	v_mfma_f32_16x16x32_bf16 v[40:43], v[228:231], v[178:181], v[40:43]
	v_mfma_f32_16x16x32_bf16 v[28:31], v[220:223], v[196:199], v[28:31]
	v_mfma_f32_16x16x32_bf16 v[24:27], v[228:231], v[196:199], v[24:27]
	v_mfma_f32_16x16x32_bf16 v[12:15], v[220:223], v[204:207], v[12:15]
	v_mfma_f32_16x16x32_bf16 v[8:11], v[228:231], v[204:207], v[8:11]
	v_mfma_f32_16x16x32_bf16 v[4:7], v[220:223], v[212:215], v[4:7]
	v_mfma_f32_16x16x32_bf16 v[0:3], v[228:231], v[212:215], v[0:3]
	s_cmp_gt_u32 s39, 5
	s_mov_b64 s[4:5], s[6:7]
	s_barrier
	s_cbranch_scc0 .LBB0_1207
	s_lshl_b32 s0, s25, 22
	s_add_u32 s0, s10, s0
	s_addc_u32 s1, s42, 0
	s_add_u32 s0, s0, 0xdd00000
	s_addc_u32 s1, s1, 0
	s_lshl_b32 s2, s24, 8
	s_add_i32 s2, s2, s35
	v_add_u32_e32 v150, s2, v154
	v_add_u32_e32 v148, 0xffffc000, v150
	s_lshl_b32 s2, s23, 8
	v_lshl_or_b32 v128, v139, 2, s2
	v_ashrrev_i32_e32 v149, 31, v148
	v_or_b32_e32 v128, s36, v128
	v_lshlrev_b64 v[148:149], 12, v[148:149]
	v_lshl_add_u64 v[148:149], s[0:1], 0, v[148:149]
	v_lshlrev_b32_e32 v128, 2, v128
	v_lshl_add_u64 v[148:149], v[148:149], 0, v[128:129]
	global_store_dwordx4 v[148:149], v[124:127], off
	global_store_dwordx4 v[148:149], v[120:123], off offset:64
	global_store_dwordx4 v[148:149], v[108:111], off offset:512
	global_store_dwordx4 v[148:149], v[100:103], off offset:576
	s_cmpk_lt_u32 s22, 0x100
	v_readlane_b32 s39, v242, 28
	v_add_u32_e32 v100, 0xffffc010, v150
	v_ashrrev_i32_e32 v101, 31, v100
	v_lshlrev_b64 v[100:101], 12, v[100:101]
	v_lshl_add_u64 v[100:101], s[0:1], 0, v[100:101]
	v_lshl_add_u64 v[100:101], v[100:101], 0, v[128:129]
	global_store_dwordx4 v[100:101], v[116:119], off
	global_store_dwordx4 v[100:101], v[112:115], off offset:64
	global_store_dwordx4 v[100:101], v[92:95], off offset:512
	global_store_dwordx4 v[100:101], v[84:87], off offset:576
	s_mov_b32 s38, 0x1ffff
	s_nop 0
	v_add_u32_e32 v84, 0xffffc020, v150
	v_ashrrev_i32_e32 v85, 31, v84
	v_lshlrev_b64 v[84:85], 12, v[84:85]
	v_lshl_add_u64 v[84:85], s[0:1], 0, v[84:85]
	v_lshl_add_u64 v[84:85], v[84:85], 0, v[128:129]
	global_store_dwordx4 v[84:85], v[104:107], off
	global_store_dwordx4 v[84:85], v[96:99], off offset:64
	global_store_dwordx4 v[84:85], v[76:79], off offset:512
	global_store_dwordx4 v[84:85], v[72:75], off offset:576
	s_nop 1
	v_add_u32_e32 v72, 0xffffc030, v150
	v_ashrrev_i32_e32 v73, 31, v72
	v_lshlrev_b64 v[72:73], 12, v[72:73]
	v_lshl_add_u64 v[72:73], s[0:1], 0, v[72:73]
	v_lshl_add_u64 v[72:73], v[72:73], 0, v[128:129]
	s_mov_b64 s[0:1], 0x80000
	global_store_dwordx4 v[72:73], v[88:91], off
	global_store_dwordx4 v[72:73], v[80:83], off offset:64
	global_store_dwordx4 v[72:73], v[68:71], off offset:512
	global_store_dwordx4 v[72:73], v[64:67], off offset:576
	s_nop 1
	v_lshl_add_u64 v[64:65], v[148:149], 0, s[0:1]
	s_mov_b32 s0, 0x80000
	v_add_co_u32_e32 v66, vcc, s0, v148
	s_mov_b64 s[0:1], 0x90000
	s_nop 0
	v_addc_co_u32_e32 v67, vcc, 0, v149, vcc
	global_store_dwordx4 v[66:67], v[60:63], off
	global_store_dwordx4 v[64:65], v[56:59], off offset:64
	global_store_dwordx4 v[64:65], v[44:47], off offset:512
	global_store_dwordx4 v[64:65], v[40:43], off offset:576
	s_nop 1
	v_lshl_add_u64 v[40:41], v[148:149], 0, s[0:1]
	s_mov_b32 s0, 0x90000
	v_add_co_u32_e32 v42, vcc, s0, v148
	s_mov_b64 s[0:1], 0xa0000
	s_nop 0
	v_addc_co_u32_e32 v43, vcc, 0, v149, vcc
	global_store_dwordx4 v[42:43], v[52:55], off
	global_store_dwordx4 v[40:41], v[48:51], off offset:64
	global_store_dwordx4 v[40:41], v[28:31], off offset:512
	global_store_dwordx4 v[40:41], v[24:27], off offset:576
	s_nop 1
	v_lshl_add_u64 v[24:25], v[148:149], 0, s[0:1]
	s_mov_b32 s0, 0xa0000
	v_add_co_u32_e32 v26, vcc, s0, v148
	s_mov_b64 s[0:1], 0xb0000
	s_nop 0
	v_addc_co_u32_e32 v27, vcc, 0, v149, vcc
	global_store_dwordx4 v[26:27], v[36:39], off
	global_store_dwordx4 v[24:25], v[32:35], off offset:64
	global_store_dwordx4 v[24:25], v[12:15], off offset:512
	global_store_dwordx4 v[24:25], v[8:11], off offset:576
	s_nop 1
	v_add_co_u32_e32 v10, vcc, 0xb0000, v148
	v_lshl_add_u64 v[8:9], v[148:149], 0, s[0:1]
	s_nop 0
	v_addc_co_u32_e32 v11, vcc, 0, v149, vcc
	global_store_dwordx4 v[10:11], v[20:23], off
	global_store_dwordx4 v[8:9], v[16:19], off offset:64
	global_store_dwordx4 v[8:9], v[4:7], off offset:512
	global_store_dwordx4 v[8:9], v[0:3], off offset:576
	s_waitcnt vmcnt(0)
	s_cbranch_scc0 .LBB0_1210
	s_barrier

; #define PG8_STAGE(bufoff, gbase, voff) do { _Pragma("unroll") for (int _i = 0; _i < 2; ++_i) \
;         __builtin_amdgcn_global_load_lds((const unsigned*)((const char*)(gbase) + (voff)[_i]), (PG8_LAS unsigned*)(lds + (bufoff) + ldsw + _i * 8192), 16, 0, 0); } while (0)
; #define PG8_LDA(dst, b, h) do { _Pragma("unroll") for (int m = 0; m < 4; ++m) _Pragma("unroll") for (int k = 0; k < 2; ++k) dst[m][k] = *(const PG8_LAS bf16x8*)(lds + PG8_SA(b, h) + aoff + m * 2048 + k * 1024); } while (0)
; #define PG8_LDB(dst, b, h) do { _Pragma("unroll") for (int n = 0; n < 2; ++n) _Pragma("unroll") for (int k = 0; k < 2; ++k) dst[n][k] = *(const PG8_LAS bf16x8*)(lds + PG8_SB(b, h) + boff + n * 2048 + k * 1024); } while (0)
; #define PG8_MMA(ai, bj, At, Bt) do { __builtin_amdgcn_s_setprio(1); _Pragma("unroll") for (int m = 0; m < 4; ++m) _Pragma("unroll") for (int n = 0; n < 2; ++n) _Pragma("unroll") for (int k = 0; k < 2; ++k) \
;         acc[ai][bj][m][n] = __builtin_amdgcn_mfma_f32_16x16x32_bf16(Bt[n][k], At[m][k], acc[ai][bj][m][n], 0, 0, 0); __builtin_amdgcn_s_setprio(0); } while (0)
; #define PG8_BAR __builtin_amdgcn_s_barrier()
; template <class Epi, class Sched, bool STAMP = false>
; __device__ __forceinline__ void gemm_phase(PG8_LAS unsigned char* lds, const Gemm g, const Sched& S, const Epi& E, unsigned long long* stamps) {
;     ...
;         for (int t = 0; t < nt; t += 2) {
;             const bool last = (t == nt - 2);
;             const char* a1 = cA + (size_t)(t + 1) * kstep;
;             const char* a2 = last ? nA : cA + (size_t)(t + 2) * kstep; const char* b2 = last ? nB : cB + (size_t)(t + 2) * kstep;
;             const char* a3 = a2 + kstep; const char* b3 = b2 + kstep;
;             if (last && has_next) S.a_ready(nxt);
;             PG8_LDB(B0, 0, 0); PG8_SCHED; PG8_LDA(At, 0, 0); PG8_STAGE(PG8_SA(1, 1), a1 + hstep, voffA);
;             PG8_WAIT_L(8); PG8_BAR; PG8_WAIT_L(0); PG8_MMA(0, 0, At, B0); PG8_BAR; PG8_SCHED;
;             PG8_LDB(B1, 0, 1); PG8_STAGE(PG8_SB(0, 0), b2, voffB);
;             PG8_BAR; PG8_WAIT_L(0); PG8_MMA(0, 1, At, B1); PG8_BAR;
;             PG8_LDA(At, 0, 1); PG8_STAGE(PG8_SA(0, 0), a2, voffA);
;             PG8_BAR; PG8_WAIT_L(0); PG8_MMA(1, 0, At, B0); PG8_BAR; PG8_SCHED;
;             PG8_STAGE(PG8_SB(0, 1), b2 + hstep, voffB);
;             PG8_WAIT_V(6); PG8_BAR; PG8_MMA(1, 1, At, B1); PG8_BAR;
.LBB0_1340:
	s_add_u32 s14, s24, 0xfffc0080
	s_addc_u32 s15, s25, -1
	s_add_i32 s16, 0, 0x10000
	ds_read_b128 v[158:161], v248
	ds_read_b128 v[162:165], v248 offset:1024
	ds_read_b128 v[170:173], v248 offset:2048
	ds_read_b128 v[174:177], v248 offset:3072
	s_cmp_eq_u32 s61, 12
	s_cselect_b32 s31, s7, s15
	s_cselect_b32 s30, s57, s14
	s_cselect_b32 s27, s5, s60
	s_cselect_b32 s26, s58, s59
	s_add_i32 m0, s23, 0xc000
	ds_read_b128 v[178:181], v168
	ds_read_b128 v[192:195], v168 offset:1024
	ds_read_b128 v[196:199], v168 offset:2048
	ds_read_b128 v[200:203], v168 offset:3072
	ds_read_b128 v[204:207], v168 offset:4096
	ds_read_b128 v[208:211], v168 offset:5120
	ds_read_b128 v[212:215], v168 offset:6144
	global_load_lds_dwordx4 v154, s[24:25]
	s_add_i32 m0, s23, 0xe000
	ds_read_b128 v[216:219], v168 offset:7168
	global_load_lds_dwordx4 v156, s[24:25]
	s_waitcnt lgkmcnt(8)
	s_barrier
	s_waitcnt lgkmcnt(0)
	v_mfma_f32_16x16x32_bf16 v[124:127], v[158:161], v[178:181], v[124:127]
	v_mfma_f32_16x16x32_bf16 v[120:123], v[170:173], v[178:181], v[120:123]
	v_mfma_f32_16x16x32_bf16 v[108:111], v[158:161], v[196:199], v[108:111]
	v_mfma_f32_16x16x32_bf16 v[104:107], v[170:173], v[196:199], v[104:107]
	v_mfma_f32_16x16x32_bf16 v[92:95], v[158:161], v[204:207], v[92:95]
	v_mfma_f32_16x16x32_bf16 v[88:91], v[170:173], v[204:207], v[88:91]
	v_mfma_f32_16x16x32_bf16 v[76:79], v[158:161], v[212:215], v[76:79]
	v_mfma_f32_16x16x32_bf16 v[72:75], v[170:173], v[212:215], v[72:75]
	v_mfma_f32_16x16x32_bf16 v[124:127], v[162:165], v[192:195], v[124:127]
	v_mfma_f32_16x16x32_bf16 v[120:123], v[174:177], v[192:195], v[120:123]
	v_mfma_f32_16x16x32_bf16 v[108:111], v[162:165], v[200:203], v[108:111]
	v_mfma_f32_16x16x32_bf16 v[104:107], v[174:177], v[200:203], v[104:107]
	v_mfma_f32_16x16x32_bf16 v[92:95], v[162:165], v[208:211], v[92:95]
	v_mfma_f32_16x16x32_bf16 v[88:91], v[174:177], v[208:211], v[88:91]
	v_mfma_f32_16x16x32_bf16 v[76:79], v[162:165], v[216:219], v[76:79]
	v_mfma_f32_16x16x32_bf16 v[72:75], v[174:177], v[216:219], v[72:75]
	s_barrier
	s_add_i32 s17, 0, 0x14000
	s_add_i32 s14, s16, s43
	s_mov_b32 m0, s14
	ds_read_b128 v[220:223], v249
	ds_read_b128 v[224:227], v249 offset:1024
	ds_read_b128 v[228:231], v249 offset:2048
	global_load_lds_dwordx4 v128, s[26:27]
	s_add_i32 m0, s14, 0x2000
	ds_read_b128 v[232:235], v249 offset:3072
	global_load_lds_dwordx4 v148, s[26:27]
	s_barrier
	s_waitcnt lgkmcnt(0)
	v_mfma_f32_16x16x32_bf16 v[116:119], v[220:223], v[178:181], v[116:119]
	v_mfma_f32_16x16x32_bf16 v[112:115], v[228:231], v[178:181], v[112:115]
	v_mfma_f32_16x16x32_bf16 v[100:103], v[220:223], v[196:199], v[100:103]
	v_mfma_f32_16x16x32_bf16 v[96:99], v[228:231], v[196:199], v[96:99]
	v_mfma_f32_16x16x32_bf16 v[84:87], v[220:223], v[204:207], v[84:87]
	v_mfma_f32_16x16x32_bf16 v[80:83], v[228:231], v[204:207], v[80:83]
	v_mfma_f32_16x16x32_bf16 v[68:71], v[220:223], v[212:215], v[68:71]
	v_mfma_f32_16x16x32_bf16 v[64:67], v[228:231], v[212:215], v[64:67]
	v_mfma_f32_16x16x32_bf16 v[116:119], v[224:227], v[192:195], v[116:119]
	v_mfma_f32_16x16x32_bf16 v[112:115], v[232:235], v[192:195], v[112:115]
	v_mfma_f32_16x16x32_bf16 v[100:103], v[224:227], v[200:203], v[100:103]
	v_mfma_f32_16x16x32_bf16 v[96:99], v[232:235], v[200:203], v[96:99]
	v_mfma_f32_16x16x32_bf16 v[84:87], v[224:227], v[208:211], v[84:87]
	v_mfma_f32_16x16x32_bf16 v[80:83], v[232:235], v[208:211], v[80:83]
	v_mfma_f32_16x16x32_bf16 v[68:71], v[224:227], v[216:219], v[68:71]
	v_mfma_f32_16x16x32_bf16 v[64:67], v[232:235], v[216:219], v[64:67]
	s_mov_b32 m0, s23
	s_barrier
	ds_read_b128 v[178:181], v168 offset:16384
	ds_read_b128 v[192:195], v168 offset:17408
	ds_read_b128 v[196:199], v168 offset:18432
	ds_read_b128 v[200:203], v168 offset:19456
	ds_read_b128 v[204:207], v168 offset:20480
	ds_read_b128 v[208:211], v168 offset:21504
	ds_read_b128 v[212:215], v168 offset:22528
	global_load_lds_dwordx4 v152, s[30:31]
	s_mov_b32 m0, s45
	ds_read_b128 v[216:219], v168 offset:23552
	global_load_lds_dwordx4 v150, s[30:31]
	s_barrier
	s_waitcnt lgkmcnt(0)
	v_mfma_f32_16x16x32_bf16 v[60:63], v[158:161], v[178:181], v[60:63]
	v_mfma_f32_16x16x32_bf16 v[56:59], v[170:173], v[178:181], v[56:59]
	v_mfma_f32_16x16x32_bf16 v[44:47], v[158:161], v[196:199], v[44:47]
	v_mfma_f32_16x16x32_bf16 v[40:43], v[170:173], v[196:199], v[40:43]
	v_mfma_f32_16x16x32_bf16 v[28:31], v[158:161], v[204:207], v[28:31]
	v_mfma_f32_16x16x32_bf16 v[24:27], v[170:173], v[204:207], v[24:27]
	v_mfma_f32_16x16x32_bf16 v[12:15], v[158:161], v[212:215], v[12:15]
	v_mfma_f32_16x16x32_bf16 v[8:11], v[170:173], v[212:215], v[8:11]
	v_mfma_f32_16x16x32_bf16 v[60:63], v[162:165], v[192:195], v[60:63]
	v_mfma_f32_16x16x32_bf16 v[56:59], v[174:177], v[192:195], v[56:59]
	v_mfma_f32_16x16x32_bf16 v[44:47], v[162:165], v[200:203], v[44:47]
	v_mfma_f32_16x16x32_bf16 v[40:43], v[174:177], v[200:203], v[40:43]
	v_mfma_f32_16x16x32_bf16 v[28:31], v[162:165], v[208:211], v[28:31]
	v_mfma_f32_16x16x32_bf16 v[24:27], v[174:177], v[208:211], v[24:27]
	v_mfma_f32_16x16x32_bf16 v[12:15], v[162:165], v[216:219], v[12:15]
	v_mfma_f32_16x16x32_bf16 v[8:11], v[174:177], v[216:219], v[8:11]
	s_barrier
	s_add_u32 s14, s26, 0x40000
	s_addc_u32 s15, s27, 0
	s_add_i32 s16, s17, s43
	s_mov_b32 m0, s16
	s_nop 0
	global_load_lds_dwordx4 v128, s[14:15]
	s_add_i32 m0, s16, 0x2000
	s_nop 0
	global_load_lds_dwordx4 v148, s[14:15]
	s_add_i32 s61, s61, 2
	s_add_u32 s24, s24, 0x100
	s_addc_u32 s25, s25, 0
	s_add_u32 s59, s59, 0x100
	s_addc_u32 s60, s60, 0
	s_waitcnt vmcnt(6)
	s_barrier
; #define PG8_STAGE(bufoff, gbase, voff) do { _Pragma("unroll") for (int _i = 0; _i < 2; ++_i) \
;         __builtin_amdgcn_global_load_lds((const unsigned*)((const char*)(gbase) + (voff)[_i]), (PG8_LAS unsigned*)(lds + (bufoff) + ldsw + _i * 8192), 16, 0, 0); } while (0)
; #define PG8_LDA(dst, b, h) do { _Pragma("unroll") for (int m = 0; m < 4; ++m) _Pragma("unroll") for (int k = 0; k < 2; ++k) dst[m][k] = *(const PG8_LAS bf16x8*)(lds + PG8_SA(b, h) + aoff + m * 2048 + k * 1024); } while (0)
; #define PG8_LDB(dst, b, h) do { _Pragma("unroll") for (int n = 0; n < 2; ++n) _Pragma("unroll") for (int k = 0; k < 2; ++k) dst[n][k] = *(const PG8_LAS bf16x8*)(lds + PG8_SB(b, h) + boff + n * 2048 + k * 1024); } while (0)
; #define PG8_MMA(ai, bj, At, Bt) do { __builtin_amdgcn_s_setprio(1); _Pragma("unroll") for (int m = 0; m < 4; ++m) _Pragma("unroll") for (int n = 0; n < 2; ++n) _Pragma("unroll") for (int k = 0; k < 2; ++k) \
;         acc[ai][bj][m][n] = __builtin_amdgcn_mfma_f32_16x16x32_bf16(Bt[n][k], At[m][k], acc[ai][bj][m][n], 0, 0, 0); __builtin_amdgcn_s_setprio(0); } while (0)
; #define PG8_WAIT_V(n) asm volatile("s_waitcnt vmcnt(" #n ")" ::: "memory")
; #define PG8_WAIT_L(n) asm volatile("s_waitcnt lgkmcnt(" #n ")" ::: "memory")
; #define PG8_BAR __builtin_amdgcn_s_barrier()
; #define PG8_SCHED __builtin_amdgcn_sched_barrier(0)
; template <class Epi, class Sched, bool STAMP = false>
; __device__ __forceinline__ void gemm_phase(PG8_LAS unsigned char* lds, const Gemm g, const Sched& S, const Epi& E, unsigned long long* stamps) {
;     ...
;             PG8_WAIT_V(6); PG8_BAR; PG8_MMA(1, 1, At, B1); PG8_BAR;
;             PG8_LDB(B0, 1, 0); PG8_SCHED; PG8_LDA(At, 1, 0); PG8_STAGE(PG8_SA(0, 1), a2 + hstep, voffA);
;             PG8_WAIT_L(8); PG8_BAR; PG8_WAIT_L(0); PG8_MMA(0, 0, At, B0); PG8_BAR; PG8_SCHED;
;             PG8_LDB(B1, 1, 1); PG8_STAGE(PG8_SB(1, 0), b3, voffB);
;             PG8_BAR; PG8_WAIT_L(0); PG8_MMA(0, 1, At, B1); PG8_BAR;
;             PG8_LDA(At, 1, 1); PG8_STAGE(PG8_SA(1, 0), a3, voffA);
;             PG8_BAR; PG8_WAIT_L(0); PG8_MMA(1, 0, At, B0); PG8_BAR; PG8_SCHED;
	v_mfma_f32_16x16x32_bf16 v[52:55], v[220:223], v[178:181], v[52:55]
	v_mfma_f32_16x16x32_bf16 v[48:51], v[228:231], v[178:181], v[48:51]
	v_mfma_f32_16x16x32_bf16 v[36:39], v[220:223], v[196:199], v[36:39]
	v_mfma_f32_16x16x32_bf16 v[32:35], v[228:231], v[196:199], v[32:35]
	v_mfma_f32_16x16x32_bf16 v[20:23], v[220:223], v[204:207], v[20:23]
	v_mfma_f32_16x16x32_bf16 v[16:19], v[228:231], v[204:207], v[16:19]
	v_mfma_f32_16x16x32_bf16 v[4:7], v[220:223], v[212:215], v[4:7]
	v_mfma_f32_16x16x32_bf16 v[0:3], v[228:231], v[212:215], v[0:3]
	v_mfma_f32_16x16x32_bf16 v[52:55], v[224:227], v[192:195], v[52:55]
	v_mfma_f32_16x16x32_bf16 v[48:51], v[232:235], v[192:195], v[48:51]
	v_mfma_f32_16x16x32_bf16 v[36:39], v[224:227], v[200:203], v[36:39]
	v_mfma_f32_16x16x32_bf16 v[32:35], v[232:235], v[200:203], v[32:35]
	v_mfma_f32_16x16x32_bf16 v[20:23], v[224:227], v[208:211], v[20:23]
	v_mfma_f32_16x16x32_bf16 v[16:19], v[232:235], v[208:211], v[16:19]
	v_mfma_f32_16x16x32_bf16 v[4:7], v[224:227], v[216:219], v[4:7]
	v_mfma_f32_16x16x32_bf16 v[0:3], v[232:235], v[216:219], v[0:3]
	s_add_i32 s16, 0, 0x18000
	s_barrier
	ds_read_b128 v[158:161], v250
	ds_read_b128 v[162:165], v250 offset:1024
	ds_read_b128 v[170:173], v250 offset:2048
	ds_read_b128 v[174:177], v250 offset:3072
	s_add_u32 s14, s30, 0x40000
	s_addc_u32 s15, s31, 0
	s_mov_b32 m0, s46
	ds_read_b128 v[178:181], v168 offset:32768
	ds_read_b128 v[192:195], v168 offset:33792
	ds_read_b128 v[196:199], v168 offset:34816
	ds_read_b128 v[200:203], v168 offset:35840
	ds_read_b128 v[204:207], v168 offset:36864
	ds_read_b128 v[208:211], v168 offset:37888
	ds_read_b128 v[212:215], v168 offset:38912
	global_load_lds_dwordx4 v152, s[14:15]
	s_mov_b32 m0, s47
	ds_read_b128 v[216:219], v168 offset:39936
	global_load_lds_dwordx4 v150, s[14:15]
	s_waitcnt lgkmcnt(8)
	s_barrier
	s_waitcnt lgkmcnt(0)
	v_mfma_f32_16x16x32_bf16 v[124:127], v[158:161], v[178:181], v[124:127]
	v_mfma_f32_16x16x32_bf16 v[120:123], v[170:173], v[178:181], v[120:123]
	v_mfma_f32_16x16x32_bf16 v[108:111], v[158:161], v[196:199], v[108:111]
	v_mfma_f32_16x16x32_bf16 v[104:107], v[170:173], v[196:199], v[104:107]
	v_mfma_f32_16x16x32_bf16 v[92:95], v[158:161], v[204:207], v[92:95]
	v_mfma_f32_16x16x32_bf16 v[88:91], v[170:173], v[204:207], v[88:91]
	v_mfma_f32_16x16x32_bf16 v[76:79], v[158:161], v[212:215], v[76:79]
	v_mfma_f32_16x16x32_bf16 v[72:75], v[170:173], v[212:215], v[72:75]
	v_mfma_f32_16x16x32_bf16 v[124:127], v[162:165], v[192:195], v[124:127]
	v_mfma_f32_16x16x32_bf16 v[120:123], v[174:177], v[192:195], v[120:123]
	v_mfma_f32_16x16x32_bf16 v[108:111], v[162:165], v[200:203], v[108:111]
	v_mfma_f32_16x16x32_bf16 v[104:107], v[174:177], v[200:203], v[104:107]
	v_mfma_f32_16x16x32_bf16 v[92:95], v[162:165], v[208:211], v[92:95]
	v_mfma_f32_16x16x32_bf16 v[88:91], v[174:177], v[208:211], v[88:91]
	v_mfma_f32_16x16x32_bf16 v[76:79], v[162:165], v[216:219], v[76:79]
	v_mfma_f32_16x16x32_bf16 v[72:75], v[174:177], v[216:219], v[72:75]
	s_barrier
	s_add_i32 s17, 0, 0x1c000
	s_add_i32 s14, s16, s43
	s_mov_b32 m0, s14
	ds_read_b128 v[220:223], v251
	ds_read_b128 v[224:227], v251 offset:1024
	ds_read_b128 v[228:231], v251 offset:2048
	global_load_lds_dwordx4 v244, s[26:27]
	s_add_i32 m0, s14, 0x2000
	ds_read_b128 v[232:235], v251 offset:3072
	global_load_lds_dwordx4 v245, s[26:27]
	s_barrier
	s_waitcnt lgkmcnt(0)
	v_mfma_f32_16x16x32_bf16 v[116:119], v[220:223], v[178:181], v[116:119]
	v_mfma_f32_16x16x32_bf16 v[112:115], v[228:231], v[178:181], v[112:115]
	v_mfma_f32_16x16x32_bf16 v[100:103], v[220:223], v[196:199], v[100:103]
	v_mfma_f32_16x16x32_bf16 v[96:99], v[228:231], v[196:199], v[96:99]
	v_mfma_f32_16x16x32_bf16 v[84:87], v[220:223], v[204:207], v[84:87]
	v_mfma_f32_16x16x32_bf16 v[80:83], v[228:231], v[204:207], v[80:83]
	v_mfma_f32_16x16x32_bf16 v[68:71], v[220:223], v[212:215], v[68:71]
	v_mfma_f32_16x16x32_bf16 v[64:67], v[228:231], v[212:215], v[64:67]
	v_mfma_f32_16x16x32_bf16 v[116:119], v[224:227], v[192:195], v[116:119]
	v_mfma_f32_16x16x32_bf16 v[112:115], v[232:235], v[192:195], v[112:115]
	v_mfma_f32_16x16x32_bf16 v[100:103], v[224:227], v[200:203], v[100:103]
	v_mfma_f32_16x16x32_bf16 v[96:99], v[232:235], v[200:203], v[96:99]
	v_mfma_f32_16x16x32_bf16 v[84:87], v[224:227], v[208:211], v[84:87]
	v_mfma_f32_16x16x32_bf16 v[80:83], v[232:235], v[208:211], v[80:83]
	v_mfma_f32_16x16x32_bf16 v[68:71], v[224:227], v[216:219], v[68:71]
	v_mfma_f32_16x16x32_bf16 v[64:67], v[232:235], v[216:219], v[64:67]
	s_mov_b32 m0, s48
	s_barrier
	ds_read_b128 v[178:181], v168 offset:49152
	ds_read_b128 v[192:195], v168 offset:50176
	ds_read_b128 v[196:199], v168 offset:51200
	ds_read_b128 v[200:203], v168 offset:52224
	ds_read_b128 v[204:207], v168 offset:53248
	ds_read_b128 v[208:211], v168 offset:54272
	ds_read_b128 v[212:215], v168 offset:55296
	global_load_lds_dwordx4 v246, s[30:31]
	s_mov_b32 m0, s49
	ds_read_b128 v[216:219], v168 offset:56320
	global_load_lds_dwordx4 v247, s[30:31]
	s_barrier
	s_waitcnt lgkmcnt(0)
	v_mfma_f32_16x16x32_bf16 v[60:63], v[158:161], v[178:181], v[60:63]
	v_mfma_f32_16x16x32_bf16 v[56:59], v[170:173], v[178:181], v[56:59]
	v_mfma_f32_16x16x32_bf16 v[44:47], v[158:161], v[196:199], v[44:47]
	v_mfma_f32_16x16x32_bf16 v[40:43], v[170:173], v[196:199], v[40:43]
	v_mfma_f32_16x16x32_bf16 v[28:31], v[158:161], v[204:207], v[28:31]
	v_mfma_f32_16x16x32_bf16 v[24:27], v[170:173], v[204:207], v[24:27]
	v_mfma_f32_16x16x32_bf16 v[12:15], v[158:161], v[212:215], v[12:15]
	v_mfma_f32_16x16x32_bf16 v[8:11], v[170:173], v[212:215], v[8:11]
	v_mfma_f32_16x16x32_bf16 v[60:63], v[162:165], v[192:195], v[60:63]
	v_mfma_f32_16x16x32_bf16 v[56:59], v[174:177], v[192:195], v[56:59]
	v_mfma_f32_16x16x32_bf16 v[44:47], v[162:165], v[200:203], v[44:47]
	v_mfma_f32_16x16x32_bf16 v[40:43], v[174:177], v[200:203], v[40:43]
	v_mfma_f32_16x16x32_bf16 v[28:31], v[162:165], v[208:211], v[28:31]
	v_mfma_f32_16x16x32_bf16 v[24:27], v[174:177], v[208:211], v[24:27]
	v_mfma_f32_16x16x32_bf16 v[12:15], v[162:165], v[216:219], v[12:15]
	v_mfma_f32_16x16x32_bf16 v[8:11], v[174:177], v[216:219], v[8:11]
	s_barrier
; __device__ __forceinline__ unsigned cvt_pk_bf16(float lo, float hi) { const f32x2_cv v = {lo, hi}; const bf16x2_cv b = __builtin_convertvector(v, bf16x2_cv); return __builtin_bit_cast(unsigned, b); }
; #define PG8_STAGE(bufoff, gbase, voff) do { _Pragma("unroll") for (int _i = 0; _i < 2; ++_i) \
;         __builtin_amdgcn_global_load_lds((const unsigned*)((const char*)(gbase) + (voff)[_i]), (PG8_LAS unsigned*)(lds + (bufoff) + ldsw + _i * 8192), 16, 0, 0); } while (0)
; #define PG8_MMA(ai, bj, At, Bt) do { __builtin_amdgcn_s_setprio(1); _Pragma("unroll") for (int m = 0; m < 4; ++m) _Pragma("unroll") for (int n = 0; n < 2; ++n) _Pragma("unroll") for (int k = 0; k < 2; ++k) \
;         acc[ai][bj][m][n] = __builtin_amdgcn_mfma_f32_16x16x32_bf16(Bt[n][k], At[m][k], acc[ai][bj][m][n], 0, 0, 0); __builtin_amdgcn_s_setprio(0); } while (0)
; #define PG8_WAIT_V(n) asm volatile("s_waitcnt vmcnt(" #n ")" ::: "memory")
; template <class Epi, class Sched, bool STAMP = false>
; __device__ __forceinline__ void gemm_phase(PG8_LAS unsigned char* lds, const Gemm g, const Sched& S, const Epi& E, unsigned long long* stamps) {
;     ...
;             PG8_STAGE(PG8_SB(1, 1), b3 + hstep, voffB);
;             PG8_WAIT_V(6); PG8_BAR; PG8_MMA(1, 1, At, B1); PG8_BAR;
;     __device__ __forceinline__ void operator()(const f32x4 (&acc)[2][2][4][2], const pg8::Unit& u, int wr, int wc, int fr, int fq) const {
;         const int row0 = u.pm * 256 + wr * 64 + fr, col0 = u.pn * 256 + wc * 32 + 8 * fq;
; #pragma unroll
;         for (int ai = 0; ai < 2; ++ai)
; #pragma unroll
;             for (int m = 0; m < 4; ++m) {
;                 const int row = row0 + ai * 128 + m * 16;
;                 const float s = (MODE == 2) ? 1.0f : rstd_of(rowss, row);
;                 bf16_t* rowp = O + (size_t)row * ldc + col0;
; #pragma unroll
;                 for (int bj = 0; bj < 2; ++bj) {
;                     f32x4 v0 = acc[ai][bj][m][0] * s, v1 = acc[ai][bj][m][1] * s;
;                     if (MODE == 1) {
; #pragma unroll
;                         for (int j = 0; j < 4; ++j) { const float a = fmaxf(v0[j], 0.f), b = fmaxf(v1[j], 0.f); v0[j] = a * a; v1[j] = b * b; } }
;                     u32x4 w; w.x = cvt_pk_bf16(v0[0], v0[1]); w.y = cvt_pk_bf16(v0[2], v0[3]); w.z = cvt_pk_bf16(v1[0], v1[1]); w.w = cvt_pk_bf16(v1[2], v1[3]);
;                     *(u32x4*)(rowp + bj * 128) = w; } }
	s_add_u32 s14, s26, 0x40080
	s_addc_u32 s15, s27, 0
	s_add_i32 s16, s17, s43
	s_mov_b32 m0, s16
	s_nop 0
	global_load_lds_dwordx4 v128, s[14:15]
	s_add_i32 m0, s16, 0x2000
	s_nop 0
	global_load_lds_dwordx4 v148, s[14:15]
	s_waitcnt vmcnt(6)
	s_barrier
	v_mfma_f32_16x16x32_bf16 v[52:55], v[220:223], v[178:181], v[52:55]
	v_mfma_f32_16x16x32_bf16 v[48:51], v[228:231], v[178:181], v[48:51]
	v_mfma_f32_16x16x32_bf16 v[36:39], v[220:223], v[196:199], v[36:39]
	v_mfma_f32_16x16x32_bf16 v[32:35], v[228:231], v[196:199], v[32:35]
	v_mfma_f32_16x16x32_bf16 v[20:23], v[220:223], v[204:207], v[20:23]
	v_mfma_f32_16x16x32_bf16 v[16:19], v[228:231], v[204:207], v[16:19]
	v_mfma_f32_16x16x32_bf16 v[4:7], v[220:223], v[212:215], v[4:7]
	v_mfma_f32_16x16x32_bf16 v[0:3], v[228:231], v[212:215], v[0:3]
	v_mfma_f32_16x16x32_bf16 v[52:55], v[224:227], v[192:195], v[52:55]
	v_mfma_f32_16x16x32_bf16 v[48:51], v[232:235], v[192:195], v[48:51]
	v_mfma_f32_16x16x32_bf16 v[36:39], v[224:227], v[200:203], v[36:39]
	v_mfma_f32_16x16x32_bf16 v[32:35], v[232:235], v[200:203], v[32:35]
	v_mfma_f32_16x16x32_bf16 v[20:23], v[224:227], v[208:211], v[20:23]
	v_mfma_f32_16x16x32_bf16 v[16:19], v[232:235], v[208:211], v[16:19]
	v_mfma_f32_16x16x32_bf16 v[4:7], v[224:227], v[216:219], v[4:7]
	v_mfma_f32_16x16x32_bf16 v[0:3], v[232:235], v[216:219], v[0:3]
	s_cmp_gt_u32 s61, 13
	s_barrier
	s_cbranch_scc0 .LBB0_1340
	v_lshl_add_u32 v162, s22, 8, v139
	v_ashrrev_i32_e32 v163, 31, v162
	v_lshl_add_u64 v[158:159], v[162:163], 2, s[0:1]
	global_load_dword v164, v[158:159], off
	global_load_dword v231, v[158:159], off offset:64
	global_load_dword v232, v[158:159], off offset:128
	global_load_dword v233, v[158:159], off offset:192
	global_load_dword v234, v[158:159], off offset:512
	global_load_dword v235, v[158:159], off offset:576
	global_load_dword v236, v[158:159], off offset:640
	global_load_dword v237, v[158:159], off offset:704
	v_lshl_or_b32 v160, s56, 8, v167
	v_ashrrev_i32_e32 v161, 31, v160
	s_mov_b32 s5, 0x80000
	s_mov_b64 s[14:15], 0x80000
	s_mov_b32 s56, s4
	s_mov_b32 s22, s6
	s_mov_b64 s[26:27], s[20:21]
	s_mov_b64 s[24:25], s[12:13]
	s_waitcnt vmcnt(0)
	v_fmamk_f32 v164, v164, 0x3a800000, v187
	v_cmp_gt_f32_e32 vcc, s67, v164
	v_mul_f32_e32 v165, 0x4b800000, v164
	s_nop 0
	v_cndmask_b32_e32 v164, v164, v165, vcc
	v_rsq_f32_e32 v164, v164
	s_nop 0
	v_mul_f32_e32 v165, 0x45800000, v164
	v_cndmask_b32_e32 v170, v164, v165, vcc
	v_lshlrev_b64 v[164:165], 12, v[162:163]
	v_lshl_add_u64 v[172:173], s[2:3], 0, v[164:165]
	v_lshlrev_b64 v[164:165], 1, v[160:161]
	v_lshl_add_u64 v[160:161], v[172:173], 0, v[164:165]
	v_pk_mul_f32 v[126:127], v[126:127], v[170:171] op_sel_hi:[1,0]
	v_pk_mul_f32 v[124:125], v[124:125], v[170:171] op_sel_hi:[1,0]
	v_pk_mul_f32 v[172:173], v[122:123], v[170:171] op_sel_hi:[1,0]
	v_pk_mul_f32 v[122:123], v[120:121], v[170:171] op_sel_hi:[1,0]
	v_cvt_pk_bf16_f32 v120, v124, v125
	v_cvt_pk_bf16_f32 v121, v126, v127
	v_cvt_pk_bf16_f32 v122, v122, v123
	v_cvt_pk_bf16_f32 v123, v172, v173
	global_store_dwordx4 v[160:161], v[120:123], off
	v_pk_mul_f32 v[118:119], v[118:119], v[170:171] op_sel_hi:[1,0]
	v_pk_mul_f32 v[116:117], v[116:117], v[170:171] op_sel_hi:[1,0]
	v_pk_mul_f32 v[120:121], v[114:115], v[170:171] op_sel_hi:[1,0]
	v_pk_mul_f32 v[114:115], v[112:113], v[170:171] op_sel_hi:[1,0]
	v_cvt_pk_bf16_f32 v112, v116, v117
	v_cvt_pk_bf16_f32 v113, v118, v119
	v_cvt_pk_bf16_f32 v114, v114, v115
	v_cvt_pk_bf16_f32 v115, v120, v121
	global_store_dwordx4 v[160:161], v[112:115], off offset:256
	s_nop 1
	v_mov_b32_e32 v114, v231
	s_nop 0
	v_or_b32_e32 v112, 16, v162
	v_ashrrev_i32_e32 v113, 31, v112
	v_lshlrev_b64 v[112:113], 12, v[112:113]
	v_lshl_add_u64 v[112:113], s[2:3], 0, v[112:113]
	v_lshl_add_u64 v[112:113], v[112:113], 0, v[164:165]
	v_fmamk_f32 v114, v114, 0x3a800000, v187
	v_cmp_gt_f32_e32 vcc, s67, v114
	v_mul_f32_e32 v115, 0x4b800000, v114
	s_nop 0
	v_cndmask_b32_e32 v114, v114, v115, vcc
	v_rsq_f32_e32 v114, v114
	s_nop 0
	v_mul_f32_e32 v115, 0x45800000, v114
	v_cndmask_b32_e32 v114, v114, v115, vcc
	v_pk_mul_f32 v[110:111], v[110:111], v[114:115] op_sel_hi:[1,0]
	v_pk_mul_f32 v[108:109], v[108:109], v[114:115] op_sel_hi:[1,0]
	v_pk_mul_f32 v[116:117], v[106:107], v[114:115] op_sel_hi:[1,0]
	v_pk_mul_f32 v[106:107], v[104:105], v[114:115] op_sel_hi:[1,0]
	v_cvt_pk_bf16_f32 v104, v108, v109
	v_cvt_pk_bf16_f32 v105, v110, v111
	v_cvt_pk_bf16_f32 v106, v106, v107
	v_cvt_pk_bf16_f32 v107, v116, v117
	global_store_dwordx4 v[112:113], v[104:107], off
	v_pk_mul_f32 v[102:103], v[102:103], v[114:115] op_sel_hi:[1,0]
	v_pk_mul_f32 v[100:101], v[100:101], v[114:115] op_sel_hi:[1,0]
	v_pk_mul_f32 v[104:105], v[98:99], v[114:115] op_sel_hi:[1,0]
	v_pk_mul_f32 v[98:99], v[96:97], v[114:115] op_sel_hi:[1,0]
	v_cvt_pk_bf16_f32 v96, v100, v101
	v_cvt_pk_bf16_f32 v97, v102, v103
	v_cvt_pk_bf16_f32 v98, v98, v99
	v_cvt_pk_bf16_f32 v99, v104, v105
	global_store_dwordx4 v[112:113], v[96:99], off offset:256
	s_nop 1
	v_mov_b32_e32 v98, v232
	s_nop 0
	v_or_b32_e32 v96, 32, v162
	v_ashrrev_i32_e32 v97, 31, v96
	v_lshlrev_b64 v[96:97], 12, v[96:97]
	v_lshl_add_u64 v[96:97], s[2:3], 0, v[96:97]
	v_lshl_add_u64 v[96:97], v[96:97], 0, v[164:165]
	v_fmamk_f32 v98, v98, 0x3a800000, v187
	v_cmp_gt_f32_e32 vcc, s67, v98
	v_mul_f32_e32 v99, 0x4b800000, v98
	s_nop 0
	v_cndmask_b32_e32 v98, v98, v99, vcc
	v_rsq_f32_e32 v98, v98
	s_nop 0
	v_mul_f32_e32 v99, 0x45800000, v98
	v_cndmask_b32_e32 v98, v98, v99, vcc
	v_pk_mul_f32 v[94:95], v[94:95], v[98:99] op_sel_hi:[1,0]
	v_pk_mul_f32 v[92:93], v[92:93], v[98:99] op_sel_hi:[1,0]
	v_pk_mul_f32 v[100:101], v[90:91], v[98:99] op_sel_hi:[1,0]
; __device__ __forceinline__ unsigned cvt_pk_bf16(float lo, float hi) { const f32x2_cv v = {lo, hi}; const bf16x2_cv b = __builtin_convertvector(v, bf16x2_cv); return __builtin_bit_cast(unsigned, b); }
; __device__ __forceinline__ float rstd_of(const float* rowss, int row) { return rsqrtf(rowss[row] * (1.0f / 1024.0f) + 1e-6f); }
;     __device__ __forceinline__ void operator()(const f32x4 (&acc)[2][2][4][2], const pg8::Unit& u, int wr, int wc, int fr, int fq) const {
;     ...
;             for (int m = 0; m < 4; ++m) {
;                 const int row = row0 + ai * 128 + m * 16;
;                 const float s = (MODE == 2) ? 1.0f : rstd_of(rowss, row);
;                 bf16_t* rowp = O + (size_t)row * ldc + col0;
; #pragma unroll
;                 for (int bj = 0; bj < 2; ++bj) {
;                     f32x4 v0 = acc[ai][bj][m][0] * s, v1 = acc[ai][bj][m][1] * s;
;                     if (MODE == 1) {
; #pragma unroll
;                         for (int j = 0; j < 4; ++j) { const float a = fmaxf(v0[j], 0.f), b = fmaxf(v1[j], 0.f); v0[j] = a * a; v1[j] = b * b; } }
;                     u32x4 w; w.x = cvt_pk_bf16(v0[0], v0[1]); w.y = cvt_pk_bf16(v0[2], v0[3]); w.z = cvt_pk_bf16(v1[0], v1[1]); w.w = cvt_pk_bf16(v1[2], v1[3]);
;                     *(u32x4*)(rowp + bj * 128) = w; } }
	v_pk_mul_f32 v[90:91], v[88:89], v[98:99] op_sel_hi:[1,0]
	v_cvt_pk_bf16_f32 v88, v92, v93
	v_cvt_pk_bf16_f32 v89, v94, v95
	v_cvt_pk_bf16_f32 v90, v90, v91
	v_cvt_pk_bf16_f32 v91, v100, v101
	global_store_dwordx4 v[96:97], v[88:91], off
	v_pk_mul_f32 v[86:87], v[86:87], v[98:99] op_sel_hi:[1,0]
	v_pk_mul_f32 v[84:85], v[84:85], v[98:99] op_sel_hi:[1,0]
	v_pk_mul_f32 v[88:89], v[82:83], v[98:99] op_sel_hi:[1,0]
	v_pk_mul_f32 v[82:83], v[80:81], v[98:99] op_sel_hi:[1,0]
	v_cvt_pk_bf16_f32 v80, v84, v85
	v_cvt_pk_bf16_f32 v81, v86, v87
	v_cvt_pk_bf16_f32 v82, v82, v83
	v_cvt_pk_bf16_f32 v83, v88, v89
	global_store_dwordx4 v[96:97], v[80:83], off offset:256
	s_nop 1
	v_mov_b32_e32 v82, v233
	s_nop 0
	v_or_b32_e32 v80, 48, v162
	v_ashrrev_i32_e32 v81, 31, v80
	v_lshlrev_b64 v[80:81], 12, v[80:81]
	v_lshl_add_u64 v[80:81], s[2:3], 0, v[80:81]
	v_lshl_add_u64 v[80:81], v[80:81], 0, v[164:165]
	v_fmamk_f32 v82, v82, 0x3a800000, v187
	v_cmp_gt_f32_e32 vcc, s67, v82
	v_mul_f32_e32 v83, 0x4b800000, v82
	s_nop 0
	v_cndmask_b32_e32 v82, v82, v83, vcc
	v_rsq_f32_e32 v82, v82
	s_nop 0
	v_mul_f32_e32 v83, 0x45800000, v82
	v_cndmask_b32_e32 v82, v82, v83, vcc
	v_pk_mul_f32 v[78:79], v[78:79], v[82:83] op_sel_hi:[1,0]
	v_pk_mul_f32 v[76:77], v[76:77], v[82:83] op_sel_hi:[1,0]
	v_pk_mul_f32 v[84:85], v[74:75], v[82:83] op_sel_hi:[1,0]
	v_pk_mul_f32 v[74:75], v[72:73], v[82:83] op_sel_hi:[1,0]
	v_cvt_pk_bf16_f32 v72, v76, v77
	v_cvt_pk_bf16_f32 v73, v78, v79
	v_cvt_pk_bf16_f32 v74, v74, v75
	v_cvt_pk_bf16_f32 v75, v84, v85
	global_store_dwordx4 v[80:81], v[72:75], off
	v_pk_mul_f32 v[70:71], v[70:71], v[82:83] op_sel_hi:[1,0]
	v_pk_mul_f32 v[68:69], v[68:69], v[82:83] op_sel_hi:[1,0]
	v_pk_mul_f32 v[72:73], v[66:67], v[82:83] op_sel_hi:[1,0]
	v_pk_mul_f32 v[66:67], v[64:65], v[82:83] op_sel_hi:[1,0]
	v_cvt_pk_bf16_f32 v64, v68, v69
	v_cvt_pk_bf16_f32 v65, v70, v71
	v_cvt_pk_bf16_f32 v66, v66, v67
	v_cvt_pk_bf16_f32 v67, v72, v73
	global_store_dwordx4 v[80:81], v[64:67], off offset:256
	s_nop 1
	v_mov_b32_e32 v64, v234
	s_nop 0
	v_lshl_add_u64 v[66:67], v[160:161], 0, s[14:15]
	s_mov_b64 s[14:15], 0x90000
	v_fmamk_f32 v64, v64, 0x3a800000, v187
	v_cmp_gt_f32_e32 vcc, s67, v64
	v_mul_f32_e32 v65, 0x4b800000, v64
	s_nop 0
	v_cndmask_b32_e32 v64, v64, v65, vcc
	v_rsq_f32_e32 v64, v64
	s_nop 0
	v_mul_f32_e32 v65, 0x45800000, v64
	v_cndmask_b32_e32 v64, v64, v65, vcc
	v_pk_mul_f32 v[60:61], v[60:61], v[64:65] op_sel_hi:[1,0]
	v_pk_mul_f32 v[62:63], v[62:63], v[64:65] op_sel_hi:[1,0]
	v_pk_mul_f32 v[68:69], v[58:59], v[64:65] op_sel_hi:[1,0]
	v_pk_mul_f32 v[58:59], v[56:57], v[64:65] op_sel_hi:[1,0]
	v_cvt_pk_bf16_f32 v56, v60, v61
	v_add_co_u32_e32 v60, vcc, s5, v160
	v_cvt_pk_bf16_f32 v57, v62, v63
	v_cvt_pk_bf16_f32 v58, v58, v59
	v_cvt_pk_bf16_f32 v59, v68, v69
	v_addc_co_u32_e32 v61, vcc, 0, v161, vcc
	global_store_dwordx4 v[60:61], v[56:59], off
	v_pk_mul_f32 v[54:55], v[54:55], v[64:65] op_sel_hi:[1,0]
	v_pk_mul_f32 v[52:53], v[52:53], v[64:65] op_sel_hi:[1,0]
	v_pk_mul_f32 v[56:57], v[50:51], v[64:65] op_sel_hi:[1,0]
	v_pk_mul_f32 v[50:51], v[48:49], v[64:65] op_sel_hi:[1,0]
	v_cvt_pk_bf16_f32 v48, v52, v53
	v_cvt_pk_bf16_f32 v49, v54, v55
	v_cvt_pk_bf16_f32 v50, v50, v51
	v_cvt_pk_bf16_f32 v51, v56, v57
	global_store_dwordx4 v[66:67], v[48:51], off offset:256
	s_nop 1
	v_mov_b32_e32 v48, v235
	s_mov_b32 s5, 0x90000
	v_lshl_add_u64 v[50:51], v[160:161], 0, s[14:15]
	s_mov_b64 s[14:15], 0xa0000
	v_fmamk_f32 v48, v48, 0x3a800000, v187
	v_cmp_gt_f32_e32 vcc, s67, v48
	v_mul_f32_e32 v49, 0x4b800000, v48
	s_nop 0
	v_cndmask_b32_e32 v48, v48, v49, vcc
	v_rsq_f32_e32 v48, v48
	s_nop 0
	v_mul_f32_e32 v49, 0x45800000, v48
; __device__ __forceinline__ unsigned cvt_pk_bf16(float lo, float hi) { const f32x2_cv v = {lo, hi}; const bf16x2_cv b = __builtin_convertvector(v, bf16x2_cv); return __builtin_bit_cast(unsigned, b); }
; #define PG8_WAIT_V(n) asm volatile("s_waitcnt vmcnt(" #n ")" ::: "memory")
; #define PG8_BAR __builtin_amdgcn_s_barrier()
; __device__ __forceinline__ float rstd_of(const float* rowss, int row) { return rsqrtf(rowss[row] * (1.0f / 1024.0f) + 1e-6f); }
; template <class Epi, class Sched, bool STAMP = false>
; __device__ __forceinline__ void gemm_phase(PG8_LAS unsigned char* lds, const Gemm g, const Sched& S, const Epi& E, unsigned long long* stamps) {
;     ...
;         if (!has_next) break;
; #pragma unroll
;         for (int a = 0; a < 2; ++a)
; #pragma unroll
;             for (int b = 0; b < 2; ++b)
; #pragma unroll
;                 for (int m = 0; m < 4; ++m)
; #pragma unroll
;                     for (int n = 0; n < 2; ++n) acc[a][b][m][n] = (f32x4){0.f, 0.f, 0.f, 0.f};
;         cur = nxt; cA = nA; cB = nB; ++ui;
;     }
;     PG8_WAIT_V(0);
;     if (wr == 0) PG8_BAR;
;     PG8_BAR;
;     __device__ __forceinline__ void operator()(const f32x4 (&acc)[2][2][4][2], const pg8::Unit& u, int wr, int wc, int fr, int fq) const {
;     ...
;             for (int m = 0; m < 4; ++m) {
;                 const int row = row0 + ai * 128 + m * 16;
;                 const float s = (MODE == 2) ? 1.0f : rstd_of(rowss, row);
;                 bf16_t* rowp = O + (size_t)row * ldc + col0;
; #pragma unroll
;                 for (int bj = 0; bj < 2; ++bj) {
;                     f32x4 v0 = acc[ai][bj][m][0] * s, v1 = acc[ai][bj][m][1] * s;
;                     if (MODE == 1) {
; #pragma unroll
;                         for (int j = 0; j < 4; ++j) { const float a = fmaxf(v0[j], 0.f), b = fmaxf(v1[j], 0.f); v0[j] = a * a; v1[j] = b * b; } }
;                     u32x4 w; w.x = cvt_pk_bf16(v0[0], v0[1]); w.y = cvt_pk_bf16(v0[2], v0[3]); w.z = cvt_pk_bf16(v1[0], v1[1]); w.w = cvt_pk_bf16(v1[2], v1[3]);
;                     *(u32x4*)(rowp + bj * 128) = w; } }
	v_cndmask_b32_e32 v48, v48, v49, vcc
	v_pk_mul_f32 v[44:45], v[44:45], v[48:49] op_sel_hi:[1,0]
	v_pk_mul_f32 v[46:47], v[46:47], v[48:49] op_sel_hi:[1,0]
	v_pk_mul_f32 v[52:53], v[42:43], v[48:49] op_sel_hi:[1,0]
	v_pk_mul_f32 v[42:43], v[40:41], v[48:49] op_sel_hi:[1,0]
	v_cvt_pk_bf16_f32 v40, v44, v45
	v_add_co_u32_e32 v44, vcc, s5, v160
	v_cvt_pk_bf16_f32 v41, v46, v47
	v_cvt_pk_bf16_f32 v42, v42, v43
	v_cvt_pk_bf16_f32 v43, v52, v53
	v_addc_co_u32_e32 v45, vcc, 0, v161, vcc
	global_store_dwordx4 v[44:45], v[40:43], off
	v_pk_mul_f32 v[38:39], v[38:39], v[48:49] op_sel_hi:[1,0]
	v_pk_mul_f32 v[36:37], v[36:37], v[48:49] op_sel_hi:[1,0]
	v_pk_mul_f32 v[40:41], v[34:35], v[48:49] op_sel_hi:[1,0]
	v_pk_mul_f32 v[34:35], v[32:33], v[48:49] op_sel_hi:[1,0]
	v_cvt_pk_bf16_f32 v32, v36, v37
	v_cvt_pk_bf16_f32 v33, v38, v39
	v_cvt_pk_bf16_f32 v34, v34, v35
	v_cvt_pk_bf16_f32 v35, v40, v41
	global_store_dwordx4 v[50:51], v[32:35], off offset:256
	s_nop 1
	v_mov_b32_e32 v32, v236
	s_mov_b32 s5, 0xa0000
	v_lshl_add_u64 v[34:35], v[160:161], 0, s[14:15]
	s_mov_b64 s[14:15], 0xb0000
	v_fmamk_f32 v32, v32, 0x3a800000, v187
	v_cmp_gt_f32_e32 vcc, s67, v32
	v_mul_f32_e32 v33, 0x4b800000, v32
	s_nop 0
	v_cndmask_b32_e32 v32, v32, v33, vcc
	v_rsq_f32_e32 v32, v32
	s_nop 0
	v_mul_f32_e32 v33, 0x45800000, v32
	v_cndmask_b32_e32 v32, v32, v33, vcc
	v_pk_mul_f32 v[28:29], v[28:29], v[32:33] op_sel_hi:[1,0]
	v_pk_mul_f32 v[30:31], v[30:31], v[32:33] op_sel_hi:[1,0]
	v_pk_mul_f32 v[36:37], v[26:27], v[32:33] op_sel_hi:[1,0]
	v_pk_mul_f32 v[26:27], v[24:25], v[32:33] op_sel_hi:[1,0]
	v_cvt_pk_bf16_f32 v24, v28, v29
	v_add_co_u32_e32 v28, vcc, s5, v160
	v_cvt_pk_bf16_f32 v25, v30, v31
	v_cvt_pk_bf16_f32 v26, v26, v27
	v_cvt_pk_bf16_f32 v27, v36, v37
	v_addc_co_u32_e32 v29, vcc, 0, v161, vcc
	global_store_dwordx4 v[28:29], v[24:27], off
	v_pk_mul_f32 v[22:23], v[22:23], v[32:33] op_sel_hi:[1,0]
	v_pk_mul_f32 v[20:21], v[20:21], v[32:33] op_sel_hi:[1,0]
	v_pk_mul_f32 v[24:25], v[18:19], v[32:33] op_sel_hi:[1,0]
	v_pk_mul_f32 v[18:19], v[16:17], v[32:33] op_sel_hi:[1,0]
	v_cvt_pk_bf16_f32 v16, v20, v21
	v_cvt_pk_bf16_f32 v17, v22, v23
	v_cvt_pk_bf16_f32 v18, v18, v19
	v_cvt_pk_bf16_f32 v19, v24, v25
	global_store_dwordx4 v[34:35], v[16:19], off offset:256
	s_nop 1
	v_mov_b32_e32 v16, v237
	s_mov_b32 s5, 0xb0000
	v_lshl_add_u64 v[18:19], v[160:161], 0, s[14:15]
	v_fmamk_f32 v16, v16, 0x3a800000, v187
	v_cmp_gt_f32_e32 vcc, s67, v16
	v_mul_f32_e32 v17, 0x4b800000, v16
	s_nop 0
	v_cndmask_b32_e32 v16, v16, v17, vcc
	v_rsq_f32_e32 v16, v16
	s_nop 0
	v_mul_f32_e32 v17, 0x45800000, v16
	v_cndmask_b32_e32 v16, v16, v17, vcc
	v_pk_mul_f32 v[12:13], v[12:13], v[16:17] op_sel_hi:[1,0]
	v_pk_mul_f32 v[14:15], v[14:15], v[16:17] op_sel_hi:[1,0]
	v_pk_mul_f32 v[20:21], v[10:11], v[16:17] op_sel_hi:[1,0]
	v_pk_mul_f32 v[10:11], v[8:9], v[16:17] op_sel_hi:[1,0]
	v_cvt_pk_bf16_f32 v8, v12, v13
	v_add_co_u32_e32 v12, vcc, s5, v160
	v_cvt_pk_bf16_f32 v9, v14, v15
	v_cvt_pk_bf16_f32 v10, v10, v11
	v_cvt_pk_bf16_f32 v11, v20, v21
	v_addc_co_u32_e32 v13, vcc, 0, v161, vcc
	global_store_dwordx4 v[12:13], v[8:11], off
	v_pk_mul_f32 v[6:7], v[6:7], v[16:17] op_sel_hi:[1,0]
	v_pk_mul_f32 v[4:5], v[4:5], v[16:17] op_sel_hi:[1,0]
	v_pk_mul_f32 v[8:9], v[2:3], v[16:17] op_sel_hi:[1,0]
	v_pk_mul_f32 v[2:3], v[0:1], v[16:17] op_sel_hi:[1,0]
	v_cvt_pk_bf16_f32 v0, v4, v5
	v_cvt_pk_bf16_f32 v1, v6, v7
	v_cvt_pk_bf16_f32 v2, v2, v3
	v_cvt_pk_bf16_f32 v3, v8, v9
	s_and_b64 vcc, exec, s[38:39]
	global_store_dwordx4 v[18:19], v[0:3], off offset:256
	s_cbranch_vccz .LBB0_1337
	s_waitcnt vmcnt(0)
	s_cmpk_gt_u32 s42, 0xff
	s_cbranch_scc1 .LBB0_1344
	s_barrier
